# converted bf16 weights stored write-through (sc0 sc1): fast store acknowledge in the conversion item loop, no L2 pollution
# baseline (speedup 1.0000x reference)
.LBB0_133:
	s_waitcnt vmcnt(0)
	ds_write2_b32 v22, v16, v17 offset1:66
	s_waitcnt vmcnt(28)
	ds_write2_b32 v22, v18, v19 offset0:132 offset1:198
	s_waitcnt vmcnt(26)
	ds_write2_b32 v28, v35, v36 offset0:8 offset1:74
	s_waitcnt vmcnt(24)
	ds_write2_b32 v28, v37, v38 offset0:140 offset1:206
	s_waitcnt vmcnt(22)
	ds_write2_b32 v29, v39, v40 offset0:16 offset1:82
	s_waitcnt vmcnt(20)
	ds_write2_b32 v29, v41, v42 offset0:148 offset1:214
	s_waitcnt vmcnt(18)
	ds_write2_b32 v30, v43, v44 offset0:24 offset1:90
	s_waitcnt vmcnt(16)
	ds_write2_b32 v30, v45, v46 offset0:156 offset1:222
	s_waitcnt vmcnt(14)
	ds_write2_b32 v31, v47, v48 offset0:32 offset1:98
	s_waitcnt vmcnt(12)
	ds_write2_b32 v31, v49, v50 offset0:164 offset1:230
	s_waitcnt vmcnt(10)
	ds_write2_b32 v32, v51, v52 offset0:40 offset1:106
	s_waitcnt vmcnt(8)
	ds_write2_b32 v32, v53, v54 offset0:172 offset1:238
	s_waitcnt vmcnt(6)
	ds_write2_b32 v33, v55, v56 offset0:48 offset1:114
	s_waitcnt vmcnt(4)
	ds_write2_b32 v33, v57, v58 offset0:180 offset1:246
	s_waitcnt vmcnt(2)
	ds_write2_b32 v34, v59, v60 offset0:56 offset1:122
	s_waitcnt vmcnt(0)
	ds_write2_b32 v34, v61, v62 offset0:188 offset1:254
	s_waitcnt lgkmcnt(0)
	ds_read2_b32 v[36:37], v24 offset1:8
	ds_read2_b32 v[38:39], v24 offset0:66 offset1:74
	ds_read2_b32 v[42:43], v24 offset0:33 offset1:41
	ds_read2_b32 v[44:45], v24 offset0:99 offset1:107
	ds_read2_b32 v[46:47], v24 offset0:132 offset1:140
	ds_read2_b32 v[48:49], v24 offset0:198 offset1:206
	ds_read2_b32 v[50:51], v24 offset0:165 offset1:173
	ds_read2_b32 v[52:53], v24 offset0:231 offset1:239
	s_waitcnt lgkmcnt(7)
	v_mov_b32_e32 v16, v36
	s_waitcnt lgkmcnt(5)
	v_mov_b32_e32 v18, v42
	s_waitcnt lgkmcnt(4)
	v_mov_b32_e32 v19, v44
	s_waitcnt lgkmcnt(3)
	v_mov_b32_e32 v54, v46
	s_waitcnt lgkmcnt(2)
	v_mov_b32_e32 v55, v48
	s_waitcnt lgkmcnt(1)
	v_mov_b32_e32 v56, v50
	s_waitcnt lgkmcnt(0)
	v_mov_b32_e32 v57, v52
	v_mov_b32_e32 v17, v38
	v_pk_mul_f32 v[18:19], v[2:3], v[18:19]
	v_pk_mul_f32 v[54:55], v[6:7], v[54:55]
	v_pk_mul_f32 v[56:57], v[4:5], v[56:57]
	v_pk_mul_f32 v[16:17], v[0:1], v[16:17]
	v_bfe_u32 v35, v57, 16, 1
	v_bfe_u32 v36, v56, 16, 1
	v_bfe_u32 v38, v19, 16, 1
	v_bfe_u32 v42, v18, 16, 1
	v_bfe_u32 v44, v54, 16, 1
	v_add3_u32 v42, v18, v42, s81
	v_add3_u32 v38, v19, v38, s81
	v_add3_u32 v18, v56, v36, s81
	v_add3_u32 v19, v57, v35, s81
	v_bfe_u32 v35, v16, 16, 1
	v_bfe_u32 v36, v17, 16, 1
	v_bfe_u32 v46, v55, 16, 1
	v_add3_u32 v44, v54, v44, s81
	v_add_u32_e32 v54, s43, v23
	s_ashr_i32 s35, s34, 31
	v_add3_u32 v46, v55, v46, s81
	v_add3_u32 v17, v17, v36, s81
	v_add3_u32 v16, v16, v35, s81
	v_ashrrev_i32_e32 v55, 31, v54
	v_lshl_add_u64 v[40:41], s[34:35], 1, v[14:15]
	v_lshrrev_b32_e32 v16, 16, v16
	v_lshrrev_b32_e32 v17, 16, v17
	v_lshrrev_b32_e32 v35, 16, v44
	v_lshrrev_b32_e32 v36, 16, v46
	v_lshlrev_b64 v[56:57], 11, v[54:55]
	v_and_or_b32 v19, v19, s71, v36
	v_and_or_b32 v18, v18, s71, v35
	v_and_or_b32 v17, v38, s71, v17
	v_and_or_b32 v16, v42, s71, v16
	v_lshl_add_u64 v[56:57], v[40:41], 0, v[56:57]
	v_mov_b32_e32 v38, v37
	v_mov_b32_e32 v44, v43
	v_mov_b32_e32 v52, v51
	global_store_dwordx4 v[56:57], v[16:19], off sc0 sc1
	v_mov_b32_e32 v48, v47
	v_pk_mul_f32 v[36:37], v[6:7], v[48:49]
	v_pk_mul_f32 v[16:17], v[0:1], v[38:39]
	v_pk_mul_f32 v[18:19], v[2:3], v[44:45]
	v_pk_mul_f32 v[38:39], v[4:5], v[52:53]
	v_bfe_u32 v43, v19, 16, 1
	v_bfe_u32 v35, v39, 16, 1
	v_bfe_u32 v42, v38, 16, 1
	v_bfe_u32 v44, v18, 16, 1
	v_add3_u32 v44, v18, v44, s81
	v_add3_u32 v43, v19, v43, s81
	v_add3_u32 v18, v38, v42, s81
	v_add3_u32 v19, v39, v35, s81
	v_bfe_u32 v39, v36, 16, 1
	v_bfe_u32 v42, v37, 16, 1
	v_bfe_u32 v35, v16, 16, 1
	v_add3_u32 v37, v37, v42, s81
	v_add3_u32 v36, v36, v39, s81
	v_add3_u32 v16, v16, v35, s81
	v_lshrrev_b32_e32 v35, 16, v36
	v_lshrrev_b32_e32 v36, 16, v37
	v_bfe_u32 v38, v17, 16, 1
	v_and_or_b32 v19, v19, s71, v36
	v_add_u32_e32 v36, 8, v54
	v_add3_u32 v17, v17, v38, s81
	v_ashrrev_i32_e32 v37, 31, v36
	v_lshrrev_b32_e32 v16, 16, v16
	v_lshrrev_b32_e32 v17, 16, v17
	v_lshlrev_b64 v[36:37], 11, v[36:37]
	v_and_or_b32 v18, v18, s71, v35
	v_and_or_b32 v17, v43, s71, v17
	v_and_or_b32 v16, v44, s71, v16
	v_lshl_add_u64 v[36:37], v[40:41], 0, v[36:37]
	ds_read2_b32 v[38:39], v24 offset0:16 offset1:24
	ds_read2_b32 v[42:43], v24 offset0:82 offset1:90
	global_store_dwordx4 v[36:37], v[16:19], off sc0 sc1
	ds_read2_b32 v[36:37], v24 offset0:49 offset1:57
	ds_read2_b32 v[44:45], v24 offset0:115 offset1:123
	ds_read2_b32 v[46:47], v24 offset0:148 offset1:156
	ds_read2_b32 v[48:49], v24 offset0:214 offset1:222
	ds_read2_b32 v[50:51], v24 offset0:181 offset1:189
	ds_read2_b32 v[52:53], v24 offset0:247 offset1:255
	s_waitcnt lgkmcnt(7)
	v_mov_b32_e32 v16, v38
	s_waitcnt lgkmcnt(5)
	v_mov_b32_e32 v18, v36
	s_waitcnt lgkmcnt(4)
	v_mov_b32_e32 v19, v44
	s_waitcnt lgkmcnt(3)
	v_mov_b32_e32 v56, v46
	s_waitcnt lgkmcnt(2)
	v_mov_b32_e32 v57, v48
	s_waitcnt lgkmcnt(1)
	v_mov_b32_e32 v58, v50
	s_waitcnt lgkmcnt(0)
	v_mov_b32_e32 v59, v52
	v_mov_b32_e32 v17, v42
	v_pk_mul_f32 v[18:19], v[2:3], v[18:19]
	v_pk_mul_f32 v[56:57], v[6:7], v[56:57]
	v_pk_mul_f32 v[58:59], v[4:5], v[58:59]
	v_pk_mul_f32 v[16:17], v[0:1], v[16:17]
	v_bfe_u32 v35, v59, 16, 1
	v_bfe_u32 v36, v58, 16, 1
	v_bfe_u32 v38, v19, 16, 1
	v_bfe_u32 v42, v18, 16, 1
	v_bfe_u32 v44, v56, 16, 1
	v_add3_u32 v42, v18, v42, s81
	v_add3_u32 v38, v19, v38, s81
	v_add3_u32 v18, v58, v36, s81
	v_add3_u32 v19, v59, v35, s81
	v_bfe_u32 v35, v16, 16, 1
	v_bfe_u32 v36, v17, 16, 1
	v_bfe_u32 v46, v57, 16, 1
	v_add3_u32 v44, v56, v44, s81
	v_add_u32_e32 v56, 16, v54
	v_add3_u32 v46, v57, v46, s81
	v_add3_u32 v17, v17, v36, s81
	v_add3_u32 v16, v16, v35, s81
	v_ashrrev_i32_e32 v57, 31, v56
	v_lshrrev_b32_e32 v16, 16, v16
	v_lshrrev_b32_e32 v17, 16, v17
	v_lshrrev_b32_e32 v35, 16, v44
	v_lshrrev_b32_e32 v36, 16, v46
	v_lshlrev_b64 v[56:57], 11, v[56:57]
	v_mov_b32_e32 v44, v37
	v_mov_b32_e32 v52, v51
	v_and_or_b32 v19, v19, s71, v36
	v_and_or_b32 v18, v18, s71, v35
	v_and_or_b32 v17, v38, s71, v17
	v_and_or_b32 v16, v42, s71, v16
	v_lshl_add_u64 v[56:57], v[40:41], 0, v[56:57]
	v_pk_mul_f32 v[2:3], v[2:3], v[44:45]
	v_mov_b32_e32 v48, v47
	v_pk_mul_f32 v[4:5], v[4:5], v[52:53]
	global_store_dwordx4 v[56:57], v[16:19], off sc0 sc1
	v_mov_b32_e32 v42, v39
	v_pk_mul_f32 v[6:7], v[6:7], v[48:49]
	v_bfe_u32 v16, v5, 16, 1
	v_bfe_u32 v18, v3, 16, 1
	v_pk_mul_f32 v[0:1], v[0:1], v[42:43]
	v_bfe_u32 v17, v4, 16, 1
	v_bfe_u32 v19, v2, 16, 1
	v_add3_u32 v18, v3, v18, s81
	v_add3_u32 v3, v5, v16, s81
	v_bfe_u32 v16, v6, 16, 1
	v_add3_u32 v19, v2, v19, s81
	v_add3_u32 v2, v4, v17, s81
	v_bfe_u32 v4, v0, 16, 1
	v_bfe_u32 v17, v7, 16, 1
	v_add3_u32 v6, v6, v16, s81
	v_bfe_u32 v5, v1, 16, 1
	v_add3_u32 v7, v7, v17, s81
	v_add3_u32 v0, v0, v4, s81
	v_lshrrev_b32_e32 v4, 16, v6
	v_add3_u32 v1, v1, v5, s81
	v_lshrrev_b32_e32 v5, 16, v7
	v_and_or_b32 v2, v2, s71, v4
	v_add_u32_e32 v4, 24, v54
	v_and_or_b32 v3, v3, s71, v5
	v_ashrrev_i32_e32 v5, 31, v4
	v_lshrrev_b32_e32 v0, 16, v0
	v_lshrrev_b32_e32 v1, 16, v1
	v_lshlrev_b64 v[4:5], 11, v[4:5]
	v_and_or_b32 v1, v18, s71, v1
	v_and_or_b32 v0, v19, s71, v0
	v_lshl_add_u64 v[4:5], v[40:41], 0, v[4:5]
	global_store_dwordx4 v[4:5], v[0:3], off sc0 sc1
	s_waitcnt lgkmcnt(0)

.LBB0_135:
	s_cmpk_gt_i32 s42, 0xaff
	s_mov_b64 s[0:1], -1
	s_cbranch_scc0 .LBB0_149
	s_cmpk_gt_u32 s42, 0x107f
	s_cbranch_scc0 .LBB0_146
	s_cmpk_gt_u32 s42, 0x167f
	s_cbranch_scc0 .LBB0_139
	s_and_b32 s0, s40, 0x7fffffc0
	s_addk_i32 s0, 0xd300
	v_or_b32_e32 v0, s0, v20
	v_mov_b32_e32 v1, v97
	v_readlane_b32 s48, v234, 47
	s_and_b32 s34, s8, 0x3e0
	v_lshlrev_b64 v[0:1], 12, v[0:1]
	v_readlane_b32 s60, v234, 59
	v_readlane_b32 s61, v234, 60
	s_lshl_b32 s46, s34, 2
	s_movk_i32 s1, 0x4000
	v_lshl_add_u64 v[0:1], s[60:61], 0, v[0:1]
	v_lshl_add_u64 v[0:1], v[0:1], 0, s[46:47]
	v_lshl_add_u64 v[0:1], v[0:1], 0, v[96:97]
	v_add_co_u32_e32 v2, vcc, 0x2000, v0
	global_load_dword v4, v[0:1], off
	s_nop 0
	v_addc_co_u32_e32 v3, vcc, 0, v1, vcc
	global_load_dword v5, v[2:3], off
	v_add_co_u32_e32 v2, vcc, s1, v0
	s_mov_b32 s1, s47
	s_nop 0
	v_addc_co_u32_e32 v3, vcc, 0, v1, vcc
	global_load_dword v6, v[2:3], off
	v_add_co_u32_e32 v2, vcc, 0x6000, v0
	v_readlane_b32 s49, v234, 48
	s_nop 0
	v_addc_co_u32_e32 v3, vcc, 0, v1, vcc
	global_load_dword v7, v[2:3], off
	v_add_co_u32_e32 v2, vcc, 0x8000, v0
	v_readlane_b32 s50, v234, 49
	s_nop 0
	v_addc_co_u32_e32 v3, vcc, 0, v1, vcc
	global_load_dword v16, v[2:3], off
	v_add_co_u32_e32 v2, vcc, 0xa000, v0
	v_readlane_b32 s51, v234, 50
	s_nop 0
	v_addc_co_u32_e32 v3, vcc, 0, v1, vcc
	global_load_dword v17, v[2:3], off
	v_add_co_u32_e32 v2, vcc, 0xc000, v0
	v_readlane_b32 s52, v234, 51
	s_nop 0
	v_addc_co_u32_e32 v3, vcc, 0, v1, vcc
	global_load_dword v18, v[2:3], off
	v_add_co_u32_e32 v2, vcc, 0xe000, v0
	v_readlane_b32 s53, v234, 52
	s_nop 0
	v_addc_co_u32_e32 v3, vcc, 0, v1, vcc
	global_load_dword v19, v[2:3], off
	v_add_co_u32_e32 v2, vcc, 0x10000, v0
	v_readlane_b32 s54, v234, 53
	s_nop 0
	v_addc_co_u32_e32 v3, vcc, 0, v1, vcc
	global_load_dword v35, v[2:3], off
	v_add_co_u32_e32 v2, vcc, 0x12000, v0
	v_readlane_b32 s55, v234, 54
	s_nop 0
	v_addc_co_u32_e32 v3, vcc, 0, v1, vcc
	global_load_dword v36, v[2:3], off
	v_add_co_u32_e32 v2, vcc, 0x14000, v0
	v_readlane_b32 s56, v234, 55
	s_nop 0
	v_addc_co_u32_e32 v3, vcc, 0, v1, vcc
	global_load_dword v37, v[2:3], off
	v_add_co_u32_e32 v2, vcc, 0x16000, v0
	v_readlane_b32 s57, v234, 56
	s_nop 0
	v_addc_co_u32_e32 v3, vcc, 0, v1, vcc
	global_load_dword v38, v[2:3], off
	v_add_co_u32_e32 v2, vcc, 0x18000, v0
	v_readlane_b32 s58, v234, 57
	s_nop 0
	v_addc_co_u32_e32 v3, vcc, 0, v1, vcc
	global_load_dword v39, v[2:3], off
	v_add_co_u32_e32 v2, vcc, 0x1a000, v0
	v_readlane_b32 s59, v234, 58
	s_nop 0
	v_addc_co_u32_e32 v3, vcc, 0, v1, vcc
	global_load_dword v40, v[2:3], off
	v_add_co_u32_e32 v2, vcc, 0x1c000, v0
	v_readlane_b32 s62, v234, 61
	s_nop 0
	v_addc_co_u32_e32 v3, vcc, 0, v1, vcc
	global_load_dword v41, v[2:3], off
	v_add_co_u32_e32 v2, vcc, 0x1e000, v0
	v_readlane_b32 s63, v234, 62
	s_nop 0
	v_addc_co_u32_e32 v3, vcc, 0, v1, vcc
	global_load_dword v42, v[2:3], off
	v_add_co_u32_e32 v2, vcc, 0x20000, v0
	s_nop 1
	v_addc_co_u32_e32 v3, vcc, 0, v1, vcc
	global_load_dword v43, v[2:3], off
	v_add_co_u32_e32 v2, vcc, 0x22000, v0
	s_nop 1
	v_addc_co_u32_e32 v3, vcc, 0, v1, vcc
	global_load_dword v44, v[2:3], off
	v_add_co_u32_e32 v2, vcc, 0x24000, v0
	s_nop 1
	v_addc_co_u32_e32 v3, vcc, 0, v1, vcc
	global_load_dword v45, v[2:3], off
	v_add_co_u32_e32 v2, vcc, 0x26000, v0
	s_nop 1
	v_addc_co_u32_e32 v3, vcc, 0, v1, vcc
	global_load_dword v46, v[2:3], off
	v_add_co_u32_e32 v2, vcc, 0x28000, v0
	s_nop 1
	v_addc_co_u32_e32 v3, vcc, 0, v1, vcc
	global_load_dword v47, v[2:3], off
	v_add_co_u32_e32 v2, vcc, 0x2a000, v0
	s_nop 1
	v_addc_co_u32_e32 v3, vcc, 0, v1, vcc
	global_load_dword v48, v[2:3], off
	v_add_co_u32_e32 v2, vcc, 0x2c000, v0
	s_nop 1
	v_addc_co_u32_e32 v3, vcc, 0, v1, vcc
	global_load_dword v49, v[2:3], off
	v_add_co_u32_e32 v2, vcc, 0x2e000, v0
	s_nop 1
	v_addc_co_u32_e32 v3, vcc, 0, v1, vcc
	global_load_dword v50, v[2:3], off
	v_add_co_u32_e32 v2, vcc, 0x30000, v0
	s_nop 1
	v_addc_co_u32_e32 v3, vcc, 0, v1, vcc
	global_load_dword v51, v[2:3], off
	v_add_co_u32_e32 v2, vcc, 0x32000, v0
	s_nop 1
	v_addc_co_u32_e32 v3, vcc, 0, v1, vcc
	global_load_dword v52, v[2:3], off
	v_add_co_u32_e32 v2, vcc, 0x34000, v0
	s_nop 1
	v_addc_co_u32_e32 v3, vcc, 0, v1, vcc
	global_load_dword v53, v[2:3], off
	v_add_co_u32_e32 v2, vcc, 0x36000, v0
	s_nop 1
	v_addc_co_u32_e32 v3, vcc, 0, v1, vcc
	global_load_dword v54, v[2:3], off
	v_add_co_u32_e32 v2, vcc, 0x38000, v0
	s_nop 1
	v_addc_co_u32_e32 v3, vcc, 0, v1, vcc
	global_load_dword v55, v[2:3], off
	v_add_co_u32_e32 v2, vcc, 0x3a000, v0
	s_nop 1
	v_addc_co_u32_e32 v3, vcc, 0, v1, vcc
	global_load_dword v56, v[2:3], off
	v_add_co_u32_e32 v2, vcc, 0x3c000, v0
	s_nop 1
	v_addc_co_u32_e32 v3, vcc, 0, v1, vcc
	v_add_co_u32_e32 v0, vcc, 0x3e000, v0
	global_load_dword v2, v[2:3], off
	s_nop 0
	v_addc_co_u32_e32 v1, vcc, 0, v1, vcc
	global_load_dword v0, v[0:1], off
	s_waitcnt vmcnt(0)
	ds_write2_b32 v22, v4, v5 offset1:66
	s_waitcnt vmcnt(28)
	ds_write2_b32 v22, v6, v7 offset0:132 offset1:198
	s_waitcnt vmcnt(26)
	ds_write2_b32 v28, v16, v17 offset0:8 offset1:74
	s_waitcnt vmcnt(24)
	ds_write2_b32 v28, v18, v19 offset0:140 offset1:206
	s_waitcnt vmcnt(22)
	ds_write2_b32 v29, v35, v36 offset0:16 offset1:82
	s_waitcnt vmcnt(20)
	ds_write2_b32 v29, v37, v38 offset0:148 offset1:214
	s_waitcnt vmcnt(18)
	ds_write2_b32 v30, v39, v40 offset0:24 offset1:90
	s_waitcnt vmcnt(16)
	ds_write2_b32 v30, v41, v42 offset0:156 offset1:222
	s_waitcnt vmcnt(14)
	ds_write2_b32 v31, v43, v44 offset0:32 offset1:98
	s_waitcnt vmcnt(12)
	ds_write2_b32 v31, v45, v46 offset0:164 offset1:230
	s_waitcnt vmcnt(10)
	ds_write2_b32 v32, v47, v48 offset0:40 offset1:106
	s_waitcnt vmcnt(8)
	ds_write2_b32 v32, v49, v50 offset0:172 offset1:238
	s_waitcnt vmcnt(6)
	ds_write2_b32 v33, v51, v52 offset0:48 offset1:114
	s_waitcnt vmcnt(4)
	ds_write2_b32 v33, v53, v54 offset0:180 offset1:246
	s_waitcnt vmcnt(2)
	ds_write2_b32 v34, v55, v56 offset0:56 offset1:122
	s_waitcnt vmcnt(0)
	ds_write2_b32 v34, v2, v0 offset0:188 offset1:254
	s_waitcnt lgkmcnt(0)
	ds_read2_b32 v[6:7], v24 offset0:33 offset1:41
	ds_read2_b32 v[16:17], v24 offset1:8
	ds_read2_b32 v[18:19], v24 offset0:66 offset1:74
	ds_read2_b32 v[36:37], v24 offset0:99 offset1:107
	ds_read2_b32 v[38:39], v24 offset0:132 offset1:140
	ds_read2_b32 v[40:41], v24 offset0:165 offset1:173
	ds_read2_b32 v[42:43], v24 offset0:198 offset1:206
	ds_read2_b32 v[44:45], v24 offset0:231 offset1:239
	s_waitcnt lgkmcnt(7)
	v_bfe_u32 v3, v6, 16, 1
	s_waitcnt lgkmcnt(6)
	v_bfe_u32 v2, v16, 16, 1
	v_add3_u32 v2, v16, v2, s81
	v_lshrrev_b32_e32 v2, 16, v2
	v_add3_u32 v3, v6, v3, s81
	v_and_or_b32 v2, v3, s71, v2
	s_waitcnt lgkmcnt(5)
	v_bfe_u32 v3, v18, 16, 1
	v_add3_u32 v3, v18, v3, s81
	s_waitcnt lgkmcnt(4)
	v_bfe_u32 v4, v36, 16, 1
	v_lshrrev_b32_e32 v3, 16, v3
	v_add3_u32 v4, v36, v4, s81
	v_and_or_b32 v3, v4, s71, v3
	s_waitcnt lgkmcnt(3)
	v_bfe_u32 v4, v38, 16, 1
	v_add3_u32 v4, v38, v4, s81
	s_waitcnt lgkmcnt(2)
	v_bfe_u32 v5, v40, 16, 1
	v_lshrrev_b32_e32 v4, 16, v4
	v_add3_u32 v5, v40, v5, s81
	v_and_or_b32 v4, v5, s71, v4
	s_waitcnt lgkmcnt(1)
	v_bfe_u32 v5, v42, 16, 1
	v_add3_u32 v5, v42, v5, s81
	s_waitcnt lgkmcnt(0)
	v_bfe_u32 v6, v44, 16, 1
	v_lshrrev_b32_e32 v5, 16, v5
	v_add3_u32 v6, v44, v6, s81
	v_and_or_b32 v5, v6, s71, v5
	v_or_b32_e32 v6, s34, v23
	v_lshl_add_u64 v[0:1], s[0:1], 1, v[8:9]
	v_lshlrev_b32_e32 v46, 11, v6
	v_mov_b32_e32 v47, v97
	v_lshl_add_u64 v[46:47], v[0:1], 0, v[46:47]
	global_store_dwordx4 v[46:47], v[2:5], off sc0 sc1
	v_bfe_u32 v6, v45, 16, 1
	v_add3_u32 v6, v45, v6, s81
	v_bfe_u32 v2, v17, 16, 1
	v_add3_u32 v2, v17, v2, s81
	v_bfe_u32 v3, v7, 16, 1
	v_lshrrev_b32_e32 v2, 16, v2
	v_add3_u32 v3, v7, v3, s81
	v_and_or_b32 v2, v3, s71, v2
	v_bfe_u32 v3, v19, 16, 1
	v_add3_u32 v3, v19, v3, s81
	v_bfe_u32 v4, v37, 16, 1
	v_lshrrev_b32_e32 v3, 16, v3
	v_add3_u32 v4, v37, v4, s81
	v_and_or_b32 v3, v4, s71, v3
	v_bfe_u32 v4, v39, 16, 1
	v_add3_u32 v4, v39, v4, s81
	v_bfe_u32 v5, v41, 16, 1
	v_lshrrev_b32_e32 v4, 16, v4
	v_add3_u32 v5, v41, v5, s81
	v_and_or_b32 v4, v5, s71, v4
	v_bfe_u32 v5, v43, 16, 1
	v_add3_u32 v5, v43, v5, s81
	v_lshrrev_b32_e32 v5, 16, v5
	v_and_or_b32 v5, v6, s71, v5
	v_or_b32_e32 v6, s34, v25
	v_lshlrev_b32_e32 v6, 11, v6
	v_mov_b32_e32 v7, v97
	v_lshl_add_u64 v[6:7], v[0:1], 0, v[6:7]
	global_store_dwordx4 v[6:7], v[2:5], off sc0 sc1
	ds_read2_b32 v[6:7], v24 offset0:49 offset1:57
	ds_read2_b32 v[16:17], v24 offset0:16 offset1:24
	ds_read2_b32 v[18:19], v24 offset0:82 offset1:90
	ds_read2_b32 v[36:37], v24 offset0:115 offset1:123
	ds_read2_b32 v[38:39], v24 offset0:148 offset1:156
	ds_read2_b32 v[40:41], v24 offset0:181 offset1:189
	ds_read2_b32 v[42:43], v24 offset0:214 offset1:222
	ds_read2_b32 v[44:45], v24 offset0:247 offset1:255
	s_waitcnt lgkmcnt(7)
	v_bfe_u32 v3, v6, 16, 1
	s_waitcnt lgkmcnt(6)
	v_bfe_u32 v2, v16, 16, 1
	v_add3_u32 v2, v16, v2, s81
	v_lshrrev_b32_e32 v2, 16, v2
	v_add3_u32 v3, v6, v3, s81
	v_and_or_b32 v2, v3, s71, v2
	s_waitcnt lgkmcnt(5)
	v_bfe_u32 v3, v18, 16, 1
	v_add3_u32 v3, v18, v3, s81
	s_waitcnt lgkmcnt(4)
	v_bfe_u32 v4, v36, 16, 1
	v_lshrrev_b32_e32 v3, 16, v3
	v_add3_u32 v4, v36, v4, s81
	v_and_or_b32 v3, v4, s71, v3
	s_waitcnt lgkmcnt(3)
	v_bfe_u32 v4, v38, 16, 1
	v_add3_u32 v4, v38, v4, s81
	s_waitcnt lgkmcnt(2)
	v_bfe_u32 v5, v40, 16, 1
	v_lshrrev_b32_e32 v4, 16, v4
	v_add3_u32 v5, v40, v5, s81
	v_and_or_b32 v4, v5, s71, v4
	s_waitcnt lgkmcnt(1)
	v_bfe_u32 v5, v42, 16, 1
	v_add3_u32 v5, v42, v5, s81
	s_waitcnt lgkmcnt(0)
	v_bfe_u32 v6, v44, 16, 1
	v_lshrrev_b32_e32 v5, 16, v5
	v_add3_u32 v6, v44, v6, s81
	v_and_or_b32 v5, v6, s71, v5
	v_or_b32_e32 v6, s34, v26
	v_lshlrev_b32_e32 v46, 11, v6
	v_mov_b32_e32 v47, v97
	v_lshl_add_u64 v[46:47], v[0:1], 0, v[46:47]
	global_store_dwordx4 v[46:47], v[2:5], off sc0 sc1
	v_bfe_u32 v6, v45, 16, 1
	v_add3_u32 v6, v45, v6, s81
	v_bfe_u32 v2, v17, 16, 1
	v_add3_u32 v2, v17, v2, s81
	v_bfe_u32 v3, v7, 16, 1
	v_lshrrev_b32_e32 v2, 16, v2
	v_add3_u32 v3, v7, v3, s81
	v_and_or_b32 v2, v3, s71, v2
	v_bfe_u32 v3, v19, 16, 1
	v_add3_u32 v3, v19, v3, s81
	v_bfe_u32 v4, v37, 16, 1
	v_lshrrev_b32_e32 v3, 16, v3
	v_add3_u32 v4, v37, v4, s81
	v_and_or_b32 v3, v4, s71, v3
	v_bfe_u32 v4, v39, 16, 1
	v_add3_u32 v4, v39, v4, s81
	v_bfe_u32 v5, v41, 16, 1
	v_lshrrev_b32_e32 v4, 16, v4
	v_add3_u32 v5, v41, v5, s81
	v_and_or_b32 v4, v5, s71, v4
	v_bfe_u32 v5, v43, 16, 1
	v_add3_u32 v5, v43, v5, s81
	v_lshrrev_b32_e32 v5, 16, v5
	v_and_or_b32 v5, v6, s71, v5
	v_or_b32_e32 v6, s34, v27
	v_lshlrev_b32_e32 v6, 11, v6
	v_mov_b32_e32 v7, v97
	v_lshl_add_u64 v[0:1], v[0:1], 0, v[6:7]
	global_store_dwordx4 v[0:1], v[2:5], off sc0 sc1
	s_waitcnt lgkmcnt(0)
	s_mov_b64 s[0:1], 0

.LBB0_144:
	s_lshl_b32 s1, s1, 6
	s_and_b32 s34, s1, 0xffc0
	v_or_b32_e32 v0, s34, v20
	v_mul_u32_u24_e32 v0, 0xc00, v0
	v_readlane_b32 s48, v234, 47
	v_lshlrev_b32_e32 v0, 2, v0
	v_mov_b32_e32 v1, v97
	v_readlane_b32 s56, v234, 55
	v_readlane_b32 s57, v234, 56
	s_ashr_i32 s1, s0, 31
	s_lshl_b32 s46, s34, 1
	v_lshl_add_u64 v[0:1], s[56:57], 0, v[0:1]
	v_lshl_add_u64 v[0:1], s[0:1], 2, v[0:1]
	v_lshl_add_u64 v[0:1], v[0:1], 0, v[96:97]
	s_movk_i32 s0, 0x6000
	v_add_co_u32_e32 v2, vcc, s0, v0
	s_mov_b32 s0, 0xc000
	s_nop 0
	v_addc_co_u32_e32 v3, vcc, 0, v1, vcc
	global_load_dword v4, v[0:1], off
	global_load_dword v5, v[2:3], off
	v_add_co_u32_e32 v2, vcc, s0, v0
	s_mov_b32 s0, 0x12000
	s_nop 0
	v_addc_co_u32_e32 v3, vcc, 0, v1, vcc
	global_load_dword v6, v[2:3], off
	v_add_co_u32_e32 v2, vcc, s0, v0
	s_mov_b32 s0, 0x18000
	s_nop 0
	v_addc_co_u32_e32 v3, vcc, 0, v1, vcc
	global_load_dword v7, v[2:3], off
	v_add_co_u32_e32 v2, vcc, s0, v0
	s_mov_b32 s0, 0x1e000
	s_nop 0
	v_addc_co_u32_e32 v3, vcc, 0, v1, vcc
	global_load_dword v16, v[2:3], off
	v_add_co_u32_e32 v2, vcc, s0, v0
	s_mov_b32 s0, 0x24000
	s_nop 0
	v_addc_co_u32_e32 v3, vcc, 0, v1, vcc
	global_load_dword v17, v[2:3], off
	v_add_co_u32_e32 v2, vcc, s0, v0
	s_mov_b32 s0, 0x2a000
	s_nop 0
	v_addc_co_u32_e32 v3, vcc, 0, v1, vcc
	global_load_dword v18, v[2:3], off
	v_add_co_u32_e32 v2, vcc, s0, v0
	s_mov_b32 s0, 0x30000
	s_nop 0
	v_addc_co_u32_e32 v3, vcc, 0, v1, vcc
	global_load_dword v19, v[2:3], off
	v_add_co_u32_e32 v2, vcc, s0, v0
	s_mov_b32 s0, 0x36000
	s_nop 0
	v_addc_co_u32_e32 v3, vcc, 0, v1, vcc
	global_load_dword v35, v[2:3], off
	v_add_co_u32_e32 v2, vcc, s0, v0
	s_mov_b32 s0, 0x3c000
	s_nop 0
	v_addc_co_u32_e32 v3, vcc, 0, v1, vcc
	global_load_dword v36, v[2:3], off
	v_add_co_u32_e32 v2, vcc, s0, v0
	s_mov_b32 s0, 0x42000
	s_nop 0
	v_addc_co_u32_e32 v3, vcc, 0, v1, vcc
	global_load_dword v37, v[2:3], off
	v_add_co_u32_e32 v2, vcc, s0, v0
	s_mov_b32 s0, 0x48000
	s_nop 0
	v_addc_co_u32_e32 v3, vcc, 0, v1, vcc
	global_load_dword v38, v[2:3], off
	v_add_co_u32_e32 v2, vcc, s0, v0
	s_mov_b32 s0, 0x4e000
	s_nop 0
	v_addc_co_u32_e32 v3, vcc, 0, v1, vcc
	global_load_dword v39, v[2:3], off
	v_add_co_u32_e32 v2, vcc, s0, v0
	s_mov_b32 s0, 0x54000
	s_nop 0
	v_addc_co_u32_e32 v3, vcc, 0, v1, vcc
	global_load_dword v40, v[2:3], off
	v_add_co_u32_e32 v2, vcc, s0, v0
	s_mov_b32 s0, 0x5a000
	s_nop 0
	v_addc_co_u32_e32 v3, vcc, 0, v1, vcc
	global_load_dword v41, v[2:3], off
	v_add_co_u32_e32 v2, vcc, s0, v0
	s_mov_b32 s0, 0x60000
	s_nop 0
	v_addc_co_u32_e32 v3, vcc, 0, v1, vcc
	global_load_dword v42, v[2:3], off
	v_add_co_u32_e32 v2, vcc, s0, v0
	s_mov_b32 s0, 0x66000
	s_nop 0
	v_addc_co_u32_e32 v3, vcc, 0, v1, vcc
	global_load_dword v43, v[2:3], off
	v_add_co_u32_e32 v2, vcc, s0, v0
	s_mov_b32 s0, 0x6c000
	s_nop 0
	v_addc_co_u32_e32 v3, vcc, 0, v1, vcc
	global_load_dword v44, v[2:3], off
	v_add_co_u32_e32 v2, vcc, s0, v0
	s_mov_b32 s0, 0x72000
	s_nop 0
	v_addc_co_u32_e32 v3, vcc, 0, v1, vcc
	global_load_dword v45, v[2:3], off
	v_add_co_u32_e32 v2, vcc, s0, v0
	s_mov_b32 s0, 0x78000
	s_nop 0
	v_addc_co_u32_e32 v3, vcc, 0, v1, vcc
	global_load_dword v46, v[2:3], off
	v_add_co_u32_e32 v2, vcc, s0, v0
	s_mov_b32 s0, 0x7e000
	s_nop 0
	v_addc_co_u32_e32 v3, vcc, 0, v1, vcc
	global_load_dword v47, v[2:3], off
	v_add_co_u32_e32 v2, vcc, s0, v0
	s_mov_b32 s0, 0x84000
	s_nop 0
	v_addc_co_u32_e32 v3, vcc, 0, v1, vcc
	global_load_dword v48, v[2:3], off
	v_add_co_u32_e32 v2, vcc, s0, v0
	s_mov_b32 s0, 0x8a000
	s_nop 0
	v_addc_co_u32_e32 v3, vcc, 0, v1, vcc
	global_load_dword v49, v[2:3], off
	v_add_co_u32_e32 v2, vcc, s0, v0
	s_mov_b32 s0, 0x90000
	s_nop 0
	v_addc_co_u32_e32 v3, vcc, 0, v1, vcc
	global_load_dword v50, v[2:3], off
	v_add_co_u32_e32 v2, vcc, s0, v0
	s_mov_b32 s0, 0x96000
	s_nop 0
	v_addc_co_u32_e32 v3, vcc, 0, v1, vcc
	global_load_dword v51, v[2:3], off
	v_add_co_u32_e32 v2, vcc, s0, v0
	s_mov_b32 s0, 0x9c000
	s_nop 0
	v_addc_co_u32_e32 v3, vcc, 0, v1, vcc
	global_load_dword v52, v[2:3], off
	v_add_co_u32_e32 v2, vcc, s0, v0
	s_mov_b32 s0, 0xa2000
	s_nop 0
	v_addc_co_u32_e32 v3, vcc, 0, v1, vcc
	global_load_dword v53, v[2:3], off
	v_add_co_u32_e32 v2, vcc, s0, v0
	s_mov_b32 s0, 0xa8000
	s_nop 0
	v_addc_co_u32_e32 v3, vcc, 0, v1, vcc
	global_load_dword v54, v[2:3], off
	v_add_co_u32_e32 v2, vcc, s0, v0
	s_mov_b32 s0, 0xae000
	s_nop 0
	v_addc_co_u32_e32 v3, vcc, 0, v1, vcc
	global_load_dword v55, v[2:3], off
	v_add_co_u32_e32 v2, vcc, s0, v0
	s_mov_b32 s0, 0xb4000
	s_nop 0
	v_addc_co_u32_e32 v3, vcc, 0, v1, vcc
	global_load_dword v56, v[2:3], off
	v_add_co_u32_e32 v2, vcc, s0, v0
	s_mov_b32 s0, 0xba000
	s_nop 0
	v_addc_co_u32_e32 v3, vcc, 0, v1, vcc
	v_add_co_u32_e32 v0, vcc, s0, v0
	global_load_dword v2, v[2:3], off
	s_nop 0
	v_addc_co_u32_e32 v1, vcc, 0, v1, vcc
	global_load_dword v0, v[0:1], off
	v_or_b32_e32 v1, s34, v21
	v_readlane_b32 s0, v236, 54
	v_lshlrev_b32_e32 v57, 2, v1
	s_waitcnt vmcnt(0)
	ds_write2_b32 v22, v4, v5 offset1:66
	s_waitcnt vmcnt(28)
	ds_write2_b32 v22, v6, v7 offset0:132 offset1:198
	s_waitcnt vmcnt(26)
	ds_write2_b32 v28, v16, v17 offset0:8 offset1:74
	s_waitcnt vmcnt(24)
	ds_write2_b32 v28, v18, v19 offset0:140 offset1:206
	s_waitcnt vmcnt(22)
	ds_write2_b32 v29, v35, v36 offset0:16 offset1:82
	s_waitcnt vmcnt(20)
	ds_write2_b32 v29, v37, v38 offset0:148 offset1:214
	s_waitcnt vmcnt(18)
	ds_write2_b32 v30, v39, v40 offset0:24 offset1:90
	s_waitcnt vmcnt(16)
	ds_write2_b32 v30, v41, v42 offset0:156 offset1:222
	s_waitcnt vmcnt(14)
	ds_write2_b32 v31, v43, v44 offset0:32 offset1:98
	s_waitcnt vmcnt(12)
	ds_write2_b32 v31, v45, v46 offset0:164 offset1:230
	s_waitcnt vmcnt(10)
	ds_write2_b32 v32, v47, v48 offset0:40 offset1:106
	s_waitcnt vmcnt(8)
	ds_write2_b32 v32, v49, v50 offset0:172 offset1:238
	s_waitcnt vmcnt(6)
	ds_write2_b32 v33, v51, v52 offset0:48 offset1:114
	s_waitcnt vmcnt(4)
	ds_write2_b32 v33, v53, v54 offset0:180 offset1:246
	s_waitcnt vmcnt(2)
	ds_write2_b32 v34, v55, v56 offset0:56 offset1:122
	s_waitcnt vmcnt(0)
	ds_write2_b32 v34, v2, v0 offset0:188 offset1:254
	v_readlane_b32 s1, v236, 55
	s_nop 4
	global_load_dwordx4 v[0:3], v57, s[0:1] offset:16
	global_load_dwordx4 v[4:7], v57, s[0:1]
	s_waitcnt lgkmcnt(0)
	v_lshl_add_u64 v[16:17], v[10:11], 0, s[46:47]
	v_readlane_b32 s49, v234, 48
	v_readlane_b32 s50, v234, 49
	v_readlane_b32 s51, v234, 50
	v_readlane_b32 s52, v234, 51
	v_readlane_b32 s53, v234, 52
	v_readlane_b32 s54, v234, 53
	v_readlane_b32 s55, v234, 54
	v_readlane_b32 s58, v234, 57
	v_readlane_b32 s59, v234, 58
	v_readlane_b32 s60, v234, 59
	v_readlane_b32 s61, v234, 60
	v_readlane_b32 s62, v234, 61
	v_readlane_b32 s63, v234, 62
	s_waitcnt vmcnt(1)
	v_mov_b32_e32 v52, v0
	s_waitcnt vmcnt(0)
	v_mov_b32_e32 v18, v4
	v_mov_b32_e32 v19, v6
	v_mov_b32_e32 v6, v5
	ds_read2_b32 v[4:5], v24 offset0:33 offset1:41
	ds_read2_b32 v[40:41], v24 offset0:66 offset1:74
	ds_read2_b32 v[42:43], v24 offset1:8
	ds_read2_b32 v[44:45], v24 offset0:99 offset1:107
	ds_read2_b32 v[46:47], v24 offset0:132 offset1:140
	ds_read2_b32 v[48:49], v24 offset0:165 offset1:173
	ds_read2_b32 v[50:51], v24 offset0:198 offset1:206
	ds_read2_b32 v[56:57], v24 offset0:231 offset1:239
	s_waitcnt lgkmcnt(7)
	v_mov_b32_e32 v38, v4
	v_mov_b32_e32 v53, v2
	s_waitcnt lgkmcnt(4)
	v_mov_b32_e32 v39, v44
	v_pk_mul_f32 v[38:39], v[6:7], v[38:39]
	s_waitcnt lgkmcnt(3)
	v_mov_b32_e32 v54, v46
	s_waitcnt lgkmcnt(1)
	v_mov_b32_e32 v55, v50
	v_mov_b32_e32 v2, v1
	v_mov_b32_e32 v0, v48
	s_waitcnt lgkmcnt(0)
	v_mov_b32_e32 v1, v56
	v_mov_b32_e32 v36, v42
	v_mov_b32_e32 v37, v40
	v_pk_mul_f32 v[54:55], v[52:53], v[54:55]
	v_pk_mul_f32 v[0:1], v[2:3], v[0:1]
	v_bfe_u32 v42, v38, 16, 1
	v_pk_mul_f32 v[36:37], v[18:19], v[36:37]
	v_bfe_u32 v4, v1, 16, 1
	v_bfe_u32 v40, v39, 16, 1
	v_add3_u32 v42, v38, v42, s81
	v_bfe_u32 v38, v54, 16, 1
	v_bfe_u32 v35, v0, 16, 1
	v_add3_u32 v40, v39, v40, s81
	v_add3_u32 v1, v1, v4, s81
	v_bfe_u32 v4, v36, 16, 1
	v_bfe_u32 v39, v55, 16, 1
	v_add3_u32 v38, v54, v38, s81
	v_add3_u32 v0, v0, v35, s81
	v_bfe_u32 v35, v37, 16, 1
	v_add3_u32 v39, v55, v39, s81
	v_add3_u32 v4, v36, v4, s81
	v_lshrrev_b32_e32 v36, 16, v38
	v_add3_u32 v35, v37, v35, s81
	v_lshrrev_b32_e32 v37, 16, v39
	v_and_or_b32 v38, v0, s71, v36
	v_or_b32_e32 v0, s43, v23
	v_lshrrev_b32_e32 v4, 16, v4
	v_lshrrev_b32_e32 v35, 16, v35
	v_and_or_b32 v39, v1, s71, v37
	v_lshlrev_b32_e32 v0, 11, v0
	v_mov_b32_e32 v1, v97
	v_and_or_b32 v37, v40, s71, v35
	v_and_or_b32 v36, v42, s71, v4
	v_lshl_add_u64 v[0:1], v[16:17], 0, v[0:1]
	v_mov_b32_e32 v44, v5
	v_mov_b32_e32 v56, v49
	global_store_dwordx4 v[0:1], v[36:39], off sc0 sc1
	v_mov_b32_e32 v40, v43
	v_pk_mul_f32 v[4:5], v[6:7], v[44:45]
	v_mov_b32_e32 v50, v47
	v_pk_mul_f32 v[38:39], v[2:3], v[56:57]
	v_pk_mul_f32 v[0:1], v[18:19], v[40:41]
	v_pk_mul_f32 v[36:37], v[52:53], v[50:51]
	v_bfe_u32 v35, v39, 16, 1
	v_bfe_u32 v41, v5, 16, 1
	v_bfe_u32 v40, v38, 16, 1
	v_bfe_u32 v42, v4, 16, 1
	v_add3_u32 v5, v5, v41, s81
	v_add3_u32 v35, v39, v35, s81
	v_bfe_u32 v39, v0, 16, 1
	v_bfe_u32 v41, v36, 16, 1
	v_add3_u32 v4, v4, v42, s81
	v_add3_u32 v38, v38, v40, s81
	v_bfe_u32 v40, v1, 16, 1
	v_bfe_u32 v42, v37, 16, 1
	v_add3_u32 v36, v36, v41, s81
	v_add3_u32 v0, v0, v39, s81
	v_add3_u32 v37, v37, v42, s81
	v_add3_u32 v1, v1, v40, s81
	v_lshrrev_b32_e32 v0, 16, v0
	v_lshrrev_b32_e32 v36, 16, v36
	v_lshrrev_b32_e32 v1, 16, v1
	v_lshrrev_b32_e32 v37, 16, v37
	v_and_or_b32 v38, v38, s71, v36
	v_and_or_b32 v36, v4, s71, v0
	v_or_b32_e32 v0, s43, v25
	v_and_or_b32 v39, v35, s71, v37
	v_and_or_b32 v37, v5, s71, v1
	v_lshlrev_b32_e32 v0, 11, v0
	v_mov_b32_e32 v1, v97
	v_lshl_add_u64 v[0:1], v[16:17], 0, v[0:1]
	global_store_dwordx4 v[0:1], v[36:39], off sc0 sc1
	ds_read2_b32 v[0:1], v24 offset0:49 offset1:57
	ds_read2_b32 v[4:5], v24 offset0:82 offset1:90
	ds_read2_b32 v[40:41], v24 offset0:115 offset1:123
	ds_read2_b32 v[42:43], v24 offset0:16 offset1:24
	ds_read2_b32 v[44:45], v24 offset0:148 offset1:156
	ds_read2_b32 v[46:47], v24 offset0:181 offset1:189
	ds_read2_b32 v[48:49], v24 offset0:214 offset1:222
	ds_read2_b32 v[50:51], v24 offset0:247 offset1:255
	s_waitcnt lgkmcnt(7)
	v_mov_b32_e32 v38, v0
	s_waitcnt lgkmcnt(3)
	v_mov_b32_e32 v54, v44
	v_mov_b32_e32 v39, v40
	s_waitcnt lgkmcnt(1)
	v_mov_b32_e32 v55, v48
	v_mov_b32_e32 v36, v42
	v_mov_b32_e32 v37, v4
	v_pk_mul_f32 v[38:39], v[6:7], v[38:39]
	v_pk_mul_f32 v[54:55], v[52:53], v[54:55]
	v_mov_b32_e32 v56, v46
	s_waitcnt lgkmcnt(0)
	v_mov_b32_e32 v57, v50
	v_pk_mul_f32 v[36:37], v[18:19], v[36:37]
	v_pk_mul_f32 v[56:57], v[2:3], v[56:57]
	v_bfe_u32 v35, v39, 16, 1
	v_bfe_u32 v40, v38, 16, 1
	v_bfe_u32 v42, v54, 16, 1
	v_bfe_u32 v44, v55, 16, 1
	v_bfe_u32 v0, v57, 16, 1
	v_bfe_u32 v4, v56, 16, 1
	v_add3_u32 v40, v38, v40, s81
	v_add3_u32 v35, v39, v35, s81
	v_bfe_u32 v38, v36, 16, 1
	v_bfe_u32 v39, v37, 16, 1
	v_add3_u32 v44, v55, v44, s81
	v_add3_u32 v42, v54, v42, s81
	v_add3_u32 v4, v56, v4, s81
	v_add3_u32 v0, v57, v0, s81
	v_add3_u32 v37, v37, v39, s81
	v_add3_u32 v36, v36, v38, s81
	v_lshrrev_b32_e32 v38, 16, v42
	v_lshrrev_b32_e32 v39, 16, v44
	v_mov_b32_e32 v50, v47
	v_lshrrev_b32_e32 v36, 16, v36
	v_and_or_b32 v39, v0, s71, v39
	v_and_or_b32 v38, v4, s71, v38
	v_or_b32_e32 v0, s43, v26
	v_mov_b32_e32 v4, v43
	v_pk_mul_f32 v[2:3], v[2:3], v[50:51]
	v_lshrrev_b32_e32 v37, 16, v37
	v_and_or_b32 v36, v40, s71, v36
	v_lshlrev_b32_e32 v54, 11, v0
	v_mov_b32_e32 v55, v97
	v_pk_mul_f32 v[4:5], v[18:19], v[4:5]
	v_mov_b32_e32 v40, v1
	v_bfe_u32 v18, v3, 16, 1
	v_and_or_b32 v37, v35, s71, v37
	v_lshl_add_u64 v[54:55], v[16:17], 0, v[54:55]
	v_pk_mul_f32 v[0:1], v[6:7], v[40:41]
	v_mov_b32_e32 v48, v45
	v_bfe_u32 v19, v2, 16, 1
	v_add3_u32 v3, v3, v18, s81
	v_bfe_u32 v18, v4, 16, 1
	global_store_dwordx4 v[54:55], v[36:39], off sc0 sc1
	v_pk_mul_f32 v[6:7], v[52:53], v[48:49]
	v_bfe_u32 v35, v1, 16, 1
	v_bfe_u32 v36, v0, 16, 1
	v_add3_u32 v2, v2, v19, s81
	v_bfe_u32 v19, v5, 16, 1
	v_add3_u32 v4, v4, v18, s81
	v_add3_u32 v0, v0, v36, s81
	v_add3_u32 v1, v1, v35, s81
	v_bfe_u32 v35, v6, 16, 1
	v_bfe_u32 v36, v7, 16, 1
	v_add3_u32 v5, v5, v19, s81
	v_lshrrev_b32_e32 v4, 16, v4
	v_add3_u32 v7, v7, v36, s81
	v_add3_u32 v6, v6, v35, s81
	v_lshrrev_b32_e32 v5, 16, v5
	v_and_or_b32 v0, v0, s71, v4
	v_or_b32_e32 v4, s43, v27
	v_lshrrev_b32_e32 v6, 16, v6
	v_lshrrev_b32_e32 v7, 16, v7
	v_and_or_b32 v1, v1, s71, v5
	v_lshlrev_b32_e32 v4, 11, v4
	v_mov_b32_e32 v5, v97
	v_and_or_b32 v3, v3, s71, v7
	v_and_or_b32 v2, v2, s71, v6
	v_lshl_add_u64 v[4:5], v[16:17], 0, v[4:5]
	global_store_dwordx4 v[4:5], v[0:3], off sc0 sc1
	s_waitcnt lgkmcnt(0)

.LBB0_146:
	s_andn2_b64 vcc, exec, s[0:1]
	s_cbranch_vccnz .LBB0_148
	s_add_i32 s0, s40, 0x1ea00
	s_and_b32 s1, s0, 0x1ffc0
	v_or_b32_e32 v0, s1, v20
	v_readlane_b32 s48, v234, 47
	s_and_b32 s0, s8, 0x3e0
	v_lshlrev_b32_e32 v0, 12, v0
	v_mov_b32_e32 v1, v97
	v_readlane_b32 s52, v234, 51
	v_readlane_b32 s53, v234, 52
	s_lshl_b32 s46, s0, 2
	s_movk_i32 s34, 0x4000
	v_lshl_add_u64 v[0:1], s[52:53], 0, v[0:1]
	v_lshl_add_u64 v[0:1], v[0:1], 0, s[46:47]
	v_lshl_add_u64 v[0:1], v[0:1], 0, v[96:97]
	v_add_co_u32_e32 v2, vcc, 0x2000, v0
	global_load_dword v4, v[0:1], off
	s_nop 0
	v_addc_co_u32_e32 v3, vcc, 0, v1, vcc
	global_load_dword v5, v[2:3], off
	v_add_co_u32_e32 v2, vcc, s34, v0
	s_lshl_b32 s46, s1, 1
	s_nop 0
	v_addc_co_u32_e32 v3, vcc, 0, v1, vcc
	global_load_dword v6, v[2:3], off
	v_add_co_u32_e32 v2, vcc, 0x6000, v0
	v_readlane_b32 s49, v234, 48
	s_nop 0
	v_addc_co_u32_e32 v3, vcc, 0, v1, vcc
	global_load_dword v7, v[2:3], off
	v_add_co_u32_e32 v2, vcc, 0x8000, v0
	v_readlane_b32 s50, v234, 49
	s_nop 0
	v_addc_co_u32_e32 v3, vcc, 0, v1, vcc
	global_load_dword v16, v[2:3], off
	v_add_co_u32_e32 v2, vcc, 0xa000, v0
	v_readlane_b32 s51, v234, 50
	s_nop 0
	v_addc_co_u32_e32 v3, vcc, 0, v1, vcc
	global_load_dword v17, v[2:3], off
	v_add_co_u32_e32 v2, vcc, 0xc000, v0
	v_readlane_b32 s54, v234, 53
	s_nop 0
	v_addc_co_u32_e32 v3, vcc, 0, v1, vcc
	global_load_dword v18, v[2:3], off
	v_add_co_u32_e32 v2, vcc, 0xe000, v0
	v_readlane_b32 s55, v234, 54
	s_nop 0
	v_addc_co_u32_e32 v3, vcc, 0, v1, vcc
	global_load_dword v19, v[2:3], off
	v_add_co_u32_e32 v2, vcc, 0x10000, v0
	v_readlane_b32 s56, v234, 55
	s_nop 0
	v_addc_co_u32_e32 v3, vcc, 0, v1, vcc
	global_load_dword v35, v[2:3], off
	v_add_co_u32_e32 v2, vcc, 0x12000, v0
	v_readlane_b32 s57, v234, 56
	s_nop 0
	v_addc_co_u32_e32 v3, vcc, 0, v1, vcc
	global_load_dword v36, v[2:3], off
	v_add_co_u32_e32 v2, vcc, 0x14000, v0
	v_readlane_b32 s58, v234, 57
	s_nop 0
	v_addc_co_u32_e32 v3, vcc, 0, v1, vcc
	global_load_dword v37, v[2:3], off
	v_add_co_u32_e32 v2, vcc, 0x16000, v0
	v_readlane_b32 s59, v234, 58
	s_nop 0
	v_addc_co_u32_e32 v3, vcc, 0, v1, vcc
	global_load_dword v38, v[2:3], off
	v_add_co_u32_e32 v2, vcc, 0x18000, v0
	v_readlane_b32 s60, v234, 59
	s_nop 0
	v_addc_co_u32_e32 v3, vcc, 0, v1, vcc
	global_load_dword v39, v[2:3], off
	v_add_co_u32_e32 v2, vcc, 0x1a000, v0
	v_readlane_b32 s61, v234, 60
	s_nop 0
	v_addc_co_u32_e32 v3, vcc, 0, v1, vcc
	global_load_dword v40, v[2:3], off
	v_add_co_u32_e32 v2, vcc, 0x1c000, v0
	v_readlane_b32 s62, v234, 61
	s_nop 0
	v_addc_co_u32_e32 v3, vcc, 0, v1, vcc
	global_load_dword v41, v[2:3], off
	v_add_co_u32_e32 v2, vcc, 0x1e000, v0
	v_readlane_b32 s63, v234, 62
	s_nop 0
	v_addc_co_u32_e32 v3, vcc, 0, v1, vcc
	global_load_dword v42, v[2:3], off
	v_add_co_u32_e32 v2, vcc, 0x20000, v0
	s_nop 1
	v_addc_co_u32_e32 v3, vcc, 0, v1, vcc
	global_load_dword v43, v[2:3], off
	v_add_co_u32_e32 v2, vcc, 0x22000, v0
	s_nop 1
	v_addc_co_u32_e32 v3, vcc, 0, v1, vcc
	global_load_dword v44, v[2:3], off
	v_add_co_u32_e32 v2, vcc, 0x24000, v0
	s_nop 1
	v_addc_co_u32_e32 v3, vcc, 0, v1, vcc
	global_load_dword v45, v[2:3], off
	v_add_co_u32_e32 v2, vcc, 0x26000, v0
	s_nop 1
	v_addc_co_u32_e32 v3, vcc, 0, v1, vcc
	global_load_dword v46, v[2:3], off
	v_add_co_u32_e32 v2, vcc, 0x28000, v0
	s_nop 1
	v_addc_co_u32_e32 v3, vcc, 0, v1, vcc
	global_load_dword v47, v[2:3], off
	v_add_co_u32_e32 v2, vcc, 0x2a000, v0
	s_nop 1
	v_addc_co_u32_e32 v3, vcc, 0, v1, vcc
	global_load_dword v48, v[2:3], off
	v_add_co_u32_e32 v2, vcc, 0x2c000, v0
	s_nop 1
	v_addc_co_u32_e32 v3, vcc, 0, v1, vcc
	global_load_dword v49, v[2:3], off
	v_add_co_u32_e32 v2, vcc, 0x2e000, v0
	s_nop 1
	v_addc_co_u32_e32 v3, vcc, 0, v1, vcc
	global_load_dword v50, v[2:3], off
	v_add_co_u32_e32 v2, vcc, 0x30000, v0
	s_nop 1
	v_addc_co_u32_e32 v3, vcc, 0, v1, vcc
	global_load_dword v51, v[2:3], off
	v_add_co_u32_e32 v2, vcc, 0x32000, v0
	s_nop 1
	v_addc_co_u32_e32 v3, vcc, 0, v1, vcc
	global_load_dword v52, v[2:3], off
	v_add_co_u32_e32 v2, vcc, 0x34000, v0
	s_nop 1
	v_addc_co_u32_e32 v3, vcc, 0, v1, vcc
	global_load_dword v53, v[2:3], off
	v_add_co_u32_e32 v2, vcc, 0x36000, v0
	s_nop 1
	v_addc_co_u32_e32 v3, vcc, 0, v1, vcc
	global_load_dword v54, v[2:3], off
	v_add_co_u32_e32 v2, vcc, 0x38000, v0
	s_nop 1
	v_addc_co_u32_e32 v3, vcc, 0, v1, vcc
	global_load_dword v55, v[2:3], off
	v_add_co_u32_e32 v2, vcc, 0x3a000, v0
	s_nop 1
	v_addc_co_u32_e32 v3, vcc, 0, v1, vcc
	global_load_dword v56, v[2:3], off
	v_add_co_u32_e32 v2, vcc, 0x3c000, v0
	s_nop 1
	v_addc_co_u32_e32 v3, vcc, 0, v1, vcc
	v_add_co_u32_e32 v0, vcc, 0x3e000, v0
	global_load_dword v2, v[2:3], off
	s_nop 0
	v_addc_co_u32_e32 v1, vcc, 0, v1, vcc
	global_load_dword v0, v[0:1], off
	s_waitcnt vmcnt(0)
	ds_write2_b32 v22, v4, v5 offset1:66
	s_waitcnt vmcnt(28)
	ds_write2_b32 v22, v6, v7 offset0:132 offset1:198
	s_waitcnt vmcnt(26)
	ds_write2_b32 v28, v16, v17 offset0:8 offset1:74
	s_waitcnt vmcnt(24)
	ds_write2_b32 v28, v18, v19 offset0:140 offset1:206
	s_waitcnt vmcnt(22)
	ds_write2_b32 v29, v35, v36 offset0:16 offset1:82
	s_waitcnt vmcnt(20)
	ds_write2_b32 v29, v37, v38 offset0:148 offset1:214
	s_waitcnt vmcnt(18)
	ds_write2_b32 v30, v39, v40 offset0:24 offset1:90
	s_waitcnt vmcnt(16)
	ds_write2_b32 v30, v41, v42 offset0:156 offset1:222
	s_waitcnt vmcnt(14)
	ds_write2_b32 v31, v43, v44 offset0:32 offset1:98
	s_waitcnt vmcnt(12)
	ds_write2_b32 v31, v45, v46 offset0:164 offset1:230
	s_waitcnt vmcnt(10)
	ds_write2_b32 v32, v47, v48 offset0:40 offset1:106
	s_waitcnt vmcnt(8)
	ds_write2_b32 v32, v49, v50 offset0:172 offset1:238
	s_waitcnt vmcnt(6)
	ds_write2_b32 v33, v51, v52 offset0:48 offset1:114
	s_waitcnt vmcnt(4)
	ds_write2_b32 v33, v53, v54 offset0:180 offset1:246
	s_waitcnt vmcnt(2)
	ds_write2_b32 v34, v55, v56 offset0:56 offset1:122
	s_waitcnt vmcnt(0)
	ds_write2_b32 v34, v2, v0 offset0:188 offset1:254
	s_waitcnt lgkmcnt(0)
	ds_read2_b32 v[6:7], v24 offset0:33 offset1:41
	ds_read2_b32 v[16:17], v24 offset1:8
	ds_read2_b32 v[18:19], v24 offset0:66 offset1:74
	ds_read2_b32 v[36:37], v24 offset0:99 offset1:107
	ds_read2_b32 v[38:39], v24 offset0:132 offset1:140
	ds_read2_b32 v[40:41], v24 offset0:165 offset1:173
	ds_read2_b32 v[42:43], v24 offset0:198 offset1:206
	ds_read2_b32 v[44:45], v24 offset0:231 offset1:239
	s_waitcnt lgkmcnt(7)
	v_bfe_u32 v3, v6, 16, 1
	s_waitcnt lgkmcnt(6)
	v_bfe_u32 v2, v16, 16, 1
	v_add3_u32 v2, v16, v2, s81
	v_lshrrev_b32_e32 v2, 16, v2
	v_add3_u32 v3, v6, v3, s81
	v_and_or_b32 v2, v3, s71, v2
	s_waitcnt lgkmcnt(5)
	v_bfe_u32 v3, v18, 16, 1
	v_add3_u32 v3, v18, v3, s81
	s_waitcnt lgkmcnt(4)
	v_bfe_u32 v4, v36, 16, 1
	v_lshrrev_b32_e32 v3, 16, v3
	v_add3_u32 v4, v36, v4, s81
	v_and_or_b32 v3, v4, s71, v3
	s_waitcnt lgkmcnt(3)
	v_bfe_u32 v4, v38, 16, 1
	v_add3_u32 v4, v38, v4, s81
	s_waitcnt lgkmcnt(2)
	v_bfe_u32 v5, v40, 16, 1
	v_lshrrev_b32_e32 v4, 16, v4
	v_add3_u32 v5, v40, v5, s81
	v_and_or_b32 v4, v5, s71, v4
	s_waitcnt lgkmcnt(1)
	v_bfe_u32 v5, v42, 16, 1
	v_add3_u32 v5, v42, v5, s81
	s_waitcnt lgkmcnt(0)
	v_bfe_u32 v6, v44, 16, 1
	v_lshrrev_b32_e32 v5, 16, v5
	v_add3_u32 v6, v44, v6, s81
	v_and_or_b32 v5, v6, s71, v5
	v_or_b32_e32 v6, s0, v23
	v_mul_u32_u24_e32 v6, 0xb00, v6
	v_lshl_add_u64 v[0:1], v[12:13], 0, s[46:47]
	v_lshlrev_b32_e32 v46, 1, v6
	v_mov_b32_e32 v47, v97
	v_lshl_add_u64 v[46:47], v[0:1], 0, v[46:47]
	global_store_dwordx4 v[46:47], v[2:5], off sc0 sc1
	v_bfe_u32 v6, v45, 16, 1
	v_add3_u32 v6, v45, v6, s81
	v_bfe_u32 v2, v17, 16, 1
	v_add3_u32 v2, v17, v2, s81
	v_bfe_u32 v3, v7, 16, 1
	v_lshrrev_b32_e32 v2, 16, v2
	v_add3_u32 v3, v7, v3, s81
	v_and_or_b32 v2, v3, s71, v2
	v_bfe_u32 v3, v19, 16, 1
	v_add3_u32 v3, v19, v3, s81
	v_bfe_u32 v4, v37, 16, 1
	v_lshrrev_b32_e32 v3, 16, v3
	v_add3_u32 v4, v37, v4, s81
	v_and_or_b32 v3, v4, s71, v3
	v_bfe_u32 v4, v39, 16, 1
	v_add3_u32 v4, v39, v4, s81
	v_bfe_u32 v5, v41, 16, 1
	v_lshrrev_b32_e32 v4, 16, v4
	v_add3_u32 v5, v41, v5, s81
	v_and_or_b32 v4, v5, s71, v4
	v_bfe_u32 v5, v43, 16, 1
	v_add3_u32 v5, v43, v5, s81
	v_lshrrev_b32_e32 v5, 16, v5
	v_and_or_b32 v5, v6, s71, v5
	v_or_b32_e32 v6, s0, v25
	v_mul_u32_u24_e32 v6, 0xb00, v6
	v_lshlrev_b32_e32 v6, 1, v6
	v_mov_b32_e32 v7, v97
	v_lshl_add_u64 v[6:7], v[0:1], 0, v[6:7]
	global_store_dwordx4 v[6:7], v[2:5], off sc0 sc1
	ds_read2_b32 v[6:7], v24 offset0:16 offset1:24
	ds_read2_b32 v[16:17], v24 offset0:49 offset1:57
	ds_read2_b32 v[18:19], v24 offset0:82 offset1:90
	ds_read2_b32 v[36:37], v24 offset0:115 offset1:123
	ds_read2_b32 v[38:39], v24 offset0:148 offset1:156
	ds_read2_b32 v[40:41], v24 offset0:181 offset1:189
	ds_read2_b32 v[42:43], v24 offset0:214 offset1:222
	ds_read2_b32 v[44:45], v24 offset0:247 offset1:255
	s_waitcnt lgkmcnt(7)
	v_bfe_u32 v2, v6, 16, 1
	v_add3_u32 v2, v6, v2, s81
	s_waitcnt lgkmcnt(6)
	v_bfe_u32 v3, v16, 16, 1
	v_lshrrev_b32_e32 v2, 16, v2
	v_add3_u32 v3, v16, v3, s81
	v_and_or_b32 v2, v3, s71, v2
	s_waitcnt lgkmcnt(5)
	v_bfe_u32 v3, v18, 16, 1
	v_add3_u32 v3, v18, v3, s81
	s_waitcnt lgkmcnt(4)
	v_bfe_u32 v4, v36, 16, 1
	v_lshrrev_b32_e32 v3, 16, v3
	v_add3_u32 v4, v36, v4, s81
	v_and_or_b32 v3, v4, s71, v3
	s_waitcnt lgkmcnt(3)
	v_bfe_u32 v4, v38, 16, 1
	v_add3_u32 v4, v38, v4, s81
	s_waitcnt lgkmcnt(2)
	v_bfe_u32 v5, v40, 16, 1
	v_lshrrev_b32_e32 v4, 16, v4
	v_add3_u32 v5, v40, v5, s81
	v_and_or_b32 v4, v5, s71, v4
	s_waitcnt lgkmcnt(1)
	v_bfe_u32 v5, v42, 16, 1
	v_add3_u32 v5, v42, v5, s81
	s_waitcnt lgkmcnt(0)
	v_bfe_u32 v6, v44, 16, 1
	v_lshrrev_b32_e32 v5, 16, v5
	v_add3_u32 v6, v44, v6, s81
	v_and_or_b32 v5, v6, s71, v5
	v_or_b32_e32 v6, s0, v26
	v_mul_u32_u24_e32 v6, 0xb00, v6
	v_lshlrev_b32_e32 v46, 1, v6
	v_mov_b32_e32 v47, v97
	v_lshl_add_u64 v[46:47], v[0:1], 0, v[46:47]
	global_store_dwordx4 v[46:47], v[2:5], off sc0 sc1
	v_bfe_u32 v6, v45, 16, 1
	v_add3_u32 v6, v45, v6, s81
	v_bfe_u32 v2, v7, 16, 1
	v_add3_u32 v2, v7, v2, s81
	v_bfe_u32 v3, v17, 16, 1
	v_lshrrev_b32_e32 v2, 16, v2
	v_add3_u32 v3, v17, v3, s81
	v_and_or_b32 v2, v3, s71, v2
	v_bfe_u32 v3, v19, 16, 1
	v_add3_u32 v3, v19, v3, s81
	v_bfe_u32 v4, v37, 16, 1
	v_lshrrev_b32_e32 v3, 16, v3
	v_add3_u32 v4, v37, v4, s81
	v_and_or_b32 v3, v4, s71, v3
	v_bfe_u32 v4, v39, 16, 1
	v_add3_u32 v4, v39, v4, s81
	v_bfe_u32 v5, v41, 16, 1
	v_lshrrev_b32_e32 v4, 16, v4
	v_add3_u32 v5, v41, v5, s81
	v_and_or_b32 v4, v5, s71, v4
	v_bfe_u32 v5, v43, 16, 1
	v_add3_u32 v5, v43, v5, s81
	v_lshrrev_b32_e32 v5, 16, v5
	v_and_or_b32 v5, v6, s71, v5
	v_or_b32_e32 v6, s0, v27
	v_mul_u32_u24_e32 v6, 0xb00, v6
	v_lshlrev_b32_e32 v6, 1, v6
	v_mov_b32_e32 v7, v97
	v_lshl_add_u64 v[0:1], v[0:1], 0, v[6:7]
	global_store_dwordx4 v[0:1], v[2:5], off sc0 sc1
	s_waitcnt lgkmcnt(0)

.LBB0_170:
	s_mov_b64 s[0:1], -1
	s_cmpk_gt_i32 s40, 0xaff
	v_lshlrev_b32_e32 v96, 2, v8
	v_add_u32_e32 v14, 0x400, v24
	v_add_u32_e32 v7, 0x800, v24
	v_add_u32_e32 v6, 0xc00, v24
	v_add_u32_e32 v5, 0x1000, v24
	v_add_u32_e32 v4, 0x1400, v24
	v_add_u32_e32 v3, 0x1800, v24
	v_add_u32_e32 v2, 0x1c00, v24
	s_cbranch_scc0 .LBB0_172
	s_and_b32 s0, s38, 0x7fffffc0
	s_addk_i32 s0, 0xea00
	v_or_b32_e32 v0, s0, v9
	v_mov_b32_e32 v1, v97
	v_readlane_b32 s42, v236, 62
	s_and_b32 s41, s8, 0x3e0
	v_lshlrev_b64 v[0:1], 12, v[0:1]
	v_readlane_b32 s43, v236, 63
	s_lshl_b32 s46, s41, 2
	s_movk_i32 s1, 0x4000
	v_lshl_add_u64 v[0:1], s[42:43], 0, v[0:1]
	v_lshl_add_u64 v[0:1], v[0:1], 0, s[46:47]
	v_lshl_add_u64 v[0:1], v[0:1], 0, v[96:97]
	v_add_co_u32_e32 v16, vcc, 0x2000, v0
	global_load_dword v15, v[0:1], off
	s_nop 0
	v_addc_co_u32_e32 v17, vcc, 0, v1, vcc
	global_load_dword v25, v[16:17], off
	v_add_co_u32_e32 v16, vcc, s1, v0
	s_mov_b32 s1, s47
	s_nop 0
	v_addc_co_u32_e32 v17, vcc, 0, v1, vcc
	global_load_dword v26, v[16:17], off
	v_add_co_u32_e32 v16, vcc, 0x6000, v0
	s_nop 1
	v_addc_co_u32_e32 v17, vcc, 0, v1, vcc
	global_load_dword v27, v[16:17], off
	v_add_co_u32_e32 v16, vcc, 0x8000, v0
	s_nop 1
	v_addc_co_u32_e32 v17, vcc, 0, v1, vcc
	global_load_dword v28, v[16:17], off
	v_add_co_u32_e32 v16, vcc, 0xa000, v0
	s_nop 1
	v_addc_co_u32_e32 v17, vcc, 0, v1, vcc
	global_load_dword v29, v[16:17], off
	v_add_co_u32_e32 v16, vcc, 0xc000, v0
	s_nop 1
	v_addc_co_u32_e32 v17, vcc, 0, v1, vcc
	global_load_dword v30, v[16:17], off
	v_add_co_u32_e32 v16, vcc, 0xe000, v0
	s_nop 1
	v_addc_co_u32_e32 v17, vcc, 0, v1, vcc
	global_load_dword v31, v[16:17], off
	v_add_co_u32_e32 v16, vcc, 0x10000, v0
	s_nop 1
	v_addc_co_u32_e32 v17, vcc, 0, v1, vcc
	global_load_dword v32, v[16:17], off
	v_add_co_u32_e32 v16, vcc, 0x12000, v0
	s_nop 1
	v_addc_co_u32_e32 v17, vcc, 0, v1, vcc
	global_load_dword v33, v[16:17], off
	v_add_co_u32_e32 v16, vcc, 0x14000, v0
	s_nop 1
	v_addc_co_u32_e32 v17, vcc, 0, v1, vcc
	global_load_dword v34, v[16:17], off
	v_add_co_u32_e32 v16, vcc, 0x16000, v0
	s_nop 1
	v_addc_co_u32_e32 v17, vcc, 0, v1, vcc
	global_load_dword v35, v[16:17], off
	v_add_co_u32_e32 v16, vcc, 0x18000, v0
	s_nop 1
	v_addc_co_u32_e32 v17, vcc, 0, v1, vcc
	global_load_dword v36, v[16:17], off
	v_add_co_u32_e32 v16, vcc, 0x1a000, v0
	s_nop 1
	v_addc_co_u32_e32 v17, vcc, 0, v1, vcc
	global_load_dword v37, v[16:17], off
	v_add_co_u32_e32 v16, vcc, 0x1c000, v0
	s_nop 1
	v_addc_co_u32_e32 v17, vcc, 0, v1, vcc
	global_load_dword v38, v[16:17], off
	v_add_co_u32_e32 v16, vcc, 0x1e000, v0
	s_nop 1
	v_addc_co_u32_e32 v17, vcc, 0, v1, vcc
	global_load_dword v39, v[16:17], off
	v_add_co_u32_e32 v16, vcc, 0x20000, v0
	s_nop 1
	v_addc_co_u32_e32 v17, vcc, 0, v1, vcc
	global_load_dword v40, v[16:17], off
	v_add_co_u32_e32 v16, vcc, 0x22000, v0
	s_nop 1
	v_addc_co_u32_e32 v17, vcc, 0, v1, vcc
	global_load_dword v41, v[16:17], off
	v_add_co_u32_e32 v16, vcc, 0x24000, v0
	s_nop 1
	v_addc_co_u32_e32 v17, vcc, 0, v1, vcc
	global_load_dword v42, v[16:17], off
	v_add_co_u32_e32 v16, vcc, 0x26000, v0
	s_nop 1
	v_addc_co_u32_e32 v17, vcc, 0, v1, vcc
	global_load_dword v43, v[16:17], off
	v_add_co_u32_e32 v16, vcc, 0x28000, v0
	s_nop 1
	v_addc_co_u32_e32 v17, vcc, 0, v1, vcc
	global_load_dword v44, v[16:17], off
	v_add_co_u32_e32 v16, vcc, 0x2a000, v0
	s_nop 1
	v_addc_co_u32_e32 v17, vcc, 0, v1, vcc
	global_load_dword v45, v[16:17], off
	v_add_co_u32_e32 v16, vcc, 0x2c000, v0
	s_nop 1
	v_addc_co_u32_e32 v17, vcc, 0, v1, vcc
	global_load_dword v46, v[16:17], off
	v_add_co_u32_e32 v16, vcc, 0x2e000, v0
	s_nop 1
	v_addc_co_u32_e32 v17, vcc, 0, v1, vcc
	global_load_dword v47, v[16:17], off
	v_add_co_u32_e32 v16, vcc, 0x30000, v0
	s_nop 1
	v_addc_co_u32_e32 v17, vcc, 0, v1, vcc
	global_load_dword v48, v[16:17], off
	v_add_co_u32_e32 v16, vcc, 0x32000, v0
	s_nop 1
	v_addc_co_u32_e32 v17, vcc, 0, v1, vcc
	global_load_dword v49, v[16:17], off
	v_add_co_u32_e32 v16, vcc, 0x34000, v0
	s_nop 1
	v_addc_co_u32_e32 v17, vcc, 0, v1, vcc
	global_load_dword v50, v[16:17], off
	v_add_co_u32_e32 v16, vcc, 0x36000, v0
	s_nop 1
	v_addc_co_u32_e32 v17, vcc, 0, v1, vcc
	global_load_dword v51, v[16:17], off
	v_add_co_u32_e32 v16, vcc, 0x38000, v0
	s_nop 1
	v_addc_co_u32_e32 v17, vcc, 0, v1, vcc
	global_load_dword v52, v[16:17], off
	v_add_co_u32_e32 v16, vcc, 0x3a000, v0
	s_nop 1
	v_addc_co_u32_e32 v17, vcc, 0, v1, vcc
	global_load_dword v53, v[16:17], off
	v_add_co_u32_e32 v16, vcc, 0x3c000, v0
	s_nop 1
	v_addc_co_u32_e32 v17, vcc, 0, v1, vcc
	v_add_co_u32_e32 v0, vcc, 0x3e000, v0
	global_load_dword v16, v[16:17], off
	s_nop 0
	v_addc_co_u32_e32 v1, vcc, 0, v1, vcc
	global_load_dword v0, v[0:1], off
	s_waitcnt vmcnt(0)
	ds_write2_b32 v24, v15, v25 offset1:66
	s_waitcnt vmcnt(28)
	ds_write2_b32 v24, v26, v27 offset0:132 offset1:198
	s_waitcnt vmcnt(26)
	ds_write2_b32 v14, v28, v29 offset0:8 offset1:74
	s_waitcnt vmcnt(24)
	ds_write2_b32 v14, v30, v31 offset0:140 offset1:206
	s_waitcnt vmcnt(22)
	ds_write2_b32 v7, v32, v33 offset0:16 offset1:82
	s_waitcnt vmcnt(20)
	ds_write2_b32 v7, v34, v35 offset0:148 offset1:214
	s_waitcnt vmcnt(18)
	ds_write2_b32 v6, v36, v37 offset0:24 offset1:90
	s_waitcnt vmcnt(16)
	ds_write2_b32 v6, v38, v39 offset0:156 offset1:222
	s_waitcnt vmcnt(14)
	ds_write2_b32 v5, v40, v41 offset0:32 offset1:98
	s_waitcnt vmcnt(12)
	ds_write2_b32 v5, v42, v43 offset0:164 offset1:230
	s_waitcnt vmcnt(10)
	ds_write2_b32 v4, v44, v45 offset0:40 offset1:106
	s_waitcnt vmcnt(8)
	ds_write2_b32 v4, v46, v47 offset0:172 offset1:238
	s_waitcnt vmcnt(6)
	ds_write2_b32 v3, v48, v49 offset0:48 offset1:114
	s_waitcnt vmcnt(4)
	ds_write2_b32 v3, v50, v51 offset0:180 offset1:246
	s_waitcnt vmcnt(2)
	ds_write2_b32 v2, v52, v53 offset0:56 offset1:122
	s_waitcnt vmcnt(0)
	ds_write2_b32 v2, v16, v0 offset0:188 offset1:254
	s_waitcnt lgkmcnt(0)
	ds_read2_b32 v[16:17], v20 offset0:33 offset1:41
	ds_read2_b32 v[30:31], v20 offset1:8
	ds_read2_b32 v[32:33], v20 offset0:66 offset1:74
	ds_read2_b32 v[34:35], v20 offset0:99 offset1:107
	ds_read2_b32 v[36:37], v20 offset0:132 offset1:140
	ds_read2_b32 v[38:39], v20 offset0:165 offset1:173
	ds_read2_b32 v[40:41], v20 offset0:198 offset1:206
	ds_read2_b32 v[42:43], v20 offset0:231 offset1:239
	s_waitcnt lgkmcnt(7)
	v_bfe_u32 v25, v16, 16, 1
	s_waitcnt lgkmcnt(6)
	v_bfe_u32 v15, v30, 16, 1
	v_add3_u32 v15, v30, v15, s81
	v_lshrrev_b32_e32 v15, 16, v15
	v_add3_u32 v16, v16, v25, s81
	v_and_or_b32 v26, v16, s71, v15
	s_waitcnt lgkmcnt(5)
	v_bfe_u32 v15, v32, 16, 1
	v_add3_u32 v15, v32, v15, s81
	s_waitcnt lgkmcnt(4)
	v_bfe_u32 v16, v34, 16, 1
	v_lshrrev_b32_e32 v15, 16, v15
	v_add3_u32 v16, v34, v16, s81
	v_and_or_b32 v27, v16, s71, v15
	s_waitcnt lgkmcnt(3)
	v_bfe_u32 v15, v36, 16, 1
	v_add3_u32 v15, v36, v15, s81
	s_waitcnt lgkmcnt(2)
	v_bfe_u32 v16, v38, 16, 1
	v_lshrrev_b32_e32 v15, 16, v15
	v_add3_u32 v16, v38, v16, s81
	v_and_or_b32 v28, v16, s71, v15
	s_waitcnt lgkmcnt(1)
	v_bfe_u32 v15, v40, 16, 1
	v_add3_u32 v15, v40, v15, s81
	s_waitcnt lgkmcnt(0)
	v_bfe_u32 v16, v42, 16, 1
	v_lshrrev_b32_e32 v15, 16, v15
	v_add3_u32 v16, v42, v16, s81
	v_and_or_b32 v29, v16, s71, v15
	v_or_b32_e32 v15, s41, v19
	v_mul_u32_u24_e32 v15, 0xb00, v15
	v_lshlrev_b32_e32 v44, 1, v15
	v_bfe_u32 v15, v31, 16, 1
	v_lshl_add_u64 v[0:1], s[0:1], 1, v[10:11]
	v_mov_b32_e32 v45, v97
	v_add3_u32 v15, v31, v15, s81
	v_bfe_u32 v16, v17, 16, 1
	v_lshl_add_u64 v[44:45], v[0:1], 0, v[44:45]
	v_lshrrev_b32_e32 v15, 16, v15
	v_add3_u32 v16, v17, v16, s81
	global_store_dwordx4 v[44:45], v[26:29], off sc0 sc1
	v_mov_b32_e32 v17, v97
	v_mov_b32_e32 v45, v97
	v_and_or_b32 v26, v16, s71, v15
	v_bfe_u32 v15, v33, 16, 1
	v_add3_u32 v15, v33, v15, s81
	v_bfe_u32 v16, v35, 16, 1
	v_lshrrev_b32_e32 v15, 16, v15
	v_add3_u32 v16, v35, v16, s81
	v_and_or_b32 v27, v16, s71, v15
	v_bfe_u32 v15, v37, 16, 1
	v_add3_u32 v15, v37, v15, s81
	v_bfe_u32 v16, v39, 16, 1
	v_lshrrev_b32_e32 v15, 16, v15
	v_add3_u32 v16, v39, v16, s81
	v_and_or_b32 v28, v16, s71, v15
	v_bfe_u32 v15, v41, 16, 1
	v_add3_u32 v15, v41, v15, s81
	v_bfe_u32 v16, v43, 16, 1
	v_lshrrev_b32_e32 v15, 16, v15
	v_add3_u32 v16, v43, v16, s81
	v_and_or_b32 v29, v16, s71, v15
	v_or_b32_e32 v15, s41, v21
	v_mul_u32_u24_e32 v15, 0xb00, v15
	v_lshlrev_b32_e32 v16, 1, v15
	v_lshl_add_u64 v[16:17], v[0:1], 0, v[16:17]
	global_store_dwordx4 v[16:17], v[26:29], off sc0 sc1
	ds_read2_b32 v[16:17], v20 offset0:16 offset1:24
	ds_read2_b32 v[30:31], v20 offset0:49 offset1:57
	ds_read2_b32 v[32:33], v20 offset0:82 offset1:90
	ds_read2_b32 v[34:35], v20 offset0:115 offset1:123
	ds_read2_b32 v[36:37], v20 offset0:148 offset1:156
	ds_read2_b32 v[38:39], v20 offset0:181 offset1:189
	ds_read2_b32 v[40:41], v20 offset0:214 offset1:222
	ds_read2_b32 v[42:43], v20 offset0:247 offset1:255
	s_waitcnt lgkmcnt(7)
	v_bfe_u32 v15, v16, 16, 1
	v_add3_u32 v15, v16, v15, s81
	s_waitcnt lgkmcnt(6)
	v_bfe_u32 v16, v30, 16, 1
	v_lshrrev_b32_e32 v15, 16, v15
	v_add3_u32 v16, v30, v16, s81
	v_and_or_b32 v26, v16, s71, v15
	s_waitcnt lgkmcnt(5)
	v_bfe_u32 v15, v32, 16, 1
	v_add3_u32 v15, v32, v15, s81
	s_waitcnt lgkmcnt(4)
	v_bfe_u32 v16, v34, 16, 1
	v_lshrrev_b32_e32 v15, 16, v15
	v_add3_u32 v16, v34, v16, s81
	v_and_or_b32 v27, v16, s71, v15
	s_waitcnt lgkmcnt(3)
	v_bfe_u32 v15, v36, 16, 1
	v_add3_u32 v15, v36, v15, s81
	s_waitcnt lgkmcnt(2)
	v_bfe_u32 v16, v38, 16, 1
	v_lshrrev_b32_e32 v15, 16, v15
	v_add3_u32 v16, v38, v16, s81
	v_and_or_b32 v28, v16, s71, v15
	s_waitcnt lgkmcnt(1)
	v_bfe_u32 v15, v40, 16, 1
	v_add3_u32 v15, v40, v15, s81
	s_waitcnt lgkmcnt(0)
	v_bfe_u32 v16, v42, 16, 1
	v_lshrrev_b32_e32 v15, 16, v15
	v_add3_u32 v16, v42, v16, s81
	v_and_or_b32 v29, v16, s71, v15
	v_or_b32_e32 v15, s41, v22
	v_mul_u32_u24_e32 v15, 0xb00, v15
	v_lshlrev_b32_e32 v44, 1, v15
	v_bfe_u32 v15, v17, 16, 1
	v_add3_u32 v15, v17, v15, s81
	v_bfe_u32 v16, v31, 16, 1
	v_lshl_add_u64 v[44:45], v[0:1], 0, v[44:45]
	v_lshrrev_b32_e32 v15, 16, v15
	v_add3_u32 v16, v31, v16, s81
	global_store_dwordx4 v[44:45], v[26:29], off sc0 sc1
	v_mov_b32_e32 v17, v97
	s_mov_b64 s[0:1], 0
	v_and_or_b32 v26, v16, s71, v15
	v_bfe_u32 v15, v33, 16, 1
	v_add3_u32 v15, v33, v15, s81
	v_bfe_u32 v16, v35, 16, 1
	v_lshrrev_b32_e32 v15, 16, v15
	v_add3_u32 v16, v35, v16, s81
	v_and_or_b32 v27, v16, s71, v15
	v_bfe_u32 v15, v37, 16, 1
	v_add3_u32 v15, v37, v15, s81
	v_bfe_u32 v16, v39, 16, 1
	v_lshrrev_b32_e32 v15, 16, v15
	v_add3_u32 v16, v39, v16, s81
	v_and_or_b32 v28, v16, s71, v15
	v_bfe_u32 v15, v41, 16, 1
	v_add3_u32 v15, v41, v15, s81
	v_bfe_u32 v16, v43, 16, 1
	v_lshrrev_b32_e32 v15, 16, v15
	v_add3_u32 v16, v43, v16, s81
	v_and_or_b32 v29, v16, s71, v15
	v_or_b32_e32 v15, s41, v23
	v_mul_u32_u24_e32 v15, 0xb00, v15
	v_lshlrev_b32_e32 v16, 1, v15
	v_lshl_add_u64 v[0:1], v[0:1], 0, v[16:17]
	global_store_dwordx4 v[0:1], v[26:29], off sc0 sc1
	s_waitcnt lgkmcnt(0)
.LBB0_172:
	s_andn2_b64 vcc, exec, s[0:1]
	s_cbranch_vccnz .LBB0_169
	s_mul_hi_i32 s0, s40, 0x2e8ba2e9
	s_lshr_b32 s1, s0, 31
	s_ashr_i32 s0, s0, 5
	s_add_i32 s1, s0, s1
	s_lshl_b32 s0, s1, 6
	s_mul_i32 s41, s1, 0xffffea00
	s_mulk_i32 s1, 0xf500
	s_bfe_i32 s42, s40, 0x10002
	s_add_i32 s1, s34, s1
	s_add_i32 s41, s8, s41
	s_and_b32 s42, s42, 0xb00
	s_and_b32 s1, s1, 0xffffff80
	v_readlane_b32 s48, v235, 0
	s_add_i32 s42, s42, s1
	s_and_b32 s1, s41, 0x60
	v_readlane_b32 s49, v235, 1
	s_or_b32 s42, s42, s1
	v_or_b32_e32 v15, s0, v9
	v_mov_b64_e32 v[0:1], s[48:49]
	s_movk_i32 s1, 0x5800
	v_mad_i64_i32 v[0:1], s[48:49], v15, s1, v[0:1]
	s_ashr_i32 s43, s42, 31
	v_lshl_add_u64 v[0:1], s[42:43], 2, v[0:1]
	v_lshl_add_u64 v[0:1], v[0:1], 0, v[96:97]
	s_mov_b32 s1, 0xb000
	v_add_co_u32_e32 v16, vcc, s1, v0
	s_mov_b32 s1, 0x16000
	s_nop 0
	v_addc_co_u32_e32 v17, vcc, 0, v1, vcc
	global_load_dword v15, v[0:1], off
	global_load_dword v25, v[16:17], off
	v_add_co_u32_e32 v16, vcc, s1, v0
	s_mov_b32 s1, 0x21000
	s_nop 0
	v_addc_co_u32_e32 v17, vcc, 0, v1, vcc
	global_load_dword v26, v[16:17], off
	v_add_co_u32_e32 v16, vcc, s1, v0
	s_mov_b32 s1, 0x2c000
	s_nop 0
	v_addc_co_u32_e32 v17, vcc, 0, v1, vcc
	global_load_dword v27, v[16:17], off
	v_add_co_u32_e32 v16, vcc, s1, v0
	s_mov_b32 s1, 0x37000
	s_nop 0
	v_addc_co_u32_e32 v17, vcc, 0, v1, vcc
	global_load_dword v28, v[16:17], off
	v_add_co_u32_e32 v16, vcc, s1, v0
	s_mov_b32 s1, 0x42000
	s_nop 0
	v_addc_co_u32_e32 v17, vcc, 0, v1, vcc
	global_load_dword v29, v[16:17], off
	v_add_co_u32_e32 v16, vcc, s1, v0
	s_mov_b32 s1, 0x4d000
	s_nop 0
	v_addc_co_u32_e32 v17, vcc, 0, v1, vcc
	global_load_dword v30, v[16:17], off
	v_add_co_u32_e32 v16, vcc, s1, v0
	s_mov_b32 s1, 0x58000
	s_nop 0
	v_addc_co_u32_e32 v17, vcc, 0, v1, vcc
	global_load_dword v31, v[16:17], off
	v_add_co_u32_e32 v16, vcc, s1, v0
	s_mov_b32 s1, 0x63000
	s_nop 0
	v_addc_co_u32_e32 v17, vcc, 0, v1, vcc
	global_load_dword v32, v[16:17], off
	v_add_co_u32_e32 v16, vcc, s1, v0
	s_mov_b32 s1, 0x6e000
	s_nop 0
	v_addc_co_u32_e32 v17, vcc, 0, v1, vcc
	global_load_dword v33, v[16:17], off
	v_add_co_u32_e32 v16, vcc, s1, v0
	s_mov_b32 s1, 0x79000
	s_nop 0
	v_addc_co_u32_e32 v17, vcc, 0, v1, vcc
	global_load_dword v34, v[16:17], off
	v_add_co_u32_e32 v16, vcc, s1, v0
	s_mov_b32 s1, 0x84000
	s_nop 0
	v_addc_co_u32_e32 v17, vcc, 0, v1, vcc
	global_load_dword v35, v[16:17], off
	v_add_co_u32_e32 v16, vcc, s1, v0
	s_mov_b32 s1, 0x8f000
	s_nop 0
	v_addc_co_u32_e32 v17, vcc, 0, v1, vcc
	global_load_dword v36, v[16:17], off
	v_add_co_u32_e32 v16, vcc, s1, v0
	s_mov_b32 s1, 0x9a000
	s_nop 0
	v_addc_co_u32_e32 v17, vcc, 0, v1, vcc
	global_load_dword v37, v[16:17], off
	v_add_co_u32_e32 v16, vcc, s1, v0
	s_mov_b32 s1, 0xa5000
	s_nop 0
	v_addc_co_u32_e32 v17, vcc, 0, v1, vcc
	global_load_dword v38, v[16:17], off
	v_add_co_u32_e32 v16, vcc, s1, v0
	s_mov_b32 s1, 0xb0000
	s_nop 0
	v_addc_co_u32_e32 v17, vcc, 0, v1, vcc
	global_load_dword v39, v[16:17], off
	v_add_co_u32_e32 v16, vcc, s1, v0
	s_mov_b32 s1, 0xbb000
	s_nop 0
	v_addc_co_u32_e32 v17, vcc, 0, v1, vcc
	global_load_dword v40, v[16:17], off
	v_add_co_u32_e32 v16, vcc, s1, v0
	s_mov_b32 s1, 0xc6000
	s_nop 0
	v_addc_co_u32_e32 v17, vcc, 0, v1, vcc
	global_load_dword v41, v[16:17], off
	v_add_co_u32_e32 v16, vcc, s1, v0
	s_mov_b32 s1, 0xd1000
	s_nop 0
	v_addc_co_u32_e32 v17, vcc, 0, v1, vcc
	global_load_dword v42, v[16:17], off
	v_add_co_u32_e32 v16, vcc, s1, v0
	s_mov_b32 s1, 0xdc000
	s_nop 0
	v_addc_co_u32_e32 v17, vcc, 0, v1, vcc
	global_load_dword v43, v[16:17], off
	v_add_co_u32_e32 v16, vcc, s1, v0
	s_mov_b32 s1, 0xe7000
	s_nop 0
	v_addc_co_u32_e32 v17, vcc, 0, v1, vcc
	global_load_dword v44, v[16:17], off
	v_add_co_u32_e32 v16, vcc, s1, v0
	s_mov_b32 s1, 0xf2000
	s_nop 0
	v_addc_co_u32_e32 v17, vcc, 0, v1, vcc
	global_load_dword v45, v[16:17], off
	v_add_co_u32_e32 v16, vcc, s1, v0
	s_mov_b32 s1, 0xfd000
	s_nop 0
	v_addc_co_u32_e32 v17, vcc, 0, v1, vcc
	global_load_dword v46, v[16:17], off
	v_add_co_u32_e32 v16, vcc, s1, v0
	s_mov_b32 s1, 0x108000
	s_nop 0
	v_addc_co_u32_e32 v17, vcc, 0, v1, vcc
	global_load_dword v47, v[16:17], off
	v_add_co_u32_e32 v16, vcc, s1, v0
	s_mov_b32 s1, 0x113000
	s_nop 0
	v_addc_co_u32_e32 v17, vcc, 0, v1, vcc
	global_load_dword v48, v[16:17], off
	v_add_co_u32_e32 v16, vcc, s1, v0
	s_mov_b32 s1, 0x11e000
	s_nop 0
	v_addc_co_u32_e32 v17, vcc, 0, v1, vcc
	global_load_dword v49, v[16:17], off
	v_add_co_u32_e32 v16, vcc, s1, v0
	s_mov_b32 s1, 0x129000
	s_nop 0
	v_addc_co_u32_e32 v17, vcc, 0, v1, vcc
	global_load_dword v50, v[16:17], off
	v_add_co_u32_e32 v16, vcc, s1, v0
	s_mov_b32 s1, 0x134000
	s_nop 0
	v_addc_co_u32_e32 v17, vcc, 0, v1, vcc
	global_load_dword v51, v[16:17], off
	v_add_co_u32_e32 v16, vcc, s1, v0
	s_mov_b32 s1, 0x13f000
	s_nop 0
	v_addc_co_u32_e32 v17, vcc, 0, v1, vcc
	global_load_dword v52, v[16:17], off
	v_add_co_u32_e32 v16, vcc, s1, v0
	s_mov_b32 s1, 0x14a000
	s_nop 0
	v_addc_co_u32_e32 v17, vcc, 0, v1, vcc
	global_load_dword v53, v[16:17], off
	v_add_co_u32_e32 v16, vcc, s1, v0
	s_mov_b32 s1, 0x155000
	s_nop 0
	v_addc_co_u32_e32 v17, vcc, 0, v1, vcc
	v_add_co_u32_e32 v0, vcc, s1, v0
	global_load_dword v16, v[16:17], off
	s_nop 0
	v_addc_co_u32_e32 v1, vcc, 0, v1, vcc
	global_load_dword v0, v[0:1], off
	s_and_b32 s1, s0, 0x3c0
	v_or_b32_e32 v1, s1, v18
	s_ashr_i32 s1, s0, 31
	s_waitcnt vmcnt(0)
	ds_write2_b32 v24, v15, v25 offset1:66
	s_waitcnt vmcnt(28)
	ds_write2_b32 v24, v26, v27 offset0:132 offset1:198
	s_waitcnt vmcnt(26)
	ds_write2_b32 v14, v28, v29 offset0:8 offset1:74
	s_waitcnt vmcnt(24)
	ds_write2_b32 v14, v30, v31 offset0:140 offset1:206
	s_waitcnt vmcnt(22)
	ds_write2_b32 v7, v32, v33 offset0:16 offset1:82
	s_waitcnt vmcnt(20)
	ds_write2_b32 v7, v34, v35 offset0:148 offset1:214
	s_waitcnt vmcnt(18)
	ds_write2_b32 v6, v36, v37 offset0:24 offset1:90
	s_waitcnt vmcnt(16)
	ds_write2_b32 v6, v38, v39 offset0:156 offset1:222
	s_waitcnt vmcnt(14)
	ds_write2_b32 v5, v40, v41 offset0:32 offset1:98
	s_waitcnt vmcnt(12)
	ds_write2_b32 v5, v42, v43 offset0:164 offset1:230
	s_waitcnt vmcnt(10)
	ds_write2_b32 v4, v44, v45 offset0:40 offset1:106
	s_waitcnt vmcnt(8)
	ds_write2_b32 v4, v46, v47 offset0:172 offset1:238
	s_waitcnt vmcnt(6)
	ds_write2_b32 v3, v48, v49 offset0:48 offset1:114
	s_waitcnt vmcnt(4)
	ds_write2_b32 v3, v50, v51 offset0:180 offset1:246
	s_waitcnt vmcnt(2)
	ds_write2_b32 v2, v52, v53 offset0:56 offset1:122
	s_waitcnt vmcnt(0)
	ds_write2_b32 v2, v16, v0 offset0:188 offset1:254
	v_lshl_add_u64 v[14:15], s[0:1], 1, v[12:13]
	v_readlane_b32 s0, v235, 2
	v_lshlrev_b32_e32 v17, 2, v1
	v_readlane_b32 s1, v235, 3
	s_nop 4
	global_load_dwordx4 v[0:3], v17, s[0:1] offset:16
	global_load_dwordx4 v[4:7], v17, s[0:1]
	s_waitcnt lgkmcnt(0)
	s_waitcnt vmcnt(1)
	v_mov_b32_e32 v42, v0
	s_waitcnt vmcnt(0)
	v_mov_b32_e32 v16, v4
	v_mov_b32_e32 v17, v6
	v_mov_b32_e32 v6, v5
	ds_read2_b32 v[4:5], v20 offset0:33 offset1:41
	ds_read2_b32 v[30:31], v20 offset0:66 offset1:74
	ds_read2_b32 v[32:33], v20 offset1:8
	ds_read2_b32 v[34:35], v20 offset0:99 offset1:107
	ds_read2_b32 v[36:37], v20 offset0:132 offset1:140
	ds_read2_b32 v[38:39], v20 offset0:165 offset1:173
	ds_read2_b32 v[40:41], v20 offset0:198 offset1:206
	ds_read2_b32 v[46:47], v20 offset0:231 offset1:239
	s_waitcnt lgkmcnt(7)
	v_mov_b32_e32 v28, v4
	v_mov_b32_e32 v43, v2
	s_waitcnt lgkmcnt(4)
	v_mov_b32_e32 v29, v34
	v_pk_mul_f32 v[28:29], v[6:7], v[28:29]
	s_waitcnt lgkmcnt(3)
	v_mov_b32_e32 v44, v36
	s_waitcnt lgkmcnt(1)
	v_mov_b32_e32 v45, v40
	v_mov_b32_e32 v2, v1
	v_mov_b32_e32 v0, v38
	s_waitcnt lgkmcnt(0)
	v_mov_b32_e32 v1, v46
	v_mov_b32_e32 v26, v32
	v_mov_b32_e32 v27, v30
	v_pk_mul_f32 v[44:45], v[42:43], v[44:45]
	v_pk_mul_f32 v[0:1], v[2:3], v[0:1]
	v_bfe_u32 v30, v29, 16, 1
	v_bfe_u32 v32, v28, 16, 1
	v_pk_mul_f32 v[26:27], v[16:17], v[26:27]
	v_bfe_u32 v4, v1, 16, 1
	v_bfe_u32 v25, v0, 16, 1
	v_add3_u32 v32, v28, v32, s81
	v_add3_u32 v30, v29, v30, s81
	v_bfe_u32 v28, v44, 16, 1
	v_bfe_u32 v29, v45, 16, 1
	v_add3_u32 v0, v0, v25, s81
	v_add3_u32 v1, v1, v4, s81
	v_bfe_u32 v4, v26, 16, 1
	v_bfe_u32 v25, v27, 16, 1
	v_add3_u32 v29, v45, v29, s81
	v_add3_u32 v28, v44, v28, s81
	v_add_u32_e32 v44, s41, v19
	v_add3_u32 v25, v27, v25, s81
	v_add3_u32 v4, v26, v4, s81
	v_lshrrev_b32_e32 v26, 16, v28
	v_lshrrev_b32_e32 v27, 16, v29
	v_ashrrev_i32_e32 v45, 31, v44
	v_lshrrev_b32_e32 v4, 16, v4
	v_lshrrev_b32_e32 v25, 16, v25
	v_and_or_b32 v29, v1, s71, v27
	v_and_or_b32 v28, v0, s71, v26
	v_lshlrev_b64 v[0:1], 11, v[44:45]
	v_and_or_b32 v27, v30, s71, v25
	v_and_or_b32 v26, v32, s71, v4
	v_lshl_add_u64 v[0:1], v[14:15], 0, v[0:1]
	v_mov_b32_e32 v34, v5
	v_mov_b32_e32 v46, v39
	global_store_dwordx4 v[0:1], v[26:29], off sc0 sc1
	v_mov_b32_e32 v30, v33
	v_pk_mul_f32 v[4:5], v[6:7], v[34:35]
	v_mov_b32_e32 v40, v37
	v_pk_mul_f32 v[28:29], v[2:3], v[46:47]
	v_pk_mul_f32 v[0:1], v[16:17], v[30:31]
	v_pk_mul_f32 v[26:27], v[42:43], v[40:41]
	v_bfe_u32 v25, v29, 16, 1
	v_bfe_u32 v31, v5, 16, 1
	v_bfe_u32 v30, v28, 16, 1
	v_bfe_u32 v32, v4, 16, 1
	v_add3_u32 v5, v5, v31, s81
	v_add3_u32 v25, v29, v25, s81
	v_bfe_u32 v29, v0, 16, 1
	v_bfe_u32 v31, v26, 16, 1
	v_add3_u32 v4, v4, v32, s81
	v_add3_u32 v28, v28, v30, s81
	v_bfe_u32 v30, v1, 16, 1
	v_bfe_u32 v32, v27, 16, 1
	v_add3_u32 v26, v26, v31, s81
	v_add3_u32 v0, v0, v29, s81
	v_add3_u32 v27, v27, v32, s81
	v_add3_u32 v1, v1, v30, s81
	v_lshrrev_b32_e32 v0, 16, v0
	v_lshrrev_b32_e32 v26, 16, v26
	v_lshrrev_b32_e32 v1, 16, v1
	v_lshrrev_b32_e32 v27, 16, v27
	v_and_or_b32 v28, v28, s71, v26
	v_and_or_b32 v26, v4, s71, v0
	v_add_u32_e32 v0, 8, v44
	v_and_or_b32 v29, v25, s71, v27
	v_and_or_b32 v27, v5, s71, v1
	v_ashrrev_i32_e32 v1, 31, v0
	v_lshlrev_b64 v[0:1], 11, v[0:1]
	v_lshl_add_u64 v[0:1], v[14:15], 0, v[0:1]
	global_store_dwordx4 v[0:1], v[26:29], off sc0 sc1
	ds_read2_b32 v[0:1], v20 offset0:49 offset1:57
	ds_read2_b32 v[4:5], v20 offset0:82 offset1:90
	ds_read2_b32 v[30:31], v20 offset0:115 offset1:123
	ds_read2_b32 v[32:33], v20 offset0:16 offset1:24
	ds_read2_b32 v[34:35], v20 offset0:148 offset1:156
	ds_read2_b32 v[36:37], v20 offset0:181 offset1:189
	ds_read2_b32 v[38:39], v20 offset0:214 offset1:222
	ds_read2_b32 v[40:41], v20 offset0:247 offset1:255
	s_waitcnt lgkmcnt(7)
	v_mov_b32_e32 v28, v0
	s_waitcnt lgkmcnt(3)
	v_mov_b32_e32 v46, v34
	v_mov_b32_e32 v29, v30
	s_waitcnt lgkmcnt(1)
	v_mov_b32_e32 v47, v38
	v_mov_b32_e32 v26, v32
	v_mov_b32_e32 v27, v4
	v_pk_mul_f32 v[28:29], v[6:7], v[28:29]
	v_pk_mul_f32 v[46:47], v[42:43], v[46:47]
	v_mov_b32_e32 v48, v36
	s_waitcnt lgkmcnt(0)
	v_mov_b32_e32 v49, v40
	v_pk_mul_f32 v[26:27], v[16:17], v[26:27]
	v_pk_mul_f32 v[48:49], v[2:3], v[48:49]
	v_bfe_u32 v30, v28, 16, 1
	v_bfe_u32 v32, v46, 16, 1
	v_bfe_u32 v4, v48, 16, 1
	v_bfe_u32 v25, v29, 16, 1
	v_add3_u32 v30, v28, v30, s81
	v_bfe_u32 v28, v26, 16, 1
	v_add3_u32 v32, v46, v32, s81
	v_add3_u32 v25, v29, v25, s81
	v_add3_u32 v4, v48, v4, s81
	v_bfe_u32 v29, v27, 16, 1
	v_bfe_u32 v34, v47, 16, 1
	v_add3_u32 v26, v26, v28, s81
	v_lshrrev_b32_e32 v28, 16, v32
	v_add_u32_e32 v46, 16, v44
	v_mov_b32_e32 v40, v37
	v_bfe_u32 v0, v49, 16, 1
	v_add3_u32 v34, v47, v34, s81
	v_add3_u32 v27, v27, v29, s81
	v_lshrrev_b32_e32 v26, 16, v26
	v_and_or_b32 v28, v4, s71, v28
	v_ashrrev_i32_e32 v47, 31, v46
	v_mov_b32_e32 v4, v33
	v_pk_mul_f32 v[2:3], v[2:3], v[40:41]
	v_add3_u32 v0, v49, v0, s81
	v_lshrrev_b32_e32 v27, 16, v27
	v_lshrrev_b32_e32 v29, 16, v34
	v_and_or_b32 v26, v30, s71, v26
	v_lshlrev_b64 v[46:47], 11, v[46:47]
	v_pk_mul_f32 v[4:5], v[16:17], v[4:5]
	v_mov_b32_e32 v30, v1
	v_bfe_u32 v16, v3, 16, 1
	v_and_or_b32 v29, v0, s71, v29
	v_and_or_b32 v27, v25, s71, v27
	v_lshl_add_u64 v[46:47], v[14:15], 0, v[46:47]
	v_pk_mul_f32 v[0:1], v[6:7], v[30:31]
	v_bfe_u32 v17, v2, 16, 1
	v_add3_u32 v3, v3, v16, s81
	v_bfe_u32 v16, v4, 16, 1
	global_store_dwordx4 v[46:47], v[26:29], off sc0 sc1
	v_mov_b32_e32 v38, v35
	v_add3_u32 v2, v2, v17, s81
	v_bfe_u32 v26, v0, 16, 1
	v_bfe_u32 v17, v5, 16, 1
	v_add3_u32 v4, v4, v16, s81
	v_pk_mul_f32 v[6:7], v[42:43], v[38:39]
	v_bfe_u32 v25, v1, 16, 1
	v_add3_u32 v0, v0, v26, s81
	v_add3_u32 v5, v5, v17, s81
	v_lshrrev_b32_e32 v4, 16, v4
	v_add3_u32 v1, v1, v25, s81
	v_bfe_u32 v25, v6, 16, 1
	v_bfe_u32 v26, v7, 16, 1
	v_lshrrev_b32_e32 v5, 16, v5
	v_and_or_b32 v0, v0, s71, v4
	v_add_u32_e32 v4, 24, v44
	v_add3_u32 v7, v7, v26, s81
	v_add3_u32 v6, v6, v25, s81
	v_and_or_b32 v1, v1, s71, v5
	v_ashrrev_i32_e32 v5, 31, v4
	v_lshrrev_b32_e32 v6, 16, v6
	v_lshrrev_b32_e32 v7, 16, v7
	v_lshlrev_b64 v[4:5], 11, v[4:5]
	v_and_or_b32 v3, v3, s71, v7
	v_and_or_b32 v2, v2, s71, v6
	v_lshl_add_u64 v[4:5], v[14:15], 0, v[4:5]
	global_store_dwordx4 v[4:5], v[0:3], off sc0 sc1
	s_waitcnt lgkmcnt(0)
	s_branch .LBB0_169

.LBB0_176:
	s_waitcnt vmcnt(0)
	ds_write2_b32 v25, v20, v21 offset1:66
	s_waitcnt vmcnt(28)
	ds_write2_b32 v25, v22, v23 offset0:132 offset1:198
	v_add_u32_e32 v20, 0x400, v25
	s_waitcnt vmcnt(26)
	ds_write2_b32 v20, v31, v32 offset0:8 offset1:74
	s_waitcnt vmcnt(24)
	ds_write2_b32 v20, v33, v34 offset0:140 offset1:206
	v_add_u32_e32 v20, 0x800, v25
	s_waitcnt vmcnt(22)
	ds_write2_b32 v20, v35, v36 offset0:16 offset1:82
	s_waitcnt vmcnt(20)
	ds_write2_b32 v20, v37, v38 offset0:148 offset1:214
	v_add_u32_e32 v20, 0xc00, v25
	s_waitcnt vmcnt(18)
	ds_write2_b32 v20, v39, v40 offset0:24 offset1:90
	s_waitcnt vmcnt(16)
	ds_write2_b32 v20, v41, v42 offset0:156 offset1:222
	v_add_u32_e32 v20, 0x1000, v25
	s_waitcnt vmcnt(14)
	ds_write2_b32 v20, v43, v44 offset0:32 offset1:98
	s_waitcnt vmcnt(12)
	ds_write2_b32 v20, v45, v46 offset0:164 offset1:230
	v_add_u32_e32 v20, 0x1400, v25
	s_waitcnt vmcnt(10)
	ds_write2_b32 v20, v47, v48 offset0:40 offset1:106
	s_waitcnt vmcnt(8)
	ds_write2_b32 v20, v49, v50 offset0:172 offset1:238
	v_add_u32_e32 v20, 0x1800, v25
	s_waitcnt vmcnt(6)
	ds_write2_b32 v20, v51, v52 offset0:48 offset1:114
	s_waitcnt vmcnt(4)
	ds_write2_b32 v20, v53, v54 offset0:180 offset1:246
	v_add_u32_e32 v20, 0x1c00, v25
	s_waitcnt vmcnt(2)
	ds_write2_b32 v20, v55, v56 offset0:56 offset1:122
	s_waitcnt vmcnt(0)
	ds_write2_b32 v20, v57, v58 offset0:188 offset1:254
	s_waitcnt lgkmcnt(0)
	ds_read2_b32 v[32:33], v27 offset1:8
	ds_read2_b32 v[34:35], v27 offset0:66 offset1:74
	ds_read2_b32 v[38:39], v27 offset0:33 offset1:41
	ds_read2_b32 v[40:41], v27 offset0:99 offset1:107
	ds_read2_b32 v[42:43], v27 offset0:132 offset1:140
	ds_read2_b32 v[44:45], v27 offset0:198 offset1:206
	ds_read2_b32 v[46:47], v27 offset0:165 offset1:173
	ds_read2_b32 v[48:49], v27 offset0:231 offset1:239
	s_sub_i32 s0, 0, s35
	s_waitcnt lgkmcnt(5)
	v_mov_b32_e32 v22, v38
	s_waitcnt lgkmcnt(4)
	v_mov_b32_e32 v23, v40
	s_waitcnt lgkmcnt(3)
	v_mov_b32_e32 v50, v42
	s_waitcnt lgkmcnt(2)
	v_mov_b32_e32 v51, v44
	s_waitcnt lgkmcnt(1)
	v_mov_b32_e32 v52, v46
	s_waitcnt lgkmcnt(0)
	v_mov_b32_e32 v53, v48
	v_mov_b32_e32 v20, v32
	v_mov_b32_e32 v21, v34
	v_pk_mul_f32 v[22:23], v[0:1], v[22:23]
	v_pk_mul_f32 v[50:51], v[6:7], v[50:51]
	v_pk_mul_f32 v[52:53], v[4:5], v[52:53]
	v_pk_mul_f32 v[20:21], v[2:3], v[20:21]
	v_bfe_u32 v31, v53, 16, 1
	v_bfe_u32 v32, v52, 16, 1
	v_bfe_u32 v34, v23, 16, 1
	v_bfe_u32 v38, v22, 16, 1
	v_bfe_u32 v40, v50, 16, 1
	s_add_i32 s0, s0, s8
	v_add3_u32 v38, v22, v38, s81
	v_add3_u32 v34, v23, v34, s81
	v_add3_u32 v22, v52, v32, s81
	v_add3_u32 v23, v53, v31, s81
	v_bfe_u32 v31, v20, 16, 1
	v_bfe_u32 v32, v21, 16, 1
	v_bfe_u32 v42, v51, 16, 1
	v_add3_u32 v40, v50, v40, s81
	v_add_u32_e32 v50, s0, v26
	s_ashr_i32 s35, s34, 31
	v_add3_u32 v42, v51, v42, s81
	v_add3_u32 v21, v21, v32, s81
	v_add3_u32 v20, v20, v31, s81
	v_ashrrev_i32_e32 v51, 31, v50
	v_lshl_add_u64 v[36:37], s[34:35], 1, v[18:19]
	v_lshrrev_b32_e32 v20, 16, v20
	v_lshrrev_b32_e32 v21, 16, v21
	v_lshrrev_b32_e32 v31, 16, v40
	v_lshrrev_b32_e32 v32, 16, v42
	v_lshlrev_b64 v[52:53], 11, v[50:51]
	v_and_or_b32 v23, v23, s71, v32
	v_and_or_b32 v22, v22, s71, v31
	v_and_or_b32 v21, v34, s71, v21
	v_and_or_b32 v20, v38, s71, v20
	v_lshl_add_u64 v[52:53], v[36:37], 0, v[52:53]
	v_mov_b32_e32 v34, v33
	v_mov_b32_e32 v40, v39
	v_mov_b32_e32 v48, v47
	global_store_dwordx4 v[52:53], v[20:23], off sc0 sc1
	v_mov_b32_e32 v44, v43
	v_pk_mul_f32 v[32:33], v[6:7], v[44:45]
	v_pk_mul_f32 v[20:21], v[2:3], v[34:35]
	v_pk_mul_f32 v[22:23], v[0:1], v[40:41]
	v_pk_mul_f32 v[34:35], v[4:5], v[48:49]
	v_bfe_u32 v39, v23, 16, 1
	v_bfe_u32 v31, v35, 16, 1
	v_bfe_u32 v38, v34, 16, 1
	v_bfe_u32 v40, v22, 16, 1
	v_add3_u32 v40, v22, v40, s81
	v_add3_u32 v39, v23, v39, s81
	v_add3_u32 v22, v34, v38, s81
	v_add3_u32 v23, v35, v31, s81
	v_bfe_u32 v35, v32, 16, 1
	v_bfe_u32 v38, v33, 16, 1
	v_bfe_u32 v31, v20, 16, 1
	v_add3_u32 v33, v33, v38, s81
	v_add3_u32 v32, v32, v35, s81
	v_add3_u32 v20, v20, v31, s81
	v_lshrrev_b32_e32 v31, 16, v32
	v_lshrrev_b32_e32 v32, 16, v33
	v_bfe_u32 v34, v21, 16, 1
	v_and_or_b32 v23, v23, s71, v32
	v_add_u32_e32 v32, 8, v50
	v_add3_u32 v21, v21, v34, s81
	v_ashrrev_i32_e32 v33, 31, v32
	v_lshrrev_b32_e32 v20, 16, v20
	v_lshrrev_b32_e32 v21, 16, v21
	v_lshlrev_b64 v[32:33], 11, v[32:33]
	v_and_or_b32 v22, v22, s71, v31
	v_and_or_b32 v21, v39, s71, v21
	v_and_or_b32 v20, v40, s71, v20
	v_lshl_add_u64 v[32:33], v[36:37], 0, v[32:33]
	ds_read2_b32 v[34:35], v27 offset0:16 offset1:24
	ds_read2_b32 v[38:39], v27 offset0:82 offset1:90
	global_store_dwordx4 v[32:33], v[20:23], off sc0 sc1
	ds_read2_b32 v[32:33], v27 offset0:49 offset1:57
	ds_read2_b32 v[40:41], v27 offset0:115 offset1:123
	ds_read2_b32 v[42:43], v27 offset0:148 offset1:156
	ds_read2_b32 v[44:45], v27 offset0:214 offset1:222
	ds_read2_b32 v[46:47], v27 offset0:181 offset1:189
	ds_read2_b32 v[48:49], v27 offset0:247 offset1:255
	s_waitcnt lgkmcnt(7)
	v_mov_b32_e32 v20, v34
	s_waitcnt lgkmcnt(5)
	v_mov_b32_e32 v22, v32
	s_waitcnt lgkmcnt(4)
	v_mov_b32_e32 v23, v40
	s_waitcnt lgkmcnt(3)
	v_mov_b32_e32 v52, v42
	s_waitcnt lgkmcnt(2)
	v_mov_b32_e32 v53, v44
	s_waitcnt lgkmcnt(1)
	v_mov_b32_e32 v54, v46
	s_waitcnt lgkmcnt(0)
	v_mov_b32_e32 v55, v48
	v_mov_b32_e32 v21, v38
	v_pk_mul_f32 v[22:23], v[0:1], v[22:23]
	v_pk_mul_f32 v[52:53], v[6:7], v[52:53]
	v_pk_mul_f32 v[54:55], v[4:5], v[54:55]
	v_pk_mul_f32 v[20:21], v[2:3], v[20:21]
	v_bfe_u32 v31, v55, 16, 1
	v_bfe_u32 v32, v54, 16, 1
	v_bfe_u32 v34, v23, 16, 1
	v_bfe_u32 v38, v22, 16, 1
	v_bfe_u32 v40, v52, 16, 1
	v_add3_u32 v38, v22, v38, s81
	v_add3_u32 v34, v23, v34, s81
	v_add3_u32 v22, v54, v32, s81
	v_add3_u32 v23, v55, v31, s81
	v_bfe_u32 v31, v20, 16, 1
	v_bfe_u32 v32, v21, 16, 1
	v_bfe_u32 v42, v53, 16, 1
	v_add3_u32 v40, v52, v40, s81
	v_add_u32_e32 v52, 16, v50
	v_add3_u32 v42, v53, v42, s81
	v_add3_u32 v21, v21, v32, s81
	v_add3_u32 v20, v20, v31, s81
	v_ashrrev_i32_e32 v53, 31, v52
	v_lshrrev_b32_e32 v20, 16, v20
	v_lshrrev_b32_e32 v21, 16, v21
	v_lshrrev_b32_e32 v31, 16, v40
	v_lshrrev_b32_e32 v32, 16, v42
	v_lshlrev_b64 v[52:53], 11, v[52:53]
	v_mov_b32_e32 v40, v33
	v_mov_b32_e32 v48, v47
	v_and_or_b32 v23, v23, s71, v32
	v_and_or_b32 v22, v22, s71, v31
	v_and_or_b32 v21, v34, s71, v21
	v_and_or_b32 v20, v38, s71, v20
	v_lshl_add_u64 v[52:53], v[36:37], 0, v[52:53]
	v_mov_b32_e32 v38, v35
	v_pk_mul_f32 v[0:1], v[0:1], v[40:41]
	v_mov_b32_e32 v44, v43
	v_pk_mul_f32 v[4:5], v[4:5], v[48:49]
	global_store_dwordx4 v[52:53], v[20:23], off sc0 sc1
	v_pk_mul_f32 v[2:3], v[2:3], v[38:39]
	v_pk_mul_f32 v[6:7], v[6:7], v[44:45]
	v_bfe_u32 v20, v5, 16, 1
	v_bfe_u32 v22, v1, 16, 1
	v_bfe_u32 v21, v4, 16, 1
	v_bfe_u32 v23, v0, 16, 1
	v_add3_u32 v1, v1, v22, s81
	v_add3_u32 v5, v5, v20, s81
	v_bfe_u32 v20, v2, 16, 1
	v_bfe_u32 v22, v6, 16, 1
	v_add3_u32 v0, v0, v23, s81
	v_add3_u32 v4, v4, v21, s81
	v_bfe_u32 v21, v3, 16, 1
	v_bfe_u32 v23, v7, 16, 1
	v_add3_u32 v6, v6, v22, s81
	v_add3_u32 v2, v2, v20, s81
	v_add3_u32 v7, v7, v23, s81
	v_add3_u32 v3, v3, v21, s81
	v_lshrrev_b32_e32 v20, 16, v2
	v_lshrrev_b32_e32 v2, 16, v6
	v_lshrrev_b32_e32 v21, 16, v3
	v_lshrrev_b32_e32 v3, 16, v7
	v_and_or_b32 v2, v4, s71, v2
	v_add_u32_e32 v4, 24, v50
	v_and_or_b32 v3, v5, s71, v3
	v_ashrrev_i32_e32 v5, 31, v4
	v_lshlrev_b64 v[4:5], 11, v[4:5]
	v_and_or_b32 v1, v1, s71, v21
	v_and_or_b32 v0, v0, s71, v20
	v_lshl_add_u64 v[4:5], v[36:37], 0, v[4:5]
	global_store_dwordx4 v[4:5], v[0:3], off sc0 sc1
	s_waitcnt lgkmcnt(0)

.LBB0_178:
	s_cmpk_gt_i32 s40, 0x1ff
	s_mov_b64 s[0:1], -1
	s_cbranch_scc0 .LBB0_208
	s_cmpk_gt_u32 s40, 0x3ff
	s_cbranch_scc0 .LBB0_189
	s_cmpk_gt_u32 s40, 0xeff
	s_cbranch_scc0 .LBB0_186
	s_and_b32 s34, s8, 0x3e0
	s_cmpk_gt_u32 s40, 0x147f
	v_or_b32_e32 v32, s34, v26
	v_or_b32_e32 v31, s34, v28
	v_or_b32_e32 v23, s34, v29
	v_or_b32_e32 v22, s34, v30
	s_cbranch_scc0 .LBB0_183
	s_and_b32 s0, s38, 0x7fffffc0
	s_addk_i32 s0, 0xd700
	v_or_b32_e32 v96, s0, v9
	v_readlane_b32 s48, v236, 0
	v_lshlrev_b64 v[0:1], 12, v[96:97]
	v_readlane_b32 s50, v236, 2
	v_readlane_b32 s51, v236, 3
	s_lshl_b32 s46, s34, 2
	v_lshlrev_b32_e32 v96, 2, v8
	v_lshl_add_u64 v[0:1], s[50:51], 0, v[0:1]
	v_lshl_add_u64 v[0:1], v[0:1], 0, s[46:47]
	v_lshl_add_u64 v[0:1], v[0:1], 0, v[96:97]
	v_add_co_u32_e32 v2, vcc, 0x2000, v0
	s_movk_i32 s1, 0x4000
	s_waitcnt lgkmcnt(0)
	v_addc_co_u32_e32 v3, vcc, 0, v1, vcc
	global_load_dword v4, v[0:1], off
	global_load_dword v5, v[2:3], off
	v_add_co_u32_e32 v2, vcc, s1, v0
	s_and_b32 s1, s0, 0x3c0
	s_nop 0
	v_addc_co_u32_e32 v3, vcc, 0, v1, vcc
	global_load_dword v6, v[2:3], off
	v_add_co_u32_e32 v2, vcc, 0x6000, v0
	v_lshlrev_b32_e32 v96, 11, v32
	s_nop 0
	v_addc_co_u32_e32 v3, vcc, 0, v1, vcc
	global_load_dword v7, v[2:3], off
	v_add_co_u32_e32 v2, vcc, 0x8000, v0
	v_readlane_b32 s49, v236, 1
	s_nop 0
	v_addc_co_u32_e32 v3, vcc, 0, v1, vcc
	global_load_dword v20, v[2:3], off
	v_add_co_u32_e32 v2, vcc, 0xa000, v0
	v_readlane_b32 s52, v236, 4
	s_nop 0
	v_addc_co_u32_e32 v3, vcc, 0, v1, vcc
	global_load_dword v21, v[2:3], off
	v_add_co_u32_e32 v2, vcc, 0xc000, v0
	v_readlane_b32 s53, v236, 5
	s_nop 0
	v_addc_co_u32_e32 v3, vcc, 0, v1, vcc
	global_load_dword v33, v[2:3], off
	v_add_co_u32_e32 v2, vcc, 0xe000, v0
	v_readlane_b32 s54, v236, 6
	s_nop 0
	v_addc_co_u32_e32 v3, vcc, 0, v1, vcc
	global_load_dword v34, v[2:3], off
	v_add_co_u32_e32 v2, vcc, 0x10000, v0
	v_readlane_b32 s55, v236, 7
	s_nop 0
	v_addc_co_u32_e32 v3, vcc, 0, v1, vcc
	global_load_dword v35, v[2:3], off
	v_add_co_u32_e32 v2, vcc, 0x12000, v0
	s_nop 1
	v_addc_co_u32_e32 v3, vcc, 0, v1, vcc
	global_load_dword v36, v[2:3], off
	v_add_co_u32_e32 v2, vcc, 0x14000, v0
	s_nop 1
	v_addc_co_u32_e32 v3, vcc, 0, v1, vcc
	global_load_dword v37, v[2:3], off
	v_add_co_u32_e32 v2, vcc, 0x16000, v0
	s_nop 1
	v_addc_co_u32_e32 v3, vcc, 0, v1, vcc
	global_load_dword v38, v[2:3], off
	v_add_co_u32_e32 v2, vcc, 0x18000, v0
	s_nop 1
	v_addc_co_u32_e32 v3, vcc, 0, v1, vcc
	global_load_dword v39, v[2:3], off
	v_add_co_u32_e32 v2, vcc, 0x1a000, v0
	s_nop 1
	v_addc_co_u32_e32 v3, vcc, 0, v1, vcc
	global_load_dword v40, v[2:3], off
	v_add_co_u32_e32 v2, vcc, 0x1c000, v0
	s_nop 1
	v_addc_co_u32_e32 v3, vcc, 0, v1, vcc
	global_load_dword v41, v[2:3], off
	v_add_co_u32_e32 v2, vcc, 0x1e000, v0
	s_nop 1
	v_addc_co_u32_e32 v3, vcc, 0, v1, vcc
	global_load_dword v42, v[2:3], off
	v_add_co_u32_e32 v2, vcc, 0x20000, v0
	s_nop 1
	v_addc_co_u32_e32 v3, vcc, 0, v1, vcc
	global_load_dword v43, v[2:3], off
	v_add_co_u32_e32 v2, vcc, 0x22000, v0
	s_nop 1
	v_addc_co_u32_e32 v3, vcc, 0, v1, vcc
	global_load_dword v44, v[2:3], off
	v_add_co_u32_e32 v2, vcc, 0x24000, v0
	s_nop 1
	v_addc_co_u32_e32 v3, vcc, 0, v1, vcc
	global_load_dword v45, v[2:3], off
	v_add_co_u32_e32 v2, vcc, 0x26000, v0
	s_nop 1
	v_addc_co_u32_e32 v3, vcc, 0, v1, vcc
	global_load_dword v46, v[2:3], off
	v_add_co_u32_e32 v2, vcc, 0x28000, v0
	s_nop 1
	v_addc_co_u32_e32 v3, vcc, 0, v1, vcc
	global_load_dword v47, v[2:3], off
	v_add_co_u32_e32 v2, vcc, 0x2a000, v0
	s_nop 1
	v_addc_co_u32_e32 v3, vcc, 0, v1, vcc
	global_load_dword v48, v[2:3], off
	v_add_co_u32_e32 v2, vcc, 0x2c000, v0
	s_nop 1
	v_addc_co_u32_e32 v3, vcc, 0, v1, vcc
	global_load_dword v49, v[2:3], off
	v_add_co_u32_e32 v2, vcc, 0x2e000, v0
	s_nop 1
	v_addc_co_u32_e32 v3, vcc, 0, v1, vcc
	global_load_dword v50, v[2:3], off
	v_add_co_u32_e32 v2, vcc, 0x30000, v0
	s_nop 1
	v_addc_co_u32_e32 v3, vcc, 0, v1, vcc
	global_load_dword v51, v[2:3], off
	v_add_co_u32_e32 v2, vcc, 0x32000, v0
	s_nop 1
	v_addc_co_u32_e32 v3, vcc, 0, v1, vcc
	global_load_dword v52, v[2:3], off
	v_add_co_u32_e32 v2, vcc, 0x34000, v0
	s_nop 1
	v_addc_co_u32_e32 v3, vcc, 0, v1, vcc
	global_load_dword v53, v[2:3], off
	v_add_co_u32_e32 v2, vcc, 0x36000, v0
	s_nop 1
	v_addc_co_u32_e32 v3, vcc, 0, v1, vcc
	global_load_dword v54, v[2:3], off
	v_add_co_u32_e32 v2, vcc, 0x38000, v0
	s_nop 1
	v_addc_co_u32_e32 v3, vcc, 0, v1, vcc
	global_load_dword v55, v[2:3], off
	v_add_co_u32_e32 v2, vcc, 0x3a000, v0
	s_nop 1
	v_addc_co_u32_e32 v3, vcc, 0, v1, vcc
	global_load_dword v56, v[2:3], off
	v_add_co_u32_e32 v2, vcc, 0x3c000, v0
	s_nop 1
	v_addc_co_u32_e32 v3, vcc, 0, v1, vcc
	v_add_co_u32_e32 v0, vcc, 0x3e000, v0
	global_load_dword v2, v[2:3], off
	s_nop 0
	v_addc_co_u32_e32 v1, vcc, 0, v1, vcc
	global_load_dword v0, v[0:1], off
	v_or_b32_e32 v1, s1, v24
	v_lshlrev_b32_e32 v3, 2, v1
	v_add_u32_e32 v1, 0x400, v25
	s_waitcnt vmcnt(0)
	ds_write2_b32 v25, v4, v5 offset1:66
	s_waitcnt vmcnt(28)
	ds_write2_b32 v25, v6, v7 offset0:132 offset1:198
	s_waitcnt vmcnt(26)
	ds_write2_b32 v1, v20, v21 offset0:8 offset1:74
	s_waitcnt vmcnt(24)
	ds_write2_b32 v1, v33, v34 offset0:140 offset1:206
	v_add_u32_e32 v1, 0x800, v25
	s_waitcnt vmcnt(22)
	ds_write2_b32 v1, v35, v36 offset0:16 offset1:82
	s_waitcnt vmcnt(20)
	ds_write2_b32 v1, v37, v38 offset0:148 offset1:214
	v_add_u32_e32 v1, 0xc00, v25
	s_waitcnt vmcnt(18)
	ds_write2_b32 v1, v39, v40 offset0:24 offset1:90
	s_waitcnt vmcnt(16)
	ds_write2_b32 v1, v41, v42 offset0:156 offset1:222
	v_add_u32_e32 v1, 0x1000, v25
	s_waitcnt vmcnt(14)
	ds_write2_b32 v1, v43, v44 offset0:32 offset1:98
	s_waitcnt vmcnt(12)
	ds_write2_b32 v1, v45, v46 offset0:164 offset1:230
	v_add_u32_e32 v1, 0x1400, v25
	s_waitcnt vmcnt(10)
	ds_write2_b32 v1, v47, v48 offset0:40 offset1:106
	s_waitcnt vmcnt(8)
	ds_write2_b32 v1, v49, v50 offset0:172 offset1:238
	v_add_u32_e32 v1, 0x1800, v25
	s_waitcnt vmcnt(6)
	ds_write2_b32 v1, v51, v52 offset0:48 offset1:114
	s_waitcnt vmcnt(4)
	ds_write2_b32 v1, v53, v54 offset0:180 offset1:246
	v_add_u32_e32 v1, 0x1c00, v25
	s_mov_b32 s1, s47
	s_waitcnt vmcnt(2)
	ds_write2_b32 v1, v55, v56 offset0:56 offset1:122
	s_waitcnt vmcnt(0)
	ds_write2_b32 v1, v2, v0 offset0:188 offset1:254
	v_lshl_add_u64 v[0:1], s[0:1], 1, v[10:11]
	v_readlane_b32 s0, v235, 4
	v_readlane_b32 s1, v235, 5
	s_nop 4
	global_load_dwordx4 v[34:37], v3, s[0:1] offset:16
	global_load_dwordx4 v[4:7], v3, s[0:1]
	s_waitcnt lgkmcnt(0)
	ds_read2_b32 v[38:39], v27 offset0:33 offset1:41
	ds_read2_b32 v[40:41], v27 offset0:66 offset1:74
	ds_read2_b32 v[42:43], v27 offset1:8
	ds_read2_b32 v[44:45], v27 offset0:99 offset1:107
	ds_read2_b32 v[46:47], v27 offset0:132 offset1:140
	ds_read2_b32 v[48:49], v27 offset0:165 offset1:173
	ds_read2_b32 v[50:51], v27 offset0:198 offset1:206
	ds_read2_b32 v[54:55], v27 offset0:231 offset1:239
	s_mov_b32 s0, 0x3e38aa3b
	s_waitcnt lgkmcnt(3)
	v_mov_b32_e32 v52, v46
	s_waitcnt lgkmcnt(2)
	v_mov_b32_e32 v56, v48
	s_waitcnt lgkmcnt(1)
	v_mov_b32_e32 v53, v50
	s_waitcnt lgkmcnt(0)
	v_mov_b32_e32 v57, v54
	v_mov_b32_e32 v54, v49
	v_mov_b32_e32 v50, v47
	s_waitcnt vmcnt(0)
	v_mov_b32_e32 v3, v6
	v_mov_b32_e32 v6, v5
	v_mov_b32_e32 v2, v4
	v_pk_mul_f32 v[4:5], v[6:7], s[0:1] op_sel_hi:[1,0]
	v_mov_b32_e32 v7, v36
	v_mov_b32_e32 v36, v35
	v_mov_b32_e32 v6, v34
	v_pk_mul_f32 v[20:21], v[36:37], s[0:1] op_sel_hi:[1,0]
	v_mov_b32_e32 v36, v38
	v_mov_b32_e32 v37, v44
	v_pk_mul_f32 v[2:3], v[2:3], s[0:1] op_sel_hi:[1,0]
	v_pk_mul_f32 v[6:7], v[6:7], s[0:1] op_sel_hi:[1,0]
	v_mov_b32_e32 v34, v42
	v_mov_b32_e32 v35, v40
	v_pk_mul_f32 v[36:37], v[4:5], v[36:37]
	v_pk_mul_f32 v[56:57], v[20:21], v[56:57]
	v_pk_mul_f32 v[34:35], v[2:3], v[34:35]
	v_pk_mul_f32 v[52:53], v[6:7], v[52:53]
	v_bfe_u32 v38, v56, 16, 1
	v_bfe_u32 v40, v37, 16, 1
	v_bfe_u32 v42, v36, 16, 1
	v_add3_u32 v42, v36, v42, s81
	v_add3_u32 v40, v37, v40, s81
	v_add3_u32 v36, v56, v38, s81
	v_bfe_u32 v37, v34, 16, 1
	v_bfe_u32 v38, v35, 16, 1
	v_bfe_u32 v44, v52, 16, 1
	v_bfe_u32 v46, v53, 16, 1
	v_bfe_u32 v33, v57, 16, 1
	v_add3_u32 v46, v53, v46, s81
	v_add3_u32 v44, v52, v44, s81
	v_add3_u32 v35, v35, v38, s81
	v_add3_u32 v34, v34, v37, s81
	v_add3_u32 v33, v57, v33, s81
	v_lshrrev_b32_e32 v34, 16, v34
	v_lshrrev_b32_e32 v35, 16, v35
	v_lshrrev_b32_e32 v38, 16, v44
	v_lshrrev_b32_e32 v37, 16, v46
	v_and_or_b32 v37, v33, s71, v37
	v_and_or_b32 v36, v36, s71, v38
	v_and_or_b32 v35, v40, s71, v35
	v_and_or_b32 v34, v42, s71, v34
	v_lshl_add_u64 v[52:53], v[0:1], 0, v[96:97]
	v_mov_b32_e32 v40, v43
	v_mov_b32_e32 v44, v39
	global_store_dwordx4 v[52:53], v[34:37], off sc0 sc1
	v_pk_mul_f32 v[38:39], v[6:7], v[50:51]
	v_lshlrev_b32_e32 v96, 11, v31
	v_pk_mul_f32 v[34:35], v[2:3], v[40:41]
	v_pk_mul_f32 v[36:37], v[4:5], v[44:45]
	v_pk_mul_f32 v[40:41], v[20:21], v[54:55]
	v_bfe_u32 v43, v37, 16, 1
	v_bfe_u32 v33, v41, 16, 1
	v_bfe_u32 v42, v40, 16, 1
	v_bfe_u32 v44, v36, 16, 1
	v_add3_u32 v44, v36, v44, s81
	v_add3_u32 v43, v37, v43, s81
	v_add3_u32 v36, v40, v42, s81
	v_add3_u32 v33, v41, v33, s81
	v_bfe_u32 v37, v34, 16, 1
	v_bfe_u32 v40, v35, 16, 1
	v_bfe_u32 v41, v38, 16, 1
	v_bfe_u32 v42, v39, 16, 1
	v_add3_u32 v39, v39, v42, s81
	v_add3_u32 v38, v38, v41, s81
	v_add3_u32 v35, v35, v40, s81
	v_add3_u32 v34, v34, v37, s81
	v_lshrrev_b32_e32 v34, 16, v34
	v_lshrrev_b32_e32 v35, 16, v35
	v_lshrrev_b32_e32 v38, 16, v38
	v_lshrrev_b32_e32 v37, 16, v39
	v_and_or_b32 v37, v33, s71, v37
	v_and_or_b32 v36, v36, s71, v38
	v_and_or_b32 v35, v43, s71, v35
	v_and_or_b32 v34, v44, s71, v34
	v_lshl_add_u64 v[38:39], v[0:1], 0, v[96:97]
	global_store_dwordx4 v[38:39], v[34:37], off sc0 sc1
	ds_read2_b32 v[38:39], v27 offset0:49 offset1:57
	ds_read2_b32 v[40:41], v27 offset0:82 offset1:90
	ds_read2_b32 v[42:43], v27 offset0:115 offset1:123
	ds_read2_b32 v[44:45], v27 offset0:16 offset1:24
	ds_read2_b32 v[46:47], v27 offset0:148 offset1:156
	ds_read2_b32 v[48:49], v27 offset0:181 offset1:189
	ds_read2_b32 v[50:51], v27 offset0:214 offset1:222
	ds_read2_b32 v[52:53], v27 offset0:247 offset1:255
	s_waitcnt lgkmcnt(7)
	v_mov_b32_e32 v36, v38
	s_waitcnt lgkmcnt(6)
	v_mov_b32_e32 v35, v40
	s_waitcnt lgkmcnt(5)
	v_mov_b32_e32 v37, v42
	s_waitcnt lgkmcnt(4)
	v_mov_b32_e32 v34, v44
	v_pk_mul_f32 v[36:37], v[4:5], v[36:37]
	s_waitcnt lgkmcnt(2)
	v_mov_b32_e32 v56, v48
	s_waitcnt lgkmcnt(0)
	v_mov_b32_e32 v57, v52
	v_pk_mul_f32 v[34:35], v[2:3], v[34:35]
	v_mov_b32_e32 v54, v46
	v_mov_b32_e32 v55, v50
	v_pk_mul_f32 v[56:57], v[20:21], v[56:57]
	v_bfe_u32 v40, v37, 16, 1
	v_pk_mul_f32 v[54:55], v[6:7], v[54:55]
	v_bfe_u32 v38, v56, 16, 1
	v_bfe_u32 v42, v36, 16, 1
	v_add3_u32 v40, v37, v40, s81
	v_bfe_u32 v37, v34, 16, 1
	v_add3_u32 v42, v36, v42, s81
	v_add3_u32 v36, v56, v38, s81
	v_bfe_u32 v38, v35, 16, 1
	v_bfe_u32 v44, v54, 16, 1
	v_bfe_u32 v46, v55, 16, 1
	v_add3_u32 v34, v34, v37, s81
	v_bfe_u32 v33, v57, 16, 1
	v_add3_u32 v46, v55, v46, s81
	v_add3_u32 v44, v54, v44, s81
	v_add3_u32 v35, v35, v38, s81
	v_lshrrev_b32_e32 v34, 16, v34
	v_add3_u32 v33, v57, v33, s81
	v_lshrrev_b32_e32 v35, 16, v35
	v_lshrrev_b32_e32 v38, 16, v44
	v_lshrrev_b32_e32 v37, 16, v46
	v_and_or_b32 v34, v42, s71, v34
	v_lshlrev_b32_e32 v96, 11, v23
	v_mov_b32_e32 v42, v39
	v_mov_b32_e32 v52, v49
	v_and_or_b32 v37, v33, s71, v37
	v_and_or_b32 v36, v36, s71, v38
	v_and_or_b32 v35, v40, s71, v35
	v_lshl_add_u64 v[54:55], v[0:1], 0, v[96:97]
	v_mov_b32_e32 v40, v45
	v_pk_mul_f32 v[4:5], v[4:5], v[42:43]
	v_mov_b32_e32 v50, v47
	v_pk_mul_f32 v[20:21], v[20:21], v[52:53]
	global_store_dwordx4 v[54:55], v[34:37], off sc0 sc1
	v_pk_mul_f32 v[2:3], v[2:3], v[40:41]
	v_pk_mul_f32 v[6:7], v[6:7], v[50:51]
	v_bfe_u32 v33, v21, 16, 1
	v_bfe_u32 v34, v20, 16, 1
	v_bfe_u32 v35, v5, 16, 1
	v_bfe_u32 v36, v4, 16, 1
	v_add3_u32 v36, v4, v36, s81
	v_add3_u32 v35, v5, v35, s81
	v_add3_u32 v4, v20, v34, s81
	v_add3_u32 v5, v21, v33, s81
	v_bfe_u32 v20, v2, 16, 1
	v_bfe_u32 v21, v3, 16, 1
	v_bfe_u32 v33, v6, 16, 1
	v_bfe_u32 v34, v7, 16, 1
	v_add3_u32 v7, v7, v34, s81
	v_add3_u32 v6, v6, v33, s81
	v_add3_u32 v3, v3, v21, s81
	v_add3_u32 v2, v2, v20, s81
	v_lshrrev_b32_e32 v2, 16, v2
	v_lshrrev_b32_e32 v3, 16, v3
	v_lshrrev_b32_e32 v6, 16, v6
	v_lshrrev_b32_e32 v7, 16, v7
	v_lshlrev_b32_e32 v96, 11, v22
	v_and_or_b32 v5, v5, s71, v7
	v_and_or_b32 v4, v4, s71, v6
	v_and_or_b32 v3, v35, s71, v3
	v_and_or_b32 v2, v36, s71, v2
	v_lshl_add_u64 v[0:1], v[0:1], 0, v[96:97]
	global_store_dwordx4 v[0:1], v[2:5], off sc0 sc1
	s_waitcnt lgkmcnt(0)
	s_mov_b64 s[0:1], 0
.LBB0_183:
	s_andn2_b64 vcc, exec, s[0:1]
	s_cbranch_vccnz .LBB0_185
	s_add_i32 s0, s38, 0x1e200
	s_and_b32 s0, s0, 0x1ffc0
	v_or_b32_e32 v0, s0, v9
	v_readlane_b32 s42, v235, 6
	v_lshlrev_b32_e32 v96, 12, v0
	v_readlane_b32 s43, v235, 7
	s_lshl_b32 s46, s34, 2
	s_movk_i32 s1, 0x4000
	v_lshl_add_u64 v[0:1], s[42:43], 0, v[96:97]
	v_lshl_add_u64 v[0:1], v[0:1], 0, s[46:47]
	v_lshlrev_b32_e32 v96, 2, v8
	v_lshl_add_u64 v[0:1], v[0:1], 0, v[96:97]
	v_add_co_u32_e32 v2, vcc, 0x2000, v0
	global_load_dword v4, v[0:1], off
	s_waitcnt lgkmcnt(0)
	v_addc_co_u32_e32 v3, vcc, 0, v1, vcc
	global_load_dword v5, v[2:3], off
	v_add_co_u32_e32 v2, vcc, s1, v0
	s_lshl_b32 s46, s0, 1
	s_nop 0
	v_addc_co_u32_e32 v3, vcc, 0, v1, vcc
	global_load_dword v6, v[2:3], off
	v_add_co_u32_e32 v2, vcc, 0x6000, v0
	s_nop 1
	v_addc_co_u32_e32 v3, vcc, 0, v1, vcc
	global_load_dword v7, v[2:3], off
	v_add_co_u32_e32 v2, vcc, 0x8000, v0
	s_nop 1
	v_addc_co_u32_e32 v3, vcc, 0, v1, vcc
	global_load_dword v20, v[2:3], off
	v_add_co_u32_e32 v2, vcc, 0xa000, v0
	s_nop 1
	v_addc_co_u32_e32 v3, vcc, 0, v1, vcc
	global_load_dword v21, v[2:3], off
	v_add_co_u32_e32 v2, vcc, 0xc000, v0
	s_nop 1
	v_addc_co_u32_e32 v3, vcc, 0, v1, vcc
	global_load_dword v33, v[2:3], off
	v_add_co_u32_e32 v2, vcc, 0xe000, v0
	s_nop 1
	v_addc_co_u32_e32 v3, vcc, 0, v1, vcc
	global_load_dword v34, v[2:3], off
	v_add_co_u32_e32 v2, vcc, 0x10000, v0
	s_nop 1
	v_addc_co_u32_e32 v3, vcc, 0, v1, vcc
	global_load_dword v35, v[2:3], off
	v_add_co_u32_e32 v2, vcc, 0x12000, v0
	s_nop 1
	v_addc_co_u32_e32 v3, vcc, 0, v1, vcc
	global_load_dword v36, v[2:3], off
	v_add_co_u32_e32 v2, vcc, 0x14000, v0
	s_nop 1
	v_addc_co_u32_e32 v3, vcc, 0, v1, vcc
	global_load_dword v37, v[2:3], off
	v_add_co_u32_e32 v2, vcc, 0x16000, v0
	s_nop 1
	v_addc_co_u32_e32 v3, vcc, 0, v1, vcc
	global_load_dword v38, v[2:3], off
	v_add_co_u32_e32 v2, vcc, 0x18000, v0
	s_nop 1
	v_addc_co_u32_e32 v3, vcc, 0, v1, vcc
	global_load_dword v39, v[2:3], off
	v_add_co_u32_e32 v2, vcc, 0x1a000, v0
	s_nop 1
	v_addc_co_u32_e32 v3, vcc, 0, v1, vcc
	global_load_dword v40, v[2:3], off
	v_add_co_u32_e32 v2, vcc, 0x1c000, v0
	s_nop 1
	v_addc_co_u32_e32 v3, vcc, 0, v1, vcc
	global_load_dword v41, v[2:3], off
	v_add_co_u32_e32 v2, vcc, 0x1e000, v0
	s_nop 1
	v_addc_co_u32_e32 v3, vcc, 0, v1, vcc
	global_load_dword v42, v[2:3], off
	v_add_co_u32_e32 v2, vcc, 0x20000, v0
	s_nop 1
	v_addc_co_u32_e32 v3, vcc, 0, v1, vcc
	global_load_dword v43, v[2:3], off
	v_add_co_u32_e32 v2, vcc, 0x22000, v0
	s_nop 1
	v_addc_co_u32_e32 v3, vcc, 0, v1, vcc
	global_load_dword v44, v[2:3], off
	v_add_co_u32_e32 v2, vcc, 0x24000, v0
	s_nop 1
	v_addc_co_u32_e32 v3, vcc, 0, v1, vcc
	global_load_dword v45, v[2:3], off
	v_add_co_u32_e32 v2, vcc, 0x26000, v0
	s_nop 1
	v_addc_co_u32_e32 v3, vcc, 0, v1, vcc
	global_load_dword v46, v[2:3], off
	v_add_co_u32_e32 v2, vcc, 0x28000, v0
	s_nop 1
	v_addc_co_u32_e32 v3, vcc, 0, v1, vcc
	global_load_dword v47, v[2:3], off
	v_add_co_u32_e32 v2, vcc, 0x2a000, v0
	s_nop 1
	v_addc_co_u32_e32 v3, vcc, 0, v1, vcc
	global_load_dword v48, v[2:3], off
	v_add_co_u32_e32 v2, vcc, 0x2c000, v0
	s_nop 1
	v_addc_co_u32_e32 v3, vcc, 0, v1, vcc
	global_load_dword v49, v[2:3], off
	v_add_co_u32_e32 v2, vcc, 0x2e000, v0
	s_nop 1
	v_addc_co_u32_e32 v3, vcc, 0, v1, vcc
	global_load_dword v50, v[2:3], off
	v_add_co_u32_e32 v2, vcc, 0x30000, v0
	s_nop 1
	v_addc_co_u32_e32 v3, vcc, 0, v1, vcc
	global_load_dword v51, v[2:3], off
	v_add_co_u32_e32 v2, vcc, 0x32000, v0
	s_nop 1
	v_addc_co_u32_e32 v3, vcc, 0, v1, vcc
	global_load_dword v52, v[2:3], off
	v_add_co_u32_e32 v2, vcc, 0x34000, v0
	s_nop 1
	v_addc_co_u32_e32 v3, vcc, 0, v1, vcc
	global_load_dword v53, v[2:3], off
	v_add_co_u32_e32 v2, vcc, 0x36000, v0
	s_nop 1
	v_addc_co_u32_e32 v3, vcc, 0, v1, vcc
	global_load_dword v54, v[2:3], off
	v_add_co_u32_e32 v2, vcc, 0x38000, v0
	s_nop 1
	v_addc_co_u32_e32 v3, vcc, 0, v1, vcc
	global_load_dword v55, v[2:3], off
	v_add_co_u32_e32 v2, vcc, 0x3a000, v0
	s_nop 1
	v_addc_co_u32_e32 v3, vcc, 0, v1, vcc
	global_load_dword v56, v[2:3], off
	v_add_co_u32_e32 v2, vcc, 0x3c000, v0
	s_nop 1
	v_addc_co_u32_e32 v3, vcc, 0, v1, vcc
	v_add_co_u32_e32 v0, vcc, 0x3e000, v0
	global_load_dword v2, v[2:3], off
	s_nop 0
	v_addc_co_u32_e32 v1, vcc, 0, v1, vcc
	global_load_dword v0, v[0:1], off
	v_add_u32_e32 v1, 0x400, v25
	s_waitcnt vmcnt(0)
	ds_write2_b32 v25, v4, v5 offset1:66
	s_waitcnt vmcnt(28)
	ds_write2_b32 v25, v6, v7 offset0:132 offset1:198
	s_waitcnt vmcnt(26)
	ds_write2_b32 v1, v20, v21 offset0:8 offset1:74
	s_waitcnt vmcnt(24)
	ds_write2_b32 v1, v33, v34 offset0:140 offset1:206
	v_add_u32_e32 v1, 0x800, v25
	s_waitcnt vmcnt(22)
	ds_write2_b32 v1, v35, v36 offset0:16 offset1:82
	s_waitcnt vmcnt(20)
	ds_write2_b32 v1, v37, v38 offset0:148 offset1:214
	v_add_u32_e32 v1, 0xc00, v25
	s_waitcnt vmcnt(18)
	ds_write2_b32 v1, v39, v40 offset0:24 offset1:90
	s_waitcnt vmcnt(16)
	ds_write2_b32 v1, v41, v42 offset0:156 offset1:222
	v_add_u32_e32 v1, 0x1000, v25
	s_waitcnt vmcnt(14)
	ds_write2_b32 v1, v43, v44 offset0:32 offset1:98
	s_waitcnt vmcnt(12)
	ds_write2_b32 v1, v45, v46 offset0:164 offset1:230
	v_add_u32_e32 v1, 0x1400, v25
	s_waitcnt vmcnt(10)
	ds_write2_b32 v1, v47, v48 offset0:40 offset1:106
	s_waitcnt vmcnt(8)
	ds_write2_b32 v1, v49, v50 offset0:172 offset1:238
	v_add_u32_e32 v1, 0x1800, v25
	s_waitcnt vmcnt(6)
	ds_write2_b32 v1, v51, v52 offset0:48 offset1:114
	s_waitcnt vmcnt(4)
	ds_write2_b32 v1, v53, v54 offset0:180 offset1:246
	v_add_u32_e32 v1, 0x1c00, v25
	s_waitcnt vmcnt(2)
	ds_write2_b32 v1, v55, v56 offset0:56 offset1:122
	s_waitcnt vmcnt(0)
	ds_write2_b32 v1, v2, v0 offset0:188 offset1:254
	s_waitcnt lgkmcnt(0)
	ds_read2_b32 v[6:7], v27 offset0:33 offset1:41
	ds_read2_b32 v[20:21], v27 offset1:8
	ds_read2_b32 v[34:35], v27 offset0:66 offset1:74
	ds_read2_b32 v[36:37], v27 offset0:99 offset1:107
	ds_read2_b32 v[38:39], v27 offset0:132 offset1:140
	ds_read2_b32 v[40:41], v27 offset0:165 offset1:173
	ds_read2_b32 v[42:43], v27 offset0:198 offset1:206
	ds_read2_b32 v[44:45], v27 offset0:231 offset1:239
	s_waitcnt lgkmcnt(7)
	v_bfe_u32 v3, v6, 16, 1
	s_waitcnt lgkmcnt(6)
	v_bfe_u32 v2, v20, 16, 1
	v_add3_u32 v2, v20, v2, s81
	v_lshrrev_b32_e32 v2, 16, v2
	v_add3_u32 v3, v6, v3, s81
	v_and_or_b32 v2, v3, s71, v2
	s_waitcnt lgkmcnt(5)
	v_bfe_u32 v3, v34, 16, 1
	v_add3_u32 v3, v34, v3, s81
	s_waitcnt lgkmcnt(4)
	v_bfe_u32 v4, v36, 16, 1
	v_lshrrev_b32_e32 v3, 16, v3
	v_add3_u32 v4, v36, v4, s81
	v_and_or_b32 v3, v4, s71, v3
	s_waitcnt lgkmcnt(3)
	v_bfe_u32 v4, v38, 16, 1
	v_add3_u32 v4, v38, v4, s81
	s_waitcnt lgkmcnt(2)
	v_bfe_u32 v5, v40, 16, 1
	v_lshrrev_b32_e32 v4, 16, v4
	v_add3_u32 v5, v40, v5, s81
	v_and_or_b32 v4, v5, s71, v4
	s_waitcnt lgkmcnt(1)
	v_bfe_u32 v5, v42, 16, 1
	v_add3_u32 v5, v42, v5, s81
	s_waitcnt lgkmcnt(0)
	v_bfe_u32 v6, v44, 16, 1
	v_lshrrev_b32_e32 v5, 16, v5
	v_add3_u32 v6, v44, v6, s81
	v_and_or_b32 v5, v6, s71, v5
	v_mul_u32_u24_e32 v6, 0xb00, v32
	v_lshl_add_u64 v[0:1], v[12:13], 0, s[46:47]
	v_lshlrev_b32_e32 v96, 1, v6
	v_lshl_add_u64 v[32:33], v[0:1], 0, v[96:97]
	global_store_dwordx4 v[32:33], v[2:5], off sc0 sc1
	v_bfe_u32 v6, v45, 16, 1
	v_add3_u32 v6, v45, v6, s81
	v_bfe_u32 v2, v21, 16, 1
	v_add3_u32 v2, v21, v2, s81
	v_bfe_u32 v3, v7, 16, 1
	v_lshrrev_b32_e32 v2, 16, v2
	v_add3_u32 v3, v7, v3, s81
	v_and_or_b32 v2, v3, s71, v2
	v_bfe_u32 v3, v35, 16, 1
	v_add3_u32 v3, v35, v3, s81
	v_bfe_u32 v4, v37, 16, 1
	v_lshrrev_b32_e32 v3, 16, v3
	v_add3_u32 v4, v37, v4, s81
	v_and_or_b32 v3, v4, s71, v3
	v_bfe_u32 v4, v39, 16, 1
	v_add3_u32 v4, v39, v4, s81
	v_bfe_u32 v5, v41, 16, 1
	v_lshrrev_b32_e32 v4, 16, v4
	v_add3_u32 v5, v41, v5, s81
	v_and_or_b32 v4, v5, s71, v4
	v_bfe_u32 v5, v43, 16, 1
	v_add3_u32 v5, v43, v5, s81
	v_lshrrev_b32_e32 v5, 16, v5
	v_and_or_b32 v5, v6, s71, v5
	v_mul_u32_u24_e32 v6, 0xb00, v31
	v_lshlrev_b32_e32 v96, 1, v6
	v_lshl_add_u64 v[6:7], v[0:1], 0, v[96:97]
	global_store_dwordx4 v[6:7], v[2:5], off sc0 sc1
	ds_read2_b32 v[6:7], v27 offset0:16 offset1:24
	ds_read2_b32 v[20:21], v27 offset0:49 offset1:57
	ds_read2_b32 v[32:33], v27 offset0:82 offset1:90
	ds_read2_b32 v[34:35], v27 offset0:115 offset1:123
	ds_read2_b32 v[36:37], v27 offset0:148 offset1:156
	ds_read2_b32 v[38:39], v27 offset0:181 offset1:189
	ds_read2_b32 v[40:41], v27 offset0:214 offset1:222
	ds_read2_b32 v[42:43], v27 offset0:247 offset1:255
	s_waitcnt lgkmcnt(7)
	v_bfe_u32 v2, v6, 16, 1
	v_add3_u32 v2, v6, v2, s81
	s_waitcnt lgkmcnt(6)
	v_bfe_u32 v3, v20, 16, 1
	v_lshrrev_b32_e32 v2, 16, v2
	v_add3_u32 v3, v20, v3, s81
	v_and_or_b32 v2, v3, s71, v2
	s_waitcnt lgkmcnt(5)
	v_bfe_u32 v3, v32, 16, 1
	v_add3_u32 v3, v32, v3, s81
	s_waitcnt lgkmcnt(4)
	v_bfe_u32 v4, v34, 16, 1
	v_lshrrev_b32_e32 v3, 16, v3
	v_add3_u32 v4, v34, v4, s81
	v_and_or_b32 v3, v4, s71, v3
	s_waitcnt lgkmcnt(3)
	v_bfe_u32 v4, v36, 16, 1
	v_add3_u32 v4, v36, v4, s81
	s_waitcnt lgkmcnt(2)
	v_bfe_u32 v5, v38, 16, 1
	v_lshrrev_b32_e32 v4, 16, v4
	v_add3_u32 v5, v38, v5, s81
	v_and_or_b32 v4, v5, s71, v4
	s_waitcnt lgkmcnt(1)
	v_bfe_u32 v5, v40, 16, 1
	v_add3_u32 v5, v40, v5, s81
	s_waitcnt lgkmcnt(0)
	v_bfe_u32 v6, v42, 16, 1
	v_lshrrev_b32_e32 v5, 16, v5
	v_add3_u32 v6, v42, v6, s81
	v_and_or_b32 v5, v6, s71, v5
	v_mul_u32_u24_e32 v6, 0xb00, v23
	v_lshlrev_b32_e32 v96, 1, v6
	v_lshl_add_u64 v[44:45], v[0:1], 0, v[96:97]
	global_store_dwordx4 v[44:45], v[2:5], off sc0 sc1
	v_bfe_u32 v6, v43, 16, 1
	v_add3_u32 v6, v43, v6, s81
	v_bfe_u32 v2, v7, 16, 1
	v_add3_u32 v2, v7, v2, s81
	v_bfe_u32 v3, v21, 16, 1
	v_lshrrev_b32_e32 v2, 16, v2
	v_add3_u32 v3, v21, v3, s81
	v_and_or_b32 v2, v3, s71, v2
	v_bfe_u32 v3, v33, 16, 1
	v_add3_u32 v3, v33, v3, s81
	v_bfe_u32 v4, v35, 16, 1
	v_lshrrev_b32_e32 v3, 16, v3
	v_add3_u32 v4, v35, v4, s81
	v_and_or_b32 v3, v4, s71, v3
	v_bfe_u32 v4, v37, 16, 1
	v_add3_u32 v4, v37, v4, s81
	v_bfe_u32 v5, v39, 16, 1
	v_lshrrev_b32_e32 v4, 16, v4
	v_add3_u32 v5, v39, v5, s81
	v_and_or_b32 v4, v5, s71, v4
	v_bfe_u32 v5, v41, 16, 1
	v_add3_u32 v5, v41, v5, s81
	v_lshrrev_b32_e32 v5, 16, v5
	v_and_or_b32 v5, v6, s71, v5
	v_mul_u32_u24_e32 v6, 0xb00, v22
	v_lshlrev_b32_e32 v96, 1, v6
	v_lshl_add_u64 v[0:1], v[0:1], 0, v[96:97]
	global_store_dwordx4 v[0:1], v[2:5], off sc0 sc1
	s_waitcnt lgkmcnt(0)

.LBB0_186:
	s_andn2_b64 vcc, exec, s[0:1]
	s_cbranch_vccnz .LBB0_188
	s_add_i32 s0, s40, 0xfc00
	s_and_b32 s1, s0, 0xffff
	s_mul_i32 s1, s1, 0xba2f
	s_lshr_b32 s1, s1, 23
	s_mul_i32 s34, s1, 0xb0
	s_sub_i32 s35, s0, s34
	s_and_b32 s0, s35, 0xffff
	s_lshl_b32 s34, s1, 6
	s_bfe_i32 s41, s35, 0x10002
	s_lshl_b32 s35, s35, 4
	s_lshl_b32 s0, s0, 5
	s_and_b32 s41, s41, 0xb00
	s_and_b32 s35, s35, 0xf80
	v_or_b32_e32 v0, s34, v9
	s_add_i32 s41, s41, s35
	s_and_b32 s35, s0, 0x60
	v_mul_u32_u24_e32 v0, 0x1600, v0
	v_readlane_b32 s42, v235, 8
	s_or_b32 s35, s41, s35
	v_lshlrev_b32_e32 v96, 2, v0
	v_readlane_b32 s43, v235, 9
	s_lshl_b32 s46, s35, 2
	s_mov_b32 s35, 0xb000
	v_lshl_add_u64 v[0:1], s[42:43], 0, v[96:97]
	v_lshl_add_u64 v[0:1], v[0:1], 0, s[46:47]
	v_lshlrev_b32_e32 v96, 2, v8
	v_lshl_add_u64 v[0:1], v[0:1], 0, v[96:97]
	v_add_co_u32_e32 v2, vcc, s35, v0
	s_mov_b32 s35, 0x16000
	s_waitcnt lgkmcnt(0)
	v_addc_co_u32_e32 v3, vcc, 0, v1, vcc
	global_load_dword v4, v[0:1], off
	global_load_dword v5, v[2:3], off
	v_add_co_u32_e32 v2, vcc, s35, v0
	s_mov_b32 s35, 0x21000
	s_nop 0
	v_addc_co_u32_e32 v3, vcc, 0, v1, vcc
	global_load_dword v6, v[2:3], off
	v_add_co_u32_e32 v2, vcc, s35, v0
	s_mov_b32 s35, 0x2c000
	s_nop 0
	v_addc_co_u32_e32 v3, vcc, 0, v1, vcc
	global_load_dword v7, v[2:3], off
	v_add_co_u32_e32 v2, vcc, s35, v0
	s_mov_b32 s35, 0x37000
	s_nop 0
	v_addc_co_u32_e32 v3, vcc, 0, v1, vcc
	global_load_dword v20, v[2:3], off
	v_add_co_u32_e32 v2, vcc, s35, v0
	s_mov_b32 s35, 0x42000
	s_nop 0
	v_addc_co_u32_e32 v3, vcc, 0, v1, vcc
	global_load_dword v21, v[2:3], off
	v_add_co_u32_e32 v2, vcc, s35, v0
	s_mov_b32 s35, 0x4d000
	s_nop 0
	v_addc_co_u32_e32 v3, vcc, 0, v1, vcc
	global_load_dword v22, v[2:3], off
	v_add_co_u32_e32 v2, vcc, s35, v0
	s_mov_b32 s35, 0x58000
	s_nop 0
	v_addc_co_u32_e32 v3, vcc, 0, v1, vcc
	global_load_dword v23, v[2:3], off
	v_add_co_u32_e32 v2, vcc, s35, v0
	s_mov_b32 s35, 0x63000
	s_nop 0
	v_addc_co_u32_e32 v3, vcc, 0, v1, vcc
	global_load_dword v31, v[2:3], off
	v_add_co_u32_e32 v2, vcc, s35, v0
	s_mov_b32 s35, 0x6e000
	s_nop 0
	v_addc_co_u32_e32 v3, vcc, 0, v1, vcc
	global_load_dword v32, v[2:3], off
	v_add_co_u32_e32 v2, vcc, s35, v0
	s_mov_b32 s35, 0x79000
	s_nop 0
	v_addc_co_u32_e32 v3, vcc, 0, v1, vcc
	global_load_dword v33, v[2:3], off
	v_add_co_u32_e32 v2, vcc, s35, v0
	s_mov_b32 s35, 0x84000
	s_nop 0
	v_addc_co_u32_e32 v3, vcc, 0, v1, vcc
	global_load_dword v34, v[2:3], off
	v_add_co_u32_e32 v2, vcc, s35, v0
	s_mov_b32 s35, 0x8f000
	s_nop 0
	v_addc_co_u32_e32 v3, vcc, 0, v1, vcc
	global_load_dword v35, v[2:3], off
	v_add_co_u32_e32 v2, vcc, s35, v0
	s_mov_b32 s35, 0x9a000
	s_nop 0
	v_addc_co_u32_e32 v3, vcc, 0, v1, vcc
	global_load_dword v36, v[2:3], off
	v_add_co_u32_e32 v2, vcc, s35, v0
	s_mov_b32 s35, 0xa5000
	s_nop 0
	v_addc_co_u32_e32 v3, vcc, 0, v1, vcc
	global_load_dword v37, v[2:3], off
	v_add_co_u32_e32 v2, vcc, s35, v0
	s_mov_b32 s35, 0xb0000
	s_nop 0
	v_addc_co_u32_e32 v3, vcc, 0, v1, vcc
	global_load_dword v38, v[2:3], off
	v_add_co_u32_e32 v2, vcc, s35, v0
	s_mov_b32 s35, 0xbb000
	s_nop 0
	v_addc_co_u32_e32 v3, vcc, 0, v1, vcc
	global_load_dword v39, v[2:3], off
	v_add_co_u32_e32 v2, vcc, s35, v0
	s_mov_b32 s35, 0xc6000
	s_nop 0
	v_addc_co_u32_e32 v3, vcc, 0, v1, vcc
	global_load_dword v40, v[2:3], off
	v_add_co_u32_e32 v2, vcc, s35, v0
	s_mov_b32 s35, 0xd1000
	s_nop 0
	v_addc_co_u32_e32 v3, vcc, 0, v1, vcc
	global_load_dword v41, v[2:3], off
	v_add_co_u32_e32 v2, vcc, s35, v0
	s_mov_b32 s35, 0xdc000
	s_nop 0
	v_addc_co_u32_e32 v3, vcc, 0, v1, vcc
	global_load_dword v42, v[2:3], off
	v_add_co_u32_e32 v2, vcc, s35, v0
	s_mov_b32 s35, 0xe7000
	s_nop 0
	v_addc_co_u32_e32 v3, vcc, 0, v1, vcc
	global_load_dword v43, v[2:3], off
	v_add_co_u32_e32 v2, vcc, s35, v0
	s_mov_b32 s35, 0xf2000
	s_nop 0
	v_addc_co_u32_e32 v3, vcc, 0, v1, vcc
	global_load_dword v44, v[2:3], off
	v_add_co_u32_e32 v2, vcc, s35, v0
	s_mov_b32 s35, 0xfd000
	s_nop 0
	v_addc_co_u32_e32 v3, vcc, 0, v1, vcc
	global_load_dword v45, v[2:3], off
	v_add_co_u32_e32 v2, vcc, s35, v0
	s_mov_b32 s35, 0x108000
	s_nop 0
	v_addc_co_u32_e32 v3, vcc, 0, v1, vcc
	global_load_dword v46, v[2:3], off
	v_add_co_u32_e32 v2, vcc, s35, v0
	s_mov_b32 s35, 0x113000
	s_nop 0
	v_addc_co_u32_e32 v3, vcc, 0, v1, vcc
	global_load_dword v47, v[2:3], off
	v_add_co_u32_e32 v2, vcc, s35, v0
	s_mov_b32 s35, 0x11e000
	s_nop 0
	v_addc_co_u32_e32 v3, vcc, 0, v1, vcc
	global_load_dword v48, v[2:3], off
	v_add_co_u32_e32 v2, vcc, s35, v0
	s_mov_b32 s35, 0x129000
	s_nop 0
	v_addc_co_u32_e32 v3, vcc, 0, v1, vcc
	global_load_dword v49, v[2:3], off
	v_add_co_u32_e32 v2, vcc, s35, v0
	s_mov_b32 s35, 0x134000
	s_nop 0
	v_addc_co_u32_e32 v3, vcc, 0, v1, vcc
	global_load_dword v50, v[2:3], off
	v_add_co_u32_e32 v2, vcc, s35, v0
	s_mov_b32 s35, 0x13f000
	s_nop 0
	v_addc_co_u32_e32 v3, vcc, 0, v1, vcc
	global_load_dword v51, v[2:3], off
	v_add_co_u32_e32 v2, vcc, s35, v0
	s_mov_b32 s35, 0x14a000
	s_nop 0
	v_addc_co_u32_e32 v3, vcc, 0, v1, vcc
	global_load_dword v52, v[2:3], off
	v_add_co_u32_e32 v2, vcc, s35, v0
	s_mov_b32 s35, 0x155000
	s_nop 0
	v_addc_co_u32_e32 v3, vcc, 0, v1, vcc
	v_add_co_u32_e32 v0, vcc, s35, v0
	global_load_dword v2, v[2:3], off
	s_nop 0
	v_addc_co_u32_e32 v1, vcc, 0, v1, vcc
	global_load_dword v0, v[0:1], off
	v_or_b32_e32 v1, s34, v24
	v_lshlrev_b32_e32 v53, 2, v1
	v_add_u32_e32 v1, 0x400, v25
	s_waitcnt vmcnt(0)
	ds_write2_b32 v25, v4, v5 offset1:66
	s_waitcnt vmcnt(28)
	ds_write2_b32 v25, v6, v7 offset0:132 offset1:198
	s_waitcnt vmcnt(26)
	ds_write2_b32 v1, v20, v21 offset0:8 offset1:74
	s_waitcnt vmcnt(24)
	ds_write2_b32 v1, v22, v23 offset0:140 offset1:206
	v_add_u32_e32 v1, 0x800, v25
	s_waitcnt vmcnt(22)
	ds_write2_b32 v1, v31, v32 offset0:16 offset1:82
	s_waitcnt vmcnt(20)
	ds_write2_b32 v1, v33, v34 offset0:148 offset1:214
	v_add_u32_e32 v1, 0xc00, v25
	s_waitcnt vmcnt(18)
	ds_write2_b32 v1, v35, v36 offset0:24 offset1:90
	s_waitcnt vmcnt(16)
	ds_write2_b32 v1, v37, v38 offset0:156 offset1:222
	v_add_u32_e32 v1, 0x1000, v25
	s_waitcnt vmcnt(14)
	ds_write2_b32 v1, v39, v40 offset0:32 offset1:98
	s_waitcnt vmcnt(12)
	ds_write2_b32 v1, v41, v42 offset0:164 offset1:230
	v_add_u32_e32 v1, 0x1400, v25
	s_waitcnt vmcnt(10)
	ds_write2_b32 v1, v43, v44 offset0:40 offset1:106
	s_waitcnt vmcnt(8)
	ds_write2_b32 v1, v45, v46 offset0:172 offset1:238
	v_add_u32_e32 v1, 0x1800, v25
	s_waitcnt vmcnt(6)
	ds_write2_b32 v1, v47, v48 offset0:48 offset1:114
	s_waitcnt vmcnt(4)
	ds_write2_b32 v1, v49, v50 offset0:180 offset1:246
	v_add_u32_e32 v1, 0x1c00, v25
	v_readlane_b32 s34, v235, 10
	s_waitcnt vmcnt(2)
	ds_write2_b32 v1, v51, v52 offset0:56 offset1:122
	s_waitcnt vmcnt(0)
	ds_write2_b32 v1, v2, v0 offset0:188 offset1:254
	v_readlane_b32 s35, v235, 11
	s_nop 4
	global_load_dwordx4 v[0:3], v53, s[34:35] offset:16
	global_load_dwordx4 v[4:7], v53, s[34:35]
	s_waitcnt lgkmcnt(0)
	s_lshl_b32 s46, s1, 7
	v_lshl_add_u64 v[20:21], v[14:15], 0, s[46:47]
	s_waitcnt vmcnt(1)
	v_mov_b32_e32 v48, v0
	s_waitcnt vmcnt(0)
	v_mov_b32_e32 v22, v4
	v_mov_b32_e32 v23, v6
	v_mov_b32_e32 v6, v5
	ds_read2_b32 v[4:5], v27 offset0:33 offset1:41
	ds_read2_b32 v[36:37], v27 offset0:66 offset1:74
	ds_read2_b32 v[38:39], v27 offset1:8
	ds_read2_b32 v[40:41], v27 offset0:99 offset1:107
	ds_read2_b32 v[42:43], v27 offset0:132 offset1:140
	ds_read2_b32 v[44:45], v27 offset0:165 offset1:173
	ds_read2_b32 v[46:47], v27 offset0:198 offset1:206
	ds_read2_b32 v[52:53], v27 offset0:231 offset1:239
	s_waitcnt lgkmcnt(7)
	v_mov_b32_e32 v34, v4
	v_mov_b32_e32 v49, v2
	s_waitcnt lgkmcnt(4)
	v_mov_b32_e32 v35, v40
	v_pk_mul_f32 v[34:35], v[6:7], v[34:35]
	s_waitcnt lgkmcnt(3)
	v_mov_b32_e32 v50, v42
	s_waitcnt lgkmcnt(1)
	v_mov_b32_e32 v51, v46
	v_mov_b32_e32 v2, v1
	v_mov_b32_e32 v0, v44
	s_waitcnt lgkmcnt(0)
	v_mov_b32_e32 v1, v52
	v_mov_b32_e32 v32, v38
	v_mov_b32_e32 v33, v36
	v_pk_mul_f32 v[50:51], v[48:49], v[50:51]
	v_pk_mul_f32 v[0:1], v[2:3], v[0:1]
	v_bfe_u32 v38, v34, 16, 1
	v_pk_mul_f32 v[32:33], v[22:23], v[32:33]
	v_bfe_u32 v4, v1, 16, 1
	v_add3_u32 v38, v34, v38, s81
	v_bfe_u32 v34, v50, 16, 1
	v_bfe_u32 v31, v0, 16, 1
	v_bfe_u32 v36, v35, 16, 1
	v_add3_u32 v1, v1, v4, s81
	v_bfe_u32 v4, v32, 16, 1
	v_add3_u32 v34, v50, v34, s81
	v_add3_u32 v36, v35, v36, s81
	v_add3_u32 v0, v0, v31, s81
	v_bfe_u32 v31, v33, 16, 1
	v_bfe_u32 v35, v51, 16, 1
	v_add3_u32 v4, v32, v4, s81
	v_lshrrev_b32_e32 v32, 16, v34
	v_add3_u32 v35, v51, v35, s81
	v_add3_u32 v31, v33, v31, s81
	v_and_or_b32 v34, v0, s71, v32
	v_or_b32_e32 v0, s0, v26
	v_lshrrev_b32_e32 v4, 16, v4
	v_lshrrev_b32_e32 v31, 16, v31
	v_lshrrev_b32_e32 v33, 16, v35
	v_lshlrev_b32_e32 v96, 11, v0
	v_and_or_b32 v35, v1, s71, v33
	v_and_or_b32 v33, v36, s71, v31
	v_and_or_b32 v32, v38, s71, v4
	v_lshl_add_u64 v[0:1], v[20:21], 0, v[96:97]
	v_mov_b32_e32 v40, v5
	v_mov_b32_e32 v52, v45
	global_store_dwordx4 v[0:1], v[32:35], off sc0 sc1
	v_mov_b32_e32 v36, v39
	v_pk_mul_f32 v[4:5], v[6:7], v[40:41]
	v_mov_b32_e32 v46, v43
	v_pk_mul_f32 v[34:35], v[2:3], v[52:53]
	v_pk_mul_f32 v[0:1], v[22:23], v[36:37]
	v_pk_mul_f32 v[32:33], v[48:49], v[46:47]
	v_bfe_u32 v31, v35, 16, 1
	v_bfe_u32 v37, v5, 16, 1
	v_add3_u32 v5, v5, v37, s81
	v_add3_u32 v31, v35, v31, s81
	v_bfe_u32 v35, v0, 16, 1
	v_bfe_u32 v37, v32, 16, 1
	v_bfe_u32 v36, v34, 16, 1
	v_bfe_u32 v38, v4, 16, 1
	v_add3_u32 v32, v32, v37, s81
	v_add3_u32 v0, v0, v35, s81
	v_add3_u32 v4, v4, v38, s81
	v_add3_u32 v34, v34, v36, s81
	v_bfe_u32 v36, v1, 16, 1
	v_bfe_u32 v38, v33, 16, 1
	v_lshrrev_b32_e32 v0, 16, v0
	v_lshrrev_b32_e32 v32, 16, v32
	v_add3_u32 v33, v33, v38, s81
	v_add3_u32 v1, v1, v36, s81
	v_and_or_b32 v34, v34, s71, v32
	v_and_or_b32 v32, v4, s71, v0
	v_or_b32_e32 v0, s0, v28
	v_lshrrev_b32_e32 v1, 16, v1
	v_lshrrev_b32_e32 v33, 16, v33
	v_lshlrev_b32_e32 v96, 11, v0
	v_and_or_b32 v35, v31, s71, v33
	v_and_or_b32 v33, v5, s71, v1
	v_lshl_add_u64 v[0:1], v[20:21], 0, v[96:97]
	global_store_dwordx4 v[0:1], v[32:35], off sc0 sc1
	ds_read2_b32 v[0:1], v27 offset0:49 offset1:57
	ds_read2_b32 v[4:5], v27 offset0:82 offset1:90
	ds_read2_b32 v[36:37], v27 offset0:115 offset1:123
	ds_read2_b32 v[38:39], v27 offset0:16 offset1:24
	ds_read2_b32 v[40:41], v27 offset0:148 offset1:156
	ds_read2_b32 v[42:43], v27 offset0:181 offset1:189
	ds_read2_b32 v[44:45], v27 offset0:214 offset1:222
	ds_read2_b32 v[46:47], v27 offset0:247 offset1:255
	s_waitcnt lgkmcnt(7)
	v_mov_b32_e32 v34, v0
	s_waitcnt lgkmcnt(3)
	v_mov_b32_e32 v50, v40
	v_mov_b32_e32 v35, v36
	s_waitcnt lgkmcnt(1)
	v_mov_b32_e32 v51, v44
	v_mov_b32_e32 v32, v38
	v_mov_b32_e32 v33, v4
	v_pk_mul_f32 v[34:35], v[6:7], v[34:35]
	v_pk_mul_f32 v[50:51], v[48:49], v[50:51]
	v_mov_b32_e32 v52, v42
	s_waitcnt lgkmcnt(0)
	v_mov_b32_e32 v53, v46
	v_pk_mul_f32 v[32:33], v[22:23], v[32:33]
	v_pk_mul_f32 v[52:53], v[2:3], v[52:53]
	v_bfe_u32 v31, v35, 16, 1
	v_bfe_u32 v36, v34, 16, 1
	v_bfe_u32 v38, v50, 16, 1
	v_bfe_u32 v40, v51, 16, 1
	v_bfe_u32 v0, v53, 16, 1
	v_bfe_u32 v4, v52, 16, 1
	v_add3_u32 v36, v34, v36, s81
	v_add3_u32 v31, v35, v31, s81
	v_bfe_u32 v34, v32, 16, 1
	v_bfe_u32 v35, v33, 16, 1
	v_add3_u32 v40, v51, v40, s81
	v_add3_u32 v38, v50, v38, s81
	v_add3_u32 v4, v52, v4, s81
	v_add3_u32 v0, v53, v0, s81
	v_add3_u32 v33, v33, v35, s81
	v_add3_u32 v32, v32, v34, s81
	v_lshrrev_b32_e32 v34, 16, v38
	v_lshrrev_b32_e32 v35, 16, v40
	v_mov_b32_e32 v46, v43
	v_lshrrev_b32_e32 v32, 16, v32
	v_and_or_b32 v35, v0, s71, v35
	v_and_or_b32 v34, v4, s71, v34
	v_or_b32_e32 v0, s0, v29
	v_mov_b32_e32 v4, v39
	v_pk_mul_f32 v[2:3], v[2:3], v[46:47]
	v_lshrrev_b32_e32 v33, 16, v33
	v_and_or_b32 v32, v36, s71, v32
	v_lshlrev_b32_e32 v96, 11, v0
	v_pk_mul_f32 v[4:5], v[22:23], v[4:5]
	v_mov_b32_e32 v36, v1
	v_bfe_u32 v22, v3, 16, 1
	v_and_or_b32 v33, v31, s71, v33
	v_lshl_add_u64 v[50:51], v[20:21], 0, v[96:97]
	v_pk_mul_f32 v[0:1], v[6:7], v[36:37]
	v_mov_b32_e32 v44, v41
	v_add3_u32 v3, v3, v22, s81
	v_bfe_u32 v22, v4, 16, 1
	global_store_dwordx4 v[50:51], v[32:35], off sc0 sc1
	v_pk_mul_f32 v[6:7], v[48:49], v[44:45]
	v_bfe_u32 v23, v2, 16, 1
	v_bfe_u32 v31, v1, 16, 1
	v_bfe_u32 v32, v0, 16, 1
	v_add3_u32 v4, v4, v22, s81
	v_add3_u32 v0, v0, v32, s81
	v_add3_u32 v1, v1, v31, s81
	v_add3_u32 v2, v2, v23, s81
	v_bfe_u32 v23, v5, 16, 1
	v_bfe_u32 v31, v6, 16, 1
	v_bfe_u32 v32, v7, 16, 1
	v_lshrrev_b32_e32 v4, 16, v4
	v_add3_u32 v7, v7, v32, s81
	v_add3_u32 v6, v6, v31, s81
	v_add3_u32 v5, v5, v23, s81
	v_and_or_b32 v0, v0, s71, v4
	v_or_b32_e32 v4, s0, v30
	v_lshrrev_b32_e32 v5, 16, v5
	v_lshrrev_b32_e32 v6, 16, v6
	v_lshrrev_b32_e32 v7, 16, v7
	v_lshlrev_b32_e32 v96, 11, v4
	v_and_or_b32 v3, v3, s71, v7
	v_and_or_b32 v2, v2, s71, v6
	v_and_or_b32 v1, v1, s71, v5
	v_lshl_add_u64 v[4:5], v[20:21], 0, v[96:97]
	global_store_dwordx4 v[4:5], v[0:3], off sc0 sc1
	s_waitcnt lgkmcnt(0)

.LBB0_206:
	s_waitcnt vmcnt(0)
	ds_write2_b32 v25, v20, v21 offset1:66
	s_waitcnt vmcnt(28)
	ds_write2_b32 v25, v22, v23 offset0:132 offset1:198
	v_add_u32_e32 v20, 0x400, v25
	s_waitcnt vmcnt(26)
	ds_write2_b32 v20, v31, v32 offset0:8 offset1:74
	s_waitcnt vmcnt(24)
	ds_write2_b32 v20, v33, v34 offset0:140 offset1:206
	v_add_u32_e32 v20, 0x800, v25
	s_waitcnt vmcnt(22)
	ds_write2_b32 v20, v35, v36 offset0:16 offset1:82
	s_waitcnt vmcnt(20)
	ds_write2_b32 v20, v37, v38 offset0:148 offset1:214
	v_add_u32_e32 v20, 0xc00, v25
	s_waitcnt vmcnt(18)
	ds_write2_b32 v20, v39, v40 offset0:24 offset1:90
	s_waitcnt vmcnt(16)
	ds_write2_b32 v20, v41, v42 offset0:156 offset1:222
	v_add_u32_e32 v20, 0x1000, v25
	s_waitcnt vmcnt(14)
	ds_write2_b32 v20, v43, v44 offset0:32 offset1:98
	s_waitcnt vmcnt(12)
	ds_write2_b32 v20, v45, v46 offset0:164 offset1:230
	v_add_u32_e32 v20, 0x1400, v25
	s_waitcnt vmcnt(10)
	ds_write2_b32 v20, v47, v48 offset0:40 offset1:106
	s_waitcnt vmcnt(8)
	ds_write2_b32 v20, v49, v50 offset0:172 offset1:238
	v_add_u32_e32 v20, 0x1800, v25
	s_waitcnt vmcnt(6)
	ds_write2_b32 v20, v51, v52 offset0:48 offset1:114
	s_waitcnt vmcnt(4)
	ds_write2_b32 v20, v53, v54 offset0:180 offset1:246
	v_add_u32_e32 v20, 0x1c00, v25
	s_waitcnt vmcnt(2)
	ds_write2_b32 v20, v55, v56 offset0:56 offset1:122
	s_waitcnt vmcnt(0)
	ds_write2_b32 v20, v57, v58 offset0:188 offset1:254
	s_waitcnt lgkmcnt(0)
	ds_read2_b32 v[32:33], v27 offset1:8
	ds_read2_b32 v[34:35], v27 offset0:66 offset1:74
	ds_read2_b32 v[38:39], v27 offset0:33 offset1:41
	ds_read2_b32 v[40:41], v27 offset0:99 offset1:107
	ds_read2_b32 v[42:43], v27 offset0:132 offset1:140
	ds_read2_b32 v[44:45], v27 offset0:198 offset1:206
	ds_read2_b32 v[46:47], v27 offset0:165 offset1:173
	ds_read2_b32 v[48:49], v27 offset0:231 offset1:239
	s_waitcnt lgkmcnt(7)
	v_mov_b32_e32 v20, v32
	s_waitcnt lgkmcnt(5)
	v_mov_b32_e32 v22, v38
	s_waitcnt lgkmcnt(4)
	v_mov_b32_e32 v23, v40
	s_waitcnt lgkmcnt(3)
	v_mov_b32_e32 v50, v42
	s_waitcnt lgkmcnt(2)
	v_mov_b32_e32 v51, v44
	s_waitcnt lgkmcnt(1)
	v_mov_b32_e32 v52, v46
	s_waitcnt lgkmcnt(0)
	v_mov_b32_e32 v53, v48
	v_mov_b32_e32 v21, v34
	v_pk_mul_f32 v[22:23], v[0:1], v[22:23]
	v_pk_mul_f32 v[50:51], v[6:7], v[50:51]
	v_pk_mul_f32 v[52:53], v[4:5], v[52:53]
	v_pk_mul_f32 v[20:21], v[2:3], v[20:21]
	v_bfe_u32 v31, v53, 16, 1
	v_bfe_u32 v34, v23, 16, 1
	v_bfe_u32 v40, v50, 16, 1
	v_bfe_u32 v32, v52, 16, 1
	v_bfe_u32 v38, v22, 16, 1
	v_add3_u32 v34, v23, v34, s81
	v_add3_u32 v23, v53, v31, s81
	v_bfe_u32 v31, v20, 16, 1
	v_add3_u32 v40, v50, v40, s81
	v_add3_u32 v38, v22, v38, s81
	v_add3_u32 v22, v52, v32, s81
	v_bfe_u32 v32, v21, 16, 1
	v_bfe_u32 v42, v51, 16, 1
	v_add3_u32 v20, v20, v31, s81
	v_lshrrev_b32_e32 v31, 16, v40
	s_lshl_b32 s46, s35, 1
	v_add3_u32 v42, v51, v42, s81
	v_add3_u32 v21, v21, v32, s81
	v_and_or_b32 v22, v22, s71, v31
	v_or_b32_e32 v31, s34, v26
	v_lshl_add_u64 v[36:37], v[16:17], 0, s[46:47]
	v_lshrrev_b32_e32 v20, 16, v20
	v_lshrrev_b32_e32 v21, 16, v21
	v_lshrrev_b32_e32 v32, 16, v42
	v_lshlrev_b32_e32 v96, 11, v31
	v_and_or_b32 v23, v23, s71, v32
	v_and_or_b32 v21, v34, s71, v21
	v_and_or_b32 v20, v38, s71, v20
	v_lshl_add_u64 v[50:51], v[36:37], 0, v[96:97]
	v_mov_b32_e32 v34, v33
	v_mov_b32_e32 v40, v39
	v_mov_b32_e32 v48, v47
	global_store_dwordx4 v[50:51], v[20:23], off sc0 sc1
	v_mov_b32_e32 v44, v43
	v_pk_mul_f32 v[32:33], v[6:7], v[44:45]
	v_pk_mul_f32 v[20:21], v[2:3], v[34:35]
	v_pk_mul_f32 v[22:23], v[0:1], v[40:41]
	v_pk_mul_f32 v[34:35], v[4:5], v[48:49]
	v_bfe_u32 v39, v23, 16, 1
	v_bfe_u32 v31, v35, 16, 1
	v_add3_u32 v39, v23, v39, s81
	v_add3_u32 v23, v35, v31, s81
	v_bfe_u32 v35, v32, 16, 1
	v_bfe_u32 v38, v34, 16, 1
	v_bfe_u32 v40, v22, 16, 1
	v_bfe_u32 v31, v20, 16, 1
	v_add3_u32 v32, v32, v35, s81
	v_add3_u32 v40, v22, v40, s81
	v_add3_u32 v22, v34, v38, s81
	v_bfe_u32 v34, v21, 16, 1
	v_bfe_u32 v38, v33, 16, 1
	v_add3_u32 v20, v20, v31, s81
	v_lshrrev_b32_e32 v31, 16, v32
	v_add3_u32 v33, v33, v38, s81
	v_add3_u32 v21, v21, v34, s81
	v_and_or_b32 v22, v22, s71, v31
	v_or_b32_e32 v31, s34, v28
	v_lshrrev_b32_e32 v20, 16, v20
	v_lshrrev_b32_e32 v21, 16, v21
	v_lshrrev_b32_e32 v32, 16, v33
	v_lshlrev_b32_e32 v96, 11, v31
	v_and_or_b32 v23, v23, s71, v32
	v_and_or_b32 v21, v39, s71, v21
	v_and_or_b32 v20, v40, s71, v20
	v_lshl_add_u64 v[32:33], v[36:37], 0, v[96:97]
	ds_read2_b32 v[34:35], v27 offset0:16 offset1:24
	ds_read2_b32 v[38:39], v27 offset0:82 offset1:90
	global_store_dwordx4 v[32:33], v[20:23], off sc0 sc1
	ds_read2_b32 v[32:33], v27 offset0:49 offset1:57
	ds_read2_b32 v[40:41], v27 offset0:115 offset1:123
	ds_read2_b32 v[42:43], v27 offset0:148 offset1:156
	ds_read2_b32 v[44:45], v27 offset0:214 offset1:222
	ds_read2_b32 v[46:47], v27 offset0:181 offset1:189
	ds_read2_b32 v[48:49], v27 offset0:247 offset1:255
	s_waitcnt lgkmcnt(7)
	v_mov_b32_e32 v20, v34
	s_waitcnt lgkmcnt(5)
	v_mov_b32_e32 v22, v32
	s_waitcnt lgkmcnt(4)
	v_mov_b32_e32 v23, v40
	s_waitcnt lgkmcnt(3)
	v_mov_b32_e32 v50, v42
	s_waitcnt lgkmcnt(2)
	v_mov_b32_e32 v51, v44
	s_waitcnt lgkmcnt(1)
	v_mov_b32_e32 v52, v46
	s_waitcnt lgkmcnt(0)
	v_mov_b32_e32 v53, v48
	v_mov_b32_e32 v21, v38
	v_pk_mul_f32 v[22:23], v[0:1], v[22:23]
	v_pk_mul_f32 v[50:51], v[6:7], v[50:51]
	v_pk_mul_f32 v[52:53], v[4:5], v[52:53]
	v_pk_mul_f32 v[20:21], v[2:3], v[20:21]
	v_bfe_u32 v31, v53, 16, 1
	v_bfe_u32 v34, v23, 16, 1
	v_bfe_u32 v40, v50, 16, 1
	v_bfe_u32 v32, v52, 16, 1
	v_bfe_u32 v38, v22, 16, 1
	v_add3_u32 v34, v23, v34, s81
	v_add3_u32 v23, v53, v31, s81
	v_bfe_u32 v31, v20, 16, 1
	v_add3_u32 v40, v50, v40, s81
	v_add3_u32 v38, v22, v38, s81
	v_add3_u32 v22, v52, v32, s81
	v_bfe_u32 v32, v21, 16, 1
	v_bfe_u32 v42, v51, 16, 1
	v_add3_u32 v20, v20, v31, s81
	v_lshrrev_b32_e32 v31, 16, v40
	v_add3_u32 v42, v51, v42, s81
	v_add3_u32 v21, v21, v32, s81
	v_and_or_b32 v22, v22, s71, v31
	v_or_b32_e32 v31, s34, v29
	v_lshrrev_b32_e32 v20, 16, v20
	v_lshrrev_b32_e32 v21, 16, v21
	v_lshrrev_b32_e32 v32, 16, v42
	v_lshlrev_b32_e32 v96, 11, v31
	v_mov_b32_e32 v40, v33
	v_mov_b32_e32 v48, v47
	v_and_or_b32 v23, v23, s71, v32
	v_and_or_b32 v21, v34, s71, v21
	v_and_or_b32 v20, v38, s71, v20
	v_lshl_add_u64 v[50:51], v[36:37], 0, v[96:97]
	v_mov_b32_e32 v38, v35
	v_pk_mul_f32 v[0:1], v[0:1], v[40:41]
	v_mov_b32_e32 v44, v43
	v_pk_mul_f32 v[4:5], v[4:5], v[48:49]
	global_store_dwordx4 v[50:51], v[20:23], off sc0 sc1
	v_pk_mul_f32 v[2:3], v[2:3], v[38:39]
	v_pk_mul_f32 v[6:7], v[6:7], v[44:45]
	v_bfe_u32 v20, v5, 16, 1
	v_bfe_u32 v22, v1, 16, 1
	v_add3_u32 v1, v1, v22, s81
	v_add3_u32 v5, v5, v20, s81
	v_bfe_u32 v20, v2, 16, 1
	v_bfe_u32 v22, v6, 16, 1
	v_bfe_u32 v21, v4, 16, 1
	v_bfe_u32 v23, v0, 16, 1
	v_add3_u32 v6, v6, v22, s81
	v_add3_u32 v2, v2, v20, s81
	v_add3_u32 v0, v0, v23, s81
	v_add3_u32 v4, v4, v21, s81
	v_bfe_u32 v21, v3, 16, 1
	v_bfe_u32 v23, v7, 16, 1
	v_lshrrev_b32_e32 v20, 16, v2
	v_lshrrev_b32_e32 v2, 16, v6
	v_add3_u32 v7, v7, v23, s81
	v_add3_u32 v3, v3, v21, s81
	v_and_or_b32 v2, v4, s71, v2
	v_or_b32_e32 v4, s34, v30
	v_lshrrev_b32_e32 v21, 16, v3
	v_lshrrev_b32_e32 v3, 16, v7
	v_lshlrev_b32_e32 v96, 11, v4
	v_and_or_b32 v3, v5, s71, v3
	v_and_or_b32 v1, v1, s71, v21
	v_and_or_b32 v0, v0, s71, v20
	v_lshl_add_u64 v[4:5], v[36:37], 0, v[96:97]
	global_store_dwordx4 v[4:5], v[0:3], off sc0 sc1
	s_waitcnt lgkmcnt(0)

.LBB0_227:
	s_waitcnt vmcnt(0)
	ds_write2_b32 v21, v16, v17 offset1:66
	s_waitcnt vmcnt(28)
	ds_write2_b32 v21, v18, v19 offset0:132 offset1:198
	v_add_u32_e32 v16, 0x400, v21
	s_waitcnt vmcnt(26)
	ds_write2_b32 v16, v27, v28 offset0:8 offset1:74
	s_waitcnt vmcnt(24)
	ds_write2_b32 v16, v29, v30 offset0:140 offset1:206
	v_add_u32_e32 v16, 0x800, v21
	s_waitcnt vmcnt(22)
	ds_write2_b32 v16, v31, v32 offset0:16 offset1:82
	s_waitcnt vmcnt(20)
	ds_write2_b32 v16, v33, v34 offset0:148 offset1:214
	v_add_u32_e32 v16, 0xc00, v21
	s_waitcnt vmcnt(18)
	ds_write2_b32 v16, v35, v36 offset0:24 offset1:90
	s_waitcnt vmcnt(16)
	ds_write2_b32 v16, v37, v38 offset0:156 offset1:222
	v_add_u32_e32 v16, 0x1000, v21
	s_waitcnt vmcnt(14)
	ds_write2_b32 v16, v39, v40 offset0:32 offset1:98
	s_waitcnt vmcnt(12)
	ds_write2_b32 v16, v41, v42 offset0:164 offset1:230
	v_add_u32_e32 v16, 0x1400, v21
	s_waitcnt vmcnt(10)
	ds_write2_b32 v16, v43, v44 offset0:40 offset1:106
	s_waitcnt vmcnt(8)
	ds_write2_b32 v16, v45, v46 offset0:172 offset1:238
	v_add_u32_e32 v16, 0x1800, v21
	s_waitcnt vmcnt(6)
	ds_write2_b32 v16, v47, v48 offset0:48 offset1:114
	s_waitcnt vmcnt(4)
	ds_write2_b32 v16, v49, v50 offset0:180 offset1:246
	v_add_u32_e32 v16, 0x1c00, v21
	s_waitcnt vmcnt(2)
	ds_write2_b32 v16, v51, v52 offset0:56 offset1:122
	s_waitcnt vmcnt(0)
	ds_write2_b32 v16, v53, v54 offset0:188 offset1:254
	s_waitcnt lgkmcnt(0)
	ds_read2_b32 v[28:29], v23 offset1:8
	ds_read2_b32 v[30:31], v23 offset0:66 offset1:74
	ds_read2_b32 v[34:35], v23 offset0:33 offset1:41
	ds_read2_b32 v[36:37], v23 offset0:99 offset1:107
	ds_read2_b32 v[38:39], v23 offset0:132 offset1:140
	ds_read2_b32 v[40:41], v23 offset0:198 offset1:206
	ds_read2_b32 v[42:43], v23 offset0:165 offset1:173
	ds_read2_b32 v[44:45], v23 offset0:231 offset1:239
	s_sub_i32 s0, 0, s35
	s_waitcnt lgkmcnt(5)
	v_mov_b32_e32 v18, v34
	s_waitcnt lgkmcnt(4)
	v_mov_b32_e32 v19, v36
	s_waitcnt lgkmcnt(3)
	v_mov_b32_e32 v46, v38
	s_waitcnt lgkmcnt(2)
	v_mov_b32_e32 v47, v40
	s_waitcnt lgkmcnt(1)
	v_mov_b32_e32 v48, v42
	s_waitcnt lgkmcnt(0)
	v_mov_b32_e32 v49, v44
	v_mov_b32_e32 v16, v28
	v_mov_b32_e32 v17, v30
	v_pk_mul_f32 v[18:19], v[0:1], v[18:19]
	v_pk_mul_f32 v[46:47], v[6:7], v[46:47]
	v_pk_mul_f32 v[48:49], v[4:5], v[48:49]
	v_pk_mul_f32 v[16:17], v[2:3], v[16:17]
	v_bfe_u32 v27, v49, 16, 1
	v_bfe_u32 v28, v48, 16, 1
	v_bfe_u32 v30, v19, 16, 1
	v_bfe_u32 v34, v18, 16, 1
	v_bfe_u32 v36, v46, 16, 1
	s_add_i32 s0, s0, s8
	v_add3_u32 v34, v18, v34, s81
	v_add3_u32 v30, v19, v30, s81
	v_add3_u32 v18, v48, v28, s81
	v_add3_u32 v19, v49, v27, s81
	v_bfe_u32 v27, v16, 16, 1
	v_bfe_u32 v28, v17, 16, 1
	v_bfe_u32 v38, v47, 16, 1
	v_add3_u32 v36, v46, v36, s81
	v_add_u32_e32 v46, s0, v22
	s_ashr_i32 s35, s34, 31
	v_add3_u32 v38, v47, v38, s81
	v_add3_u32 v17, v17, v28, s81
	v_add3_u32 v16, v16, v27, s81
	v_ashrrev_i32_e32 v47, 31, v46
	v_lshl_add_u64 v[32:33], s[34:35], 1, v[14:15]
	v_lshrrev_b32_e32 v16, 16, v16
	v_lshrrev_b32_e32 v17, 16, v17
	v_lshrrev_b32_e32 v27, 16, v36
	v_lshrrev_b32_e32 v28, 16, v38
	v_lshlrev_b64 v[48:49], 11, v[46:47]
	v_and_or_b32 v19, v19, s71, v28
	v_and_or_b32 v18, v18, s71, v27
	v_and_or_b32 v17, v30, s71, v17
	v_and_or_b32 v16, v34, s71, v16
	v_lshl_add_u64 v[48:49], v[32:33], 0, v[48:49]
	v_mov_b32_e32 v30, v29
	v_mov_b32_e32 v36, v35
	v_mov_b32_e32 v44, v43
	global_store_dwordx4 v[48:49], v[16:19], off sc0 sc1
	v_mov_b32_e32 v40, v39
	v_pk_mul_f32 v[28:29], v[6:7], v[40:41]
	v_pk_mul_f32 v[16:17], v[2:3], v[30:31]
	v_pk_mul_f32 v[18:19], v[0:1], v[36:37]
	v_pk_mul_f32 v[30:31], v[4:5], v[44:45]
	v_bfe_u32 v35, v19, 16, 1
	v_bfe_u32 v27, v31, 16, 1
	v_bfe_u32 v34, v30, 16, 1
	v_bfe_u32 v36, v18, 16, 1
	v_add3_u32 v36, v18, v36, s81
	v_add3_u32 v35, v19, v35, s81
	v_add3_u32 v18, v30, v34, s81
	v_add3_u32 v19, v31, v27, s81
	v_bfe_u32 v31, v28, 16, 1
	v_bfe_u32 v34, v29, 16, 1
	v_bfe_u32 v27, v16, 16, 1
	v_add3_u32 v29, v29, v34, s81
	v_add3_u32 v28, v28, v31, s81
	v_add3_u32 v16, v16, v27, s81
	v_lshrrev_b32_e32 v27, 16, v28
	v_lshrrev_b32_e32 v28, 16, v29
	v_bfe_u32 v30, v17, 16, 1
	v_and_or_b32 v19, v19, s71, v28
	v_add_u32_e32 v28, 8, v46
	v_add3_u32 v17, v17, v30, s81
	v_ashrrev_i32_e32 v29, 31, v28
	v_lshrrev_b32_e32 v16, 16, v16
	v_lshrrev_b32_e32 v17, 16, v17
	v_lshlrev_b64 v[28:29], 11, v[28:29]
	v_and_or_b32 v18, v18, s71, v27
	v_and_or_b32 v17, v35, s71, v17
	v_and_or_b32 v16, v36, s71, v16
	v_lshl_add_u64 v[28:29], v[32:33], 0, v[28:29]
	ds_read2_b32 v[30:31], v23 offset0:16 offset1:24
	ds_read2_b32 v[34:35], v23 offset0:82 offset1:90
	global_store_dwordx4 v[28:29], v[16:19], off sc0 sc1
	ds_read2_b32 v[28:29], v23 offset0:49 offset1:57
	ds_read2_b32 v[36:37], v23 offset0:115 offset1:123
	ds_read2_b32 v[38:39], v23 offset0:148 offset1:156
	ds_read2_b32 v[40:41], v23 offset0:214 offset1:222
	ds_read2_b32 v[42:43], v23 offset0:181 offset1:189
	ds_read2_b32 v[44:45], v23 offset0:247 offset1:255
	s_waitcnt lgkmcnt(7)
	v_mov_b32_e32 v16, v30
	s_waitcnt lgkmcnt(5)
	v_mov_b32_e32 v18, v28
	s_waitcnt lgkmcnt(4)
	v_mov_b32_e32 v19, v36
	s_waitcnt lgkmcnt(3)
	v_mov_b32_e32 v48, v38
	s_waitcnt lgkmcnt(2)
	v_mov_b32_e32 v49, v40
	s_waitcnt lgkmcnt(1)
	v_mov_b32_e32 v50, v42
	s_waitcnt lgkmcnt(0)
	v_mov_b32_e32 v51, v44
	v_mov_b32_e32 v17, v34
	v_pk_mul_f32 v[18:19], v[0:1], v[18:19]
	v_pk_mul_f32 v[48:49], v[6:7], v[48:49]
	v_pk_mul_f32 v[50:51], v[4:5], v[50:51]
	v_pk_mul_f32 v[16:17], v[2:3], v[16:17]
	v_bfe_u32 v27, v51, 16, 1
	v_bfe_u32 v28, v50, 16, 1
	v_bfe_u32 v30, v19, 16, 1
	v_bfe_u32 v34, v18, 16, 1
	v_bfe_u32 v36, v48, 16, 1
	v_add3_u32 v34, v18, v34, s81
	v_add3_u32 v30, v19, v30, s81
	v_add3_u32 v18, v50, v28, s81
	v_add3_u32 v19, v51, v27, s81
	v_bfe_u32 v27, v16, 16, 1
	v_bfe_u32 v28, v17, 16, 1
	v_bfe_u32 v38, v49, 16, 1
	v_add3_u32 v36, v48, v36, s81
	v_add_u32_e32 v48, 16, v46
	v_add3_u32 v38, v49, v38, s81
	v_add3_u32 v17, v17, v28, s81
	v_add3_u32 v16, v16, v27, s81
	v_ashrrev_i32_e32 v49, 31, v48
	v_lshrrev_b32_e32 v16, 16, v16
	v_lshrrev_b32_e32 v17, 16, v17
	v_lshrrev_b32_e32 v27, 16, v36
	v_lshrrev_b32_e32 v28, 16, v38
	v_lshlrev_b64 v[48:49], 11, v[48:49]
	v_mov_b32_e32 v36, v29
	v_mov_b32_e32 v44, v43
	v_and_or_b32 v19, v19, s71, v28
	v_and_or_b32 v18, v18, s71, v27
	v_and_or_b32 v17, v30, s71, v17
	v_and_or_b32 v16, v34, s71, v16
	v_lshl_add_u64 v[48:49], v[32:33], 0, v[48:49]
	v_mov_b32_e32 v34, v31
	v_pk_mul_f32 v[0:1], v[0:1], v[36:37]
	v_mov_b32_e32 v40, v39
	v_pk_mul_f32 v[4:5], v[4:5], v[44:45]
	global_store_dwordx4 v[48:49], v[16:19], off sc0 sc1
	v_pk_mul_f32 v[2:3], v[2:3], v[34:35]
	v_pk_mul_f32 v[6:7], v[6:7], v[40:41]
	v_bfe_u32 v16, v5, 16, 1
	v_bfe_u32 v18, v1, 16, 1
	v_bfe_u32 v17, v4, 16, 1
	v_bfe_u32 v19, v0, 16, 1
	v_add3_u32 v1, v1, v18, s81
	v_add3_u32 v5, v5, v16, s81
	v_bfe_u32 v16, v2, 16, 1
	v_bfe_u32 v18, v6, 16, 1
	v_add3_u32 v0, v0, v19, s81
	v_add3_u32 v4, v4, v17, s81
	v_bfe_u32 v17, v3, 16, 1
	v_bfe_u32 v19, v7, 16, 1
	v_add3_u32 v6, v6, v18, s81
	v_add3_u32 v2, v2, v16, s81
	v_add3_u32 v7, v7, v19, s81
	v_add3_u32 v3, v3, v17, s81
	v_lshrrev_b32_e32 v16, 16, v2
	v_lshrrev_b32_e32 v2, 16, v6
	v_lshrrev_b32_e32 v17, 16, v3
	v_lshrrev_b32_e32 v3, 16, v7
	v_and_or_b32 v2, v4, s71, v2
	v_add_u32_e32 v4, 24, v46
	v_and_or_b32 v3, v5, s71, v3
	v_ashrrev_i32_e32 v5, 31, v4
	v_lshlrev_b64 v[4:5], 11, v[4:5]
	v_and_or_b32 v1, v1, s71, v17
	v_and_or_b32 v0, v0, s71, v16
	v_lshl_add_u64 v[4:5], v[32:33], 0, v[4:5]
	global_store_dwordx4 v[4:5], v[0:3], off sc0 sc1
	s_waitcnt lgkmcnt(0)

.LBB0_229:
	s_cmpk_gt_i32 s40, 0x1ff
	s_mov_b64 s[0:1], -1
	s_cbranch_scc0 .LBB0_235
	s_cmpk_gt_u32 s40, 0xcff
	s_cbranch_scc0 .LBB0_232
	s_and_b32 s0, s38, 0x7fffffc0
	s_addk_i32 s0, 0xe600
	v_or_b32_e32 v96, s0, v9
	v_readlane_b32 s42, v235, 14
	s_and_b32 s34, s8, 0x3e0
	v_lshlrev_b64 v[0:1], 12, v[96:97]
	v_readlane_b32 s43, v235, 15
	s_lshl_b32 s46, s34, 2
	v_lshlrev_b32_e32 v96, 2, v8
	v_lshl_add_u64 v[0:1], s[42:43], 0, v[0:1]
	v_lshl_add_u64 v[0:1], v[0:1], 0, s[46:47]
	v_lshl_add_u64 v[0:1], v[0:1], 0, v[96:97]
	v_add_co_u32_e32 v2, vcc, 0x2000, v0
	s_movk_i32 s1, 0x4000
	s_waitcnt lgkmcnt(0)
	v_addc_co_u32_e32 v3, vcc, 0, v1, vcc
	global_load_dword v4, v[0:1], off
	global_load_dword v5, v[2:3], off
	v_add_co_u32_e32 v2, vcc, s1, v0
	s_mov_b32 s1, s47
	s_nop 0
	v_addc_co_u32_e32 v3, vcc, 0, v1, vcc
	global_load_dword v6, v[2:3], off
	v_add_co_u32_e32 v2, vcc, 0x6000, v0
	s_nop 1
	v_addc_co_u32_e32 v3, vcc, 0, v1, vcc
	global_load_dword v7, v[2:3], off
	v_add_co_u32_e32 v2, vcc, 0x8000, v0
	s_nop 1
	v_addc_co_u32_e32 v3, vcc, 0, v1, vcc
	global_load_dword v16, v[2:3], off
	v_add_co_u32_e32 v2, vcc, 0xa000, v0
	s_nop 1
	v_addc_co_u32_e32 v3, vcc, 0, v1, vcc
	global_load_dword v17, v[2:3], off
	v_add_co_u32_e32 v2, vcc, 0xc000, v0
	s_nop 1
	v_addc_co_u32_e32 v3, vcc, 0, v1, vcc
	global_load_dword v18, v[2:3], off
	v_add_co_u32_e32 v2, vcc, 0xe000, v0
	s_nop 1
	v_addc_co_u32_e32 v3, vcc, 0, v1, vcc
	global_load_dword v19, v[2:3], off
	v_add_co_u32_e32 v2, vcc, 0x10000, v0
	s_nop 1
	v_addc_co_u32_e32 v3, vcc, 0, v1, vcc
	global_load_dword v27, v[2:3], off
	v_add_co_u32_e32 v2, vcc, 0x12000, v0
	s_nop 1
	v_addc_co_u32_e32 v3, vcc, 0, v1, vcc
	global_load_dword v28, v[2:3], off
	v_add_co_u32_e32 v2, vcc, 0x14000, v0
	s_nop 1
	v_addc_co_u32_e32 v3, vcc, 0, v1, vcc
	global_load_dword v29, v[2:3], off
	v_add_co_u32_e32 v2, vcc, 0x16000, v0
	s_nop 1
	v_addc_co_u32_e32 v3, vcc, 0, v1, vcc
	global_load_dword v30, v[2:3], off
	v_add_co_u32_e32 v2, vcc, 0x18000, v0
	s_nop 1
	v_addc_co_u32_e32 v3, vcc, 0, v1, vcc
	global_load_dword v31, v[2:3], off
	v_add_co_u32_e32 v2, vcc, 0x1a000, v0
	s_nop 1
	v_addc_co_u32_e32 v3, vcc, 0, v1, vcc
	global_load_dword v32, v[2:3], off
	v_add_co_u32_e32 v2, vcc, 0x1c000, v0
	s_nop 1
	v_addc_co_u32_e32 v3, vcc, 0, v1, vcc
	global_load_dword v33, v[2:3], off
	v_add_co_u32_e32 v2, vcc, 0x1e000, v0
	s_nop 1
	v_addc_co_u32_e32 v3, vcc, 0, v1, vcc
	global_load_dword v34, v[2:3], off
	v_add_co_u32_e32 v2, vcc, 0x20000, v0
	s_nop 1
	v_addc_co_u32_e32 v3, vcc, 0, v1, vcc
	global_load_dword v35, v[2:3], off
	v_add_co_u32_e32 v2, vcc, 0x22000, v0
	s_nop 1
	v_addc_co_u32_e32 v3, vcc, 0, v1, vcc
	global_load_dword v36, v[2:3], off
	v_add_co_u32_e32 v2, vcc, 0x24000, v0
	s_nop 1
	v_addc_co_u32_e32 v3, vcc, 0, v1, vcc
	global_load_dword v37, v[2:3], off
	v_add_co_u32_e32 v2, vcc, 0x26000, v0
	s_nop 1
	v_addc_co_u32_e32 v3, vcc, 0, v1, vcc
	global_load_dword v38, v[2:3], off
	v_add_co_u32_e32 v2, vcc, 0x28000, v0
	s_nop 1
	v_addc_co_u32_e32 v3, vcc, 0, v1, vcc
	global_load_dword v39, v[2:3], off
	v_add_co_u32_e32 v2, vcc, 0x2a000, v0
	s_nop 1
	v_addc_co_u32_e32 v3, vcc, 0, v1, vcc
	global_load_dword v40, v[2:3], off
	v_add_co_u32_e32 v2, vcc, 0x2c000, v0
	s_nop 1
	v_addc_co_u32_e32 v3, vcc, 0, v1, vcc
	global_load_dword v41, v[2:3], off
	v_add_co_u32_e32 v2, vcc, 0x2e000, v0
	s_nop 1
	v_addc_co_u32_e32 v3, vcc, 0, v1, vcc
	global_load_dword v42, v[2:3], off
	v_add_co_u32_e32 v2, vcc, 0x30000, v0
	s_nop 1
	v_addc_co_u32_e32 v3, vcc, 0, v1, vcc
	global_load_dword v43, v[2:3], off
	v_add_co_u32_e32 v2, vcc, 0x32000, v0
	s_nop 1
	v_addc_co_u32_e32 v3, vcc, 0, v1, vcc
	global_load_dword v44, v[2:3], off
	v_add_co_u32_e32 v2, vcc, 0x34000, v0
	s_nop 1
	v_addc_co_u32_e32 v3, vcc, 0, v1, vcc
	global_load_dword v45, v[2:3], off
	v_add_co_u32_e32 v2, vcc, 0x36000, v0
	s_nop 1
	v_addc_co_u32_e32 v3, vcc, 0, v1, vcc
	global_load_dword v46, v[2:3], off
	v_add_co_u32_e32 v2, vcc, 0x38000, v0
	s_nop 1
	v_addc_co_u32_e32 v3, vcc, 0, v1, vcc
	global_load_dword v47, v[2:3], off
	v_add_co_u32_e32 v2, vcc, 0x3a000, v0
	s_nop 1
	v_addc_co_u32_e32 v3, vcc, 0, v1, vcc
	global_load_dword v48, v[2:3], off
	v_add_co_u32_e32 v2, vcc, 0x3c000, v0
	s_nop 1
	v_addc_co_u32_e32 v3, vcc, 0, v1, vcc
	v_add_co_u32_e32 v0, vcc, 0x3e000, v0
	global_load_dword v2, v[2:3], off
	s_nop 0
	v_addc_co_u32_e32 v1, vcc, 0, v1, vcc
	global_load_dword v0, v[0:1], off
	v_add_u32_e32 v1, 0x400, v21
	s_waitcnt vmcnt(0)
	ds_write2_b32 v21, v4, v5 offset1:66
	s_waitcnt vmcnt(28)
	ds_write2_b32 v21, v6, v7 offset0:132 offset1:198
	s_waitcnt vmcnt(26)
	ds_write2_b32 v1, v16, v17 offset0:8 offset1:74
	s_waitcnt vmcnt(24)
	ds_write2_b32 v1, v18, v19 offset0:140 offset1:206
	v_add_u32_e32 v1, 0x800, v21
	s_waitcnt vmcnt(22)
	ds_write2_b32 v1, v27, v28 offset0:16 offset1:82
	s_waitcnt vmcnt(20)
	ds_write2_b32 v1, v29, v30 offset0:148 offset1:214
	v_add_u32_e32 v1, 0xc00, v21
	s_waitcnt vmcnt(18)
	ds_write2_b32 v1, v31, v32 offset0:24 offset1:90
	s_waitcnt vmcnt(16)
	ds_write2_b32 v1, v33, v34 offset0:156 offset1:222
	v_add_u32_e32 v1, 0x1000, v21
	s_waitcnt vmcnt(14)
	ds_write2_b32 v1, v35, v36 offset0:32 offset1:98
	s_waitcnt vmcnt(12)
	ds_write2_b32 v1, v37, v38 offset0:164 offset1:230
	v_add_u32_e32 v1, 0x1400, v21
	s_waitcnt vmcnt(10)
	ds_write2_b32 v1, v39, v40 offset0:40 offset1:106
	s_waitcnt vmcnt(8)
	ds_write2_b32 v1, v41, v42 offset0:172 offset1:238
	v_add_u32_e32 v1, 0x1800, v21
	s_waitcnt vmcnt(6)
	ds_write2_b32 v1, v43, v44 offset0:48 offset1:114
	s_waitcnt vmcnt(4)
	ds_write2_b32 v1, v45, v46 offset0:180 offset1:246
	v_add_u32_e32 v1, 0x1c00, v21
	s_waitcnt vmcnt(2)
	ds_write2_b32 v1, v47, v48 offset0:56 offset1:122
	s_waitcnt vmcnt(0)
	ds_write2_b32 v1, v2, v0 offset0:188 offset1:254
	s_waitcnt lgkmcnt(0)
	ds_read2_b32 v[6:7], v23 offset0:33 offset1:41
	ds_read2_b32 v[16:17], v23 offset1:8
	ds_read2_b32 v[18:19], v23 offset0:66 offset1:74
	ds_read2_b32 v[28:29], v23 offset0:99 offset1:107
	ds_read2_b32 v[30:31], v23 offset0:132 offset1:140
	ds_read2_b32 v[32:33], v23 offset0:165 offset1:173
	ds_read2_b32 v[34:35], v23 offset0:198 offset1:206
	ds_read2_b32 v[36:37], v23 offset0:231 offset1:239
	s_waitcnt lgkmcnt(7)
	v_bfe_u32 v3, v6, 16, 1
	s_waitcnt lgkmcnt(6)
	v_bfe_u32 v2, v16, 16, 1
	v_add3_u32 v2, v16, v2, s81
	v_lshrrev_b32_e32 v2, 16, v2
	v_add3_u32 v3, v6, v3, s81
	v_and_or_b32 v2, v3, s71, v2
	s_waitcnt lgkmcnt(5)
	v_bfe_u32 v3, v18, 16, 1
	v_add3_u32 v3, v18, v3, s81
	s_waitcnt lgkmcnt(4)
	v_bfe_u32 v4, v28, 16, 1
	v_lshrrev_b32_e32 v3, 16, v3
	v_add3_u32 v4, v28, v4, s81
	v_and_or_b32 v3, v4, s71, v3
	s_waitcnt lgkmcnt(3)
	v_bfe_u32 v4, v30, 16, 1
	v_add3_u32 v4, v30, v4, s81
	s_waitcnt lgkmcnt(2)
	v_bfe_u32 v5, v32, 16, 1
	v_lshrrev_b32_e32 v4, 16, v4
	v_add3_u32 v5, v32, v5, s81
	v_and_or_b32 v4, v5, s71, v4
	s_waitcnt lgkmcnt(1)
	v_bfe_u32 v5, v34, 16, 1
	v_add3_u32 v5, v34, v5, s81
	s_waitcnt lgkmcnt(0)
	v_bfe_u32 v6, v36, 16, 1
	v_lshrrev_b32_e32 v5, 16, v5
	v_add3_u32 v6, v36, v6, s81
	v_and_or_b32 v5, v6, s71, v5
	v_or_b32_e32 v6, s34, v22
	v_mul_u32_u24_e32 v6, 0xb00, v6
	v_lshl_add_u64 v[0:1], s[0:1], 1, v[10:11]
	v_lshlrev_b32_e32 v96, 1, v6
	v_lshl_add_u64 v[38:39], v[0:1], 0, v[96:97]
	global_store_dwordx4 v[38:39], v[2:5], off sc0 sc1
	v_bfe_u32 v6, v37, 16, 1
	v_add3_u32 v6, v37, v6, s81
	v_bfe_u32 v2, v17, 16, 1
	v_add3_u32 v2, v17, v2, s81
	v_bfe_u32 v3, v7, 16, 1
	v_lshrrev_b32_e32 v2, 16, v2
	v_add3_u32 v3, v7, v3, s81
	v_and_or_b32 v2, v3, s71, v2
	v_bfe_u32 v3, v19, 16, 1
	v_add3_u32 v3, v19, v3, s81
	v_bfe_u32 v4, v29, 16, 1
	v_lshrrev_b32_e32 v3, 16, v3
	v_add3_u32 v4, v29, v4, s81
	v_and_or_b32 v3, v4, s71, v3
	v_bfe_u32 v4, v31, 16, 1
	v_add3_u32 v4, v31, v4, s81
	v_bfe_u32 v5, v33, 16, 1
	v_lshrrev_b32_e32 v4, 16, v4
	v_add3_u32 v5, v33, v5, s81
	v_and_or_b32 v4, v5, s71, v4
	v_bfe_u32 v5, v35, 16, 1
	v_add3_u32 v5, v35, v5, s81
	v_lshrrev_b32_e32 v5, 16, v5
	v_and_or_b32 v5, v6, s71, v5
	v_or_b32_e32 v6, s34, v24
	v_mul_u32_u24_e32 v6, 0xb00, v6
	v_lshlrev_b32_e32 v96, 1, v6
	v_lshl_add_u64 v[6:7], v[0:1], 0, v[96:97]
	global_store_dwordx4 v[6:7], v[2:5], off sc0 sc1
	ds_read2_b32 v[6:7], v23 offset0:16 offset1:24
	ds_read2_b32 v[16:17], v23 offset0:49 offset1:57
	ds_read2_b32 v[18:19], v23 offset0:82 offset1:90
	ds_read2_b32 v[28:29], v23 offset0:115 offset1:123
	ds_read2_b32 v[30:31], v23 offset0:148 offset1:156
	ds_read2_b32 v[32:33], v23 offset0:181 offset1:189
	ds_read2_b32 v[34:35], v23 offset0:214 offset1:222
	ds_read2_b32 v[36:37], v23 offset0:247 offset1:255
	s_waitcnt lgkmcnt(7)
	v_bfe_u32 v2, v6, 16, 1
	v_add3_u32 v2, v6, v2, s81
	s_waitcnt lgkmcnt(6)
	v_bfe_u32 v3, v16, 16, 1
	v_lshrrev_b32_e32 v2, 16, v2
	v_add3_u32 v3, v16, v3, s81
	v_and_or_b32 v2, v3, s71, v2
	s_waitcnt lgkmcnt(5)
	v_bfe_u32 v3, v18, 16, 1
	v_add3_u32 v3, v18, v3, s81
	s_waitcnt lgkmcnt(4)
	v_bfe_u32 v4, v28, 16, 1
	v_lshrrev_b32_e32 v3, 16, v3
	v_add3_u32 v4, v28, v4, s81
	v_and_or_b32 v3, v4, s71, v3
	s_waitcnt lgkmcnt(3)
	v_bfe_u32 v4, v30, 16, 1
	v_add3_u32 v4, v30, v4, s81
	s_waitcnt lgkmcnt(2)
	v_bfe_u32 v5, v32, 16, 1
	v_lshrrev_b32_e32 v4, 16, v4
	v_add3_u32 v5, v32, v5, s81
	v_and_or_b32 v4, v5, s71, v4
	s_waitcnt lgkmcnt(1)
	v_bfe_u32 v5, v34, 16, 1
	v_add3_u32 v5, v34, v5, s81
	s_waitcnt lgkmcnt(0)
	v_bfe_u32 v6, v36, 16, 1
	v_lshrrev_b32_e32 v5, 16, v5
	v_add3_u32 v6, v36, v6, s81
	v_and_or_b32 v5, v6, s71, v5
	v_or_b32_e32 v6, s34, v25
	v_mul_u32_u24_e32 v6, 0xb00, v6
	v_lshlrev_b32_e32 v96, 1, v6
	v_lshl_add_u64 v[38:39], v[0:1], 0, v[96:97]
	global_store_dwordx4 v[38:39], v[2:5], off sc0 sc1
	v_bfe_u32 v6, v37, 16, 1
	v_add3_u32 v6, v37, v6, s81
	v_bfe_u32 v2, v7, 16, 1
	v_add3_u32 v2, v7, v2, s81
	v_bfe_u32 v3, v17, 16, 1
	v_lshrrev_b32_e32 v2, 16, v2
	v_add3_u32 v3, v17, v3, s81
	v_and_or_b32 v2, v3, s71, v2
	v_bfe_u32 v3, v19, 16, 1
	v_add3_u32 v3, v19, v3, s81
	v_bfe_u32 v4, v29, 16, 1
	v_lshrrev_b32_e32 v3, 16, v3
	v_add3_u32 v4, v29, v4, s81
	v_and_or_b32 v3, v4, s71, v3
	v_bfe_u32 v4, v31, 16, 1
	v_add3_u32 v4, v31, v4, s81
	v_bfe_u32 v5, v33, 16, 1
	v_lshrrev_b32_e32 v4, 16, v4
	v_add3_u32 v5, v33, v5, s81
	v_and_or_b32 v4, v5, s71, v4
	v_bfe_u32 v5, v35, 16, 1
	v_add3_u32 v5, v35, v5, s81
	v_lshrrev_b32_e32 v5, 16, v5
	v_and_or_b32 v5, v6, s71, v5
	v_or_b32_e32 v6, s34, v26
	v_mul_u32_u24_e32 v6, 0xb00, v6
	v_lshlrev_b32_e32 v96, 1, v6
	v_lshl_add_u64 v[0:1], v[0:1], 0, v[96:97]
	global_store_dwordx4 v[0:1], v[2:5], off sc0 sc1
	s_waitcnt lgkmcnt(0)
	s_mov_b64 s[0:1], 0
.LBB0_232:
	s_andn2_b64 vcc, exec, s[0:1]
	s_cbranch_vccnz .LBB0_234
	s_add_i32 s0, s40, 0xfe00
	s_and_b32 s1, s0, 0xffff
	s_mul_i32 s1, s1, 0xba2f
	s_lshr_b32 s1, s1, 23
	s_mul_i32 s34, s1, 0xb0
	s_sub_i32 s35, s0, s34
	s_and_b32 s0, s35, 0xffff
	s_lshl_b32 s34, s1, 6
	s_bfe_i32 s41, s35, 0x10002
	s_lshl_b32 s35, s35, 4
	s_lshl_b32 s0, s0, 5
	s_and_b32 s41, s41, 0xb00
	s_and_b32 s35, s35, 0xf80
	v_or_b32_e32 v0, s34, v9
	s_add_i32 s41, s41, s35
	s_and_b32 s35, s0, 0x60
	v_mul_u32_u24_e32 v0, 0x1600, v0
	v_readlane_b32 s42, v235, 16
	s_or_b32 s35, s41, s35
	v_lshlrev_b32_e32 v96, 2, v0
	v_readlane_b32 s43, v235, 17
	s_lshl_b32 s46, s35, 2
	s_mov_b32 s35, 0xb000
	v_lshl_add_u64 v[0:1], s[42:43], 0, v[96:97]
	v_lshl_add_u64 v[0:1], v[0:1], 0, s[46:47]
	v_lshlrev_b32_e32 v96, 2, v8
	v_lshl_add_u64 v[0:1], v[0:1], 0, v[96:97]
	v_add_co_u32_e32 v2, vcc, s35, v0
	s_mov_b32 s35, 0x16000
	s_waitcnt lgkmcnt(0)
	v_addc_co_u32_e32 v3, vcc, 0, v1, vcc
	global_load_dword v4, v[0:1], off
	global_load_dword v5, v[2:3], off
	v_add_co_u32_e32 v2, vcc, s35, v0
	s_mov_b32 s35, 0x21000
	s_nop 0
	v_addc_co_u32_e32 v3, vcc, 0, v1, vcc
	global_load_dword v6, v[2:3], off
	v_add_co_u32_e32 v2, vcc, s35, v0
	s_mov_b32 s35, 0x2c000
	s_nop 0
	v_addc_co_u32_e32 v3, vcc, 0, v1, vcc
	global_load_dword v7, v[2:3], off
	v_add_co_u32_e32 v2, vcc, s35, v0
	s_mov_b32 s35, 0x37000
	s_nop 0
	v_addc_co_u32_e32 v3, vcc, 0, v1, vcc
	global_load_dword v16, v[2:3], off
	v_add_co_u32_e32 v2, vcc, s35, v0
	s_mov_b32 s35, 0x42000
	s_nop 0
	v_addc_co_u32_e32 v3, vcc, 0, v1, vcc
	global_load_dword v17, v[2:3], off
	v_add_co_u32_e32 v2, vcc, s35, v0
	s_mov_b32 s35, 0x4d000
	s_nop 0
	v_addc_co_u32_e32 v3, vcc, 0, v1, vcc
	global_load_dword v18, v[2:3], off
	v_add_co_u32_e32 v2, vcc, s35, v0
	s_mov_b32 s35, 0x58000
	s_nop 0
	v_addc_co_u32_e32 v3, vcc, 0, v1, vcc
	global_load_dword v19, v[2:3], off
	v_add_co_u32_e32 v2, vcc, s35, v0
	s_mov_b32 s35, 0x63000
	s_nop 0
	v_addc_co_u32_e32 v3, vcc, 0, v1, vcc
	global_load_dword v27, v[2:3], off
	v_add_co_u32_e32 v2, vcc, s35, v0
	s_mov_b32 s35, 0x6e000
	s_nop 0
	v_addc_co_u32_e32 v3, vcc, 0, v1, vcc
	global_load_dword v28, v[2:3], off
	v_add_co_u32_e32 v2, vcc, s35, v0
	s_mov_b32 s35, 0x79000
	s_nop 0
	v_addc_co_u32_e32 v3, vcc, 0, v1, vcc
	global_load_dword v29, v[2:3], off
	v_add_co_u32_e32 v2, vcc, s35, v0
	s_mov_b32 s35, 0x84000
	s_nop 0
	v_addc_co_u32_e32 v3, vcc, 0, v1, vcc
	global_load_dword v30, v[2:3], off
	v_add_co_u32_e32 v2, vcc, s35, v0
	s_mov_b32 s35, 0x8f000
	s_nop 0
	v_addc_co_u32_e32 v3, vcc, 0, v1, vcc
	global_load_dword v31, v[2:3], off
	v_add_co_u32_e32 v2, vcc, s35, v0
	s_mov_b32 s35, 0x9a000
	s_nop 0
	v_addc_co_u32_e32 v3, vcc, 0, v1, vcc
	global_load_dword v32, v[2:3], off
	v_add_co_u32_e32 v2, vcc, s35, v0
	s_mov_b32 s35, 0xa5000
	s_nop 0
	v_addc_co_u32_e32 v3, vcc, 0, v1, vcc
	global_load_dword v33, v[2:3], off
	v_add_co_u32_e32 v2, vcc, s35, v0
	s_mov_b32 s35, 0xb0000
	s_nop 0
	v_addc_co_u32_e32 v3, vcc, 0, v1, vcc
	global_load_dword v34, v[2:3], off
	v_add_co_u32_e32 v2, vcc, s35, v0
	s_mov_b32 s35, 0xbb000
	s_nop 0
	v_addc_co_u32_e32 v3, vcc, 0, v1, vcc
	global_load_dword v35, v[2:3], off
	v_add_co_u32_e32 v2, vcc, s35, v0
	s_mov_b32 s35, 0xc6000
	s_nop 0
	v_addc_co_u32_e32 v3, vcc, 0, v1, vcc
	global_load_dword v36, v[2:3], off
	v_add_co_u32_e32 v2, vcc, s35, v0
	s_mov_b32 s35, 0xd1000
	s_nop 0
	v_addc_co_u32_e32 v3, vcc, 0, v1, vcc
	global_load_dword v37, v[2:3], off
	v_add_co_u32_e32 v2, vcc, s35, v0
	s_mov_b32 s35, 0xdc000
	s_nop 0
	v_addc_co_u32_e32 v3, vcc, 0, v1, vcc
	global_load_dword v38, v[2:3], off
	v_add_co_u32_e32 v2, vcc, s35, v0
	s_mov_b32 s35, 0xe7000
	s_nop 0
	v_addc_co_u32_e32 v3, vcc, 0, v1, vcc
	global_load_dword v39, v[2:3], off
	v_add_co_u32_e32 v2, vcc, s35, v0
	s_mov_b32 s35, 0xf2000
	s_nop 0
	v_addc_co_u32_e32 v3, vcc, 0, v1, vcc
	global_load_dword v40, v[2:3], off
	v_add_co_u32_e32 v2, vcc, s35, v0
	s_mov_b32 s35, 0xfd000
	s_nop 0
	v_addc_co_u32_e32 v3, vcc, 0, v1, vcc
	global_load_dword v41, v[2:3], off
	v_add_co_u32_e32 v2, vcc, s35, v0
	s_mov_b32 s35, 0x108000
	s_nop 0
	v_addc_co_u32_e32 v3, vcc, 0, v1, vcc
	global_load_dword v42, v[2:3], off
	v_add_co_u32_e32 v2, vcc, s35, v0
	s_mov_b32 s35, 0x113000
	s_nop 0
	v_addc_co_u32_e32 v3, vcc, 0, v1, vcc
	global_load_dword v43, v[2:3], off
	v_add_co_u32_e32 v2, vcc, s35, v0
	s_mov_b32 s35, 0x11e000
	s_nop 0
	v_addc_co_u32_e32 v3, vcc, 0, v1, vcc
	global_load_dword v44, v[2:3], off
	v_add_co_u32_e32 v2, vcc, s35, v0
	s_mov_b32 s35, 0x129000
	s_nop 0
	v_addc_co_u32_e32 v3, vcc, 0, v1, vcc
	global_load_dword v45, v[2:3], off
	v_add_co_u32_e32 v2, vcc, s35, v0
	s_mov_b32 s35, 0x134000
	s_nop 0
	v_addc_co_u32_e32 v3, vcc, 0, v1, vcc
	global_load_dword v46, v[2:3], off
	v_add_co_u32_e32 v2, vcc, s35, v0
	s_mov_b32 s35, 0x13f000
	s_nop 0
	v_addc_co_u32_e32 v3, vcc, 0, v1, vcc
	global_load_dword v47, v[2:3], off
	v_add_co_u32_e32 v2, vcc, s35, v0
	s_mov_b32 s35, 0x14a000
	s_nop 0
	v_addc_co_u32_e32 v3, vcc, 0, v1, vcc
	global_load_dword v48, v[2:3], off
	v_add_co_u32_e32 v2, vcc, s35, v0
	s_mov_b32 s35, 0x155000
	s_nop 0
	v_addc_co_u32_e32 v3, vcc, 0, v1, vcc
	v_add_co_u32_e32 v0, vcc, s35, v0
	global_load_dword v2, v[2:3], off
	s_nop 0
	v_addc_co_u32_e32 v1, vcc, 0, v1, vcc
	global_load_dword v0, v[0:1], off
	v_or_b32_e32 v1, s34, v20
	v_lshlrev_b32_e32 v49, 2, v1
	v_add_u32_e32 v1, 0x400, v21
	s_waitcnt vmcnt(0)
	ds_write2_b32 v21, v4, v5 offset1:66
	s_waitcnt vmcnt(28)
	ds_write2_b32 v21, v6, v7 offset0:132 offset1:198
	s_waitcnt vmcnt(26)
	ds_write2_b32 v1, v16, v17 offset0:8 offset1:74
	s_waitcnt vmcnt(24)
	ds_write2_b32 v1, v18, v19 offset0:140 offset1:206
	v_add_u32_e32 v1, 0x800, v21
	s_waitcnt vmcnt(22)
	ds_write2_b32 v1, v27, v28 offset0:16 offset1:82
	s_waitcnt vmcnt(20)
	ds_write2_b32 v1, v29, v30 offset0:148 offset1:214
	v_add_u32_e32 v1, 0xc00, v21
	s_waitcnt vmcnt(18)
	ds_write2_b32 v1, v31, v32 offset0:24 offset1:90
	s_waitcnt vmcnt(16)
	ds_write2_b32 v1, v33, v34 offset0:156 offset1:222
	v_add_u32_e32 v1, 0x1000, v21
	s_waitcnt vmcnt(14)
	ds_write2_b32 v1, v35, v36 offset0:32 offset1:98
	s_waitcnt vmcnt(12)
	ds_write2_b32 v1, v37, v38 offset0:164 offset1:230
	v_add_u32_e32 v1, 0x1400, v21
	s_waitcnt vmcnt(10)
	ds_write2_b32 v1, v39, v40 offset0:40 offset1:106
	s_waitcnt vmcnt(8)
	ds_write2_b32 v1, v41, v42 offset0:172 offset1:238
	v_add_u32_e32 v1, 0x1800, v21
	s_waitcnt vmcnt(6)
	ds_write2_b32 v1, v43, v44 offset0:48 offset1:114
	s_waitcnt vmcnt(4)
	ds_write2_b32 v1, v45, v46 offset0:180 offset1:246
	v_add_u32_e32 v1, 0x1c00, v21
	v_readlane_b32 s34, v235, 18
	s_waitcnt vmcnt(2)
	ds_write2_b32 v1, v47, v48 offset0:56 offset1:122
	s_waitcnt vmcnt(0)
	ds_write2_b32 v1, v2, v0 offset0:188 offset1:254
	v_readlane_b32 s35, v235, 19
	s_nop 4
	global_load_dwordx4 v[0:3], v49, s[34:35] offset:16
	global_load_dwordx4 v[4:7], v49, s[34:35]
	s_waitcnt lgkmcnt(0)
	s_lshl_b32 s46, s1, 7
	v_lshl_add_u64 v[16:17], v[12:13], 0, s[46:47]
	s_waitcnt vmcnt(1)
	v_mov_b32_e32 v44, v0
	s_waitcnt vmcnt(0)
	v_mov_b32_e32 v18, v4
	v_mov_b32_e32 v19, v6
	v_mov_b32_e32 v6, v5
	ds_read2_b32 v[4:5], v23 offset0:33 offset1:41
	ds_read2_b32 v[32:33], v23 offset0:66 offset1:74
	ds_read2_b32 v[34:35], v23 offset1:8
	ds_read2_b32 v[36:37], v23 offset0:99 offset1:107
	ds_read2_b32 v[38:39], v23 offset0:132 offset1:140
	ds_read2_b32 v[40:41], v23 offset0:165 offset1:173
	ds_read2_b32 v[42:43], v23 offset0:198 offset1:206
	ds_read2_b32 v[48:49], v23 offset0:231 offset1:239
	s_waitcnt lgkmcnt(7)
	v_mov_b32_e32 v30, v4
	v_mov_b32_e32 v45, v2
	s_waitcnt lgkmcnt(4)
	v_mov_b32_e32 v31, v36
	v_pk_mul_f32 v[30:31], v[6:7], v[30:31]
	s_waitcnt lgkmcnt(3)
	v_mov_b32_e32 v46, v38
	s_waitcnt lgkmcnt(1)
	v_mov_b32_e32 v47, v42
	v_mov_b32_e32 v2, v1
	v_mov_b32_e32 v0, v40
	s_waitcnt lgkmcnt(0)
	v_mov_b32_e32 v1, v48
	v_mov_b32_e32 v28, v34
	v_mov_b32_e32 v29, v32
	v_pk_mul_f32 v[46:47], v[44:45], v[46:47]
	v_pk_mul_f32 v[0:1], v[2:3], v[0:1]
	v_bfe_u32 v34, v30, 16, 1
	v_pk_mul_f32 v[28:29], v[18:19], v[28:29]
	v_bfe_u32 v4, v1, 16, 1
	v_add3_u32 v34, v30, v34, s81
	v_bfe_u32 v30, v46, 16, 1
	v_bfe_u32 v27, v0, 16, 1
	v_bfe_u32 v32, v31, 16, 1
	v_add3_u32 v1, v1, v4, s81
	v_bfe_u32 v4, v28, 16, 1
	v_add3_u32 v30, v46, v30, s81
	v_add3_u32 v32, v31, v32, s81
	v_add3_u32 v0, v0, v27, s81
	v_bfe_u32 v27, v29, 16, 1
	v_bfe_u32 v31, v47, 16, 1
	v_add3_u32 v4, v28, v4, s81
	v_lshrrev_b32_e32 v28, 16, v30
	v_add3_u32 v31, v47, v31, s81
	v_add3_u32 v27, v29, v27, s81
	v_and_or_b32 v30, v0, s71, v28
	v_or_b32_e32 v0, s0, v22
	v_lshrrev_b32_e32 v4, 16, v4
	v_lshrrev_b32_e32 v27, 16, v27
	v_lshrrev_b32_e32 v29, 16, v31
	v_lshlrev_b32_e32 v96, 11, v0
	v_and_or_b32 v31, v1, s71, v29
	v_and_or_b32 v29, v32, s71, v27
	v_and_or_b32 v28, v34, s71, v4
	v_lshl_add_u64 v[0:1], v[16:17], 0, v[96:97]
	v_mov_b32_e32 v36, v5
	v_mov_b32_e32 v48, v41
	global_store_dwordx4 v[0:1], v[28:31], off sc0 sc1
	v_mov_b32_e32 v32, v35
	v_pk_mul_f32 v[4:5], v[6:7], v[36:37]
	v_mov_b32_e32 v42, v39
	v_pk_mul_f32 v[30:31], v[2:3], v[48:49]
	v_pk_mul_f32 v[0:1], v[18:19], v[32:33]
	v_pk_mul_f32 v[28:29], v[44:45], v[42:43]
	v_bfe_u32 v27, v31, 16, 1
	v_bfe_u32 v33, v5, 16, 1
	v_add3_u32 v5, v5, v33, s81
	v_add3_u32 v27, v31, v27, s81
	v_bfe_u32 v31, v0, 16, 1
	v_bfe_u32 v33, v28, 16, 1
	v_bfe_u32 v32, v30, 16, 1
	v_bfe_u32 v34, v4, 16, 1
	v_add3_u32 v28, v28, v33, s81
	v_add3_u32 v0, v0, v31, s81
	v_add3_u32 v4, v4, v34, s81
	v_add3_u32 v30, v30, v32, s81
	v_bfe_u32 v32, v1, 16, 1
	v_bfe_u32 v34, v29, 16, 1
	v_lshrrev_b32_e32 v0, 16, v0
	v_lshrrev_b32_e32 v28, 16, v28
	v_add3_u32 v29, v29, v34, s81
	v_add3_u32 v1, v1, v32, s81
	v_and_or_b32 v30, v30, s71, v28
	v_and_or_b32 v28, v4, s71, v0
	v_or_b32_e32 v0, s0, v24
	v_lshrrev_b32_e32 v1, 16, v1
	v_lshrrev_b32_e32 v29, 16, v29
	v_lshlrev_b32_e32 v96, 11, v0
	v_and_or_b32 v31, v27, s71, v29
	v_and_or_b32 v29, v5, s71, v1
	v_lshl_add_u64 v[0:1], v[16:17], 0, v[96:97]
	global_store_dwordx4 v[0:1], v[28:31], off sc0 sc1
	ds_read2_b32 v[0:1], v23 offset0:49 offset1:57
	ds_read2_b32 v[4:5], v23 offset0:82 offset1:90
	ds_read2_b32 v[32:33], v23 offset0:115 offset1:123
	ds_read2_b32 v[34:35], v23 offset0:16 offset1:24
	ds_read2_b32 v[36:37], v23 offset0:148 offset1:156
	ds_read2_b32 v[38:39], v23 offset0:181 offset1:189
	ds_read2_b32 v[40:41], v23 offset0:214 offset1:222
	ds_read2_b32 v[42:43], v23 offset0:247 offset1:255
	s_waitcnt lgkmcnt(7)
	v_mov_b32_e32 v30, v0
	s_waitcnt lgkmcnt(3)
	v_mov_b32_e32 v46, v36
	v_mov_b32_e32 v31, v32
	s_waitcnt lgkmcnt(1)
	v_mov_b32_e32 v47, v40
	v_mov_b32_e32 v28, v34
	v_mov_b32_e32 v29, v4
	v_pk_mul_f32 v[30:31], v[6:7], v[30:31]
	v_pk_mul_f32 v[46:47], v[44:45], v[46:47]
	v_mov_b32_e32 v48, v38
	s_waitcnt lgkmcnt(0)
	v_mov_b32_e32 v49, v42
	v_pk_mul_f32 v[28:29], v[18:19], v[28:29]
	v_pk_mul_f32 v[48:49], v[2:3], v[48:49]
	v_bfe_u32 v27, v31, 16, 1
	v_bfe_u32 v32, v30, 16, 1
	v_bfe_u32 v34, v46, 16, 1
	v_bfe_u32 v36, v47, 16, 1
	v_bfe_u32 v0, v49, 16, 1
	v_bfe_u32 v4, v48, 16, 1
	v_add3_u32 v32, v30, v32, s81
	v_add3_u32 v27, v31, v27, s81
	v_bfe_u32 v30, v28, 16, 1
	v_bfe_u32 v31, v29, 16, 1
	v_add3_u32 v36, v47, v36, s81
	v_add3_u32 v34, v46, v34, s81
	v_add3_u32 v4, v48, v4, s81
	v_add3_u32 v0, v49, v0, s81
	v_add3_u32 v29, v29, v31, s81
	v_add3_u32 v28, v28, v30, s81
	v_lshrrev_b32_e32 v30, 16, v34
	v_lshrrev_b32_e32 v31, 16, v36
	v_mov_b32_e32 v42, v39
	v_lshrrev_b32_e32 v28, 16, v28
	v_and_or_b32 v31, v0, s71, v31
	v_and_or_b32 v30, v4, s71, v30
	v_or_b32_e32 v0, s0, v25
	v_mov_b32_e32 v4, v35
	v_pk_mul_f32 v[2:3], v[2:3], v[42:43]
	v_lshrrev_b32_e32 v29, 16, v29
	v_and_or_b32 v28, v32, s71, v28
	v_lshlrev_b32_e32 v96, 11, v0
	v_pk_mul_f32 v[4:5], v[18:19], v[4:5]
	v_mov_b32_e32 v32, v1
	v_bfe_u32 v18, v3, 16, 1
	v_and_or_b32 v29, v27, s71, v29
	v_lshl_add_u64 v[46:47], v[16:17], 0, v[96:97]
	v_pk_mul_f32 v[0:1], v[6:7], v[32:33]
	v_mov_b32_e32 v40, v37
	v_add3_u32 v3, v3, v18, s81
	v_bfe_u32 v18, v4, 16, 1
	global_store_dwordx4 v[46:47], v[28:31], off sc0 sc1
	v_pk_mul_f32 v[6:7], v[44:45], v[40:41]
	v_bfe_u32 v19, v2, 16, 1
	v_bfe_u32 v27, v1, 16, 1
	v_bfe_u32 v28, v0, 16, 1
	v_add3_u32 v4, v4, v18, s81
	v_add3_u32 v0, v0, v28, s81
	v_add3_u32 v1, v1, v27, s81
	v_add3_u32 v2, v2, v19, s81
	v_bfe_u32 v19, v5, 16, 1
	v_bfe_u32 v27, v6, 16, 1
	v_bfe_u32 v28, v7, 16, 1
	v_lshrrev_b32_e32 v4, 16, v4
	v_add3_u32 v7, v7, v28, s81
	v_add3_u32 v6, v6, v27, s81
	v_add3_u32 v5, v5, v19, s81
	v_and_or_b32 v0, v0, s71, v4
	v_or_b32_e32 v4, s0, v26
	v_lshrrev_b32_e32 v5, 16, v5
	v_lshrrev_b32_e32 v6, 16, v6
	v_lshrrev_b32_e32 v7, 16, v7
	v_lshlrev_b32_e32 v96, 11, v4
	v_and_or_b32 v3, v3, s71, v7
	v_and_or_b32 v2, v2, s71, v6
	v_and_or_b32 v1, v1, s71, v5
	v_lshl_add_u64 v[4:5], v[16:17], 0, v[96:97]
	global_store_dwordx4 v[4:5], v[0:3], off sc0 sc1
	s_waitcnt lgkmcnt(0)

.LBB0_403:
	s_mov_b64 s[0:1], -1
	s_and_b64 vcc, exec, s[8:9]
	s_cbranch_vccz .LBB0_480
	s_cmpk_gt_i32 s42, 0x1ff
	s_cselect_b64 s[34:35], -1, 0
	s_and_b64 vcc, exec, s[38:39]
	s_cbranch_vccz .LBB0_430
	s_and_b64 vcc, exec, s[34:35]
	s_cbranch_vccz .LBB0_411
	s_cmpk_gt_u32 s42, 0xcff
	s_cbranch_scc0 .LBB0_408
	s_and_b32 s0, s74, 0x7fffffc0
	s_addk_i32 s0, 0xe600
	v_or_b32_e32 v96, s0, v9
	v_readlane_b32 s48, v235, 14
	s_and_b32 s40, s72, 0x3e0
	v_lshlrev_b64 v[0:1], 12, v[96:97]
	v_readlane_b32 s49, v235, 15
	s_lshl_b32 s46, s40, 2
	v_lshlrev_b32_e32 v96, 2, v8
	v_lshl_add_u64 v[0:1], s[48:49], 0, v[0:1]
	v_lshl_add_u64 v[0:1], v[0:1], 0, s[46:47]
	v_lshl_add_u64 v[0:1], v[0:1], 0, v[96:97]
	v_add_co_u32_e32 v2, vcc, 0x2000, v0
	s_movk_i32 s1, 0x4000
	s_waitcnt lgkmcnt(0)
	v_addc_co_u32_e32 v3, vcc, 0, v1, vcc
	global_load_dword v4, v[0:1], off
	global_load_dword v5, v[2:3], off
	v_add_co_u32_e32 v2, vcc, s1, v0
	s_mov_b32 s1, s47
	s_nop 0
	v_addc_co_u32_e32 v3, vcc, 0, v1, vcc
	global_load_dword v6, v[2:3], off
	v_add_co_u32_e32 v2, vcc, 0x6000, v0
	s_nop 1
	v_addc_co_u32_e32 v3, vcc, 0, v1, vcc
	global_load_dword v7, v[2:3], off
	v_add_co_u32_e32 v2, vcc, 0x8000, v0
	s_nop 1
	v_addc_co_u32_e32 v3, vcc, 0, v1, vcc
	global_load_dword v30, v[2:3], off
	v_add_co_u32_e32 v2, vcc, 0xa000, v0
	s_nop 1
	v_addc_co_u32_e32 v3, vcc, 0, v1, vcc
	global_load_dword v31, v[2:3], off
	v_add_co_u32_e32 v2, vcc, 0xc000, v0
	s_nop 1
	v_addc_co_u32_e32 v3, vcc, 0, v1, vcc
	global_load_dword v32, v[2:3], off
	v_add_co_u32_e32 v2, vcc, 0xe000, v0
	s_nop 1
	v_addc_co_u32_e32 v3, vcc, 0, v1, vcc
	global_load_dword v33, v[2:3], off
	v_add_co_u32_e32 v2, vcc, 0x10000, v0
	s_nop 1
	v_addc_co_u32_e32 v3, vcc, 0, v1, vcc
	global_load_dword v41, v[2:3], off
	v_add_co_u32_e32 v2, vcc, 0x12000, v0
	s_nop 1
	v_addc_co_u32_e32 v3, vcc, 0, v1, vcc
	global_load_dword v42, v[2:3], off
	v_add_co_u32_e32 v2, vcc, 0x14000, v0
	s_nop 1
	v_addc_co_u32_e32 v3, vcc, 0, v1, vcc
	global_load_dword v43, v[2:3], off
	v_add_co_u32_e32 v2, vcc, 0x16000, v0
	s_nop 1
	v_addc_co_u32_e32 v3, vcc, 0, v1, vcc
	global_load_dword v44, v[2:3], off
	v_add_co_u32_e32 v2, vcc, 0x18000, v0
	s_nop 1
	v_addc_co_u32_e32 v3, vcc, 0, v1, vcc
	global_load_dword v45, v[2:3], off
	v_add_co_u32_e32 v2, vcc, 0x1a000, v0
	s_nop 1
	v_addc_co_u32_e32 v3, vcc, 0, v1, vcc
	global_load_dword v46, v[2:3], off
	v_add_co_u32_e32 v2, vcc, 0x1c000, v0
	s_nop 1
	v_addc_co_u32_e32 v3, vcc, 0, v1, vcc
	global_load_dword v47, v[2:3], off
	v_add_co_u32_e32 v2, vcc, 0x1e000, v0
	s_nop 1
	v_addc_co_u32_e32 v3, vcc, 0, v1, vcc
	global_load_dword v48, v[2:3], off
	v_add_co_u32_e32 v2, vcc, 0x20000, v0
	s_nop 1
	v_addc_co_u32_e32 v3, vcc, 0, v1, vcc
	global_load_dword v49, v[2:3], off
	v_add_co_u32_e32 v2, vcc, 0x22000, v0
	s_nop 1
	v_addc_co_u32_e32 v3, vcc, 0, v1, vcc
	global_load_dword v50, v[2:3], off
	v_add_co_u32_e32 v2, vcc, 0x24000, v0
	s_nop 1
	v_addc_co_u32_e32 v3, vcc, 0, v1, vcc
	global_load_dword v51, v[2:3], off
	v_add_co_u32_e32 v2, vcc, 0x26000, v0
	s_nop 1
	v_addc_co_u32_e32 v3, vcc, 0, v1, vcc
	global_load_dword v52, v[2:3], off
	v_add_co_u32_e32 v2, vcc, 0x28000, v0
	s_nop 1
	v_addc_co_u32_e32 v3, vcc, 0, v1, vcc
	global_load_dword v53, v[2:3], off
	v_add_co_u32_e32 v2, vcc, 0x2a000, v0
	s_nop 1
	v_addc_co_u32_e32 v3, vcc, 0, v1, vcc
	global_load_dword v54, v[2:3], off
	v_add_co_u32_e32 v2, vcc, 0x2c000, v0
	s_nop 1
	v_addc_co_u32_e32 v3, vcc, 0, v1, vcc
	global_load_dword v55, v[2:3], off
	v_add_co_u32_e32 v2, vcc, 0x2e000, v0
	s_nop 1
	v_addc_co_u32_e32 v3, vcc, 0, v1, vcc
	global_load_dword v56, v[2:3], off
	v_add_co_u32_e32 v2, vcc, 0x30000, v0
	s_nop 1
	v_addc_co_u32_e32 v3, vcc, 0, v1, vcc
	global_load_dword v57, v[2:3], off
	v_add_co_u32_e32 v2, vcc, 0x32000, v0
	s_nop 1
	v_addc_co_u32_e32 v3, vcc, 0, v1, vcc
	global_load_dword v58, v[2:3], off
	v_add_co_u32_e32 v2, vcc, 0x34000, v0
	s_nop 1
	v_addc_co_u32_e32 v3, vcc, 0, v1, vcc
	global_load_dword v59, v[2:3], off
	v_add_co_u32_e32 v2, vcc, 0x36000, v0
	s_nop 1
	v_addc_co_u32_e32 v3, vcc, 0, v1, vcc
	global_load_dword v60, v[2:3], off
	v_add_co_u32_e32 v2, vcc, 0x38000, v0
	s_nop 1
	v_addc_co_u32_e32 v3, vcc, 0, v1, vcc
	global_load_dword v61, v[2:3], off
	v_add_co_u32_e32 v2, vcc, 0x3a000, v0
	s_nop 1
	v_addc_co_u32_e32 v3, vcc, 0, v1, vcc
	global_load_dword v62, v[2:3], off
	v_add_co_u32_e32 v2, vcc, 0x3c000, v0
	s_nop 1
	v_addc_co_u32_e32 v3, vcc, 0, v1, vcc
	v_add_co_u32_e32 v0, vcc, 0x3e000, v0
	global_load_dword v2, v[2:3], off
	s_nop 0
	v_addc_co_u32_e32 v1, vcc, 0, v1, vcc
	global_load_dword v0, v[0:1], off
	v_add_u32_e32 v1, 0x400, v35
	s_waitcnt vmcnt(0)
	ds_write2_b32 v35, v4, v5 offset1:66
	ds_write2_b32 v35, v6, v7 offset0:132 offset1:198
	ds_write2_b32 v1, v30, v31 offset0:8 offset1:74
	ds_write2_b32 v1, v32, v33 offset0:140 offset1:206
	v_add_u32_e32 v1, 0x800, v35
	ds_write2_b32 v1, v41, v42 offset0:16 offset1:82
	ds_write2_b32 v1, v43, v44 offset0:148 offset1:214
	v_add_u32_e32 v1, 0xc00, v35
	ds_write2_b32 v1, v45, v46 offset0:24 offset1:90
	ds_write2_b32 v1, v47, v48 offset0:156 offset1:222
	v_add_u32_e32 v1, 0x1000, v35
	ds_write2_b32 v1, v49, v50 offset0:32 offset1:98
	ds_write2_b32 v1, v51, v52 offset0:164 offset1:230
	v_add_u32_e32 v1, 0x1400, v35
	ds_write2_b32 v1, v53, v54 offset0:40 offset1:106
	ds_write2_b32 v1, v55, v56 offset0:172 offset1:238
	v_add_u32_e32 v1, 0x1800, v35
	ds_write2_b32 v1, v57, v58 offset0:48 offset1:114
	ds_write2_b32 v1, v59, v60 offset0:180 offset1:246
	v_add_u32_e32 v1, 0x1c00, v35
	ds_write2_b32 v1, v61, v62 offset0:56 offset1:122
	ds_write2_b32 v1, v2, v0 offset0:188 offset1:254
	s_waitcnt lgkmcnt(0)
	ds_read2_b32 v[6:7], v37 offset0:33 offset1:41
	ds_read2_b32 v[30:31], v37 offset1:8
	ds_read2_b32 v[32:33], v37 offset0:66 offset1:74
	ds_read2_b32 v[42:43], v37 offset0:99 offset1:107
	ds_read2_b32 v[44:45], v37 offset0:132 offset1:140
	ds_read2_b32 v[46:47], v37 offset0:165 offset1:173
	ds_read2_b32 v[48:49], v37 offset0:198 offset1:206
	ds_read2_b32 v[50:51], v37 offset0:231 offset1:239
	s_waitcnt lgkmcnt(7)
	v_bfe_u32 v3, v6, 16, 1
	s_waitcnt lgkmcnt(6)
	v_bfe_u32 v2, v30, 16, 1
	v_add3_u32 v2, v30, v2, s81
	v_lshrrev_b32_e32 v2, 16, v2
	v_add3_u32 v3, v6, v3, s81
	v_and_or_b32 v2, v3, s71, v2
	s_waitcnt lgkmcnt(5)
	v_bfe_u32 v3, v32, 16, 1
	v_add3_u32 v3, v32, v3, s81
	s_waitcnt lgkmcnt(4)
	v_bfe_u32 v4, v42, 16, 1
	v_lshrrev_b32_e32 v3, 16, v3
	v_add3_u32 v4, v42, v4, s81
	v_and_or_b32 v3, v4, s71, v3
	s_waitcnt lgkmcnt(3)
	v_bfe_u32 v4, v44, 16, 1
	v_add3_u32 v4, v44, v4, s81
	s_waitcnt lgkmcnt(2)
	v_bfe_u32 v5, v46, 16, 1
	v_lshrrev_b32_e32 v4, 16, v4
	v_add3_u32 v5, v46, v5, s81
	v_and_or_b32 v4, v5, s71, v4
	s_waitcnt lgkmcnt(1)
	v_bfe_u32 v5, v48, 16, 1
	v_add3_u32 v5, v48, v5, s81
	s_waitcnt lgkmcnt(0)
	v_bfe_u32 v6, v50, 16, 1
	v_lshrrev_b32_e32 v5, 16, v5
	v_add3_u32 v6, v50, v6, s81
	v_and_or_b32 v5, v6, s71, v5
	v_or_b32_e32 v6, s40, v36
	v_mul_u32_u24_e32 v6, 0xb00, v6
	v_lshl_add_u64 v[0:1], s[0:1], 1, v[10:11]
	v_lshlrev_b32_e32 v96, 1, v6
	v_lshl_add_u64 v[52:53], v[0:1], 0, v[96:97]
	global_store_dwordx4 v[52:53], v[2:5], off sc0 sc1
	v_bfe_u32 v6, v51, 16, 1
	v_add3_u32 v6, v51, v6, s81
	v_bfe_u32 v2, v31, 16, 1
	v_add3_u32 v2, v31, v2, s81
	v_bfe_u32 v3, v7, 16, 1
	v_lshrrev_b32_e32 v2, 16, v2
	v_add3_u32 v3, v7, v3, s81
	v_and_or_b32 v2, v3, s71, v2
	v_bfe_u32 v3, v33, 16, 1
	v_add3_u32 v3, v33, v3, s81
	v_bfe_u32 v4, v43, 16, 1
	v_lshrrev_b32_e32 v3, 16, v3
	v_add3_u32 v4, v43, v4, s81
	v_and_or_b32 v3, v4, s71, v3
	v_bfe_u32 v4, v45, 16, 1
	v_add3_u32 v4, v45, v4, s81
	v_bfe_u32 v5, v47, 16, 1
	v_lshrrev_b32_e32 v4, 16, v4
	v_add3_u32 v5, v47, v5, s81
	v_and_or_b32 v4, v5, s71, v4
	v_bfe_u32 v5, v49, 16, 1
	v_add3_u32 v5, v49, v5, s81
	v_lshrrev_b32_e32 v5, 16, v5
	v_and_or_b32 v5, v6, s71, v5
	v_or_b32_e32 v6, s40, v38
	v_mul_u32_u24_e32 v6, 0xb00, v6
	v_lshlrev_b32_e32 v96, 1, v6
	v_lshl_add_u64 v[6:7], v[0:1], 0, v[96:97]
	global_store_dwordx4 v[6:7], v[2:5], off sc0 sc1
	ds_read2_b32 v[6:7], v37 offset0:16 offset1:24
	ds_read2_b32 v[30:31], v37 offset0:49 offset1:57
	ds_read2_b32 v[32:33], v37 offset0:82 offset1:90
	ds_read2_b32 v[42:43], v37 offset0:115 offset1:123
	ds_read2_b32 v[44:45], v37 offset0:148 offset1:156
	ds_read2_b32 v[46:47], v37 offset0:181 offset1:189
	ds_read2_b32 v[48:49], v37 offset0:214 offset1:222
	ds_read2_b32 v[50:51], v37 offset0:247 offset1:255
	s_waitcnt lgkmcnt(7)
	v_bfe_u32 v2, v6, 16, 1
	v_add3_u32 v2, v6, v2, s81
	s_waitcnt lgkmcnt(6)
	v_bfe_u32 v3, v30, 16, 1
	v_lshrrev_b32_e32 v2, 16, v2
	v_add3_u32 v3, v30, v3, s81
	v_and_or_b32 v2, v3, s71, v2
	s_waitcnt lgkmcnt(5)
	v_bfe_u32 v3, v32, 16, 1
	v_add3_u32 v3, v32, v3, s81
	s_waitcnt lgkmcnt(4)
	v_bfe_u32 v4, v42, 16, 1
	v_lshrrev_b32_e32 v3, 16, v3
	v_add3_u32 v4, v42, v4, s81
	v_and_or_b32 v3, v4, s71, v3
	s_waitcnt lgkmcnt(3)
	v_bfe_u32 v4, v44, 16, 1
	v_add3_u32 v4, v44, v4, s81
	s_waitcnt lgkmcnt(2)
	v_bfe_u32 v5, v46, 16, 1
	v_lshrrev_b32_e32 v4, 16, v4
	v_add3_u32 v5, v46, v5, s81
	v_and_or_b32 v4, v5, s71, v4
	s_waitcnt lgkmcnt(1)
	v_bfe_u32 v5, v48, 16, 1
	v_add3_u32 v5, v48, v5, s81
	s_waitcnt lgkmcnt(0)
	v_bfe_u32 v6, v50, 16, 1
	v_lshrrev_b32_e32 v5, 16, v5
	v_add3_u32 v6, v50, v6, s81
	v_and_or_b32 v5, v6, s71, v5
	v_or_b32_e32 v6, s40, v39
	v_mul_u32_u24_e32 v6, 0xb00, v6
	v_lshlrev_b32_e32 v96, 1, v6
	v_lshl_add_u64 v[52:53], v[0:1], 0, v[96:97]
	global_store_dwordx4 v[52:53], v[2:5], off sc0 sc1
	v_bfe_u32 v6, v51, 16, 1
	v_add3_u32 v6, v51, v6, s81
	v_bfe_u32 v2, v7, 16, 1
	v_add3_u32 v2, v7, v2, s81
	v_bfe_u32 v3, v31, 16, 1
	v_lshrrev_b32_e32 v2, 16, v2
	v_add3_u32 v3, v31, v3, s81
	v_and_or_b32 v2, v3, s71, v2
	v_bfe_u32 v3, v33, 16, 1
	v_add3_u32 v3, v33, v3, s81
	v_bfe_u32 v4, v43, 16, 1
	v_lshrrev_b32_e32 v3, 16, v3
	v_add3_u32 v4, v43, v4, s81
	v_and_or_b32 v3, v4, s71, v3
	v_bfe_u32 v4, v45, 16, 1
	v_add3_u32 v4, v45, v4, s81
	v_bfe_u32 v5, v47, 16, 1
	v_lshrrev_b32_e32 v4, 16, v4
	v_add3_u32 v5, v47, v5, s81
	v_and_or_b32 v4, v5, s71, v4
	v_bfe_u32 v5, v49, 16, 1
	v_add3_u32 v5, v49, v5, s81
	v_lshrrev_b32_e32 v5, 16, v5
	v_and_or_b32 v5, v6, s71, v5
	v_or_b32_e32 v6, s40, v40
	v_mul_u32_u24_e32 v6, 0xb00, v6
	v_lshlrev_b32_e32 v96, 1, v6
	v_lshl_add_u64 v[0:1], v[0:1], 0, v[96:97]
	global_store_dwordx4 v[0:1], v[2:5], off sc0 sc1
	s_waitcnt lgkmcnt(0)
	s_mov_b64 s[0:1], 0
.LBB0_408:
	s_andn2_b64 vcc, exec, s[0:1]
	s_cbranch_vccnz .LBB0_410
	s_add_i32 s0, s42, 0xfe00
	s_and_b32 s1, s0, 0xffff
	s_mul_i32 s1, s1, 0xba2f
	s_lshr_b32 s1, s1, 23
	s_mul_i32 s40, s1, 0xb0
	s_sub_i32 s41, s0, s40
	s_and_b32 s0, s41, 0xffff
	s_lshl_b32 s40, s1, 6
	s_bfe_i32 s46, s41, 0x10002
	s_lshl_b32 s41, s41, 4
	s_lshl_b32 s0, s0, 5
	s_and_b32 s46, s46, 0xb00
	s_and_b32 s41, s41, 0xf80
	v_or_b32_e32 v0, s40, v9
	s_add_i32 s46, s46, s41
	s_and_b32 s41, s0, 0x60
	v_mul_u32_u24_e32 v0, 0x1600, v0
	v_readlane_b32 s48, v235, 16
	s_or_b32 s41, s46, s41
	v_lshlrev_b32_e32 v96, 2, v0
	v_readlane_b32 s49, v235, 17
	s_lshl_b32 s46, s41, 2
	s_mov_b32 s41, 0xb000
	v_lshl_add_u64 v[0:1], s[48:49], 0, v[96:97]
	v_lshl_add_u64 v[0:1], v[0:1], 0, s[46:47]
	v_lshlrev_b32_e32 v96, 2, v8
	v_lshl_add_u64 v[0:1], v[0:1], 0, v[96:97]
	v_add_co_u32_e32 v2, vcc, s41, v0
	s_mov_b32 s41, 0x16000
	s_waitcnt lgkmcnt(0)
	v_addc_co_u32_e32 v3, vcc, 0, v1, vcc
	global_load_dword v4, v[0:1], off
	global_load_dword v5, v[2:3], off
	v_add_co_u32_e32 v2, vcc, s41, v0
	s_mov_b32 s41, 0x21000
	s_nop 0
	v_addc_co_u32_e32 v3, vcc, 0, v1, vcc
	global_load_dword v6, v[2:3], off
	v_add_co_u32_e32 v2, vcc, s41, v0
	s_mov_b32 s41, 0x2c000
	s_nop 0
	v_addc_co_u32_e32 v3, vcc, 0, v1, vcc
	global_load_dword v7, v[2:3], off
	v_add_co_u32_e32 v2, vcc, s41, v0
	s_mov_b32 s41, 0x37000
	s_nop 0
	v_addc_co_u32_e32 v3, vcc, 0, v1, vcc
	global_load_dword v30, v[2:3], off
	v_add_co_u32_e32 v2, vcc, s41, v0
	s_mov_b32 s41, 0x42000
	s_nop 0
	v_addc_co_u32_e32 v3, vcc, 0, v1, vcc
	global_load_dword v31, v[2:3], off
	v_add_co_u32_e32 v2, vcc, s41, v0
	s_mov_b32 s41, 0x4d000
	s_nop 0
	v_addc_co_u32_e32 v3, vcc, 0, v1, vcc
	global_load_dword v32, v[2:3], off
	v_add_co_u32_e32 v2, vcc, s41, v0
	s_mov_b32 s41, 0x58000
	s_nop 0
	v_addc_co_u32_e32 v3, vcc, 0, v1, vcc
	global_load_dword v33, v[2:3], off
	v_add_co_u32_e32 v2, vcc, s41, v0
	s_mov_b32 s41, 0x63000
	s_nop 0
	v_addc_co_u32_e32 v3, vcc, 0, v1, vcc
	global_load_dword v41, v[2:3], off
	v_add_co_u32_e32 v2, vcc, s41, v0
	s_mov_b32 s41, 0x6e000
	s_nop 0
	v_addc_co_u32_e32 v3, vcc, 0, v1, vcc
	global_load_dword v42, v[2:3], off
	v_add_co_u32_e32 v2, vcc, s41, v0
	s_mov_b32 s41, 0x79000
	s_nop 0
	v_addc_co_u32_e32 v3, vcc, 0, v1, vcc
	global_load_dword v43, v[2:3], off
	v_add_co_u32_e32 v2, vcc, s41, v0
	s_mov_b32 s41, 0x84000
	s_nop 0
	v_addc_co_u32_e32 v3, vcc, 0, v1, vcc
	global_load_dword v44, v[2:3], off
	v_add_co_u32_e32 v2, vcc, s41, v0
	s_mov_b32 s41, 0x8f000
	s_nop 0
	v_addc_co_u32_e32 v3, vcc, 0, v1, vcc
	global_load_dword v45, v[2:3], off
	v_add_co_u32_e32 v2, vcc, s41, v0
	s_mov_b32 s41, 0x9a000
	s_nop 0
	v_addc_co_u32_e32 v3, vcc, 0, v1, vcc
	global_load_dword v46, v[2:3], off
	v_add_co_u32_e32 v2, vcc, s41, v0
	s_mov_b32 s41, 0xa5000
	s_nop 0
	v_addc_co_u32_e32 v3, vcc, 0, v1, vcc
	global_load_dword v47, v[2:3], off
	v_add_co_u32_e32 v2, vcc, s41, v0
	s_mov_b32 s41, 0xb0000
	s_nop 0
	v_addc_co_u32_e32 v3, vcc, 0, v1, vcc
	global_load_dword v48, v[2:3], off
	v_add_co_u32_e32 v2, vcc, s41, v0
	s_mov_b32 s41, 0xbb000
	s_nop 0
	v_addc_co_u32_e32 v3, vcc, 0, v1, vcc
	global_load_dword v49, v[2:3], off
	v_add_co_u32_e32 v2, vcc, s41, v0
	s_mov_b32 s41, 0xc6000
	s_nop 0
	v_addc_co_u32_e32 v3, vcc, 0, v1, vcc
	global_load_dword v50, v[2:3], off
	v_add_co_u32_e32 v2, vcc, s41, v0
	s_mov_b32 s41, 0xd1000
	s_nop 0
	v_addc_co_u32_e32 v3, vcc, 0, v1, vcc
	global_load_dword v51, v[2:3], off
	v_add_co_u32_e32 v2, vcc, s41, v0
	s_mov_b32 s41, 0xdc000
	s_nop 0
	v_addc_co_u32_e32 v3, vcc, 0, v1, vcc
	global_load_dword v52, v[2:3], off
	v_add_co_u32_e32 v2, vcc, s41, v0
	s_mov_b32 s41, 0xe7000
	s_nop 0
	v_addc_co_u32_e32 v3, vcc, 0, v1, vcc
	global_load_dword v53, v[2:3], off
	v_add_co_u32_e32 v2, vcc, s41, v0
	s_mov_b32 s41, 0xf2000
	s_nop 0
	v_addc_co_u32_e32 v3, vcc, 0, v1, vcc
	global_load_dword v54, v[2:3], off
	v_add_co_u32_e32 v2, vcc, s41, v0
	s_mov_b32 s41, 0xfd000
	s_nop 0
	v_addc_co_u32_e32 v3, vcc, 0, v1, vcc
	global_load_dword v55, v[2:3], off
	v_add_co_u32_e32 v2, vcc, s41, v0
	s_mov_b32 s41, 0x108000
	s_nop 0
	v_addc_co_u32_e32 v3, vcc, 0, v1, vcc
	global_load_dword v56, v[2:3], off
	v_add_co_u32_e32 v2, vcc, s41, v0
	s_mov_b32 s41, 0x113000
	s_nop 0
	v_addc_co_u32_e32 v3, vcc, 0, v1, vcc
	global_load_dword v57, v[2:3], off
	v_add_co_u32_e32 v2, vcc, s41, v0
	s_mov_b32 s41, 0x11e000
	s_nop 0
	v_addc_co_u32_e32 v3, vcc, 0, v1, vcc
	global_load_dword v58, v[2:3], off
	v_add_co_u32_e32 v2, vcc, s41, v0
	s_mov_b32 s41, 0x129000
	s_nop 0
	v_addc_co_u32_e32 v3, vcc, 0, v1, vcc
	global_load_dword v59, v[2:3], off
	v_add_co_u32_e32 v2, vcc, s41, v0
	s_mov_b32 s41, 0x134000
	s_nop 0
	v_addc_co_u32_e32 v3, vcc, 0, v1, vcc
	global_load_dword v60, v[2:3], off
	v_add_co_u32_e32 v2, vcc, s41, v0
	s_mov_b32 s41, 0x13f000
	s_nop 0
	v_addc_co_u32_e32 v3, vcc, 0, v1, vcc
	global_load_dword v61, v[2:3], off
	v_add_co_u32_e32 v2, vcc, s41, v0
	s_mov_b32 s41, 0x14a000
	s_nop 0
	v_addc_co_u32_e32 v3, vcc, 0, v1, vcc
	global_load_dword v62, v[2:3], off
	v_add_co_u32_e32 v2, vcc, s41, v0
	s_mov_b32 s41, 0x155000
	s_nop 0
	v_addc_co_u32_e32 v3, vcc, 0, v1, vcc
	v_add_co_u32_e32 v0, vcc, s41, v0
	global_load_dword v2, v[2:3], off
	s_nop 0
	v_addc_co_u32_e32 v1, vcc, 0, v1, vcc
	global_load_dword v0, v[0:1], off
	v_or_b32_e32 v1, s40, v34
	v_lshlrev_b32_e32 v63, 2, v1
	v_add_u32_e32 v1, 0x400, v35
	s_waitcnt vmcnt(0)
	ds_write2_b32 v35, v4, v5 offset1:66
	ds_write2_b32 v35, v6, v7 offset0:132 offset1:198
	ds_write2_b32 v1, v30, v31 offset0:8 offset1:74
	ds_write2_b32 v1, v32, v33 offset0:140 offset1:206
	v_add_u32_e32 v1, 0x800, v35
	ds_write2_b32 v1, v41, v42 offset0:16 offset1:82
	ds_write2_b32 v1, v43, v44 offset0:148 offset1:214
	v_add_u32_e32 v1, 0xc00, v35
	ds_write2_b32 v1, v45, v46 offset0:24 offset1:90
	ds_write2_b32 v1, v47, v48 offset0:156 offset1:222
	v_add_u32_e32 v1, 0x1000, v35
	ds_write2_b32 v1, v49, v50 offset0:32 offset1:98
	ds_write2_b32 v1, v51, v52 offset0:164 offset1:230
	v_add_u32_e32 v1, 0x1400, v35
	ds_write2_b32 v1, v53, v54 offset0:40 offset1:106
	ds_write2_b32 v1, v55, v56 offset0:172 offset1:238
	v_add_u32_e32 v1, 0x1800, v35
	ds_write2_b32 v1, v57, v58 offset0:48 offset1:114
	ds_write2_b32 v1, v59, v60 offset0:180 offset1:246
	v_add_u32_e32 v1, 0x1c00, v35
	v_readlane_b32 s40, v235, 18
	ds_write2_b32 v1, v61, v62 offset0:56 offset1:122
	ds_write2_b32 v1, v2, v0 offset0:188 offset1:254
	v_readlane_b32 s41, v235, 19
	s_nop 4
	global_load_dwordx4 v[0:3], v63, s[40:41] offset:16
	global_load_dwordx4 v[4:7], v63, s[40:41]
	s_waitcnt lgkmcnt(0)
	s_lshl_b32 s46, s1, 7
	v_lshl_add_u64 v[30:31], v[12:13], 0, s[46:47]
	s_waitcnt vmcnt(1)
	v_mov_b32_e32 v58, v0
	s_waitcnt vmcnt(0)
	v_mov_b32_e32 v32, v4
	v_mov_b32_e32 v33, v6
	v_mov_b32_e32 v6, v5
	ds_read2_b32 v[4:5], v37 offset0:33 offset1:41
	ds_read2_b32 v[46:47], v37 offset0:66 offset1:74
	ds_read2_b32 v[48:49], v37 offset1:8
	ds_read2_b32 v[50:51], v37 offset0:99 offset1:107
	ds_read2_b32 v[52:53], v37 offset0:132 offset1:140
	ds_read2_b32 v[54:55], v37 offset0:165 offset1:173
	ds_read2_b32 v[56:57], v37 offset0:198 offset1:206
	ds_read2_b32 v[62:63], v37 offset0:231 offset1:239
	s_waitcnt lgkmcnt(7)
	v_mov_b32_e32 v44, v4
	v_mov_b32_e32 v59, v2
	s_waitcnt lgkmcnt(4)
	v_mov_b32_e32 v45, v50
	v_pk_mul_f32 v[44:45], v[6:7], v[44:45]
	s_waitcnt lgkmcnt(3)
	v_mov_b32_e32 v60, v52
	s_waitcnt lgkmcnt(1)
	v_mov_b32_e32 v61, v56
	v_mov_b32_e32 v2, v1
	v_mov_b32_e32 v0, v54
	s_waitcnt lgkmcnt(0)
	v_mov_b32_e32 v1, v62
	v_mov_b32_e32 v42, v48
	v_mov_b32_e32 v43, v46
	v_pk_mul_f32 v[60:61], v[58:59], v[60:61]
	v_pk_mul_f32 v[0:1], v[2:3], v[0:1]
	v_bfe_u32 v48, v44, 16, 1
	v_pk_mul_f32 v[42:43], v[32:33], v[42:43]
	v_bfe_u32 v4, v1, 16, 1
	v_add3_u32 v48, v44, v48, s81
	v_bfe_u32 v44, v60, 16, 1
	v_bfe_u32 v41, v0, 16, 1
	v_bfe_u32 v46, v45, 16, 1
	v_add3_u32 v1, v1, v4, s81
	v_bfe_u32 v4, v42, 16, 1
	v_add3_u32 v44, v60, v44, s81
	v_add3_u32 v46, v45, v46, s81
	v_add3_u32 v0, v0, v41, s81
	v_bfe_u32 v41, v43, 16, 1
	v_bfe_u32 v45, v61, 16, 1
	v_add3_u32 v4, v42, v4, s81
	v_lshrrev_b32_e32 v42, 16, v44
	v_add3_u32 v45, v61, v45, s81
	v_add3_u32 v41, v43, v41, s81
	v_and_or_b32 v44, v0, s71, v42
	v_or_b32_e32 v0, s0, v36
	v_lshrrev_b32_e32 v4, 16, v4
	v_lshrrev_b32_e32 v41, 16, v41
	v_lshrrev_b32_e32 v43, 16, v45
	v_lshlrev_b32_e32 v96, 11, v0
	v_and_or_b32 v45, v1, s71, v43
	v_and_or_b32 v43, v46, s71, v41
	v_and_or_b32 v42, v48, s71, v4
	v_lshl_add_u64 v[0:1], v[30:31], 0, v[96:97]
	v_mov_b32_e32 v50, v5
	v_mov_b32_e32 v62, v55
	global_store_dwordx4 v[0:1], v[42:45], off sc0 sc1
	v_mov_b32_e32 v46, v49
	v_pk_mul_f32 v[4:5], v[6:7], v[50:51]
	v_mov_b32_e32 v56, v53
	v_pk_mul_f32 v[44:45], v[2:3], v[62:63]
	v_pk_mul_f32 v[0:1], v[32:33], v[46:47]
	v_pk_mul_f32 v[42:43], v[58:59], v[56:57]
	v_bfe_u32 v41, v45, 16, 1
	v_bfe_u32 v47, v5, 16, 1
	v_add3_u32 v5, v5, v47, s81
	v_add3_u32 v41, v45, v41, s81
	v_bfe_u32 v45, v0, 16, 1
	v_bfe_u32 v47, v42, 16, 1
	v_bfe_u32 v46, v44, 16, 1
	v_bfe_u32 v48, v4, 16, 1
	v_add3_u32 v42, v42, v47, s81
	v_add3_u32 v0, v0, v45, s81
	v_add3_u32 v4, v4, v48, s81
	v_add3_u32 v44, v44, v46, s81
	v_bfe_u32 v46, v1, 16, 1
	v_bfe_u32 v48, v43, 16, 1
	v_lshrrev_b32_e32 v0, 16, v0
	v_lshrrev_b32_e32 v42, 16, v42
	v_add3_u32 v43, v43, v48, s81
	v_add3_u32 v1, v1, v46, s81
	v_and_or_b32 v44, v44, s71, v42
	v_and_or_b32 v42, v4, s71, v0
	v_or_b32_e32 v0, s0, v38
	v_lshrrev_b32_e32 v1, 16, v1
	v_lshrrev_b32_e32 v43, 16, v43
	v_lshlrev_b32_e32 v96, 11, v0
	v_and_or_b32 v45, v41, s71, v43
	v_and_or_b32 v43, v5, s71, v1
	v_lshl_add_u64 v[0:1], v[30:31], 0, v[96:97]
	global_store_dwordx4 v[0:1], v[42:45], off sc0 sc1
	ds_read2_b32 v[0:1], v37 offset0:49 offset1:57
	ds_read2_b32 v[4:5], v37 offset0:82 offset1:90
	ds_read2_b32 v[46:47], v37 offset0:115 offset1:123
	ds_read2_b32 v[48:49], v37 offset0:16 offset1:24
	ds_read2_b32 v[50:51], v37 offset0:148 offset1:156
	ds_read2_b32 v[52:53], v37 offset0:181 offset1:189
	ds_read2_b32 v[54:55], v37 offset0:214 offset1:222
	ds_read2_b32 v[56:57], v37 offset0:247 offset1:255
	s_waitcnt lgkmcnt(7)
	v_mov_b32_e32 v44, v0
	s_waitcnt lgkmcnt(3)
	v_mov_b32_e32 v60, v50
	v_mov_b32_e32 v45, v46
	s_waitcnt lgkmcnt(1)
	v_mov_b32_e32 v61, v54
	v_mov_b32_e32 v42, v48
	v_mov_b32_e32 v43, v4
	v_pk_mul_f32 v[44:45], v[6:7], v[44:45]
	v_pk_mul_f32 v[60:61], v[58:59], v[60:61]
	v_mov_b32_e32 v62, v52
	s_waitcnt lgkmcnt(0)
	v_mov_b32_e32 v63, v56
	v_pk_mul_f32 v[42:43], v[32:33], v[42:43]
	v_pk_mul_f32 v[62:63], v[2:3], v[62:63]
	v_bfe_u32 v41, v45, 16, 1
	v_bfe_u32 v46, v44, 16, 1
	v_bfe_u32 v48, v60, 16, 1
	v_bfe_u32 v50, v61, 16, 1
	v_bfe_u32 v0, v63, 16, 1
	v_bfe_u32 v4, v62, 16, 1
	v_add3_u32 v46, v44, v46, s81
	v_add3_u32 v41, v45, v41, s81
	v_bfe_u32 v44, v42, 16, 1
	v_bfe_u32 v45, v43, 16, 1
	v_add3_u32 v50, v61, v50, s81
	v_add3_u32 v48, v60, v48, s81
	v_add3_u32 v4, v62, v4, s81
	v_add3_u32 v0, v63, v0, s81
	v_add3_u32 v43, v43, v45, s81
	v_add3_u32 v42, v42, v44, s81
	v_lshrrev_b32_e32 v44, 16, v48
	v_lshrrev_b32_e32 v45, 16, v50
	v_mov_b32_e32 v56, v53
	v_lshrrev_b32_e32 v42, 16, v42
	v_and_or_b32 v45, v0, s71, v45
	v_and_or_b32 v44, v4, s71, v44
	v_or_b32_e32 v0, s0, v39
	v_mov_b32_e32 v4, v49
	v_pk_mul_f32 v[2:3], v[2:3], v[56:57]
	v_lshrrev_b32_e32 v43, 16, v43
	v_and_or_b32 v42, v46, s71, v42
	v_lshlrev_b32_e32 v96, 11, v0
	v_pk_mul_f32 v[4:5], v[32:33], v[4:5]
	v_mov_b32_e32 v46, v1
	v_bfe_u32 v32, v3, 16, 1
	v_and_or_b32 v43, v41, s71, v43
	v_lshl_add_u64 v[60:61], v[30:31], 0, v[96:97]
	v_pk_mul_f32 v[0:1], v[6:7], v[46:47]
	v_mov_b32_e32 v54, v51
	v_add3_u32 v3, v3, v32, s81
	v_bfe_u32 v32, v4, 16, 1
	global_store_dwordx4 v[60:61], v[42:45], off sc0 sc1
	v_pk_mul_f32 v[6:7], v[58:59], v[54:55]
	v_bfe_u32 v33, v2, 16, 1
	v_bfe_u32 v41, v1, 16, 1
	v_bfe_u32 v42, v0, 16, 1
	v_add3_u32 v4, v4, v32, s81
	v_add3_u32 v0, v0, v42, s81
	v_add3_u32 v1, v1, v41, s81
	v_add3_u32 v2, v2, v33, s81
	v_bfe_u32 v33, v5, 16, 1
	v_bfe_u32 v41, v6, 16, 1
	v_bfe_u32 v42, v7, 16, 1
	v_lshrrev_b32_e32 v4, 16, v4
	v_add3_u32 v7, v7, v42, s81
	v_add3_u32 v6, v6, v41, s81
	v_add3_u32 v5, v5, v33, s81
	v_and_or_b32 v0, v0, s71, v4
	v_or_b32_e32 v4, s0, v40
	v_lshrrev_b32_e32 v5, 16, v5
	v_lshrrev_b32_e32 v6, 16, v6
	v_lshrrev_b32_e32 v7, 16, v7
	v_lshlrev_b32_e32 v96, 11, v4
	v_and_or_b32 v3, v3, s71, v7
	v_and_or_b32 v2, v2, s71, v6
	v_and_or_b32 v1, v1, s71, v5
	v_lshl_add_u64 v[4:5], v[30:31], 0, v[96:97]
	global_store_dwordx4 v[4:5], v[0:3], off sc0 sc1
	s_waitcnt lgkmcnt(0)

.LBB0_428:
	s_waitcnt vmcnt(0)
	ds_write2_b32 v35, v30, v31 offset1:66
	ds_write2_b32 v35, v32, v33 offset0:132 offset1:198
	v_add_u32_e32 v30, 0x400, v35
	ds_write2_b32 v30, v41, v42 offset0:8 offset1:74
	ds_write2_b32 v30, v43, v44 offset0:140 offset1:206
	v_add_u32_e32 v30, 0x800, v35
	ds_write2_b32 v30, v45, v46 offset0:16 offset1:82
	ds_write2_b32 v30, v47, v48 offset0:148 offset1:214
	v_add_u32_e32 v30, 0xc00, v35
	ds_write2_b32 v30, v49, v50 offset0:24 offset1:90
	ds_write2_b32 v30, v51, v52 offset0:156 offset1:222
	v_add_u32_e32 v30, 0x1000, v35
	ds_write2_b32 v30, v53, v54 offset0:32 offset1:98
	ds_write2_b32 v30, v55, v56 offset0:164 offset1:230
	v_add_u32_e32 v30, 0x1400, v35
	ds_write2_b32 v30, v57, v58 offset0:40 offset1:106
	ds_write2_b32 v30, v59, v60 offset0:172 offset1:238
	v_add_u32_e32 v30, 0x1800, v35
	ds_write2_b32 v30, v61, v62 offset0:48 offset1:114
	ds_write2_b32 v30, v63, v64 offset0:180 offset1:246
	v_add_u32_e32 v30, 0x1c00, v35
	ds_write2_b32 v30, v65, v66 offset0:56 offset1:122
	ds_write2_b32 v30, v67, v68 offset0:188 offset1:254
	s_waitcnt lgkmcnt(0)
	ds_read2_b32 v[42:43], v37 offset1:8
	ds_read2_b32 v[44:45], v37 offset0:66 offset1:74
	ds_read2_b32 v[48:49], v37 offset0:33 offset1:41
	ds_read2_b32 v[50:51], v37 offset0:99 offset1:107
	ds_read2_b32 v[52:53], v37 offset0:132 offset1:140
	ds_read2_b32 v[54:55], v37 offset0:198 offset1:206
	ds_read2_b32 v[56:57], v37 offset0:165 offset1:173
	ds_read2_b32 v[58:59], v37 offset0:231 offset1:239
	s_sub_i32 s0, 0, s41
	s_waitcnt lgkmcnt(5)
	v_mov_b32_e32 v32, v48
	s_waitcnt lgkmcnt(4)
	v_mov_b32_e32 v33, v50
	s_waitcnt lgkmcnt(3)
	v_mov_b32_e32 v60, v52
	s_waitcnt lgkmcnt(2)
	v_mov_b32_e32 v61, v54
	s_waitcnt lgkmcnt(1)
	v_mov_b32_e32 v62, v56
	s_waitcnt lgkmcnt(0)
	v_mov_b32_e32 v63, v58
	v_mov_b32_e32 v30, v42
	v_mov_b32_e32 v31, v44
	v_pk_mul_f32 v[32:33], v[0:1], v[32:33]
	v_pk_mul_f32 v[60:61], v[6:7], v[60:61]
	v_pk_mul_f32 v[62:63], v[4:5], v[62:63]
	v_pk_mul_f32 v[30:31], v[2:3], v[30:31]
	v_bfe_u32 v41, v63, 16, 1
	v_bfe_u32 v42, v62, 16, 1
	v_bfe_u32 v44, v33, 16, 1
	v_bfe_u32 v48, v32, 16, 1
	v_bfe_u32 v50, v60, 16, 1
	s_add_i32 s0, s0, s72
	v_add3_u32 v48, v32, v48, s81
	v_add3_u32 v44, v33, v44, s81
	v_add3_u32 v32, v62, v42, s81
	v_add3_u32 v33, v63, v41, s81
	v_bfe_u32 v41, v30, 16, 1
	v_bfe_u32 v42, v31, 16, 1
	v_bfe_u32 v52, v61, 16, 1
	v_add3_u32 v50, v60, v50, s81
	v_add_u32_e32 v60, s0, v36
	s_ashr_i32 s41, s40, 31
	v_add3_u32 v52, v61, v52, s81
	v_add3_u32 v31, v31, v42, s81
	v_add3_u32 v30, v30, v41, s81
	v_ashrrev_i32_e32 v61, 31, v60
	v_lshl_add_u64 v[46:47], s[40:41], 1, v[14:15]
	v_lshrrev_b32_e32 v30, 16, v30
	v_lshrrev_b32_e32 v31, 16, v31
	v_lshrrev_b32_e32 v41, 16, v50
	v_lshrrev_b32_e32 v42, 16, v52
	v_lshlrev_b64 v[62:63], 11, v[60:61]
	v_and_or_b32 v33, v33, s71, v42
	v_and_or_b32 v32, v32, s71, v41
	v_and_or_b32 v31, v44, s71, v31
	v_and_or_b32 v30, v48, s71, v30
	v_lshl_add_u64 v[62:63], v[46:47], 0, v[62:63]
	v_mov_b32_e32 v44, v43
	v_mov_b32_e32 v50, v49
	v_mov_b32_e32 v58, v57
	global_store_dwordx4 v[62:63], v[30:33], off sc0 sc1
	v_mov_b32_e32 v54, v53
	v_pk_mul_f32 v[42:43], v[6:7], v[54:55]
	v_pk_mul_f32 v[30:31], v[2:3], v[44:45]
	v_pk_mul_f32 v[32:33], v[0:1], v[50:51]
	v_pk_mul_f32 v[44:45], v[4:5], v[58:59]
	v_bfe_u32 v49, v33, 16, 1
	v_bfe_u32 v41, v45, 16, 1
	v_bfe_u32 v48, v44, 16, 1
	v_bfe_u32 v50, v32, 16, 1
	v_add3_u32 v50, v32, v50, s81
	v_add3_u32 v49, v33, v49, s81
	v_add3_u32 v32, v44, v48, s81
	v_add3_u32 v33, v45, v41, s81
	v_bfe_u32 v45, v42, 16, 1
	v_bfe_u32 v48, v43, 16, 1
	v_bfe_u32 v41, v30, 16, 1
	v_add3_u32 v43, v43, v48, s81
	v_add3_u32 v42, v42, v45, s81
	v_add3_u32 v30, v30, v41, s81
	v_lshrrev_b32_e32 v41, 16, v42
	v_lshrrev_b32_e32 v42, 16, v43
	v_bfe_u32 v44, v31, 16, 1
	v_and_or_b32 v33, v33, s71, v42
	v_add_u32_e32 v42, 8, v60
	v_add3_u32 v31, v31, v44, s81
	v_ashrrev_i32_e32 v43, 31, v42
	v_lshrrev_b32_e32 v30, 16, v30
	v_lshrrev_b32_e32 v31, 16, v31
	v_lshlrev_b64 v[42:43], 11, v[42:43]
	v_and_or_b32 v32, v32, s71, v41
	v_and_or_b32 v31, v49, s71, v31
	v_and_or_b32 v30, v50, s71, v30
	v_lshl_add_u64 v[42:43], v[46:47], 0, v[42:43]
	ds_read2_b32 v[44:45], v37 offset0:16 offset1:24
	ds_read2_b32 v[48:49], v37 offset0:82 offset1:90
	global_store_dwordx4 v[42:43], v[30:33], off sc0 sc1
	ds_read2_b32 v[42:43], v37 offset0:49 offset1:57
	ds_read2_b32 v[50:51], v37 offset0:115 offset1:123
	ds_read2_b32 v[52:53], v37 offset0:148 offset1:156
	ds_read2_b32 v[54:55], v37 offset0:214 offset1:222
	ds_read2_b32 v[56:57], v37 offset0:181 offset1:189
	ds_read2_b32 v[58:59], v37 offset0:247 offset1:255
	s_waitcnt lgkmcnt(7)
	v_mov_b32_e32 v30, v44
	s_waitcnt lgkmcnt(5)
	v_mov_b32_e32 v32, v42
	s_waitcnt lgkmcnt(4)
	v_mov_b32_e32 v33, v50
	s_waitcnt lgkmcnt(3)
	v_mov_b32_e32 v62, v52
	s_waitcnt lgkmcnt(2)
	v_mov_b32_e32 v63, v54
	s_waitcnt lgkmcnt(1)
	v_mov_b32_e32 v64, v56
	s_waitcnt lgkmcnt(0)
	v_mov_b32_e32 v65, v58
	v_mov_b32_e32 v31, v48
	v_pk_mul_f32 v[32:33], v[0:1], v[32:33]
	v_pk_mul_f32 v[62:63], v[6:7], v[62:63]
	v_pk_mul_f32 v[64:65], v[4:5], v[64:65]
	v_pk_mul_f32 v[30:31], v[2:3], v[30:31]
	v_bfe_u32 v41, v65, 16, 1
	v_bfe_u32 v42, v64, 16, 1
	v_bfe_u32 v44, v33, 16, 1
	v_bfe_u32 v48, v32, 16, 1
	v_bfe_u32 v50, v62, 16, 1
	v_add3_u32 v48, v32, v48, s81
	v_add3_u32 v44, v33, v44, s81
	v_add3_u32 v32, v64, v42, s81
	v_add3_u32 v33, v65, v41, s81
	v_bfe_u32 v41, v30, 16, 1
	v_bfe_u32 v42, v31, 16, 1
	v_bfe_u32 v52, v63, 16, 1
	v_add3_u32 v50, v62, v50, s81
	v_add_u32_e32 v62, 16, v60
	v_add3_u32 v52, v63, v52, s81
	v_add3_u32 v31, v31, v42, s81
	v_add3_u32 v30, v30, v41, s81
	v_ashrrev_i32_e32 v63, 31, v62
	v_lshrrev_b32_e32 v30, 16, v30
	v_lshrrev_b32_e32 v31, 16, v31
	v_lshrrev_b32_e32 v41, 16, v50
	v_lshrrev_b32_e32 v42, 16, v52
	v_lshlrev_b64 v[62:63], 11, v[62:63]
	v_mov_b32_e32 v50, v43
	v_mov_b32_e32 v58, v57
	v_and_or_b32 v33, v33, s71, v42
	v_and_or_b32 v32, v32, s71, v41
	v_and_or_b32 v31, v44, s71, v31
	v_and_or_b32 v30, v48, s71, v30
	v_lshl_add_u64 v[62:63], v[46:47], 0, v[62:63]
	v_mov_b32_e32 v48, v45
	v_pk_mul_f32 v[0:1], v[0:1], v[50:51]
	v_mov_b32_e32 v54, v53
	v_pk_mul_f32 v[4:5], v[4:5], v[58:59]
	global_store_dwordx4 v[62:63], v[30:33], off sc0 sc1
	v_pk_mul_f32 v[2:3], v[2:3], v[48:49]
	v_pk_mul_f32 v[6:7], v[6:7], v[54:55]
	v_bfe_u32 v30, v5, 16, 1
	v_bfe_u32 v32, v1, 16, 1
	v_bfe_u32 v31, v4, 16, 1
	v_bfe_u32 v33, v0, 16, 1
	v_add3_u32 v1, v1, v32, s81
	v_add3_u32 v5, v5, v30, s81
	v_bfe_u32 v30, v2, 16, 1
	v_bfe_u32 v32, v6, 16, 1
	v_add3_u32 v0, v0, v33, s81
	v_add3_u32 v4, v4, v31, s81
	v_bfe_u32 v31, v3, 16, 1
	v_bfe_u32 v33, v7, 16, 1
	v_add3_u32 v6, v6, v32, s81
	v_add3_u32 v2, v2, v30, s81
	v_add3_u32 v7, v7, v33, s81
	v_add3_u32 v3, v3, v31, s81
	v_lshrrev_b32_e32 v30, 16, v2
	v_lshrrev_b32_e32 v2, 16, v6
	v_lshrrev_b32_e32 v31, 16, v3
	v_lshrrev_b32_e32 v3, 16, v7
	v_and_or_b32 v2, v4, s71, v2
	v_add_u32_e32 v4, 24, v60
	v_and_or_b32 v3, v5, s71, v3
	v_ashrrev_i32_e32 v5, 31, v4
	v_lshlrev_b64 v[4:5], 11, v[4:5]
	v_and_or_b32 v1, v1, s71, v31
	v_and_or_b32 v0, v0, s71, v30
	v_lshl_add_u64 v[4:5], v[46:47], 0, v[4:5]
	global_store_dwordx4 v[4:5], v[0:3], off sc0 sc1
	s_waitcnt lgkmcnt(0)

.LBB0_430:
	s_andn2_b64 vcc, exec, s[0:1]
	s_cbranch_vccnz .LBB0_479
	s_mov_b64 s[0:1], -1
	s_and_b64 vcc, exec, s[34:35]
	s_cbranch_vccz .LBB0_461
	s_cmpk_gt_u32 s42, 0x3ff
	s_cbranch_scc0 .LBB0_442
	s_cmpk_gt_u32 s42, 0xeff
	s_cbranch_scc0 .LBB0_439
	s_and_b32 s34, s72, 0x3e0
	s_cmpk_gt_u32 s42, 0x147f
	v_or_b32_e32 v42, s34, v36
	v_or_b32_e32 v41, s34, v38
	v_or_b32_e32 v33, s34, v39
	v_or_b32_e32 v32, s34, v40
	s_cbranch_scc0 .LBB0_436
	s_and_b32 s0, s74, 0x7fffffc0
	s_addk_i32 s0, 0xd700
	v_or_b32_e32 v96, s0, v9
	v_readlane_b32 s48, v236, 0
	v_lshlrev_b64 v[0:1], 12, v[96:97]
	v_readlane_b32 s50, v236, 2
	v_readlane_b32 s51, v236, 3
	s_lshl_b32 s46, s34, 2
	v_lshlrev_b32_e32 v96, 2, v8
	v_lshl_add_u64 v[0:1], s[50:51], 0, v[0:1]
	v_lshl_add_u64 v[0:1], v[0:1], 0, s[46:47]
	v_lshl_add_u64 v[0:1], v[0:1], 0, v[96:97]
	v_add_co_u32_e32 v2, vcc, 0x2000, v0
	s_movk_i32 s1, 0x4000
	s_waitcnt lgkmcnt(0)
	v_addc_co_u32_e32 v3, vcc, 0, v1, vcc
	global_load_dword v4, v[0:1], off
	global_load_dword v5, v[2:3], off
	v_add_co_u32_e32 v2, vcc, s1, v0
	s_and_b32 s1, s0, 0x3c0
	s_nop 0
	v_addc_co_u32_e32 v3, vcc, 0, v1, vcc
	global_load_dword v6, v[2:3], off
	v_add_co_u32_e32 v2, vcc, 0x6000, v0
	v_lshlrev_b32_e32 v96, 11, v42
	s_nop 0
	v_addc_co_u32_e32 v3, vcc, 0, v1, vcc
	global_load_dword v7, v[2:3], off
	v_add_co_u32_e32 v2, vcc, 0x8000, v0
	v_readlane_b32 s49, v236, 1
	s_nop 0
	v_addc_co_u32_e32 v3, vcc, 0, v1, vcc
	global_load_dword v30, v[2:3], off
	v_add_co_u32_e32 v2, vcc, 0xa000, v0
	v_readlane_b32 s52, v236, 4
	s_nop 0
	v_addc_co_u32_e32 v3, vcc, 0, v1, vcc
	global_load_dword v31, v[2:3], off
	v_add_co_u32_e32 v2, vcc, 0xc000, v0
	v_readlane_b32 s53, v236, 5
	s_nop 0
	v_addc_co_u32_e32 v3, vcc, 0, v1, vcc
	global_load_dword v43, v[2:3], off
	v_add_co_u32_e32 v2, vcc, 0xe000, v0
	v_readlane_b32 s54, v236, 6
	s_nop 0
	v_addc_co_u32_e32 v3, vcc, 0, v1, vcc
	global_load_dword v44, v[2:3], off
	v_add_co_u32_e32 v2, vcc, 0x10000, v0
	v_readlane_b32 s55, v236, 7
	s_nop 0
	v_addc_co_u32_e32 v3, vcc, 0, v1, vcc
	global_load_dword v45, v[2:3], off
	v_add_co_u32_e32 v2, vcc, 0x12000, v0
	s_nop 1
	v_addc_co_u32_e32 v3, vcc, 0, v1, vcc
	global_load_dword v46, v[2:3], off
	v_add_co_u32_e32 v2, vcc, 0x14000, v0
	s_nop 1
	v_addc_co_u32_e32 v3, vcc, 0, v1, vcc
	global_load_dword v47, v[2:3], off
	v_add_co_u32_e32 v2, vcc, 0x16000, v0
	s_nop 1
	v_addc_co_u32_e32 v3, vcc, 0, v1, vcc
	global_load_dword v48, v[2:3], off
	v_add_co_u32_e32 v2, vcc, 0x18000, v0
	s_nop 1
	v_addc_co_u32_e32 v3, vcc, 0, v1, vcc
	global_load_dword v49, v[2:3], off
	v_add_co_u32_e32 v2, vcc, 0x1a000, v0
	s_nop 1
	v_addc_co_u32_e32 v3, vcc, 0, v1, vcc
	global_load_dword v50, v[2:3], off
	v_add_co_u32_e32 v2, vcc, 0x1c000, v0
	s_nop 1
	v_addc_co_u32_e32 v3, vcc, 0, v1, vcc
	global_load_dword v51, v[2:3], off
	v_add_co_u32_e32 v2, vcc, 0x1e000, v0
	s_nop 1
	v_addc_co_u32_e32 v3, vcc, 0, v1, vcc
	global_load_dword v52, v[2:3], off
	v_add_co_u32_e32 v2, vcc, 0x20000, v0
	s_nop 1
	v_addc_co_u32_e32 v3, vcc, 0, v1, vcc
	global_load_dword v53, v[2:3], off
	v_add_co_u32_e32 v2, vcc, 0x22000, v0
	s_nop 1
	v_addc_co_u32_e32 v3, vcc, 0, v1, vcc
	global_load_dword v54, v[2:3], off
	v_add_co_u32_e32 v2, vcc, 0x24000, v0
	s_nop 1
	v_addc_co_u32_e32 v3, vcc, 0, v1, vcc
	global_load_dword v55, v[2:3], off
	v_add_co_u32_e32 v2, vcc, 0x26000, v0
	s_nop 1
	v_addc_co_u32_e32 v3, vcc, 0, v1, vcc
	global_load_dword v56, v[2:3], off
	v_add_co_u32_e32 v2, vcc, 0x28000, v0
	s_nop 1
	v_addc_co_u32_e32 v3, vcc, 0, v1, vcc
	global_load_dword v57, v[2:3], off
	v_add_co_u32_e32 v2, vcc, 0x2a000, v0
	s_nop 1
	v_addc_co_u32_e32 v3, vcc, 0, v1, vcc
	global_load_dword v58, v[2:3], off
	v_add_co_u32_e32 v2, vcc, 0x2c000, v0
	s_nop 1
	v_addc_co_u32_e32 v3, vcc, 0, v1, vcc
	global_load_dword v59, v[2:3], off
	v_add_co_u32_e32 v2, vcc, 0x2e000, v0
	s_nop 1
	v_addc_co_u32_e32 v3, vcc, 0, v1, vcc
	global_load_dword v60, v[2:3], off
	v_add_co_u32_e32 v2, vcc, 0x30000, v0
	s_nop 1
	v_addc_co_u32_e32 v3, vcc, 0, v1, vcc
	global_load_dword v61, v[2:3], off
	v_add_co_u32_e32 v2, vcc, 0x32000, v0
	s_nop 1
	v_addc_co_u32_e32 v3, vcc, 0, v1, vcc
	global_load_dword v62, v[2:3], off
	v_add_co_u32_e32 v2, vcc, 0x34000, v0
	s_nop 1
	v_addc_co_u32_e32 v3, vcc, 0, v1, vcc
	global_load_dword v63, v[2:3], off
	v_add_co_u32_e32 v2, vcc, 0x36000, v0
	s_nop 1
	v_addc_co_u32_e32 v3, vcc, 0, v1, vcc
	global_load_dword v64, v[2:3], off
	v_add_co_u32_e32 v2, vcc, 0x38000, v0
	s_nop 1
	v_addc_co_u32_e32 v3, vcc, 0, v1, vcc
	global_load_dword v65, v[2:3], off
	v_add_co_u32_e32 v2, vcc, 0x3a000, v0
	s_nop 1
	v_addc_co_u32_e32 v3, vcc, 0, v1, vcc
	global_load_dword v66, v[2:3], off
	v_add_co_u32_e32 v2, vcc, 0x3c000, v0
	s_nop 1
	v_addc_co_u32_e32 v3, vcc, 0, v1, vcc
	v_add_co_u32_e32 v0, vcc, 0x3e000, v0
	global_load_dword v2, v[2:3], off
	s_nop 0
	v_addc_co_u32_e32 v1, vcc, 0, v1, vcc
	global_load_dword v0, v[0:1], off
	v_or_b32_e32 v1, s1, v34
	v_lshlrev_b32_e32 v3, 2, v1
	v_add_u32_e32 v1, 0x400, v35
	s_waitcnt vmcnt(0)
	ds_write2_b32 v35, v4, v5 offset1:66
	ds_write2_b32 v35, v6, v7 offset0:132 offset1:198
	ds_write2_b32 v1, v30, v31 offset0:8 offset1:74
	ds_write2_b32 v1, v43, v44 offset0:140 offset1:206
	v_add_u32_e32 v1, 0x800, v35
	ds_write2_b32 v1, v45, v46 offset0:16 offset1:82
	ds_write2_b32 v1, v47, v48 offset0:148 offset1:214
	v_add_u32_e32 v1, 0xc00, v35
	ds_write2_b32 v1, v49, v50 offset0:24 offset1:90
	ds_write2_b32 v1, v51, v52 offset0:156 offset1:222
	v_add_u32_e32 v1, 0x1000, v35
	ds_write2_b32 v1, v53, v54 offset0:32 offset1:98
	ds_write2_b32 v1, v55, v56 offset0:164 offset1:230
	v_add_u32_e32 v1, 0x1400, v35
	ds_write2_b32 v1, v57, v58 offset0:40 offset1:106
	ds_write2_b32 v1, v59, v60 offset0:172 offset1:238
	v_add_u32_e32 v1, 0x1800, v35
	ds_write2_b32 v1, v61, v62 offset0:48 offset1:114
	ds_write2_b32 v1, v63, v64 offset0:180 offset1:246
	v_add_u32_e32 v1, 0x1c00, v35
	s_mov_b32 s1, s47
	ds_write2_b32 v1, v65, v66 offset0:56 offset1:122
	ds_write2_b32 v1, v2, v0 offset0:188 offset1:254
	v_lshl_add_u64 v[0:1], s[0:1], 1, v[16:17]
	v_readlane_b32 s0, v235, 4
	v_readlane_b32 s1, v235, 5
	s_nop 4
	global_load_dwordx4 v[44:47], v3, s[0:1] offset:16
	global_load_dwordx4 v[4:7], v3, s[0:1]
	s_waitcnt lgkmcnt(0)
	ds_read2_b32 v[48:49], v37 offset0:33 offset1:41
	ds_read2_b32 v[50:51], v37 offset0:66 offset1:74
	ds_read2_b32 v[52:53], v37 offset1:8
	ds_read2_b32 v[54:55], v37 offset0:99 offset1:107
	ds_read2_b32 v[56:57], v37 offset0:132 offset1:140
	ds_read2_b32 v[58:59], v37 offset0:165 offset1:173
	ds_read2_b32 v[60:61], v37 offset0:198 offset1:206
	ds_read2_b32 v[64:65], v37 offset0:231 offset1:239
	s_mov_b32 s0, 0x3e38aa3b
	s_waitcnt lgkmcnt(3)
	v_mov_b32_e32 v62, v56
	s_waitcnt lgkmcnt(2)
	v_mov_b32_e32 v66, v58
	s_waitcnt lgkmcnt(1)
	v_mov_b32_e32 v63, v60
	s_waitcnt lgkmcnt(0)
	v_mov_b32_e32 v67, v64
	v_mov_b32_e32 v64, v59
	v_mov_b32_e32 v60, v57
	s_waitcnt vmcnt(0)
	v_mov_b32_e32 v3, v6
	v_mov_b32_e32 v6, v5
	v_mov_b32_e32 v2, v4
	v_pk_mul_f32 v[4:5], v[6:7], s[0:1] op_sel_hi:[1,0]
	v_mov_b32_e32 v7, v46
	v_mov_b32_e32 v46, v45
	v_mov_b32_e32 v6, v44
	v_pk_mul_f32 v[30:31], v[46:47], s[0:1] op_sel_hi:[1,0]
	v_mov_b32_e32 v46, v48
	v_mov_b32_e32 v47, v54
	v_pk_mul_f32 v[2:3], v[2:3], s[0:1] op_sel_hi:[1,0]
	v_pk_mul_f32 v[6:7], v[6:7], s[0:1] op_sel_hi:[1,0]
	v_mov_b32_e32 v44, v52
	v_mov_b32_e32 v45, v50
	v_pk_mul_f32 v[46:47], v[4:5], v[46:47]
	v_pk_mul_f32 v[66:67], v[30:31], v[66:67]
	v_pk_mul_f32 v[44:45], v[2:3], v[44:45]
	v_pk_mul_f32 v[62:63], v[6:7], v[62:63]
	v_bfe_u32 v48, v66, 16, 1
	v_bfe_u32 v50, v47, 16, 1
	v_bfe_u32 v52, v46, 16, 1
	v_add3_u32 v52, v46, v52, s81
	v_add3_u32 v50, v47, v50, s81
	v_add3_u32 v46, v66, v48, s81
	v_bfe_u32 v47, v44, 16, 1
	v_bfe_u32 v48, v45, 16, 1
	v_bfe_u32 v54, v62, 16, 1
	v_bfe_u32 v56, v63, 16, 1
	v_bfe_u32 v43, v67, 16, 1
	v_add3_u32 v56, v63, v56, s81
	v_add3_u32 v54, v62, v54, s81
	v_add3_u32 v45, v45, v48, s81
	v_add3_u32 v44, v44, v47, s81
	v_add3_u32 v43, v67, v43, s81
	v_lshrrev_b32_e32 v44, 16, v44
	v_lshrrev_b32_e32 v45, 16, v45
	v_lshrrev_b32_e32 v48, 16, v54
	v_lshrrev_b32_e32 v47, 16, v56
	v_and_or_b32 v47, v43, s71, v47
	v_and_or_b32 v46, v46, s71, v48
	v_and_or_b32 v45, v50, s71, v45
	v_and_or_b32 v44, v52, s71, v44
	v_lshl_add_u64 v[62:63], v[0:1], 0, v[96:97]
	v_mov_b32_e32 v50, v53
	v_mov_b32_e32 v54, v49
	global_store_dwordx4 v[62:63], v[44:47], off sc0 sc1
	v_pk_mul_f32 v[48:49], v[6:7], v[60:61]
	v_lshlrev_b32_e32 v96, 11, v41
	v_pk_mul_f32 v[44:45], v[2:3], v[50:51]
	v_pk_mul_f32 v[46:47], v[4:5], v[54:55]
	v_pk_mul_f32 v[50:51], v[30:31], v[64:65]
	v_bfe_u32 v53, v47, 16, 1
	v_bfe_u32 v43, v51, 16, 1
	v_bfe_u32 v52, v50, 16, 1
	v_bfe_u32 v54, v46, 16, 1
	v_add3_u32 v54, v46, v54, s81
	v_add3_u32 v53, v47, v53, s81
	v_add3_u32 v46, v50, v52, s81
	v_add3_u32 v43, v51, v43, s81
	v_bfe_u32 v47, v44, 16, 1
	v_bfe_u32 v50, v45, 16, 1
	v_bfe_u32 v51, v48, 16, 1
	v_bfe_u32 v52, v49, 16, 1
	v_add3_u32 v49, v49, v52, s81
	v_add3_u32 v48, v48, v51, s81
	v_add3_u32 v45, v45, v50, s81
	v_add3_u32 v44, v44, v47, s81
	v_lshrrev_b32_e32 v44, 16, v44
	v_lshrrev_b32_e32 v45, 16, v45
	v_lshrrev_b32_e32 v48, 16, v48
	v_lshrrev_b32_e32 v47, 16, v49
	v_and_or_b32 v47, v43, s71, v47
	v_and_or_b32 v46, v46, s71, v48
	v_and_or_b32 v45, v53, s71, v45
	v_and_or_b32 v44, v54, s71, v44
	v_lshl_add_u64 v[48:49], v[0:1], 0, v[96:97]
	global_store_dwordx4 v[48:49], v[44:47], off sc0 sc1
	ds_read2_b32 v[48:49], v37 offset0:49 offset1:57
	ds_read2_b32 v[50:51], v37 offset0:82 offset1:90
	ds_read2_b32 v[52:53], v37 offset0:115 offset1:123
	ds_read2_b32 v[54:55], v37 offset0:16 offset1:24
	ds_read2_b32 v[56:57], v37 offset0:148 offset1:156
	ds_read2_b32 v[58:59], v37 offset0:181 offset1:189
	ds_read2_b32 v[60:61], v37 offset0:214 offset1:222
	ds_read2_b32 v[62:63], v37 offset0:247 offset1:255
	s_waitcnt lgkmcnt(7)
	v_mov_b32_e32 v46, v48
	s_waitcnt lgkmcnt(6)
	v_mov_b32_e32 v45, v50
	s_waitcnt lgkmcnt(5)
	v_mov_b32_e32 v47, v52
	s_waitcnt lgkmcnt(4)
	v_mov_b32_e32 v44, v54
	v_pk_mul_f32 v[46:47], v[4:5], v[46:47]
	s_waitcnt lgkmcnt(2)
	v_mov_b32_e32 v66, v58
	s_waitcnt lgkmcnt(0)
	v_mov_b32_e32 v67, v62
	v_pk_mul_f32 v[44:45], v[2:3], v[44:45]
	v_mov_b32_e32 v64, v56
	v_mov_b32_e32 v65, v60
	v_pk_mul_f32 v[66:67], v[30:31], v[66:67]
	v_bfe_u32 v50, v47, 16, 1
	v_pk_mul_f32 v[64:65], v[6:7], v[64:65]
	v_bfe_u32 v48, v66, 16, 1
	v_bfe_u32 v52, v46, 16, 1
	v_add3_u32 v50, v47, v50, s81
	v_bfe_u32 v47, v44, 16, 1
	v_add3_u32 v52, v46, v52, s81
	v_add3_u32 v46, v66, v48, s81
	v_bfe_u32 v48, v45, 16, 1
	v_bfe_u32 v54, v64, 16, 1
	v_bfe_u32 v56, v65, 16, 1
	v_add3_u32 v44, v44, v47, s81
	v_bfe_u32 v43, v67, 16, 1
	v_add3_u32 v56, v65, v56, s81
	v_add3_u32 v54, v64, v54, s81
	v_add3_u32 v45, v45, v48, s81
	v_lshrrev_b32_e32 v44, 16, v44
	v_add3_u32 v43, v67, v43, s81
	v_lshrrev_b32_e32 v45, 16, v45
	v_lshrrev_b32_e32 v48, 16, v54
	v_lshrrev_b32_e32 v47, 16, v56
	v_and_or_b32 v44, v52, s71, v44
	v_lshlrev_b32_e32 v96, 11, v33
	v_mov_b32_e32 v52, v49
	v_mov_b32_e32 v62, v59
	v_and_or_b32 v47, v43, s71, v47
	v_and_or_b32 v46, v46, s71, v48
	v_and_or_b32 v45, v50, s71, v45
	v_lshl_add_u64 v[64:65], v[0:1], 0, v[96:97]
	v_mov_b32_e32 v50, v55
	v_pk_mul_f32 v[4:5], v[4:5], v[52:53]
	v_mov_b32_e32 v60, v57
	v_pk_mul_f32 v[30:31], v[30:31], v[62:63]
	global_store_dwordx4 v[64:65], v[44:47], off sc0 sc1
	v_pk_mul_f32 v[2:3], v[2:3], v[50:51]
	v_pk_mul_f32 v[6:7], v[6:7], v[60:61]
	v_bfe_u32 v43, v31, 16, 1
	v_bfe_u32 v44, v30, 16, 1
	v_bfe_u32 v45, v5, 16, 1
	v_bfe_u32 v46, v4, 16, 1
	v_add3_u32 v46, v4, v46, s81
	v_add3_u32 v45, v5, v45, s81
	v_add3_u32 v4, v30, v44, s81
	v_add3_u32 v5, v31, v43, s81
	v_bfe_u32 v30, v2, 16, 1
	v_bfe_u32 v31, v3, 16, 1
	v_bfe_u32 v43, v6, 16, 1
	v_bfe_u32 v44, v7, 16, 1
	v_add3_u32 v7, v7, v44, s81
	v_add3_u32 v6, v6, v43, s81
	v_add3_u32 v3, v3, v31, s81
	v_add3_u32 v2, v2, v30, s81
	v_lshrrev_b32_e32 v2, 16, v2
	v_lshrrev_b32_e32 v3, 16, v3
	v_lshrrev_b32_e32 v6, 16, v6
	v_lshrrev_b32_e32 v7, 16, v7
	v_lshlrev_b32_e32 v96, 11, v32
	v_and_or_b32 v5, v5, s71, v7
	v_and_or_b32 v4, v4, s71, v6
	v_and_or_b32 v3, v45, s71, v3
	v_and_or_b32 v2, v46, s71, v2
	v_lshl_add_u64 v[0:1], v[0:1], 0, v[96:97]
	global_store_dwordx4 v[0:1], v[2:5], off sc0 sc1
	s_waitcnt lgkmcnt(0)
	s_mov_b64 s[0:1], 0
.LBB0_436:
	s_andn2_b64 vcc, exec, s[0:1]
	s_cbranch_vccnz .LBB0_438
	s_add_i32 s0, s74, 0x1e200
	s_and_b32 s0, s0, 0x1ffc0
	v_or_b32_e32 v0, s0, v9
	v_readlane_b32 s40, v235, 6
	v_lshlrev_b32_e32 v96, 12, v0
	v_readlane_b32 s41, v235, 7
	s_lshl_b32 s46, s34, 2
	s_movk_i32 s1, 0x4000
	v_lshl_add_u64 v[0:1], s[40:41], 0, v[96:97]
	v_lshl_add_u64 v[0:1], v[0:1], 0, s[46:47]
	v_lshlrev_b32_e32 v96, 2, v8
	v_lshl_add_u64 v[0:1], v[0:1], 0, v[96:97]
	v_add_co_u32_e32 v2, vcc, 0x2000, v0
	global_load_dword v4, v[0:1], off
	s_waitcnt lgkmcnt(0)
	v_addc_co_u32_e32 v3, vcc, 0, v1, vcc
	global_load_dword v5, v[2:3], off
	v_add_co_u32_e32 v2, vcc, s1, v0
	s_lshl_b32 s46, s0, 1
	s_nop 0
	v_addc_co_u32_e32 v3, vcc, 0, v1, vcc
	global_load_dword v6, v[2:3], off
	v_add_co_u32_e32 v2, vcc, 0x6000, v0
	s_nop 1
	v_addc_co_u32_e32 v3, vcc, 0, v1, vcc
	global_load_dword v7, v[2:3], off
	v_add_co_u32_e32 v2, vcc, 0x8000, v0
	s_nop 1
	v_addc_co_u32_e32 v3, vcc, 0, v1, vcc
	global_load_dword v30, v[2:3], off
	v_add_co_u32_e32 v2, vcc, 0xa000, v0
	s_nop 1
	v_addc_co_u32_e32 v3, vcc, 0, v1, vcc
	global_load_dword v31, v[2:3], off
	v_add_co_u32_e32 v2, vcc, 0xc000, v0
	s_nop 1
	v_addc_co_u32_e32 v3, vcc, 0, v1, vcc
	global_load_dword v43, v[2:3], off
	v_add_co_u32_e32 v2, vcc, 0xe000, v0
	s_nop 1
	v_addc_co_u32_e32 v3, vcc, 0, v1, vcc
	global_load_dword v44, v[2:3], off
	v_add_co_u32_e32 v2, vcc, 0x10000, v0
	s_nop 1
	v_addc_co_u32_e32 v3, vcc, 0, v1, vcc
	global_load_dword v45, v[2:3], off
	v_add_co_u32_e32 v2, vcc, 0x12000, v0
	s_nop 1
	v_addc_co_u32_e32 v3, vcc, 0, v1, vcc
	global_load_dword v46, v[2:3], off
	v_add_co_u32_e32 v2, vcc, 0x14000, v0
	s_nop 1
	v_addc_co_u32_e32 v3, vcc, 0, v1, vcc
	global_load_dword v47, v[2:3], off
	v_add_co_u32_e32 v2, vcc, 0x16000, v0
	s_nop 1
	v_addc_co_u32_e32 v3, vcc, 0, v1, vcc
	global_load_dword v48, v[2:3], off
	v_add_co_u32_e32 v2, vcc, 0x18000, v0
	s_nop 1
	v_addc_co_u32_e32 v3, vcc, 0, v1, vcc
	global_load_dword v49, v[2:3], off
	v_add_co_u32_e32 v2, vcc, 0x1a000, v0
	s_nop 1
	v_addc_co_u32_e32 v3, vcc, 0, v1, vcc
	global_load_dword v50, v[2:3], off
	v_add_co_u32_e32 v2, vcc, 0x1c000, v0
	s_nop 1
	v_addc_co_u32_e32 v3, vcc, 0, v1, vcc
	global_load_dword v51, v[2:3], off
	v_add_co_u32_e32 v2, vcc, 0x1e000, v0
	s_nop 1
	v_addc_co_u32_e32 v3, vcc, 0, v1, vcc
	global_load_dword v52, v[2:3], off
	v_add_co_u32_e32 v2, vcc, 0x20000, v0
	s_nop 1
	v_addc_co_u32_e32 v3, vcc, 0, v1, vcc
	global_load_dword v53, v[2:3], off
	v_add_co_u32_e32 v2, vcc, 0x22000, v0
	s_nop 1
	v_addc_co_u32_e32 v3, vcc, 0, v1, vcc
	global_load_dword v54, v[2:3], off
	v_add_co_u32_e32 v2, vcc, 0x24000, v0
	s_nop 1
	v_addc_co_u32_e32 v3, vcc, 0, v1, vcc
	global_load_dword v55, v[2:3], off
	v_add_co_u32_e32 v2, vcc, 0x26000, v0
	s_nop 1
	v_addc_co_u32_e32 v3, vcc, 0, v1, vcc
	global_load_dword v56, v[2:3], off
	v_add_co_u32_e32 v2, vcc, 0x28000, v0
	s_nop 1
	v_addc_co_u32_e32 v3, vcc, 0, v1, vcc
	global_load_dword v57, v[2:3], off
	v_add_co_u32_e32 v2, vcc, 0x2a000, v0
	s_nop 1
	v_addc_co_u32_e32 v3, vcc, 0, v1, vcc
	global_load_dword v58, v[2:3], off
	v_add_co_u32_e32 v2, vcc, 0x2c000, v0
	s_nop 1
	v_addc_co_u32_e32 v3, vcc, 0, v1, vcc
	global_load_dword v59, v[2:3], off
	v_add_co_u32_e32 v2, vcc, 0x2e000, v0
	s_nop 1
	v_addc_co_u32_e32 v3, vcc, 0, v1, vcc
	global_load_dword v60, v[2:3], off
	v_add_co_u32_e32 v2, vcc, 0x30000, v0
	s_nop 1
	v_addc_co_u32_e32 v3, vcc, 0, v1, vcc
	global_load_dword v61, v[2:3], off
	v_add_co_u32_e32 v2, vcc, 0x32000, v0
	s_nop 1
	v_addc_co_u32_e32 v3, vcc, 0, v1, vcc
	global_load_dword v62, v[2:3], off
	v_add_co_u32_e32 v2, vcc, 0x34000, v0
	s_nop 1
	v_addc_co_u32_e32 v3, vcc, 0, v1, vcc
	global_load_dword v63, v[2:3], off
	v_add_co_u32_e32 v2, vcc, 0x36000, v0
	s_nop 1
	v_addc_co_u32_e32 v3, vcc, 0, v1, vcc
	global_load_dword v64, v[2:3], off
	v_add_co_u32_e32 v2, vcc, 0x38000, v0
	s_nop 1
	v_addc_co_u32_e32 v3, vcc, 0, v1, vcc
	global_load_dword v65, v[2:3], off
	v_add_co_u32_e32 v2, vcc, 0x3a000, v0
	s_nop 1
	v_addc_co_u32_e32 v3, vcc, 0, v1, vcc
	global_load_dword v66, v[2:3], off
	v_add_co_u32_e32 v2, vcc, 0x3c000, v0
	s_nop 1
	v_addc_co_u32_e32 v3, vcc, 0, v1, vcc
	v_add_co_u32_e32 v0, vcc, 0x3e000, v0
	global_load_dword v2, v[2:3], off
	s_nop 0
	v_addc_co_u32_e32 v1, vcc, 0, v1, vcc
	global_load_dword v0, v[0:1], off
	v_add_u32_e32 v1, 0x400, v35
	s_waitcnt vmcnt(0)
	ds_write2_b32 v35, v4, v5 offset1:66
	ds_write2_b32 v35, v6, v7 offset0:132 offset1:198
	ds_write2_b32 v1, v30, v31 offset0:8 offset1:74
	ds_write2_b32 v1, v43, v44 offset0:140 offset1:206
	v_add_u32_e32 v1, 0x800, v35
	ds_write2_b32 v1, v45, v46 offset0:16 offset1:82
	ds_write2_b32 v1, v47, v48 offset0:148 offset1:214
	v_add_u32_e32 v1, 0xc00, v35
	ds_write2_b32 v1, v49, v50 offset0:24 offset1:90
	ds_write2_b32 v1, v51, v52 offset0:156 offset1:222
	v_add_u32_e32 v1, 0x1000, v35
	ds_write2_b32 v1, v53, v54 offset0:32 offset1:98
	ds_write2_b32 v1, v55, v56 offset0:164 offset1:230
	v_add_u32_e32 v1, 0x1400, v35
	ds_write2_b32 v1, v57, v58 offset0:40 offset1:106
	ds_write2_b32 v1, v59, v60 offset0:172 offset1:238
	v_add_u32_e32 v1, 0x1800, v35
	ds_write2_b32 v1, v61, v62 offset0:48 offset1:114
	ds_write2_b32 v1, v63, v64 offset0:180 offset1:246
	v_add_u32_e32 v1, 0x1c00, v35
	ds_write2_b32 v1, v65, v66 offset0:56 offset1:122
	ds_write2_b32 v1, v2, v0 offset0:188 offset1:254
	s_waitcnt lgkmcnt(0)
	ds_read2_b32 v[6:7], v37 offset0:33 offset1:41
	ds_read2_b32 v[30:31], v37 offset1:8
	ds_read2_b32 v[44:45], v37 offset0:66 offset1:74
	ds_read2_b32 v[46:47], v37 offset0:99 offset1:107
	ds_read2_b32 v[48:49], v37 offset0:132 offset1:140
	ds_read2_b32 v[50:51], v37 offset0:165 offset1:173
	ds_read2_b32 v[52:53], v37 offset0:198 offset1:206
	ds_read2_b32 v[54:55], v37 offset0:231 offset1:239
	s_waitcnt lgkmcnt(7)
	v_bfe_u32 v3, v6, 16, 1
	s_waitcnt lgkmcnt(6)
	v_bfe_u32 v2, v30, 16, 1
	v_add3_u32 v2, v30, v2, s81
	v_lshrrev_b32_e32 v2, 16, v2
	v_add3_u32 v3, v6, v3, s81
	v_and_or_b32 v2, v3, s71, v2
	s_waitcnt lgkmcnt(5)
	v_bfe_u32 v3, v44, 16, 1
	v_add3_u32 v3, v44, v3, s81
	s_waitcnt lgkmcnt(4)
	v_bfe_u32 v4, v46, 16, 1
	v_lshrrev_b32_e32 v3, 16, v3
	v_add3_u32 v4, v46, v4, s81
	v_and_or_b32 v3, v4, s71, v3
	s_waitcnt lgkmcnt(3)
	v_bfe_u32 v4, v48, 16, 1
	v_add3_u32 v4, v48, v4, s81
	s_waitcnt lgkmcnt(2)
	v_bfe_u32 v5, v50, 16, 1
	v_lshrrev_b32_e32 v4, 16, v4
	v_add3_u32 v5, v50, v5, s81
	v_and_or_b32 v4, v5, s71, v4
	s_waitcnt lgkmcnt(1)
	v_bfe_u32 v5, v52, 16, 1
	v_add3_u32 v5, v52, v5, s81
	s_waitcnt lgkmcnt(0)
	v_bfe_u32 v6, v54, 16, 1
	v_lshrrev_b32_e32 v5, 16, v5
	v_add3_u32 v6, v54, v6, s81
	v_and_or_b32 v5, v6, s71, v5
	v_mul_u32_u24_e32 v6, 0xb00, v42
	v_lshl_add_u64 v[0:1], v[18:19], 0, s[46:47]
	v_lshlrev_b32_e32 v96, 1, v6
	v_lshl_add_u64 v[42:43], v[0:1], 0, v[96:97]
	global_store_dwordx4 v[42:43], v[2:5], off sc0 sc1
	v_bfe_u32 v6, v55, 16, 1
	v_add3_u32 v6, v55, v6, s81
	v_bfe_u32 v2, v31, 16, 1
	v_add3_u32 v2, v31, v2, s81
	v_bfe_u32 v3, v7, 16, 1
	v_lshrrev_b32_e32 v2, 16, v2
	v_add3_u32 v3, v7, v3, s81
	v_and_or_b32 v2, v3, s71, v2
	v_bfe_u32 v3, v45, 16, 1
	v_add3_u32 v3, v45, v3, s81
	v_bfe_u32 v4, v47, 16, 1
	v_lshrrev_b32_e32 v3, 16, v3
	v_add3_u32 v4, v47, v4, s81
	v_and_or_b32 v3, v4, s71, v3
	v_bfe_u32 v4, v49, 16, 1
	v_add3_u32 v4, v49, v4, s81
	v_bfe_u32 v5, v51, 16, 1
	v_lshrrev_b32_e32 v4, 16, v4
	v_add3_u32 v5, v51, v5, s81
	v_and_or_b32 v4, v5, s71, v4
	v_bfe_u32 v5, v53, 16, 1
	v_add3_u32 v5, v53, v5, s81
	v_lshrrev_b32_e32 v5, 16, v5
	v_and_or_b32 v5, v6, s71, v5
	v_mul_u32_u24_e32 v6, 0xb00, v41
	v_lshlrev_b32_e32 v96, 1, v6
	v_lshl_add_u64 v[6:7], v[0:1], 0, v[96:97]
	global_store_dwordx4 v[6:7], v[2:5], off sc0 sc1
	ds_read2_b32 v[6:7], v37 offset0:16 offset1:24
	ds_read2_b32 v[30:31], v37 offset0:49 offset1:57
	ds_read2_b32 v[42:43], v37 offset0:82 offset1:90
	ds_read2_b32 v[44:45], v37 offset0:115 offset1:123
	ds_read2_b32 v[46:47], v37 offset0:148 offset1:156
	ds_read2_b32 v[48:49], v37 offset0:181 offset1:189
	ds_read2_b32 v[50:51], v37 offset0:214 offset1:222
	ds_read2_b32 v[52:53], v37 offset0:247 offset1:255
	s_waitcnt lgkmcnt(7)
	v_bfe_u32 v2, v6, 16, 1
	v_add3_u32 v2, v6, v2, s81
	s_waitcnt lgkmcnt(6)
	v_bfe_u32 v3, v30, 16, 1
	v_lshrrev_b32_e32 v2, 16, v2
	v_add3_u32 v3, v30, v3, s81
	v_and_or_b32 v2, v3, s71, v2
	s_waitcnt lgkmcnt(5)
	v_bfe_u32 v3, v42, 16, 1
	v_add3_u32 v3, v42, v3, s81
	s_waitcnt lgkmcnt(4)
	v_bfe_u32 v4, v44, 16, 1
	v_lshrrev_b32_e32 v3, 16, v3
	v_add3_u32 v4, v44, v4, s81
	v_and_or_b32 v3, v4, s71, v3
	s_waitcnt lgkmcnt(3)
	v_bfe_u32 v4, v46, 16, 1
	v_add3_u32 v4, v46, v4, s81
	s_waitcnt lgkmcnt(2)
	v_bfe_u32 v5, v48, 16, 1
	v_lshrrev_b32_e32 v4, 16, v4
	v_add3_u32 v5, v48, v5, s81
	v_and_or_b32 v4, v5, s71, v4
	s_waitcnt lgkmcnt(1)
	v_bfe_u32 v5, v50, 16, 1
	v_add3_u32 v5, v50, v5, s81
	s_waitcnt lgkmcnt(0)
	v_bfe_u32 v6, v52, 16, 1
	v_lshrrev_b32_e32 v5, 16, v5
	v_add3_u32 v6, v52, v6, s81
	v_and_or_b32 v5, v6, s71, v5
	v_mul_u32_u24_e32 v6, 0xb00, v33
	v_lshlrev_b32_e32 v96, 1, v6
	v_lshl_add_u64 v[54:55], v[0:1], 0, v[96:97]
	global_store_dwordx4 v[54:55], v[2:5], off sc0 sc1
	v_bfe_u32 v6, v53, 16, 1
	v_add3_u32 v6, v53, v6, s81
	v_bfe_u32 v2, v7, 16, 1
	v_add3_u32 v2, v7, v2, s81
	v_bfe_u32 v3, v31, 16, 1
	v_lshrrev_b32_e32 v2, 16, v2
	v_add3_u32 v3, v31, v3, s81
	v_and_or_b32 v2, v3, s71, v2
	v_bfe_u32 v3, v43, 16, 1
	v_add3_u32 v3, v43, v3, s81
	v_bfe_u32 v4, v45, 16, 1
	v_lshrrev_b32_e32 v3, 16, v3
	v_add3_u32 v4, v45, v4, s81
	v_and_or_b32 v3, v4, s71, v3
	v_bfe_u32 v4, v47, 16, 1
	v_add3_u32 v4, v47, v4, s81
	v_bfe_u32 v5, v49, 16, 1
	v_lshrrev_b32_e32 v4, 16, v4
	v_add3_u32 v5, v49, v5, s81
	v_and_or_b32 v4, v5, s71, v4
	v_bfe_u32 v5, v51, 16, 1
	v_add3_u32 v5, v51, v5, s81
	v_lshrrev_b32_e32 v5, 16, v5
	v_and_or_b32 v5, v6, s71, v5
	v_mul_u32_u24_e32 v6, 0xb00, v32
	v_lshlrev_b32_e32 v96, 1, v6
	v_lshl_add_u64 v[0:1], v[0:1], 0, v[96:97]
	global_store_dwordx4 v[0:1], v[2:5], off sc0 sc1
	s_waitcnt lgkmcnt(0)

.LBB0_439:
	s_andn2_b64 vcc, exec, s[0:1]
	s_cbranch_vccnz .LBB0_441
	s_add_i32 s0, s42, 0xfc00
	s_and_b32 s1, s0, 0xffff
	s_mul_i32 s1, s1, 0xba2f
	s_lshr_b32 s1, s1, 23
	s_mul_i32 s34, s1, 0xb0
	s_sub_i32 s35, s0, s34
	s_and_b32 s0, s35, 0xffff
	s_bfe_i32 s40, s35, 0x10002
	s_lshl_b32 s35, s35, 4
	s_lshl_b32 s34, s1, 6
	s_lshl_b32 s0, s0, 5
	s_and_b32 s40, s40, 0xb00
	s_and_b32 s35, s35, 0xf80
	s_add_i32 s40, s40, s35
	s_and_b32 s35, s0, 0x60
	v_or_b32_e32 v0, s34, v9
	s_or_b32 s35, s40, s35
	v_mul_u32_u24_e32 v0, 0x1600, v0
	v_readlane_b32 s40, v235, 8
	v_lshlrev_b32_e32 v96, 2, v0
	v_readlane_b32 s41, v235, 9
	s_lshl_b32 s46, s35, 2
	s_mov_b32 s35, 0xb000
	v_lshl_add_u64 v[0:1], s[40:41], 0, v[96:97]
	v_lshl_add_u64 v[0:1], v[0:1], 0, s[46:47]
	v_lshlrev_b32_e32 v96, 2, v8
	v_lshl_add_u64 v[0:1], v[0:1], 0, v[96:97]
	v_add_co_u32_e32 v2, vcc, s35, v0
	s_mov_b32 s35, 0x16000
	s_waitcnt lgkmcnt(0)
	v_addc_co_u32_e32 v3, vcc, 0, v1, vcc
	global_load_dword v4, v[0:1], off
	global_load_dword v5, v[2:3], off
	v_add_co_u32_e32 v2, vcc, s35, v0
	s_mov_b32 s35, 0x21000
	s_nop 0
	v_addc_co_u32_e32 v3, vcc, 0, v1, vcc
	global_load_dword v6, v[2:3], off
	v_add_co_u32_e32 v2, vcc, s35, v0
	s_mov_b32 s35, 0x2c000
	s_nop 0
	v_addc_co_u32_e32 v3, vcc, 0, v1, vcc
	global_load_dword v7, v[2:3], off
	v_add_co_u32_e32 v2, vcc, s35, v0
	s_mov_b32 s35, 0x37000
	s_nop 0
	v_addc_co_u32_e32 v3, vcc, 0, v1, vcc
	global_load_dword v30, v[2:3], off
	v_add_co_u32_e32 v2, vcc, s35, v0
	s_mov_b32 s35, 0x42000
	s_nop 0
	v_addc_co_u32_e32 v3, vcc, 0, v1, vcc
	global_load_dword v31, v[2:3], off
	v_add_co_u32_e32 v2, vcc, s35, v0
	s_mov_b32 s35, 0x4d000
	s_nop 0
	v_addc_co_u32_e32 v3, vcc, 0, v1, vcc
	global_load_dword v32, v[2:3], off
	v_add_co_u32_e32 v2, vcc, s35, v0
	s_mov_b32 s35, 0x58000
	s_nop 0
	v_addc_co_u32_e32 v3, vcc, 0, v1, vcc
	global_load_dword v33, v[2:3], off
	v_add_co_u32_e32 v2, vcc, s35, v0
	s_mov_b32 s35, 0x63000
	s_nop 0
	v_addc_co_u32_e32 v3, vcc, 0, v1, vcc
	global_load_dword v41, v[2:3], off
	v_add_co_u32_e32 v2, vcc, s35, v0
	s_mov_b32 s35, 0x6e000
	s_nop 0
	v_addc_co_u32_e32 v3, vcc, 0, v1, vcc
	global_load_dword v42, v[2:3], off
	v_add_co_u32_e32 v2, vcc, s35, v0
	s_mov_b32 s35, 0x79000
	s_nop 0
	v_addc_co_u32_e32 v3, vcc, 0, v1, vcc
	global_load_dword v43, v[2:3], off
	v_add_co_u32_e32 v2, vcc, s35, v0
	s_mov_b32 s35, 0x84000
	s_nop 0
	v_addc_co_u32_e32 v3, vcc, 0, v1, vcc
	global_load_dword v44, v[2:3], off
	v_add_co_u32_e32 v2, vcc, s35, v0
	s_mov_b32 s35, 0x8f000
	s_nop 0
	v_addc_co_u32_e32 v3, vcc, 0, v1, vcc
	global_load_dword v45, v[2:3], off
	v_add_co_u32_e32 v2, vcc, s35, v0
	s_mov_b32 s35, 0x9a000
	s_nop 0
	v_addc_co_u32_e32 v3, vcc, 0, v1, vcc
	global_load_dword v46, v[2:3], off
	v_add_co_u32_e32 v2, vcc, s35, v0
	s_mov_b32 s35, 0xa5000
	s_nop 0
	v_addc_co_u32_e32 v3, vcc, 0, v1, vcc
	global_load_dword v47, v[2:3], off
	v_add_co_u32_e32 v2, vcc, s35, v0
	s_mov_b32 s35, 0xb0000
	s_nop 0
	v_addc_co_u32_e32 v3, vcc, 0, v1, vcc
	global_load_dword v48, v[2:3], off
	v_add_co_u32_e32 v2, vcc, s35, v0
	s_mov_b32 s35, 0xbb000
	s_nop 0
	v_addc_co_u32_e32 v3, vcc, 0, v1, vcc
	global_load_dword v49, v[2:3], off
	v_add_co_u32_e32 v2, vcc, s35, v0
	s_mov_b32 s35, 0xc6000
	s_nop 0
	v_addc_co_u32_e32 v3, vcc, 0, v1, vcc
	global_load_dword v50, v[2:3], off
	v_add_co_u32_e32 v2, vcc, s35, v0
	s_mov_b32 s35, 0xd1000
	s_nop 0
	v_addc_co_u32_e32 v3, vcc, 0, v1, vcc
	global_load_dword v51, v[2:3], off
	v_add_co_u32_e32 v2, vcc, s35, v0
	s_mov_b32 s35, 0xdc000
	s_nop 0
	v_addc_co_u32_e32 v3, vcc, 0, v1, vcc
	global_load_dword v52, v[2:3], off
	v_add_co_u32_e32 v2, vcc, s35, v0
	s_mov_b32 s35, 0xe7000
	s_nop 0
	v_addc_co_u32_e32 v3, vcc, 0, v1, vcc
	global_load_dword v53, v[2:3], off
	v_add_co_u32_e32 v2, vcc, s35, v0
	s_mov_b32 s35, 0xf2000
	s_nop 0
	v_addc_co_u32_e32 v3, vcc, 0, v1, vcc
	global_load_dword v54, v[2:3], off
	v_add_co_u32_e32 v2, vcc, s35, v0
	s_mov_b32 s35, 0xfd000
	s_nop 0
	v_addc_co_u32_e32 v3, vcc, 0, v1, vcc
	global_load_dword v55, v[2:3], off
	v_add_co_u32_e32 v2, vcc, s35, v0
	s_mov_b32 s35, 0x108000
	s_nop 0
	v_addc_co_u32_e32 v3, vcc, 0, v1, vcc
	global_load_dword v56, v[2:3], off
	v_add_co_u32_e32 v2, vcc, s35, v0
	s_mov_b32 s35, 0x113000
	s_nop 0
	v_addc_co_u32_e32 v3, vcc, 0, v1, vcc
	global_load_dword v57, v[2:3], off
	v_add_co_u32_e32 v2, vcc, s35, v0
	s_mov_b32 s35, 0x11e000
	s_nop 0
	v_addc_co_u32_e32 v3, vcc, 0, v1, vcc
	global_load_dword v58, v[2:3], off
	v_add_co_u32_e32 v2, vcc, s35, v0
	s_mov_b32 s35, 0x129000
	s_nop 0
	v_addc_co_u32_e32 v3, vcc, 0, v1, vcc
	global_load_dword v59, v[2:3], off
	v_add_co_u32_e32 v2, vcc, s35, v0
	s_mov_b32 s35, 0x134000
	s_nop 0
	v_addc_co_u32_e32 v3, vcc, 0, v1, vcc
	global_load_dword v60, v[2:3], off
	v_add_co_u32_e32 v2, vcc, s35, v0
	s_mov_b32 s35, 0x13f000
	s_nop 0
	v_addc_co_u32_e32 v3, vcc, 0, v1, vcc
	global_load_dword v61, v[2:3], off
	v_add_co_u32_e32 v2, vcc, s35, v0
	s_mov_b32 s35, 0x14a000
	s_nop 0
	v_addc_co_u32_e32 v3, vcc, 0, v1, vcc
	global_load_dword v62, v[2:3], off
	v_add_co_u32_e32 v2, vcc, s35, v0
	s_mov_b32 s35, 0x155000
	s_nop 0
	v_addc_co_u32_e32 v3, vcc, 0, v1, vcc
	v_add_co_u32_e32 v0, vcc, s35, v0
	global_load_dword v2, v[2:3], off
	s_nop 0
	v_addc_co_u32_e32 v1, vcc, 0, v1, vcc
	global_load_dword v0, v[0:1], off
	v_or_b32_e32 v1, s34, v34
	v_lshlrev_b32_e32 v63, 2, v1
	v_add_u32_e32 v1, 0x400, v35
	s_waitcnt vmcnt(0)
	ds_write2_b32 v35, v4, v5 offset1:66
	ds_write2_b32 v35, v6, v7 offset0:132 offset1:198
	ds_write2_b32 v1, v30, v31 offset0:8 offset1:74
	ds_write2_b32 v1, v32, v33 offset0:140 offset1:206
	v_add_u32_e32 v1, 0x800, v35
	ds_write2_b32 v1, v41, v42 offset0:16 offset1:82
	ds_write2_b32 v1, v43, v44 offset0:148 offset1:214
	v_add_u32_e32 v1, 0xc00, v35
	ds_write2_b32 v1, v45, v46 offset0:24 offset1:90
	ds_write2_b32 v1, v47, v48 offset0:156 offset1:222
	v_add_u32_e32 v1, 0x1000, v35
	ds_write2_b32 v1, v49, v50 offset0:32 offset1:98
	ds_write2_b32 v1, v51, v52 offset0:164 offset1:230
	v_add_u32_e32 v1, 0x1400, v35
	ds_write2_b32 v1, v53, v54 offset0:40 offset1:106
	ds_write2_b32 v1, v55, v56 offset0:172 offset1:238
	v_add_u32_e32 v1, 0x1800, v35
	ds_write2_b32 v1, v57, v58 offset0:48 offset1:114
	ds_write2_b32 v1, v59, v60 offset0:180 offset1:246
	v_add_u32_e32 v1, 0x1c00, v35
	v_readlane_b32 s34, v235, 10
	ds_write2_b32 v1, v61, v62 offset0:56 offset1:122
	ds_write2_b32 v1, v2, v0 offset0:188 offset1:254
	v_readlane_b32 s35, v235, 11
	s_nop 4
	global_load_dwordx4 v[0:3], v63, s[34:35] offset:16
	global_load_dwordx4 v[4:7], v63, s[34:35]
	s_waitcnt lgkmcnt(0)
	s_lshl_b32 s46, s1, 7
	v_lshl_add_u64 v[30:31], v[20:21], 0, s[46:47]
	s_waitcnt vmcnt(1)
	v_mov_b32_e32 v58, v0
	s_waitcnt vmcnt(0)
	v_mov_b32_e32 v32, v4
	v_mov_b32_e32 v33, v6
	v_mov_b32_e32 v6, v5
	ds_read2_b32 v[4:5], v37 offset0:33 offset1:41
	ds_read2_b32 v[46:47], v37 offset0:66 offset1:74
	ds_read2_b32 v[48:49], v37 offset1:8
	ds_read2_b32 v[50:51], v37 offset0:99 offset1:107
	ds_read2_b32 v[52:53], v37 offset0:132 offset1:140
	ds_read2_b32 v[54:55], v37 offset0:165 offset1:173
	ds_read2_b32 v[56:57], v37 offset0:198 offset1:206
	ds_read2_b32 v[62:63], v37 offset0:231 offset1:239
	s_waitcnt lgkmcnt(7)
	v_mov_b32_e32 v44, v4
	v_mov_b32_e32 v59, v2
	s_waitcnt lgkmcnt(4)
	v_mov_b32_e32 v45, v50
	v_pk_mul_f32 v[44:45], v[6:7], v[44:45]
	s_waitcnt lgkmcnt(3)
	v_mov_b32_e32 v60, v52
	s_waitcnt lgkmcnt(1)
	v_mov_b32_e32 v61, v56
	v_mov_b32_e32 v2, v1
	v_mov_b32_e32 v0, v54
	s_waitcnt lgkmcnt(0)
	v_mov_b32_e32 v1, v62
	v_mov_b32_e32 v42, v48
	v_mov_b32_e32 v43, v46
	v_pk_mul_f32 v[60:61], v[58:59], v[60:61]
	v_pk_mul_f32 v[0:1], v[2:3], v[0:1]
	v_bfe_u32 v48, v44, 16, 1
	v_pk_mul_f32 v[42:43], v[32:33], v[42:43]
	v_bfe_u32 v4, v1, 16, 1
	v_add3_u32 v48, v44, v48, s81
	v_bfe_u32 v44, v60, 16, 1
	v_bfe_u32 v41, v0, 16, 1
	v_bfe_u32 v46, v45, 16, 1
	v_add3_u32 v1, v1, v4, s81
	v_bfe_u32 v4, v42, 16, 1
	v_add3_u32 v44, v60, v44, s81
	v_add3_u32 v46, v45, v46, s81
	v_add3_u32 v0, v0, v41, s81
	v_bfe_u32 v41, v43, 16, 1
	v_bfe_u32 v45, v61, 16, 1
	v_add3_u32 v4, v42, v4, s81
	v_lshrrev_b32_e32 v42, 16, v44
	v_add3_u32 v45, v61, v45, s81
	v_add3_u32 v41, v43, v41, s81
	v_and_or_b32 v44, v0, s71, v42
	v_or_b32_e32 v0, s0, v36
	v_lshrrev_b32_e32 v4, 16, v4
	v_lshrrev_b32_e32 v41, 16, v41
	v_lshrrev_b32_e32 v43, 16, v45
	v_lshlrev_b32_e32 v96, 11, v0
	v_and_or_b32 v45, v1, s71, v43
	v_and_or_b32 v43, v46, s71, v41
	v_and_or_b32 v42, v48, s71, v4
	v_lshl_add_u64 v[0:1], v[30:31], 0, v[96:97]
	v_mov_b32_e32 v50, v5
	v_mov_b32_e32 v62, v55
	global_store_dwordx4 v[0:1], v[42:45], off sc0 sc1
	v_mov_b32_e32 v46, v49
	v_pk_mul_f32 v[4:5], v[6:7], v[50:51]
	v_mov_b32_e32 v56, v53
	v_pk_mul_f32 v[44:45], v[2:3], v[62:63]
	v_pk_mul_f32 v[0:1], v[32:33], v[46:47]
	v_pk_mul_f32 v[42:43], v[58:59], v[56:57]
	v_bfe_u32 v41, v45, 16, 1
	v_bfe_u32 v47, v5, 16, 1
	v_add3_u32 v5, v5, v47, s81
	v_add3_u32 v41, v45, v41, s81
	v_bfe_u32 v45, v0, 16, 1
	v_bfe_u32 v47, v42, 16, 1
	v_bfe_u32 v46, v44, 16, 1
	v_bfe_u32 v48, v4, 16, 1
	v_add3_u32 v42, v42, v47, s81
	v_add3_u32 v0, v0, v45, s81
	v_add3_u32 v4, v4, v48, s81
	v_add3_u32 v44, v44, v46, s81
	v_bfe_u32 v46, v1, 16, 1
	v_bfe_u32 v48, v43, 16, 1
	v_lshrrev_b32_e32 v0, 16, v0
	v_lshrrev_b32_e32 v42, 16, v42
	v_add3_u32 v43, v43, v48, s81
	v_add3_u32 v1, v1, v46, s81
	v_and_or_b32 v44, v44, s71, v42
	v_and_or_b32 v42, v4, s71, v0
	v_or_b32_e32 v0, s0, v38
	v_lshrrev_b32_e32 v1, 16, v1
	v_lshrrev_b32_e32 v43, 16, v43
	v_lshlrev_b32_e32 v96, 11, v0
	v_and_or_b32 v45, v41, s71, v43
	v_and_or_b32 v43, v5, s71, v1
	v_lshl_add_u64 v[0:1], v[30:31], 0, v[96:97]
	global_store_dwordx4 v[0:1], v[42:45], off sc0 sc1
	ds_read2_b32 v[0:1], v37 offset0:49 offset1:57
	ds_read2_b32 v[4:5], v37 offset0:82 offset1:90
	ds_read2_b32 v[46:47], v37 offset0:115 offset1:123
	ds_read2_b32 v[48:49], v37 offset0:16 offset1:24
	ds_read2_b32 v[50:51], v37 offset0:148 offset1:156
	ds_read2_b32 v[52:53], v37 offset0:181 offset1:189
	ds_read2_b32 v[54:55], v37 offset0:214 offset1:222
	ds_read2_b32 v[56:57], v37 offset0:247 offset1:255
	s_waitcnt lgkmcnt(7)
	v_mov_b32_e32 v44, v0
	s_waitcnt lgkmcnt(3)
	v_mov_b32_e32 v60, v50
	v_mov_b32_e32 v45, v46
	s_waitcnt lgkmcnt(1)
	v_mov_b32_e32 v61, v54
	v_mov_b32_e32 v42, v48
	v_mov_b32_e32 v43, v4
	v_pk_mul_f32 v[44:45], v[6:7], v[44:45]
	v_pk_mul_f32 v[60:61], v[58:59], v[60:61]
	v_mov_b32_e32 v62, v52
	s_waitcnt lgkmcnt(0)
	v_mov_b32_e32 v63, v56
	v_pk_mul_f32 v[42:43], v[32:33], v[42:43]
	v_pk_mul_f32 v[62:63], v[2:3], v[62:63]
	v_bfe_u32 v41, v45, 16, 1
	v_bfe_u32 v46, v44, 16, 1
	v_bfe_u32 v48, v60, 16, 1
	v_bfe_u32 v50, v61, 16, 1
	v_bfe_u32 v0, v63, 16, 1
	v_bfe_u32 v4, v62, 16, 1
	v_add3_u32 v46, v44, v46, s81
	v_add3_u32 v41, v45, v41, s81
	v_bfe_u32 v44, v42, 16, 1
	v_bfe_u32 v45, v43, 16, 1
	v_add3_u32 v50, v61, v50, s81
	v_add3_u32 v48, v60, v48, s81
	v_add3_u32 v4, v62, v4, s81
	v_add3_u32 v0, v63, v0, s81
	v_add3_u32 v43, v43, v45, s81
	v_add3_u32 v42, v42, v44, s81
	v_lshrrev_b32_e32 v44, 16, v48
	v_lshrrev_b32_e32 v45, 16, v50
	v_mov_b32_e32 v56, v53
	v_lshrrev_b32_e32 v42, 16, v42
	v_and_or_b32 v45, v0, s71, v45
	v_and_or_b32 v44, v4, s71, v44
	v_or_b32_e32 v0, s0, v39
	v_mov_b32_e32 v4, v49
	v_pk_mul_f32 v[2:3], v[2:3], v[56:57]
	v_lshrrev_b32_e32 v43, 16, v43
	v_and_or_b32 v42, v46, s71, v42
	v_lshlrev_b32_e32 v96, 11, v0
	v_pk_mul_f32 v[4:5], v[32:33], v[4:5]
	v_mov_b32_e32 v46, v1
	v_bfe_u32 v32, v3, 16, 1
	v_and_or_b32 v43, v41, s71, v43
	v_lshl_add_u64 v[60:61], v[30:31], 0, v[96:97]
	v_pk_mul_f32 v[0:1], v[6:7], v[46:47]
	v_mov_b32_e32 v54, v51
	v_add3_u32 v3, v3, v32, s81
	v_bfe_u32 v32, v4, 16, 1
	global_store_dwordx4 v[60:61], v[42:45], off sc0 sc1
	v_pk_mul_f32 v[6:7], v[58:59], v[54:55]
	v_bfe_u32 v33, v2, 16, 1
	v_bfe_u32 v41, v1, 16, 1
	v_bfe_u32 v42, v0, 16, 1
	v_add3_u32 v4, v4, v32, s81
	v_add3_u32 v0, v0, v42, s81
	v_add3_u32 v1, v1, v41, s81
	v_add3_u32 v2, v2, v33, s81
	v_bfe_u32 v33, v5, 16, 1
	v_bfe_u32 v41, v6, 16, 1
	v_bfe_u32 v42, v7, 16, 1
	v_lshrrev_b32_e32 v4, 16, v4
	v_add3_u32 v7, v7, v42, s81
	v_add3_u32 v6, v6, v41, s81
	v_add3_u32 v5, v5, v33, s81
	v_and_or_b32 v0, v0, s71, v4
	v_or_b32_e32 v4, s0, v40
	v_lshrrev_b32_e32 v5, 16, v5
	v_lshrrev_b32_e32 v6, 16, v6
	v_lshrrev_b32_e32 v7, 16, v7
	v_lshlrev_b32_e32 v96, 11, v4
	v_and_or_b32 v3, v3, s71, v7
	v_and_or_b32 v2, v2, s71, v6
	v_and_or_b32 v1, v1, s71, v5
	v_lshl_add_u64 v[4:5], v[30:31], 0, v[96:97]
	global_store_dwordx4 v[4:5], v[0:3], off sc0 sc1
	s_waitcnt lgkmcnt(0)

.LBB0_459:
	s_waitcnt vmcnt(0)
	ds_write2_b32 v35, v30, v31 offset1:66
	ds_write2_b32 v35, v32, v33 offset0:132 offset1:198
	v_add_u32_e32 v30, 0x400, v35
	ds_write2_b32 v30, v41, v42 offset0:8 offset1:74
	ds_write2_b32 v30, v43, v44 offset0:140 offset1:206
	v_add_u32_e32 v30, 0x800, v35
	ds_write2_b32 v30, v45, v46 offset0:16 offset1:82
	ds_write2_b32 v30, v47, v48 offset0:148 offset1:214
	v_add_u32_e32 v30, 0xc00, v35
	ds_write2_b32 v30, v49, v50 offset0:24 offset1:90
	ds_write2_b32 v30, v51, v52 offset0:156 offset1:222
	v_add_u32_e32 v30, 0x1000, v35
	ds_write2_b32 v30, v53, v54 offset0:32 offset1:98
	ds_write2_b32 v30, v55, v56 offset0:164 offset1:230
	v_add_u32_e32 v30, 0x1400, v35
	ds_write2_b32 v30, v57, v58 offset0:40 offset1:106
	ds_write2_b32 v30, v59, v60 offset0:172 offset1:238
	v_add_u32_e32 v30, 0x1800, v35
	ds_write2_b32 v30, v61, v62 offset0:48 offset1:114
	ds_write2_b32 v30, v63, v64 offset0:180 offset1:246
	v_add_u32_e32 v30, 0x1c00, v35
	ds_write2_b32 v30, v65, v66 offset0:56 offset1:122
	ds_write2_b32 v30, v67, v68 offset0:188 offset1:254
	s_waitcnt lgkmcnt(0)
	ds_read2_b32 v[42:43], v37 offset1:8
	ds_read2_b32 v[44:45], v37 offset0:66 offset1:74
	ds_read2_b32 v[48:49], v37 offset0:33 offset1:41
	ds_read2_b32 v[50:51], v37 offset0:99 offset1:107
	ds_read2_b32 v[52:53], v37 offset0:132 offset1:140
	ds_read2_b32 v[54:55], v37 offset0:198 offset1:206
	ds_read2_b32 v[56:57], v37 offset0:165 offset1:173
	ds_read2_b32 v[58:59], v37 offset0:231 offset1:239
	s_waitcnt lgkmcnt(7)
	v_mov_b32_e32 v30, v42
	s_waitcnt lgkmcnt(5)
	v_mov_b32_e32 v32, v48
	s_waitcnt lgkmcnt(4)
	v_mov_b32_e32 v33, v50
	s_waitcnt lgkmcnt(3)
	v_mov_b32_e32 v60, v52
	s_waitcnt lgkmcnt(2)
	v_mov_b32_e32 v61, v54
	s_waitcnt lgkmcnt(1)
	v_mov_b32_e32 v62, v56
	s_waitcnt lgkmcnt(0)
	v_mov_b32_e32 v63, v58
	v_mov_b32_e32 v31, v44
	v_pk_mul_f32 v[32:33], v[0:1], v[32:33]
	v_pk_mul_f32 v[60:61], v[6:7], v[60:61]
	v_pk_mul_f32 v[62:63], v[4:5], v[62:63]
	v_pk_mul_f32 v[30:31], v[2:3], v[30:31]
	v_bfe_u32 v41, v63, 16, 1
	v_bfe_u32 v44, v33, 16, 1
	v_bfe_u32 v50, v60, 16, 1
	v_bfe_u32 v42, v62, 16, 1
	v_bfe_u32 v48, v32, 16, 1
	v_add3_u32 v44, v33, v44, s81
	v_add3_u32 v33, v63, v41, s81
	v_bfe_u32 v41, v30, 16, 1
	v_add3_u32 v50, v60, v50, s81
	v_add3_u32 v48, v32, v48, s81
	v_add3_u32 v32, v62, v42, s81
	v_bfe_u32 v42, v31, 16, 1
	v_bfe_u32 v52, v61, 16, 1
	v_add3_u32 v30, v30, v41, s81
	v_lshrrev_b32_e32 v41, 16, v50
	s_lshl_b32 s46, s35, 1
	v_add3_u32 v52, v61, v52, s81
	v_add3_u32 v31, v31, v42, s81
	v_and_or_b32 v32, v32, s71, v41
	v_or_b32_e32 v41, s34, v36
	v_lshl_add_u64 v[46:47], v[22:23], 0, s[46:47]
	v_lshrrev_b32_e32 v30, 16, v30
	v_lshrrev_b32_e32 v31, 16, v31
	v_lshrrev_b32_e32 v42, 16, v52
	v_lshlrev_b32_e32 v96, 11, v41
	v_and_or_b32 v33, v33, s71, v42
	v_and_or_b32 v31, v44, s71, v31
	v_and_or_b32 v30, v48, s71, v30
	v_lshl_add_u64 v[60:61], v[46:47], 0, v[96:97]
	v_mov_b32_e32 v44, v43
	v_mov_b32_e32 v50, v49
	v_mov_b32_e32 v58, v57
	global_store_dwordx4 v[60:61], v[30:33], off sc0 sc1
	v_mov_b32_e32 v54, v53
	v_pk_mul_f32 v[42:43], v[6:7], v[54:55]
	v_pk_mul_f32 v[30:31], v[2:3], v[44:45]
	v_pk_mul_f32 v[32:33], v[0:1], v[50:51]
	v_pk_mul_f32 v[44:45], v[4:5], v[58:59]
	v_bfe_u32 v49, v33, 16, 1
	v_bfe_u32 v41, v45, 16, 1
	v_add3_u32 v49, v33, v49, s81
	v_add3_u32 v33, v45, v41, s81
	v_bfe_u32 v45, v42, 16, 1
	v_bfe_u32 v48, v44, 16, 1
	v_bfe_u32 v50, v32, 16, 1
	v_bfe_u32 v41, v30, 16, 1
	v_add3_u32 v42, v42, v45, s81
	v_add3_u32 v50, v32, v50, s81
	v_add3_u32 v32, v44, v48, s81
	v_bfe_u32 v44, v31, 16, 1
	v_bfe_u32 v48, v43, 16, 1
	v_add3_u32 v30, v30, v41, s81
	v_lshrrev_b32_e32 v41, 16, v42
	v_add3_u32 v43, v43, v48, s81
	v_add3_u32 v31, v31, v44, s81
	v_and_or_b32 v32, v32, s71, v41
	v_or_b32_e32 v41, s34, v38
	v_lshrrev_b32_e32 v30, 16, v30
	v_lshrrev_b32_e32 v31, 16, v31
	v_lshrrev_b32_e32 v42, 16, v43
	v_lshlrev_b32_e32 v96, 11, v41
	v_and_or_b32 v33, v33, s71, v42
	v_and_or_b32 v31, v49, s71, v31
	v_and_or_b32 v30, v50, s71, v30
	v_lshl_add_u64 v[42:43], v[46:47], 0, v[96:97]
	ds_read2_b32 v[44:45], v37 offset0:16 offset1:24
	ds_read2_b32 v[48:49], v37 offset0:82 offset1:90
	global_store_dwordx4 v[42:43], v[30:33], off sc0 sc1
	ds_read2_b32 v[42:43], v37 offset0:49 offset1:57
	ds_read2_b32 v[50:51], v37 offset0:115 offset1:123
	ds_read2_b32 v[52:53], v37 offset0:148 offset1:156
	ds_read2_b32 v[54:55], v37 offset0:214 offset1:222
	ds_read2_b32 v[56:57], v37 offset0:181 offset1:189
	ds_read2_b32 v[58:59], v37 offset0:247 offset1:255
	s_waitcnt lgkmcnt(7)
	v_mov_b32_e32 v30, v44
	s_waitcnt lgkmcnt(5)
	v_mov_b32_e32 v32, v42
	s_waitcnt lgkmcnt(4)
	v_mov_b32_e32 v33, v50
	s_waitcnt lgkmcnt(3)
	v_mov_b32_e32 v60, v52
	s_waitcnt lgkmcnt(2)
	v_mov_b32_e32 v61, v54
	s_waitcnt lgkmcnt(1)
	v_mov_b32_e32 v62, v56
	s_waitcnt lgkmcnt(0)
	v_mov_b32_e32 v63, v58
	v_mov_b32_e32 v31, v48
	v_pk_mul_f32 v[32:33], v[0:1], v[32:33]
	v_pk_mul_f32 v[60:61], v[6:7], v[60:61]
	v_pk_mul_f32 v[62:63], v[4:5], v[62:63]
	v_pk_mul_f32 v[30:31], v[2:3], v[30:31]
	v_bfe_u32 v41, v63, 16, 1
	v_bfe_u32 v44, v33, 16, 1
	v_bfe_u32 v50, v60, 16, 1
	v_bfe_u32 v42, v62, 16, 1
	v_bfe_u32 v48, v32, 16, 1
	v_add3_u32 v44, v33, v44, s81
	v_add3_u32 v33, v63, v41, s81
	v_bfe_u32 v41, v30, 16, 1
	v_add3_u32 v50, v60, v50, s81
	v_add3_u32 v48, v32, v48, s81
	v_add3_u32 v32, v62, v42, s81
	v_bfe_u32 v42, v31, 16, 1
	v_bfe_u32 v52, v61, 16, 1
	v_add3_u32 v30, v30, v41, s81
	v_lshrrev_b32_e32 v41, 16, v50
	v_add3_u32 v52, v61, v52, s81
	v_add3_u32 v31, v31, v42, s81
	v_and_or_b32 v32, v32, s71, v41
	v_or_b32_e32 v41, s34, v39
	v_lshrrev_b32_e32 v30, 16, v30
	v_lshrrev_b32_e32 v31, 16, v31
	v_lshrrev_b32_e32 v42, 16, v52
	v_lshlrev_b32_e32 v96, 11, v41
	v_mov_b32_e32 v50, v43
	v_mov_b32_e32 v58, v57
	v_and_or_b32 v33, v33, s71, v42
	v_and_or_b32 v31, v44, s71, v31
	v_and_or_b32 v30, v48, s71, v30
	v_lshl_add_u64 v[60:61], v[46:47], 0, v[96:97]
	v_mov_b32_e32 v48, v45
	v_pk_mul_f32 v[0:1], v[0:1], v[50:51]
	v_mov_b32_e32 v54, v53
	v_pk_mul_f32 v[4:5], v[4:5], v[58:59]
	global_store_dwordx4 v[60:61], v[30:33], off sc0 sc1
	v_pk_mul_f32 v[2:3], v[2:3], v[48:49]
	v_pk_mul_f32 v[6:7], v[6:7], v[54:55]
	v_bfe_u32 v30, v5, 16, 1
	v_bfe_u32 v32, v1, 16, 1
	v_add3_u32 v1, v1, v32, s81
	v_add3_u32 v5, v5, v30, s81
	v_bfe_u32 v30, v2, 16, 1
	v_bfe_u32 v32, v6, 16, 1
	v_bfe_u32 v31, v4, 16, 1
	v_bfe_u32 v33, v0, 16, 1
	v_add3_u32 v6, v6, v32, s81
	v_add3_u32 v2, v2, v30, s81
	v_add3_u32 v0, v0, v33, s81
	v_add3_u32 v4, v4, v31, s81
	v_bfe_u32 v31, v3, 16, 1
	v_bfe_u32 v33, v7, 16, 1
	v_lshrrev_b32_e32 v30, 16, v2
	v_lshrrev_b32_e32 v2, 16, v6
	v_add3_u32 v7, v7, v33, s81
	v_add3_u32 v3, v3, v31, s81
	v_and_or_b32 v2, v4, s71, v2
	v_or_b32_e32 v4, s34, v40
	v_lshrrev_b32_e32 v31, 16, v3
	v_lshrrev_b32_e32 v3, 16, v7
	v_lshlrev_b32_e32 v96, 11, v4
	v_and_or_b32 v3, v5, s71, v3
	v_and_or_b32 v1, v1, s71, v31
	v_and_or_b32 v0, v0, s71, v30
	v_lshl_add_u64 v[4:5], v[46:47], 0, v[96:97]
	global_store_dwordx4 v[4:5], v[0:3], off sc0 sc1
	s_waitcnt lgkmcnt(0)

.LBB0_478:
	s_waitcnt vmcnt(0)
	ds_write2_b32 v35, v30, v31 offset1:66
	ds_write2_b32 v35, v32, v33 offset0:132 offset1:198
	v_add_u32_e32 v30, 0x400, v35
	ds_write2_b32 v30, v41, v42 offset0:8 offset1:74
	ds_write2_b32 v30, v43, v44 offset0:140 offset1:206
	v_add_u32_e32 v30, 0x800, v35
	ds_write2_b32 v30, v45, v46 offset0:16 offset1:82
	ds_write2_b32 v30, v47, v48 offset0:148 offset1:214
	v_add_u32_e32 v30, 0xc00, v35
	ds_write2_b32 v30, v49, v50 offset0:24 offset1:90
	ds_write2_b32 v30, v51, v52 offset0:156 offset1:222
	v_add_u32_e32 v30, 0x1000, v35
	ds_write2_b32 v30, v53, v54 offset0:32 offset1:98
	ds_write2_b32 v30, v55, v56 offset0:164 offset1:230
	v_add_u32_e32 v30, 0x1400, v35
	ds_write2_b32 v30, v57, v58 offset0:40 offset1:106
	ds_write2_b32 v30, v59, v60 offset0:172 offset1:238
	v_add_u32_e32 v30, 0x1800, v35
	ds_write2_b32 v30, v61, v62 offset0:48 offset1:114
	ds_write2_b32 v30, v63, v64 offset0:180 offset1:246
	v_add_u32_e32 v30, 0x1c00, v35
	ds_write2_b32 v30, v65, v66 offset0:56 offset1:122
	ds_write2_b32 v30, v67, v68 offset0:188 offset1:254
	s_waitcnt lgkmcnt(0)
	ds_read2_b32 v[42:43], v37 offset1:8
	ds_read2_b32 v[44:45], v37 offset0:66 offset1:74
	ds_read2_b32 v[48:49], v37 offset0:33 offset1:41
	ds_read2_b32 v[50:51], v37 offset0:99 offset1:107
	ds_read2_b32 v[52:53], v37 offset0:132 offset1:140
	ds_read2_b32 v[54:55], v37 offset0:198 offset1:206
	ds_read2_b32 v[56:57], v37 offset0:165 offset1:173
	ds_read2_b32 v[58:59], v37 offset0:231 offset1:239
	s_waitcnt lgkmcnt(7)
	v_mov_b32_e32 v30, v42
	s_waitcnt lgkmcnt(5)
	v_mov_b32_e32 v32, v48
	s_waitcnt lgkmcnt(4)
	v_mov_b32_e32 v33, v50
	s_waitcnt lgkmcnt(3)
	v_mov_b32_e32 v60, v52
	s_waitcnt lgkmcnt(2)
	v_mov_b32_e32 v61, v54
	s_waitcnt lgkmcnt(1)
	v_mov_b32_e32 v62, v56
	s_waitcnt lgkmcnt(0)
	v_mov_b32_e32 v63, v58
	v_mov_b32_e32 v31, v44
	v_pk_mul_f32 v[32:33], v[0:1], v[32:33]
	v_pk_mul_f32 v[60:61], v[6:7], v[60:61]
	v_pk_mul_f32 v[62:63], v[4:5], v[62:63]
	v_pk_mul_f32 v[30:31], v[2:3], v[30:31]
	v_bfe_u32 v41, v63, 16, 1
	v_bfe_u32 v42, v62, 16, 1
	v_bfe_u32 v44, v33, 16, 1
	v_bfe_u32 v48, v32, 16, 1
	v_bfe_u32 v50, v60, 16, 1
	v_add3_u32 v48, v32, v48, s81
	v_add3_u32 v44, v33, v44, s81
	v_add3_u32 v32, v62, v42, s81
	v_add3_u32 v33, v63, v41, s81
	v_bfe_u32 v41, v30, 16, 1
	v_bfe_u32 v42, v31, 16, 1
	v_bfe_u32 v52, v61, 16, 1
	v_add3_u32 v50, v60, v50, s81
	v_or_b32_e32 v60, s34, v36
	s_ashr_i32 s41, s40, 31
	v_add3_u32 v52, v61, v52, s81
	v_add3_u32 v31, v31, v42, s81
	v_add3_u32 v30, v30, v41, s81
	v_ashrrev_i32_e32 v61, 31, v60
	v_lshl_add_u64 v[46:47], s[40:41], 1, v[24:25]
	v_lshrrev_b32_e32 v30, 16, v30
	v_lshrrev_b32_e32 v31, 16, v31
	v_lshrrev_b32_e32 v41, 16, v50
	v_lshrrev_b32_e32 v42, 16, v52
	v_lshlrev_b64 v[60:61], 11, v[60:61]
	v_and_or_b32 v33, v33, s71, v42
	v_and_or_b32 v32, v32, s71, v41
	v_and_or_b32 v31, v44, s71, v31
	v_and_or_b32 v30, v48, s71, v30
	v_lshl_add_u64 v[60:61], v[46:47], 0, v[60:61]
	v_mov_b32_e32 v44, v43
	v_mov_b32_e32 v50, v49
	v_mov_b32_e32 v58, v57
	global_store_dwordx4 v[60:61], v[30:33], off sc0 sc1
	v_mov_b32_e32 v54, v53
	v_pk_mul_f32 v[42:43], v[6:7], v[54:55]
	v_pk_mul_f32 v[30:31], v[2:3], v[44:45]
	v_pk_mul_f32 v[32:33], v[0:1], v[50:51]
	v_pk_mul_f32 v[44:45], v[4:5], v[58:59]
	v_bfe_u32 v49, v33, 16, 1
	v_bfe_u32 v41, v45, 16, 1
	v_bfe_u32 v48, v44, 16, 1
	v_bfe_u32 v50, v32, 16, 1
	v_add3_u32 v50, v32, v50, s81
	v_add3_u32 v49, v33, v49, s81
	v_add3_u32 v32, v44, v48, s81
	v_add3_u32 v33, v45, v41, s81
	v_bfe_u32 v45, v42, 16, 1
	v_bfe_u32 v48, v43, 16, 1
	v_bfe_u32 v41, v30, 16, 1
	v_add3_u32 v43, v43, v48, s81
	v_add3_u32 v42, v42, v45, s81
	v_add3_u32 v30, v30, v41, s81
	v_lshrrev_b32_e32 v41, 16, v42
	v_lshrrev_b32_e32 v42, 16, v43
	v_bfe_u32 v44, v31, 16, 1
	v_and_or_b32 v33, v33, s71, v42
	v_or_b32_e32 v42, s34, v38
	v_add3_u32 v31, v31, v44, s81
	v_ashrrev_i32_e32 v43, 31, v42
	v_lshrrev_b32_e32 v30, 16, v30
	v_lshrrev_b32_e32 v31, 16, v31
	v_lshlrev_b64 v[42:43], 11, v[42:43]
	v_and_or_b32 v32, v32, s71, v41
	v_and_or_b32 v31, v49, s71, v31
	v_and_or_b32 v30, v50, s71, v30
	v_lshl_add_u64 v[42:43], v[46:47], 0, v[42:43]
	ds_read2_b32 v[44:45], v37 offset0:16 offset1:24
	ds_read2_b32 v[48:49], v37 offset0:82 offset1:90
	global_store_dwordx4 v[42:43], v[30:33], off sc0 sc1
	ds_read2_b32 v[42:43], v37 offset0:49 offset1:57
	ds_read2_b32 v[50:51], v37 offset0:115 offset1:123
	ds_read2_b32 v[52:53], v37 offset0:148 offset1:156
	ds_read2_b32 v[54:55], v37 offset0:214 offset1:222
	ds_read2_b32 v[56:57], v37 offset0:181 offset1:189
	ds_read2_b32 v[58:59], v37 offset0:247 offset1:255
	s_waitcnt lgkmcnt(7)
	v_mov_b32_e32 v30, v44
	s_waitcnt lgkmcnt(5)
	v_mov_b32_e32 v32, v42
	s_waitcnt lgkmcnt(4)
	v_mov_b32_e32 v33, v50
	s_waitcnt lgkmcnt(3)
	v_mov_b32_e32 v60, v52
	s_waitcnt lgkmcnt(2)
	v_mov_b32_e32 v61, v54
	s_waitcnt lgkmcnt(1)
	v_mov_b32_e32 v62, v56
	s_waitcnt lgkmcnt(0)
	v_mov_b32_e32 v63, v58
	v_mov_b32_e32 v31, v48
	v_pk_mul_f32 v[32:33], v[0:1], v[32:33]
	v_pk_mul_f32 v[60:61], v[6:7], v[60:61]
	v_pk_mul_f32 v[62:63], v[4:5], v[62:63]
	v_pk_mul_f32 v[30:31], v[2:3], v[30:31]
	v_bfe_u32 v41, v63, 16, 1
	v_bfe_u32 v42, v62, 16, 1
	v_bfe_u32 v44, v33, 16, 1
	v_bfe_u32 v48, v32, 16, 1
	v_bfe_u32 v50, v60, 16, 1
	v_add3_u32 v48, v32, v48, s81
	v_add3_u32 v44, v33, v44, s81
	v_add3_u32 v32, v62, v42, s81
	v_add3_u32 v33, v63, v41, s81
	v_bfe_u32 v41, v30, 16, 1
	v_bfe_u32 v42, v31, 16, 1
	v_bfe_u32 v52, v61, 16, 1
	v_add3_u32 v50, v60, v50, s81
	v_or_b32_e32 v60, s34, v39
	v_add3_u32 v52, v61, v52, s81
	v_add3_u32 v31, v31, v42, s81
	v_add3_u32 v30, v30, v41, s81
	v_ashrrev_i32_e32 v61, 31, v60
	v_lshrrev_b32_e32 v30, 16, v30
	v_lshrrev_b32_e32 v31, 16, v31
	v_lshrrev_b32_e32 v41, 16, v50
	v_lshrrev_b32_e32 v42, 16, v52
	v_lshlrev_b64 v[60:61], 11, v[60:61]
	v_mov_b32_e32 v50, v43
	v_mov_b32_e32 v58, v57
	v_and_or_b32 v33, v33, s71, v42
	v_and_or_b32 v32, v32, s71, v41
	v_and_or_b32 v31, v44, s71, v31
	v_and_or_b32 v30, v48, s71, v30
	v_lshl_add_u64 v[60:61], v[46:47], 0, v[60:61]
	v_mov_b32_e32 v48, v45
	v_pk_mul_f32 v[0:1], v[0:1], v[50:51]
	v_mov_b32_e32 v54, v53
	v_pk_mul_f32 v[4:5], v[4:5], v[58:59]
	global_store_dwordx4 v[60:61], v[30:33], off sc0 sc1
	v_pk_mul_f32 v[2:3], v[2:3], v[48:49]
	v_pk_mul_f32 v[6:7], v[6:7], v[54:55]
	v_bfe_u32 v30, v5, 16, 1
	v_bfe_u32 v32, v1, 16, 1
	v_bfe_u32 v31, v4, 16, 1
	v_bfe_u32 v33, v0, 16, 1
	v_add3_u32 v1, v1, v32, s81
	v_add3_u32 v5, v5, v30, s81
	v_bfe_u32 v30, v2, 16, 1
	v_bfe_u32 v32, v6, 16, 1
	v_add3_u32 v0, v0, v33, s81
	v_add3_u32 v4, v4, v31, s81
	v_bfe_u32 v31, v3, 16, 1
	v_bfe_u32 v33, v7, 16, 1
	v_add3_u32 v6, v6, v32, s81
	v_add3_u32 v2, v2, v30, s81
	v_add3_u32 v7, v7, v33, s81
	v_add3_u32 v3, v3, v31, s81
	v_lshrrev_b32_e32 v30, 16, v2
	v_lshrrev_b32_e32 v2, 16, v6
	v_lshrrev_b32_e32 v31, 16, v3
	v_lshrrev_b32_e32 v3, 16, v7
	v_and_or_b32 v2, v4, s71, v2
	v_or_b32_e32 v4, s34, v40
	v_and_or_b32 v3, v5, s71, v3
	v_ashrrev_i32_e32 v5, 31, v4
	v_lshlrev_b64 v[4:5], 11, v[4:5]
	v_and_or_b32 v1, v1, s71, v31
	v_and_or_b32 v0, v0, s71, v30
	v_lshl_add_u64 v[4:5], v[46:47], 0, v[4:5]
	global_store_dwordx4 v[4:5], v[0:3], off sc0 sc1
	s_waitcnt lgkmcnt(0)

.LBB0_480:
	s_andn2_b64 vcc, exec, s[0:1]
	s_cbranch_vccnz .LBB0_402
	s_mov_b64 s[0:1], -1
	s_cmpk_gt_i32 s42, 0xaff
	v_lshlrev_b32_e32 v96, 2, v8
	v_add_u32_e32 v30, 0x400, v35
	v_add_u32_e32 v7, 0x800, v35
	v_add_u32_e32 v6, 0xc00, v35
	v_add_u32_e32 v5, 0x1000, v35
	v_add_u32_e32 v4, 0x1400, v35
	s_waitcnt lgkmcnt(0)
	v_add_u32_e32 v3, 0x1800, v35
	v_add_u32_e32 v2, 0x1c00, v35
	s_cbranch_scc0 .LBB0_483
	s_and_b32 s0, s74, 0x7fffffc0
	s_addk_i32 s0, 0xea00
	v_or_b32_e32 v0, s0, v9
	v_mov_b32_e32 v1, v97
	v_readlane_b32 s40, v236, 62
	s_and_b32 s34, s72, 0x3e0
	v_lshlrev_b64 v[0:1], 12, v[0:1]
	v_readlane_b32 s41, v236, 63
	s_lshl_b32 s46, s34, 2
	s_movk_i32 s1, 0x4000
	v_lshl_add_u64 v[0:1], s[40:41], 0, v[0:1]
	v_lshl_add_u64 v[0:1], v[0:1], 0, s[46:47]
	v_lshl_add_u64 v[0:1], v[0:1], 0, v[96:97]
	v_add_co_u32_e32 v32, vcc, 0x2000, v0
	global_load_dword v31, v[0:1], off
	s_nop 0
	v_addc_co_u32_e32 v33, vcc, 0, v1, vcc
	global_load_dword v41, v[32:33], off
	v_add_co_u32_e32 v32, vcc, s1, v0
	s_mov_b32 s1, s47
	s_nop 0
	v_addc_co_u32_e32 v33, vcc, 0, v1, vcc
	global_load_dword v42, v[32:33], off
	v_add_co_u32_e32 v32, vcc, 0x6000, v0
	s_nop 1
	v_addc_co_u32_e32 v33, vcc, 0, v1, vcc
	global_load_dword v43, v[32:33], off
	v_add_co_u32_e32 v32, vcc, 0x8000, v0
	s_nop 1
	v_addc_co_u32_e32 v33, vcc, 0, v1, vcc
	global_load_dword v44, v[32:33], off
	v_add_co_u32_e32 v32, vcc, 0xa000, v0
	s_nop 1
	v_addc_co_u32_e32 v33, vcc, 0, v1, vcc
	global_load_dword v45, v[32:33], off
	v_add_co_u32_e32 v32, vcc, 0xc000, v0
	s_nop 1
	v_addc_co_u32_e32 v33, vcc, 0, v1, vcc
	global_load_dword v46, v[32:33], off
	v_add_co_u32_e32 v32, vcc, 0xe000, v0
	s_nop 1
	v_addc_co_u32_e32 v33, vcc, 0, v1, vcc
	global_load_dword v47, v[32:33], off
	v_add_co_u32_e32 v32, vcc, 0x10000, v0
	s_nop 1
	v_addc_co_u32_e32 v33, vcc, 0, v1, vcc
	global_load_dword v48, v[32:33], off
	v_add_co_u32_e32 v32, vcc, 0x12000, v0
	s_nop 1
	v_addc_co_u32_e32 v33, vcc, 0, v1, vcc
	global_load_dword v49, v[32:33], off
	v_add_co_u32_e32 v32, vcc, 0x14000, v0
	s_nop 1
	v_addc_co_u32_e32 v33, vcc, 0, v1, vcc
	global_load_dword v50, v[32:33], off
	v_add_co_u32_e32 v32, vcc, 0x16000, v0
	s_nop 1
	v_addc_co_u32_e32 v33, vcc, 0, v1, vcc
	global_load_dword v51, v[32:33], off
	v_add_co_u32_e32 v32, vcc, 0x18000, v0
	s_nop 1
	v_addc_co_u32_e32 v33, vcc, 0, v1, vcc
	global_load_dword v52, v[32:33], off
	v_add_co_u32_e32 v32, vcc, 0x1a000, v0
	s_nop 1
	v_addc_co_u32_e32 v33, vcc, 0, v1, vcc
	global_load_dword v53, v[32:33], off
	v_add_co_u32_e32 v32, vcc, 0x1c000, v0
	s_nop 1
	v_addc_co_u32_e32 v33, vcc, 0, v1, vcc
	global_load_dword v54, v[32:33], off
	v_add_co_u32_e32 v32, vcc, 0x1e000, v0
	s_nop 1
	v_addc_co_u32_e32 v33, vcc, 0, v1, vcc
	global_load_dword v55, v[32:33], off
	v_add_co_u32_e32 v32, vcc, 0x20000, v0
	s_nop 1
	v_addc_co_u32_e32 v33, vcc, 0, v1, vcc
	global_load_dword v56, v[32:33], off
	v_add_co_u32_e32 v32, vcc, 0x22000, v0
	s_nop 1
	v_addc_co_u32_e32 v33, vcc, 0, v1, vcc
	global_load_dword v57, v[32:33], off
	v_add_co_u32_e32 v32, vcc, 0x24000, v0
	s_nop 1
	v_addc_co_u32_e32 v33, vcc, 0, v1, vcc
	global_load_dword v58, v[32:33], off
	v_add_co_u32_e32 v32, vcc, 0x26000, v0
	s_nop 1
	v_addc_co_u32_e32 v33, vcc, 0, v1, vcc
	global_load_dword v59, v[32:33], off
	v_add_co_u32_e32 v32, vcc, 0x28000, v0
	s_nop 1
	v_addc_co_u32_e32 v33, vcc, 0, v1, vcc
	global_load_dword v60, v[32:33], off
	v_add_co_u32_e32 v32, vcc, 0x2a000, v0
	s_nop 1
	v_addc_co_u32_e32 v33, vcc, 0, v1, vcc
	global_load_dword v61, v[32:33], off
	v_add_co_u32_e32 v32, vcc, 0x2c000, v0
	s_nop 1
	v_addc_co_u32_e32 v33, vcc, 0, v1, vcc
	global_load_dword v62, v[32:33], off
	v_add_co_u32_e32 v32, vcc, 0x2e000, v0
	s_nop 1
	v_addc_co_u32_e32 v33, vcc, 0, v1, vcc
	global_load_dword v63, v[32:33], off
	v_add_co_u32_e32 v32, vcc, 0x30000, v0
	s_nop 1
	v_addc_co_u32_e32 v33, vcc, 0, v1, vcc
	global_load_dword v64, v[32:33], off
	v_add_co_u32_e32 v32, vcc, 0x32000, v0
	s_nop 1
	v_addc_co_u32_e32 v33, vcc, 0, v1, vcc
	global_load_dword v65, v[32:33], off
	v_add_co_u32_e32 v32, vcc, 0x34000, v0
	s_nop 1
	v_addc_co_u32_e32 v33, vcc, 0, v1, vcc
	global_load_dword v66, v[32:33], off
	v_add_co_u32_e32 v32, vcc, 0x36000, v0
	s_nop 1
	v_addc_co_u32_e32 v33, vcc, 0, v1, vcc
	global_load_dword v67, v[32:33], off
	v_add_co_u32_e32 v32, vcc, 0x38000, v0
	s_nop 1
	v_addc_co_u32_e32 v33, vcc, 0, v1, vcc
	global_load_dword v68, v[32:33], off
	v_add_co_u32_e32 v32, vcc, 0x3a000, v0
	s_nop 1
	v_addc_co_u32_e32 v33, vcc, 0, v1, vcc
	global_load_dword v69, v[32:33], off
	v_add_co_u32_e32 v32, vcc, 0x3c000, v0
	s_nop 1
	v_addc_co_u32_e32 v33, vcc, 0, v1, vcc
	v_add_co_u32_e32 v0, vcc, 0x3e000, v0
	global_load_dword v32, v[32:33], off
	s_nop 0
	v_addc_co_u32_e32 v1, vcc, 0, v1, vcc
	global_load_dword v0, v[0:1], off
	s_waitcnt vmcnt(0)
	ds_write2_b32 v35, v31, v41 offset1:66
	ds_write2_b32 v35, v42, v43 offset0:132 offset1:198
	ds_write2_b32 v30, v44, v45 offset0:8 offset1:74
	ds_write2_b32 v30, v46, v47 offset0:140 offset1:206
	ds_write2_b32 v7, v48, v49 offset0:16 offset1:82
	ds_write2_b32 v7, v50, v51 offset0:148 offset1:214
	ds_write2_b32 v6, v52, v53 offset0:24 offset1:90
	ds_write2_b32 v6, v54, v55 offset0:156 offset1:222
	ds_write2_b32 v5, v56, v57 offset0:32 offset1:98
	ds_write2_b32 v5, v58, v59 offset0:164 offset1:230
	ds_write2_b32 v4, v60, v61 offset0:40 offset1:106
	ds_write2_b32 v4, v62, v63 offset0:172 offset1:238
	ds_write2_b32 v3, v64, v65 offset0:48 offset1:114
	ds_write2_b32 v3, v66, v67 offset0:180 offset1:246
	ds_write2_b32 v2, v68, v69 offset0:56 offset1:122
	ds_write2_b32 v2, v32, v0 offset0:188 offset1:254
	s_waitcnt lgkmcnt(0)
	ds_read2_b32 v[32:33], v37 offset0:33 offset1:41
	ds_read2_b32 v[46:47], v37 offset1:8
	ds_read2_b32 v[48:49], v37 offset0:66 offset1:74
	ds_read2_b32 v[50:51], v37 offset0:99 offset1:107
	ds_read2_b32 v[52:53], v37 offset0:132 offset1:140
	ds_read2_b32 v[54:55], v37 offset0:165 offset1:173
	ds_read2_b32 v[56:57], v37 offset0:198 offset1:206
	ds_read2_b32 v[58:59], v37 offset0:231 offset1:239
	s_waitcnt lgkmcnt(7)
	v_bfe_u32 v41, v32, 16, 1
	s_waitcnt lgkmcnt(6)
	v_bfe_u32 v31, v46, 16, 1
	v_add3_u32 v31, v46, v31, s81
	v_lshrrev_b32_e32 v31, 16, v31
	v_add3_u32 v32, v32, v41, s81
	v_and_or_b32 v42, v32, s71, v31
	s_waitcnt lgkmcnt(5)
	v_bfe_u32 v31, v48, 16, 1
	v_add3_u32 v31, v48, v31, s81
	s_waitcnt lgkmcnt(4)
	v_bfe_u32 v32, v50, 16, 1
	v_lshrrev_b32_e32 v31, 16, v31
	v_add3_u32 v32, v50, v32, s81
	v_and_or_b32 v43, v32, s71, v31
	s_waitcnt lgkmcnt(3)
	v_bfe_u32 v31, v52, 16, 1
	v_add3_u32 v31, v52, v31, s81
	s_waitcnt lgkmcnt(2)
	v_bfe_u32 v32, v54, 16, 1
	v_lshrrev_b32_e32 v31, 16, v31
	v_add3_u32 v32, v54, v32, s81
	v_and_or_b32 v44, v32, s71, v31
	s_waitcnt lgkmcnt(1)
	v_bfe_u32 v31, v56, 16, 1
	v_add3_u32 v31, v56, v31, s81
	s_waitcnt lgkmcnt(0)
	v_bfe_u32 v32, v58, 16, 1
	v_lshrrev_b32_e32 v31, 16, v31
	v_add3_u32 v32, v58, v32, s81
	v_and_or_b32 v45, v32, s71, v31
	v_or_b32_e32 v31, s34, v36
	v_mul_u32_u24_e32 v31, 0xb00, v31
	v_lshlrev_b32_e32 v60, 1, v31
	v_bfe_u32 v31, v47, 16, 1
	v_lshl_add_u64 v[0:1], s[0:1], 1, v[26:27]
	v_mov_b32_e32 v61, v97
	v_add3_u32 v31, v47, v31, s81
	v_bfe_u32 v32, v33, 16, 1
	v_lshl_add_u64 v[60:61], v[0:1], 0, v[60:61]
	v_lshrrev_b32_e32 v31, 16, v31
	v_add3_u32 v32, v33, v32, s81
	global_store_dwordx4 v[60:61], v[42:45], off sc0 sc1
	v_mov_b32_e32 v33, v97
	v_mov_b32_e32 v61, v97
	v_and_or_b32 v42, v32, s71, v31
	v_bfe_u32 v31, v49, 16, 1
	v_add3_u32 v31, v49, v31, s81
	v_bfe_u32 v32, v51, 16, 1
	v_lshrrev_b32_e32 v31, 16, v31
	v_add3_u32 v32, v51, v32, s81
	v_and_or_b32 v43, v32, s71, v31
	v_bfe_u32 v31, v53, 16, 1
	v_add3_u32 v31, v53, v31, s81
	v_bfe_u32 v32, v55, 16, 1
	v_lshrrev_b32_e32 v31, 16, v31
	v_add3_u32 v32, v55, v32, s81
	v_and_or_b32 v44, v32, s71, v31
	v_bfe_u32 v31, v57, 16, 1
	v_add3_u32 v31, v57, v31, s81
	v_bfe_u32 v32, v59, 16, 1
	v_lshrrev_b32_e32 v31, 16, v31
	v_add3_u32 v32, v59, v32, s81
	v_and_or_b32 v45, v32, s71, v31
	v_or_b32_e32 v31, s34, v38
	v_mul_u32_u24_e32 v31, 0xb00, v31
	v_lshlrev_b32_e32 v32, 1, v31
	v_lshl_add_u64 v[32:33], v[0:1], 0, v[32:33]
	global_store_dwordx4 v[32:33], v[42:45], off sc0 sc1
	ds_read2_b32 v[32:33], v37 offset0:16 offset1:24
	ds_read2_b32 v[46:47], v37 offset0:49 offset1:57
	ds_read2_b32 v[48:49], v37 offset0:82 offset1:90
	ds_read2_b32 v[50:51], v37 offset0:115 offset1:123
	ds_read2_b32 v[52:53], v37 offset0:148 offset1:156
	ds_read2_b32 v[54:55], v37 offset0:181 offset1:189
	ds_read2_b32 v[56:57], v37 offset0:214 offset1:222
	ds_read2_b32 v[58:59], v37 offset0:247 offset1:255
	s_waitcnt lgkmcnt(7)
	v_bfe_u32 v31, v32, 16, 1
	v_add3_u32 v31, v32, v31, s81
	s_waitcnt lgkmcnt(6)
	v_bfe_u32 v32, v46, 16, 1
	v_lshrrev_b32_e32 v31, 16, v31
	v_add3_u32 v32, v46, v32, s81
	v_and_or_b32 v42, v32, s71, v31
	s_waitcnt lgkmcnt(5)
	v_bfe_u32 v31, v48, 16, 1
	v_add3_u32 v31, v48, v31, s81
	s_waitcnt lgkmcnt(4)
	v_bfe_u32 v32, v50, 16, 1
	v_lshrrev_b32_e32 v31, 16, v31
	v_add3_u32 v32, v50, v32, s81
	v_and_or_b32 v43, v32, s71, v31
	s_waitcnt lgkmcnt(3)
	v_bfe_u32 v31, v52, 16, 1
	v_add3_u32 v31, v52, v31, s81
	s_waitcnt lgkmcnt(2)
	v_bfe_u32 v32, v54, 16, 1
	v_lshrrev_b32_e32 v31, 16, v31
	v_add3_u32 v32, v54, v32, s81
	v_and_or_b32 v44, v32, s71, v31
	s_waitcnt lgkmcnt(1)
	v_bfe_u32 v31, v56, 16, 1
	v_add3_u32 v31, v56, v31, s81
	s_waitcnt lgkmcnt(0)
	v_bfe_u32 v32, v58, 16, 1
	v_lshrrev_b32_e32 v31, 16, v31
	v_add3_u32 v32, v58, v32, s81
	v_and_or_b32 v45, v32, s71, v31
	v_or_b32_e32 v31, s34, v39
	v_mul_u32_u24_e32 v31, 0xb00, v31
	v_lshlrev_b32_e32 v60, 1, v31
	v_bfe_u32 v31, v33, 16, 1
	v_add3_u32 v31, v33, v31, s81
	v_bfe_u32 v32, v47, 16, 1
	v_lshl_add_u64 v[60:61], v[0:1], 0, v[60:61]
	v_lshrrev_b32_e32 v31, 16, v31
	v_add3_u32 v32, v47, v32, s81
	global_store_dwordx4 v[60:61], v[42:45], off sc0 sc1
	v_mov_b32_e32 v33, v97
	s_mov_b64 s[0:1], 0
	v_and_or_b32 v42, v32, s71, v31
	v_bfe_u32 v31, v49, 16, 1
	v_add3_u32 v31, v49, v31, s81
	v_bfe_u32 v32, v51, 16, 1
	v_lshrrev_b32_e32 v31, 16, v31
	v_add3_u32 v32, v51, v32, s81
	v_and_or_b32 v43, v32, s71, v31
	v_bfe_u32 v31, v53, 16, 1
	v_add3_u32 v31, v53, v31, s81
	v_bfe_u32 v32, v55, 16, 1
	v_lshrrev_b32_e32 v31, 16, v31
	v_add3_u32 v32, v55, v32, s81
	v_and_or_b32 v44, v32, s71, v31
	v_bfe_u32 v31, v57, 16, 1
	v_add3_u32 v31, v57, v31, s81
	v_bfe_u32 v32, v59, 16, 1
	v_lshrrev_b32_e32 v31, 16, v31
	v_add3_u32 v32, v59, v32, s81
	v_and_or_b32 v45, v32, s71, v31
	v_or_b32_e32 v31, s34, v40
	v_mul_u32_u24_e32 v31, 0xb00, v31
	v_lshlrev_b32_e32 v32, 1, v31
	v_lshl_add_u64 v[0:1], v[0:1], 0, v[32:33]
	global_store_dwordx4 v[0:1], v[42:45], off sc0 sc1
	s_waitcnt lgkmcnt(0)
.LBB0_483:
	s_andn2_b64 vcc, exec, s[0:1]
	s_cbranch_vccnz .LBB0_402
	s_mul_hi_i32 s0, s42, 0x2e8ba2e9
	s_lshr_b32 s1, s0, 31
	s_ashr_i32 s0, s0, 5
	s_add_i32 s1, s0, s1
	s_lshl_b32 s0, s1, 6
	s_mul_i32 s34, s1, 0xffffea00
	s_mulk_i32 s1, 0xf500
	s_bfe_i32 s35, s42, 0x10002
	s_add_i32 s1, s73, s1
	s_add_i32 s34, s72, s34
	s_and_b32 s35, s35, 0xb00
	s_and_b32 s1, s1, 0xffffff80
	v_readlane_b32 s48, v235, 0
	s_add_i32 s35, s35, s1
	s_and_b32 s1, s34, 0x60
	v_readlane_b32 s49, v235, 1
	s_or_b32 s40, s35, s1
	v_or_b32_e32 v31, s0, v9
	v_mov_b64_e32 v[0:1], s[48:49]
	s_movk_i32 s1, 0x5800
	v_mad_i64_i32 v[0:1], s[48:49], v31, s1, v[0:1]
	s_ashr_i32 s41, s40, 31
	v_lshl_add_u64 v[0:1], s[40:41], 2, v[0:1]
	v_lshl_add_u64 v[0:1], v[0:1], 0, v[96:97]
	s_mov_b32 s1, 0xb000
	v_add_co_u32_e32 v32, vcc, s1, v0
	s_mov_b32 s1, 0x16000
	s_nop 0
	v_addc_co_u32_e32 v33, vcc, 0, v1, vcc
	global_load_dword v31, v[0:1], off
	global_load_dword v41, v[32:33], off
	v_add_co_u32_e32 v32, vcc, s1, v0
	s_mov_b32 s1, 0x21000
	s_nop 0
	v_addc_co_u32_e32 v33, vcc, 0, v1, vcc
	global_load_dword v42, v[32:33], off
	v_add_co_u32_e32 v32, vcc, s1, v0
	s_mov_b32 s1, 0x2c000
	s_nop 0
	v_addc_co_u32_e32 v33, vcc, 0, v1, vcc
	global_load_dword v43, v[32:33], off
	v_add_co_u32_e32 v32, vcc, s1, v0
	s_mov_b32 s1, 0x37000
	s_nop 0
	v_addc_co_u32_e32 v33, vcc, 0, v1, vcc
	global_load_dword v44, v[32:33], off
	v_add_co_u32_e32 v32, vcc, s1, v0
	s_mov_b32 s1, 0x42000
	s_nop 0
	v_addc_co_u32_e32 v33, vcc, 0, v1, vcc
	global_load_dword v45, v[32:33], off
	v_add_co_u32_e32 v32, vcc, s1, v0
	s_mov_b32 s1, 0x4d000
	s_nop 0
	v_addc_co_u32_e32 v33, vcc, 0, v1, vcc
	global_load_dword v46, v[32:33], off
	v_add_co_u32_e32 v32, vcc, s1, v0
	s_mov_b32 s1, 0x58000
	s_nop 0
	v_addc_co_u32_e32 v33, vcc, 0, v1, vcc
	global_load_dword v47, v[32:33], off
	v_add_co_u32_e32 v32, vcc, s1, v0
	s_mov_b32 s1, 0x63000
	s_nop 0
	v_addc_co_u32_e32 v33, vcc, 0, v1, vcc
	global_load_dword v48, v[32:33], off
	v_add_co_u32_e32 v32, vcc, s1, v0
	s_mov_b32 s1, 0x6e000
	s_nop 0
	v_addc_co_u32_e32 v33, vcc, 0, v1, vcc
	global_load_dword v49, v[32:33], off
	v_add_co_u32_e32 v32, vcc, s1, v0
	s_mov_b32 s1, 0x79000
	s_nop 0
	v_addc_co_u32_e32 v33, vcc, 0, v1, vcc
	global_load_dword v50, v[32:33], off
	v_add_co_u32_e32 v32, vcc, s1, v0
	s_mov_b32 s1, 0x84000
	s_nop 0
	v_addc_co_u32_e32 v33, vcc, 0, v1, vcc
	global_load_dword v51, v[32:33], off
	v_add_co_u32_e32 v32, vcc, s1, v0
	s_mov_b32 s1, 0x8f000
	s_nop 0
	v_addc_co_u32_e32 v33, vcc, 0, v1, vcc
	global_load_dword v52, v[32:33], off
	v_add_co_u32_e32 v32, vcc, s1, v0
	s_mov_b32 s1, 0x9a000
	s_nop 0
	v_addc_co_u32_e32 v33, vcc, 0, v1, vcc
	global_load_dword v53, v[32:33], off
	v_add_co_u32_e32 v32, vcc, s1, v0
	s_mov_b32 s1, 0xa5000
	s_nop 0
	v_addc_co_u32_e32 v33, vcc, 0, v1, vcc
	global_load_dword v54, v[32:33], off
	v_add_co_u32_e32 v32, vcc, s1, v0
	s_mov_b32 s1, 0xb0000
	s_nop 0
	v_addc_co_u32_e32 v33, vcc, 0, v1, vcc
	global_load_dword v55, v[32:33], off
	v_add_co_u32_e32 v32, vcc, s1, v0
	s_mov_b32 s1, 0xbb000
	s_nop 0
	v_addc_co_u32_e32 v33, vcc, 0, v1, vcc
	global_load_dword v56, v[32:33], off
	v_add_co_u32_e32 v32, vcc, s1, v0
	s_mov_b32 s1, 0xc6000
	s_nop 0
	v_addc_co_u32_e32 v33, vcc, 0, v1, vcc
	global_load_dword v57, v[32:33], off
	v_add_co_u32_e32 v32, vcc, s1, v0
	s_mov_b32 s1, 0xd1000
	s_nop 0
	v_addc_co_u32_e32 v33, vcc, 0, v1, vcc
	global_load_dword v58, v[32:33], off
	v_add_co_u32_e32 v32, vcc, s1, v0
	s_mov_b32 s1, 0xdc000
	s_nop 0
	v_addc_co_u32_e32 v33, vcc, 0, v1, vcc
	global_load_dword v59, v[32:33], off
	v_add_co_u32_e32 v32, vcc, s1, v0
	s_mov_b32 s1, 0xe7000
	s_nop 0
	v_addc_co_u32_e32 v33, vcc, 0, v1, vcc
	global_load_dword v60, v[32:33], off
	v_add_co_u32_e32 v32, vcc, s1, v0
	s_mov_b32 s1, 0xf2000
	s_nop 0
	v_addc_co_u32_e32 v33, vcc, 0, v1, vcc
	global_load_dword v61, v[32:33], off
	v_add_co_u32_e32 v32, vcc, s1, v0
	s_mov_b32 s1, 0xfd000
	s_nop 0
	v_addc_co_u32_e32 v33, vcc, 0, v1, vcc
	global_load_dword v62, v[32:33], off
	v_add_co_u32_e32 v32, vcc, s1, v0
	s_mov_b32 s1, 0x108000
	s_nop 0
	v_addc_co_u32_e32 v33, vcc, 0, v1, vcc
	global_load_dword v63, v[32:33], off
	v_add_co_u32_e32 v32, vcc, s1, v0
	s_mov_b32 s1, 0x113000
	s_nop 0
	v_addc_co_u32_e32 v33, vcc, 0, v1, vcc
	global_load_dword v64, v[32:33], off
	v_add_co_u32_e32 v32, vcc, s1, v0
	s_mov_b32 s1, 0x11e000
	s_nop 0
	v_addc_co_u32_e32 v33, vcc, 0, v1, vcc
	global_load_dword v65, v[32:33], off
	v_add_co_u32_e32 v32, vcc, s1, v0
	s_mov_b32 s1, 0x129000
	s_nop 0
	v_addc_co_u32_e32 v33, vcc, 0, v1, vcc
	global_load_dword v66, v[32:33], off
	v_add_co_u32_e32 v32, vcc, s1, v0
	s_mov_b32 s1, 0x134000
	s_nop 0
	v_addc_co_u32_e32 v33, vcc, 0, v1, vcc
	global_load_dword v67, v[32:33], off
	v_add_co_u32_e32 v32, vcc, s1, v0
	s_mov_b32 s1, 0x13f000
	s_nop 0
	v_addc_co_u32_e32 v33, vcc, 0, v1, vcc
	global_load_dword v68, v[32:33], off
	v_add_co_u32_e32 v32, vcc, s1, v0
	s_mov_b32 s1, 0x14a000
	s_nop 0
	v_addc_co_u32_e32 v33, vcc, 0, v1, vcc
	global_load_dword v69, v[32:33], off
	v_add_co_u32_e32 v32, vcc, s1, v0
	s_mov_b32 s1, 0x155000
	s_nop 0
	v_addc_co_u32_e32 v33, vcc, 0, v1, vcc
	v_add_co_u32_e32 v0, vcc, s1, v0
	global_load_dword v32, v[32:33], off
	s_nop 0
	v_addc_co_u32_e32 v1, vcc, 0, v1, vcc
	global_load_dword v0, v[0:1], off
	s_and_b32 s1, s0, 0x3c0
	v_or_b32_e32 v1, s1, v34
	s_ashr_i32 s1, s0, 31
	s_waitcnt vmcnt(0)
	ds_write2_b32 v35, v31, v41 offset1:66
	ds_write2_b32 v35, v42, v43 offset0:132 offset1:198
	ds_write2_b32 v30, v44, v45 offset0:8 offset1:74
	ds_write2_b32 v30, v46, v47 offset0:140 offset1:206
	ds_write2_b32 v7, v48, v49 offset0:16 offset1:82
	ds_write2_b32 v7, v50, v51 offset0:148 offset1:214
	ds_write2_b32 v6, v52, v53 offset0:24 offset1:90
	ds_write2_b32 v6, v54, v55 offset0:156 offset1:222
	ds_write2_b32 v5, v56, v57 offset0:32 offset1:98
	ds_write2_b32 v5, v58, v59 offset0:164 offset1:230
	ds_write2_b32 v4, v60, v61 offset0:40 offset1:106
	ds_write2_b32 v4, v62, v63 offset0:172 offset1:238
	ds_write2_b32 v3, v64, v65 offset0:48 offset1:114
	ds_write2_b32 v3, v66, v67 offset0:180 offset1:246
	ds_write2_b32 v2, v68, v69 offset0:56 offset1:122
	ds_write2_b32 v2, v32, v0 offset0:188 offset1:254
	v_lshl_add_u64 v[30:31], s[0:1], 1, v[28:29]
	v_readlane_b32 s0, v235, 2
	v_lshlrev_b32_e32 v33, 2, v1
	v_readlane_b32 s1, v235, 3
	s_nop 4
	global_load_dwordx4 v[0:3], v33, s[0:1] offset:16
	global_load_dwordx4 v[4:7], v33, s[0:1]
	s_waitcnt lgkmcnt(0)
	s_waitcnt vmcnt(1)
	v_mov_b32_e32 v58, v0
	s_waitcnt vmcnt(0)
	v_mov_b32_e32 v32, v4
	v_mov_b32_e32 v33, v6
	v_mov_b32_e32 v6, v5
	ds_read2_b32 v[4:5], v37 offset0:33 offset1:41
	ds_read2_b32 v[46:47], v37 offset0:66 offset1:74
	ds_read2_b32 v[48:49], v37 offset1:8
	ds_read2_b32 v[50:51], v37 offset0:99 offset1:107
	ds_read2_b32 v[52:53], v37 offset0:132 offset1:140
	ds_read2_b32 v[54:55], v37 offset0:165 offset1:173
	ds_read2_b32 v[56:57], v37 offset0:198 offset1:206
	ds_read2_b32 v[62:63], v37 offset0:231 offset1:239
	s_waitcnt lgkmcnt(7)
	v_mov_b32_e32 v44, v4
	v_mov_b32_e32 v59, v2
	s_waitcnt lgkmcnt(4)
	v_mov_b32_e32 v45, v50
	v_pk_mul_f32 v[44:45], v[6:7], v[44:45]
	s_waitcnt lgkmcnt(3)
	v_mov_b32_e32 v60, v52
	s_waitcnt lgkmcnt(1)
	v_mov_b32_e32 v61, v56
	v_mov_b32_e32 v2, v1
	v_mov_b32_e32 v0, v54
	s_waitcnt lgkmcnt(0)
	v_mov_b32_e32 v1, v62
	v_mov_b32_e32 v42, v48
	v_mov_b32_e32 v43, v46
	v_pk_mul_f32 v[60:61], v[58:59], v[60:61]
	v_pk_mul_f32 v[0:1], v[2:3], v[0:1]
	v_bfe_u32 v46, v45, 16, 1
	v_bfe_u32 v48, v44, 16, 1
	v_pk_mul_f32 v[42:43], v[32:33], v[42:43]
	v_bfe_u32 v4, v1, 16, 1
	v_bfe_u32 v41, v0, 16, 1
	v_add3_u32 v48, v44, v48, s81
	v_add3_u32 v46, v45, v46, s81
	v_bfe_u32 v44, v60, 16, 1
	v_bfe_u32 v45, v61, 16, 1
	v_add3_u32 v0, v0, v41, s81
	v_add3_u32 v1, v1, v4, s81
	v_bfe_u32 v4, v42, 16, 1
	v_bfe_u32 v41, v43, 16, 1
	v_add3_u32 v45, v61, v45, s81
	v_add3_u32 v44, v60, v44, s81
	v_add_u32_e32 v60, s34, v36
	v_add3_u32 v41, v43, v41, s81
	v_add3_u32 v4, v42, v4, s81
	v_lshrrev_b32_e32 v42, 16, v44
	v_lshrrev_b32_e32 v43, 16, v45
	v_ashrrev_i32_e32 v61, 31, v60
	v_lshrrev_b32_e32 v4, 16, v4
	v_lshrrev_b32_e32 v41, 16, v41
	v_and_or_b32 v45, v1, s71, v43
	v_and_or_b32 v44, v0, s71, v42
	v_lshlrev_b64 v[0:1], 11, v[60:61]
	v_and_or_b32 v43, v46, s71, v41
	v_and_or_b32 v42, v48, s71, v4
	v_lshl_add_u64 v[0:1], v[30:31], 0, v[0:1]
	v_mov_b32_e32 v50, v5
	v_mov_b32_e32 v62, v55
	global_store_dwordx4 v[0:1], v[42:45], off sc0 sc1
	v_mov_b32_e32 v46, v49
	v_pk_mul_f32 v[4:5], v[6:7], v[50:51]
	v_mov_b32_e32 v56, v53
	v_pk_mul_f32 v[44:45], v[2:3], v[62:63]
	v_pk_mul_f32 v[0:1], v[32:33], v[46:47]
	v_pk_mul_f32 v[42:43], v[58:59], v[56:57]
	v_bfe_u32 v41, v45, 16, 1
	v_bfe_u32 v47, v5, 16, 1
	v_bfe_u32 v46, v44, 16, 1
	v_bfe_u32 v48, v4, 16, 1
	v_add3_u32 v5, v5, v47, s81
	v_add3_u32 v41, v45, v41, s81
	v_bfe_u32 v45, v0, 16, 1
	v_bfe_u32 v47, v42, 16, 1
	v_add3_u32 v4, v4, v48, s81
	v_add3_u32 v44, v44, v46, s81
	v_bfe_u32 v46, v1, 16, 1
	v_bfe_u32 v48, v43, 16, 1
	v_add3_u32 v42, v42, v47, s81
	v_add3_u32 v0, v0, v45, s81
	v_add3_u32 v43, v43, v48, s81
	v_add3_u32 v1, v1, v46, s81
	v_lshrrev_b32_e32 v0, 16, v0
	v_lshrrev_b32_e32 v42, 16, v42
	v_lshrrev_b32_e32 v1, 16, v1
	v_lshrrev_b32_e32 v43, 16, v43
	v_and_or_b32 v44, v44, s71, v42
	v_and_or_b32 v42, v4, s71, v0
	v_add_u32_e32 v0, 8, v60
	v_and_or_b32 v45, v41, s71, v43
	v_and_or_b32 v43, v5, s71, v1
	v_ashrrev_i32_e32 v1, 31, v0
	v_lshlrev_b64 v[0:1], 11, v[0:1]
	v_lshl_add_u64 v[0:1], v[30:31], 0, v[0:1]
	global_store_dwordx4 v[0:1], v[42:45], off sc0 sc1
	ds_read2_b32 v[0:1], v37 offset0:49 offset1:57
	ds_read2_b32 v[4:5], v37 offset0:82 offset1:90
	ds_read2_b32 v[46:47], v37 offset0:115 offset1:123
	ds_read2_b32 v[48:49], v37 offset0:16 offset1:24
	ds_read2_b32 v[50:51], v37 offset0:148 offset1:156
	ds_read2_b32 v[52:53], v37 offset0:181 offset1:189
	ds_read2_b32 v[54:55], v37 offset0:214 offset1:222
	ds_read2_b32 v[56:57], v37 offset0:247 offset1:255
	s_waitcnt lgkmcnt(7)
	v_mov_b32_e32 v44, v0
	s_waitcnt lgkmcnt(3)
	v_mov_b32_e32 v62, v50
	v_mov_b32_e32 v45, v46
	s_waitcnt lgkmcnt(1)
	v_mov_b32_e32 v63, v54
	v_mov_b32_e32 v42, v48
	v_mov_b32_e32 v43, v4
	v_pk_mul_f32 v[44:45], v[6:7], v[44:45]
	v_pk_mul_f32 v[62:63], v[58:59], v[62:63]
	v_mov_b32_e32 v64, v52
	s_waitcnt lgkmcnt(0)
	v_mov_b32_e32 v65, v56
	v_pk_mul_f32 v[42:43], v[32:33], v[42:43]
	v_pk_mul_f32 v[64:65], v[2:3], v[64:65]
	v_bfe_u32 v46, v44, 16, 1
	v_bfe_u32 v48, v62, 16, 1
	v_bfe_u32 v4, v64, 16, 1
	v_bfe_u32 v41, v45, 16, 1
	v_add3_u32 v46, v44, v46, s81
	v_bfe_u32 v44, v42, 16, 1
	v_add3_u32 v48, v62, v48, s81
	v_add3_u32 v41, v45, v41, s81
	v_add3_u32 v4, v64, v4, s81
	v_bfe_u32 v45, v43, 16, 1
	v_bfe_u32 v50, v63, 16, 1
	v_add3_u32 v42, v42, v44, s81
	v_lshrrev_b32_e32 v44, 16, v48
	v_add_u32_e32 v62, 16, v60
	v_mov_b32_e32 v56, v53
	v_bfe_u32 v0, v65, 16, 1
	v_add3_u32 v50, v63, v50, s81
	v_add3_u32 v43, v43, v45, s81
	v_lshrrev_b32_e32 v42, 16, v42
	v_and_or_b32 v44, v4, s71, v44
	v_ashrrev_i32_e32 v63, 31, v62
	v_mov_b32_e32 v4, v49
	v_pk_mul_f32 v[2:3], v[2:3], v[56:57]
	v_add3_u32 v0, v65, v0, s81
	v_lshrrev_b32_e32 v43, 16, v43
	v_lshrrev_b32_e32 v45, 16, v50
	v_and_or_b32 v42, v46, s71, v42
	v_lshlrev_b64 v[62:63], 11, v[62:63]
	v_pk_mul_f32 v[4:5], v[32:33], v[4:5]
	v_mov_b32_e32 v46, v1
	v_bfe_u32 v32, v3, 16, 1
	v_and_or_b32 v45, v0, s71, v45
	v_and_or_b32 v43, v41, s71, v43
	v_lshl_add_u64 v[62:63], v[30:31], 0, v[62:63]
	v_pk_mul_f32 v[0:1], v[6:7], v[46:47]
	v_bfe_u32 v33, v2, 16, 1
	v_add3_u32 v3, v3, v32, s81
	v_bfe_u32 v32, v4, 16, 1
	global_store_dwordx4 v[62:63], v[42:45], off sc0 sc1
	v_mov_b32_e32 v54, v51
	v_add3_u32 v2, v2, v33, s81
	v_bfe_u32 v42, v0, 16, 1
	v_bfe_u32 v33, v5, 16, 1
	v_add3_u32 v4, v4, v32, s81
	v_pk_mul_f32 v[6:7], v[58:59], v[54:55]
	v_bfe_u32 v41, v1, 16, 1
	v_add3_u32 v0, v0, v42, s81
	v_add3_u32 v5, v5, v33, s81
	v_lshrrev_b32_e32 v4, 16, v4
	v_add3_u32 v1, v1, v41, s81
	v_bfe_u32 v41, v6, 16, 1
	v_bfe_u32 v42, v7, 16, 1
	v_lshrrev_b32_e32 v5, 16, v5
	v_and_or_b32 v0, v0, s71, v4
	v_add_u32_e32 v4, 24, v60
	v_add3_u32 v7, v7, v42, s81
	v_add3_u32 v6, v6, v41, s81
	v_and_or_b32 v1, v1, s71, v5
	v_ashrrev_i32_e32 v5, 31, v4
	v_lshrrev_b32_e32 v6, 16, v6
	v_lshrrev_b32_e32 v7, 16, v7
	v_lshlrev_b64 v[4:5], 11, v[4:5]
	v_and_or_b32 v3, v3, s71, v7
	v_and_or_b32 v2, v2, s71, v6
	v_lshl_add_u64 v[4:5], v[30:31], 0, v[4:5]
	global_store_dwordx4 v[4:5], v[0:3], off sc0 sc1
	s_waitcnt lgkmcnt(0)
	s_branch .LBB0_402
